# outproj 2x2 wave tiling (64x64 per wave: 8 instead of 10 LDS fragment reads per 16 MFMAs), epilogue transposes 32x64 per pass
# baseline (speedup 1.0000x reference)
.LBB0_313:
	s_or_b64 exec, exec, s[0:1]
	s_cmpk_lt_i32 s2, 0x400
	s_cselect_b64 s[16:17], -1, 0
	s_cmpk_gt_i32 s2, 0x3ff
	s_waitcnt lgkmcnt(0)
	s_barrier
	s_cbranch_scc1 .LBB0_318
	v_lshrrev_b32_e32 v141, 4, v129
	v_and_b32_e32 v0, 15, v141
	v_bfe_u32 v1, v141, 4, 2
	v_bfe_u32 v2, v141, 1, 3
	v_xor_b32_e32 v2, v1, v2
	v_lshlrev_b32_e32 v2, 4, v2
	v_lshl_or_b32 v3, v0, 7, v2
	v_bfe_u32 v4, v141, 7, 1
	v_bfe_u32 v5, v141, 6, 1
	v_lshl_add_u32 v150, v4, 13, v3
	v_xor_b32_e32 v151, 64, v150
	v_lshl_add_u32 v162, v5, 13, v3
	v_xor_b32_e32 v163, 64, v162
	v_bfe_u32 v6, v141, 4, 3
	v_and_b32_e32 v7, 7, v141
	v_xor_b32_e32 v6, v6, v7
	v_lshlrev_b32_e32 v6, 4, v6
	v_lshrrev_b32_e32 v8, 3, v141
	v_lshl_or_b32 v164, v8, 12, v6
	v_add_u32_e32 v165, 131072, v164
	v_add_u32_e32 v166, 262144, v164
	v_add_u32_e32 v167, 393216, v164
	v_bfe_u32 v9, v141, 3, 3
	v_lshlrev_b32_e32 v10, 8, v5
	v_lshl_add_u32 v148, v7, 5, v10
	v_lshl_add_u32 v10, v4, 6, v9
	v_lshl_add_u32 v168, v10, 12, v148
	v_lshrrev_b32_e32 v10, 6, v141
	v_lshlrev_b32_e32 v10, 13, v10
	v_lshl_add_u32 v11, v1, 10, v10
	v_add_u32_e32 v12, 0, v1
	v_and_b32_e32 v12, 3, v12
	v_lshl_add_u32 v12, v12, 4, v0
	v_lshl_add_u32 v169, v12, 2, v11
	v_add_u32_e32 v12, 1, v1
	v_and_b32_e32 v12, 3, v12
	v_lshl_add_u32 v12, v12, 4, v0
	v_lshl_add_u32 v170, v12, 2, v11
	v_add_u32_e32 v12, 2, v1
	v_and_b32_e32 v12, 3, v12
	v_lshl_add_u32 v12, v12, 4, v0
	v_lshl_add_u32 v171, v12, 2, v11
	v_add_u32_e32 v12, 3, v1
	v_and_b32_e32 v12, 3, v12
	v_lshl_add_u32 v12, v12, 4, v0
	v_lshl_add_u32 v228, v12, 2, v11
	v_lshl_add_u32 v11, v9, 8, v10
	v_lshrrev_b32_e32 v13, 2, v9
	v_lshlrev_b32_e32 v14, 3, v7
	v_add_u32_e32 v12, 0, v13
	v_and_b32_e32 v12, 3, v12
	v_lshl_add_u32 v12, v12, 4, v14
	v_and_b32_e32 v12, 63, v12
	v_lshl_add_u32 v220, v12, 2, v11
	v_add_u32_e32 v12, 2, v13
	v_and_b32_e32 v12, 3, v12
	v_lshl_add_u32 v12, v12, 4, v14
	v_and_b32_e32 v12, 63, v12
	v_lshl_add_u32 v222, v12, 2, v11
	v_add_u32_e32 v222, 2048, v222
	v_add_u32_e32 v12, 4, v13
	v_and_b32_e32 v12, 3, v12
	v_lshl_add_u32 v12, v12, 4, v14
	v_and_b32_e32 v12, 63, v12
	v_lshl_add_u32 v224, v12, 2, v11
	v_add_u32_e32 v224, 4096, v224
	v_add_u32_e32 v12, 6, v13
	v_and_b32_e32 v12, 3, v12
	v_lshl_add_u32 v12, v12, 4, v14
	v_and_b32_e32 v12, 63, v12
	v_lshl_add_u32 v226, v12, 2, v11
	v_add_u32_e32 v226, 6144, v226
	v_readfirstlane_b32 s38, v129
	s_mov_b32 s52, s2
.Lmy_op0_tile:
	s_and_b32 s10, s52, 7
	s_lshr_b32 s11, s52, 9
	s_lshl_b32 s11, s11, 3
	s_add_i32 s10, s10, s11
	s_bfe_u32 s11, s52, 0x30003
	s_lshl_b32 s12, s10, 3
	s_or_b32 s12, s12, s11
	s_bfe_u32 s13, s52, 0x30006
	s_lshl_b32 s10, s12, 19
	s_add_u32 s98, s50, s10
	s_addc_u32 s99, s51, 0
	s_add_u32 s98, s98, 0x5a00000
	s_addc_u32 s99, s99, 0
	s_lshl_b32 s11, s13, 19
	s_add_u32 s100, s50, s11
	s_addc_u32 s101, s51, 0
	s_add_u32 s100, s100, 0x2800000
	s_addc_u32 s101, s101, 0
	s_lshr_b32 s11, s12, 5
	s_mul_i32 s11, s11, 0x3000
	s_lshl_b32 s20, s13, 9
	s_add_i32 s11, s11, s20
	s_add_i32 s11, s11, 0x10c2000
	s_add_u32 s4, s50, s11
	s_addc_u32 s5, s51, 0
	s_add_i32 s10, s10, s20
	s_add_u32 s6, s68, s10
	s_addc_u32 s7, s69, 0
	s_add_u32 s8, s48, s10
	s_addc_u32 s9, s49, 0
	s_mov_b32 s14, s6
	s_mov_b32 s15, s7
	s_mov_b32 s18, s8
	s_mov_b32 s19, s9
	global_load_dwordx4 v[172:175], v148, s[4:5]
	global_load_dwordx4 v[176:179], v148, s[4:5] offset:16
	s_add_u32 s4, s4, 0xc000
	s_addc_u32 s5, s5, 0
	global_load_dwordx4 v[180:183], v148, s[4:5]
	global_load_dwordx4 v[184:187], v148, s[4:5] offset:16
	s_add_u32 s4, s4, 0xc000
	s_addc_u32 s5, s5, 0
	global_load_dwordx4 v[188:191], v148, s[4:5]
	global_load_dwordx4 v[192:195], v148, s[4:5] offset:16
	s_add_u32 s4, s4, 0xc000
	s_addc_u32 s5, s5, 0
	global_load_dwordx4 v[196:199], v148, s[4:5]
	global_load_dwordx4 v[200:203], v148, s[4:5] offset:16
	s_add_u32 s4, s4, 0xc000
	s_addc_u32 s5, s5, 0
	global_load_dwordx4 v[204:207], v148, s[4:5]
	global_load_dwordx4 v[208:211], v148, s[4:5] offset:16
	s_add_u32 s4, s4, 0xc000
	s_addc_u32 s5, s5, 0
	global_load_dwordx4 v[212:215], v148, s[4:5]
	global_load_dwordx4 v[216:219], v148, s[4:5] offset:16
	s_add_u32 s4, s4, 0xc000
	s_addc_u32 s5, s5, 0
	global_load_dwordx4 v[230:233], v148, s[4:5]
	global_load_dwordx4 v[234:237], v148, s[4:5] offset:16
	s_add_u32 s4, s4, 0xc000
	s_addc_u32 s5, s5, 0
	global_load_dwordx4 v[238:241], v148, s[4:5]
	global_load_dwordx4 v[242:245], v148, s[4:5] offset:16
	s_barrier
	s_add_u32 m0, s38, 0
	v_mov_b32_e32 v0, 0
	v_mov_b32_e32 v1, 0
	global_load_lds_dwordx4 v164, s[98:99]
	s_add_u32 m0, s38, 4096
	v_mov_b32_e32 v2, 0
	v_mov_b32_e32 v3, 0
	global_load_lds_dwordx4 v165, s[98:99]
	s_add_u32 m0, s38, 8192
	v_mov_b32_e32 v4, 0
	v_mov_b32_e32 v5, 0
	global_load_lds_dwordx4 v166, s[98:99]
	s_add_u32 m0, s38, 12288
	v_mov_b32_e32 v6, 0
	v_mov_b32_e32 v7, 0
	global_load_lds_dwordx4 v167, s[98:99]
	s_add_u32 s98, s98, 128
	s_addc_u32 s99, s99, 0
	s_add_u32 m0, s38, 16384
	v_mov_b32_e32 v8, 0
	v_mov_b32_e32 v9, 0
	global_load_lds_dwordx4 v164, s[100:101]
	s_add_u32 m0, s38, 20480
	v_mov_b32_e32 v10, 0
	v_mov_b32_e32 v11, 0
	global_load_lds_dwordx4 v165, s[100:101]
	s_add_u32 m0, s38, 24576
	v_mov_b32_e32 v12, 0
	v_mov_b32_e32 v13, 0
	global_load_lds_dwordx4 v166, s[100:101]
	s_add_u32 m0, s38, 28672
	v_mov_b32_e32 v14, 0
	v_mov_b32_e32 v15, 0
	global_load_lds_dwordx4 v167, s[100:101]
	s_add_u32 s100, s100, 128
	s_addc_u32 s101, s101, 0
	s_add_u32 m0, s38, 32768
	v_mov_b32_e32 v16, 0
	v_mov_b32_e32 v17, 0
	global_load_lds_dwordx4 v164, s[98:99]
	s_add_u32 m0, s38, 36864
	v_mov_b32_e32 v18, 0
	v_mov_b32_e32 v19, 0
	global_load_lds_dwordx4 v165, s[98:99]
	s_add_u32 m0, s38, 40960
	v_mov_b32_e32 v20, 0
	v_mov_b32_e32 v21, 0
	global_load_lds_dwordx4 v166, s[98:99]
	s_add_u32 m0, s38, 45056
	v_mov_b32_e32 v22, 0
	v_mov_b32_e32 v23, 0
	global_load_lds_dwordx4 v167, s[98:99]
	s_add_u32 s98, s98, 128
	s_addc_u32 s99, s99, 0
	s_add_u32 m0, s38, 49152
	v_mov_b32_e32 v24, 0
	v_mov_b32_e32 v25, 0
	global_load_lds_dwordx4 v164, s[100:101]
	s_add_u32 m0, s38, 53248
	v_mov_b32_e32 v26, 0
	v_mov_b32_e32 v27, 0
	global_load_lds_dwordx4 v165, s[100:101]
	s_add_u32 m0, s38, 57344
	v_mov_b32_e32 v28, 0
	v_mov_b32_e32 v29, 0
	global_load_lds_dwordx4 v166, s[100:101]
	s_add_u32 m0, s38, 61440
	v_mov_b32_e32 v30, 0
	v_mov_b32_e32 v31, 0
	global_load_lds_dwordx4 v167, s[100:101]
	s_add_u32 s100, s100, 128
	s_addc_u32 s101, s101, 0
	v_mov_b32_e32 v32, 0
	v_mov_b32_e32 v33, 0
	v_mov_b32_e32 v34, 0
	v_mov_b32_e32 v35, 0
	v_mov_b32_e32 v36, 0
	v_mov_b32_e32 v37, 0
	v_mov_b32_e32 v38, 0
	v_mov_b32_e32 v39, 0
	v_mov_b32_e32 v40, 0
	v_mov_b32_e32 v41, 0
	v_mov_b32_e32 v42, 0
	v_mov_b32_e32 v43, 0
	v_mov_b32_e32 v44, 0
	v_mov_b32_e32 v45, 0
	v_mov_b32_e32 v46, 0
	v_mov_b32_e32 v47, 0
	v_mov_b32_e32 v48, 0
	v_mov_b32_e32 v49, 0
	v_mov_b32_e32 v50, 0
	v_mov_b32_e32 v51, 0
	v_mov_b32_e32 v52, 0
	v_mov_b32_e32 v53, 0
	v_mov_b32_e32 v54, 0
	v_mov_b32_e32 v55, 0
	v_mov_b32_e32 v56, 0
	v_mov_b32_e32 v57, 0
	v_mov_b32_e32 v58, 0
	v_mov_b32_e32 v59, 0
	v_mov_b32_e32 v60, 0
	v_mov_b32_e32 v61, 0
	v_mov_b32_e32 v62, 0
	v_mov_b32_e32 v63, 0
	s_waitcnt vmcnt(8)
	s_barrier
	ds_read_b128 v[64:67], v150 offset:0
	ds_read_b128 v[96:99], v162 offset:16384
	ds_read_b128 v[100:103], v162 offset:18432
	ds_read_b128 v[104:107], v162 offset:20480
	ds_read_b128 v[108:111], v162 offset:22528
	ds_read_b128 v[68:71], v150 offset:2048
	ds_read_b128 v[72:75], v150 offset:4096
	ds_read_b128 v[76:79], v150 offset:6144
	v_add_f32_e32 v142, 0, v172
	v_add_f32_e32 v143, 0, v173
	v_add_f32_e32 v144, 0, v174
	v_add_f32_e32 v145, 0, v175
	s_waitcnt lgkmcnt(6)
	v_mfma_f32_16x16x32_bf16 v[0:3], v[64:67], v[96:99], v[0:3]
	ds_read_b128 v[80:83], v151 offset:0
	v_add_f32_e32 v146, 0, v176
	v_add_f32_e32 v147, 0, v177
	v_add_f32_e32 v160, 0, v178
	v_add_f32_e32 v161, 0, v179
	s_waitcnt lgkmcnt(6)
	v_mfma_f32_16x16x32_bf16 v[4:7], v[64:67], v[100:103], v[4:7]
	ds_read_b128 v[112:115], v163 offset:16384
	v_add_f32_e32 v142, v142, v180
	v_add_f32_e32 v143, v143, v181
	v_add_f32_e32 v144, v144, v182
	v_add_f32_e32 v145, v145, v183
	s_waitcnt lgkmcnt(6)
	v_mfma_f32_16x16x32_bf16 v[8:11], v[64:67], v[104:107], v[8:11]
	ds_read_b128 v[116:119], v163 offset:18432
	v_add_f32_e32 v146, v146, v184
	v_add_f32_e32 v147, v147, v185
	v_add_f32_e32 v160, v160, v186
	v_add_f32_e32 v161, v161, v187
	s_waitcnt lgkmcnt(6)
	v_mfma_f32_16x16x32_bf16 v[12:15], v[64:67], v[108:111], v[12:15]
	ds_read_b128 v[120:123], v163 offset:20480
	v_add_f32_e32 v142, v142, v188
	v_add_f32_e32 v143, v143, v189
	v_add_f32_e32 v144, v144, v190
	v_add_f32_e32 v145, v145, v191
	s_waitcnt lgkmcnt(6)
	v_mfma_f32_16x16x32_bf16 v[16:19], v[68:71], v[96:99], v[16:19]
	ds_read_b128 v[124:127], v163 offset:22528
	v_add_f32_e32 v146, v146, v192
	v_add_f32_e32 v147, v147, v193
	v_add_f32_e32 v160, v160, v194
	v_add_f32_e32 v161, v161, v195
	s_waitcnt lgkmcnt(7)
	v_mfma_f32_16x16x32_bf16 v[20:23], v[68:71], v[100:103], v[20:23]
	ds_read_b128 v[84:87], v151 offset:2048
	v_add_f32_e32 v142, v142, v196
	v_add_f32_e32 v143, v143, v197
	v_add_f32_e32 v144, v144, v198
	v_add_f32_e32 v145, v145, v199
	s_waitcnt lgkmcnt(8)
	v_mfma_f32_16x16x32_bf16 v[24:27], v[68:71], v[104:107], v[24:27]
	ds_read_b128 v[88:91], v151 offset:4096
	v_add_f32_e32 v146, v146, v200
	v_add_f32_e32 v147, v147, v201
	v_add_f32_e32 v160, v160, v202
	v_add_f32_e32 v161, v161, v203
	s_waitcnt lgkmcnt(9)
	v_mfma_f32_16x16x32_bf16 v[28:31], v[68:71], v[108:111], v[28:31]
	ds_read_b128 v[92:95], v151 offset:6144
	v_add_f32_e32 v142, v142, v204
	v_add_f32_e32 v143, v143, v205
	v_add_f32_e32 v144, v144, v206
	v_add_f32_e32 v145, v145, v207
	s_waitcnt lgkmcnt(9)
	v_mfma_f32_16x16x32_bf16 v[32:35], v[72:75], v[96:99], v[32:35]
	v_add_f32_e32 v146, v146, v208
	v_add_f32_e32 v147, v147, v209
	v_add_f32_e32 v160, v160, v210
	v_add_f32_e32 v161, v161, v211
	s_waitcnt lgkmcnt(9)
	v_mfma_f32_16x16x32_bf16 v[36:39], v[72:75], v[100:103], v[36:39]
	v_add_f32_e32 v142, v142, v212
	v_add_f32_e32 v143, v143, v213
	v_add_f32_e32 v144, v144, v214
	v_add_f32_e32 v145, v145, v215
	s_waitcnt lgkmcnt(9)
	v_mfma_f32_16x16x32_bf16 v[40:43], v[72:75], v[104:107], v[40:43]
	v_add_f32_e32 v146, v146, v216
	v_add_f32_e32 v147, v147, v217
	v_add_f32_e32 v160, v160, v218
	v_add_f32_e32 v161, v161, v219
	s_waitcnt lgkmcnt(9)
	v_mfma_f32_16x16x32_bf16 v[44:47], v[72:75], v[108:111], v[44:47]
	s_waitcnt vmcnt(0) lgkmcnt(0)
	s_barrier
	s_add_u32 m0, s38, 0
	s_nop 0
	global_load_lds_dwordx4 v164, s[98:99]
	v_add_f32_e32 v142, v142, v230
	v_add_f32_e32 v143, v143, v231
	v_add_f32_e32 v144, v144, v232
	v_add_f32_e32 v145, v145, v233
	s_waitcnt lgkmcnt(8)
	v_mfma_f32_16x16x32_bf16 v[48:51], v[76:79], v[96:99], v[48:51]
	s_add_u32 m0, s38, 4096
	s_nop 0
	global_load_lds_dwordx4 v165, s[98:99]
	v_add_f32_e32 v146, v146, v234
	v_add_f32_e32 v147, v147, v235
	v_add_f32_e32 v160, v160, v236
	v_add_f32_e32 v161, v161, v237
	s_waitcnt lgkmcnt(8)
	v_mfma_f32_16x16x32_bf16 v[52:55], v[76:79], v[100:103], v[52:55]
	s_add_u32 m0, s38, 8192
	s_nop 0
	global_load_lds_dwordx4 v166, s[98:99]
	v_add_f32_e32 v142, v142, v238
	v_add_f32_e32 v143, v143, v239
	v_add_f32_e32 v144, v144, v240
	v_add_f32_e32 v145, v145, v241
	s_waitcnt lgkmcnt(8)
	v_mfma_f32_16x16x32_bf16 v[56:59], v[76:79], v[104:107], v[56:59]
	s_add_u32 m0, s38, 12288
	s_nop 0
	global_load_lds_dwordx4 v167, s[98:99]
	s_add_u32 s98, s98, 128
	s_addc_u32 s99, s99, 0
	v_add_f32_e32 v146, v146, v242
	v_add_f32_e32 v147, v147, v243
	v_add_f32_e32 v160, v160, v244
	v_add_f32_e32 v161, v161, v245
	s_waitcnt lgkmcnt(8)
	v_mfma_f32_16x16x32_bf16 v[60:63], v[76:79], v[108:111], v[60:63]
	s_add_u32 m0, s38, 16384
	s_nop 0
	global_load_lds_dwordx4 v164, s[100:101]
	s_waitcnt lgkmcnt(6)
	v_mfma_f32_16x16x32_bf16 v[0:3], v[80:83], v[112:115], v[0:3]
	ds_read_b128 v[64:67], v150 offset:32768
	s_add_u32 m0, s38, 20480
	s_nop 0
	global_load_lds_dwordx4 v165, s[100:101]
	s_waitcnt lgkmcnt(6)
	v_mfma_f32_16x16x32_bf16 v[4:7], v[80:83], v[116:119], v[4:7]
	ds_read_b128 v[96:99], v162 offset:49152
	s_add_u32 m0, s38, 24576
	s_nop 0
	global_load_lds_dwordx4 v166, s[100:101]
	s_waitcnt lgkmcnt(6)
	v_mfma_f32_16x16x32_bf16 v[8:11], v[80:83], v[120:123], v[8:11]
	ds_read_b128 v[100:103], v162 offset:51200
	s_add_u32 m0, s38, 28672
	s_nop 0
	global_load_lds_dwordx4 v167, s[100:101]
	s_add_u32 s100, s100, 128
	s_addc_u32 s101, s101, 0
	s_waitcnt lgkmcnt(6)
	v_mfma_f32_16x16x32_bf16 v[12:15], v[80:83], v[124:127], v[12:15]
	ds_read_b128 v[104:107], v162 offset:53248
	s_waitcnt lgkmcnt(6)
	v_mfma_f32_16x16x32_bf16 v[16:19], v[84:87], v[112:115], v[16:19]
	ds_read_b128 v[108:111], v162 offset:55296
	s_waitcnt lgkmcnt(7)
	v_mfma_f32_16x16x32_bf16 v[20:23], v[84:87], v[116:119], v[20:23]
	ds_read_b128 v[68:71], v150 offset:34816
	s_waitcnt lgkmcnt(8)
	v_mfma_f32_16x16x32_bf16 v[24:27], v[84:87], v[120:123], v[24:27]
	ds_read_b128 v[72:75], v150 offset:36864
	s_waitcnt lgkmcnt(9)
	v_mfma_f32_16x16x32_bf16 v[28:31], v[84:87], v[124:127], v[28:31]
	ds_read_b128 v[76:79], v150 offset:38912
	s_waitcnt lgkmcnt(9)
	v_mfma_f32_16x16x32_bf16 v[32:35], v[88:91], v[112:115], v[32:35]
	s_waitcnt lgkmcnt(9)
	v_mfma_f32_16x16x32_bf16 v[36:39], v[88:91], v[116:119], v[36:39]
	s_waitcnt lgkmcnt(9)
	v_mfma_f32_16x16x32_bf16 v[40:43], v[88:91], v[120:123], v[40:43]
	s_waitcnt lgkmcnt(9)
	v_mfma_f32_16x16x32_bf16 v[44:47], v[88:91], v[124:127], v[44:47]
	s_waitcnt lgkmcnt(8)
	v_mfma_f32_16x16x32_bf16 v[48:51], v[92:95], v[112:115], v[48:51]
	s_waitcnt lgkmcnt(8)
	v_mfma_f32_16x16x32_bf16 v[52:55], v[92:95], v[116:119], v[52:55]
	s_waitcnt lgkmcnt(8)
	v_mfma_f32_16x16x32_bf16 v[56:59], v[92:95], v[120:123], v[56:59]
	s_waitcnt lgkmcnt(8)
	v_mfma_f32_16x16x32_bf16 v[60:63], v[92:95], v[124:127], v[60:63]
	s_waitcnt lgkmcnt(6)
	v_mfma_f32_16x16x32_bf16 v[0:3], v[64:67], v[96:99], v[0:3]
	ds_read_b128 v[80:83], v151 offset:32768
	s_waitcnt lgkmcnt(6)
	v_mfma_f32_16x16x32_bf16 v[4:7], v[64:67], v[100:103], v[4:7]
	ds_read_b128 v[112:115], v163 offset:49152
	s_waitcnt lgkmcnt(6)
	v_mfma_f32_16x16x32_bf16 v[8:11], v[64:67], v[104:107], v[8:11]
	ds_read_b128 v[116:119], v163 offset:51200
	s_waitcnt lgkmcnt(6)
	v_mfma_f32_16x16x32_bf16 v[12:15], v[64:67], v[108:111], v[12:15]
	ds_read_b128 v[120:123], v163 offset:53248
	s_waitcnt lgkmcnt(6)
	v_mfma_f32_16x16x32_bf16 v[16:19], v[68:71], v[96:99], v[16:19]
	ds_read_b128 v[124:127], v163 offset:55296
	s_waitcnt lgkmcnt(7)
	v_mfma_f32_16x16x32_bf16 v[20:23], v[68:71], v[100:103], v[20:23]
	ds_read_b128 v[84:87], v151 offset:34816
	s_waitcnt lgkmcnt(8)
	v_mfma_f32_16x16x32_bf16 v[24:27], v[68:71], v[104:107], v[24:27]
	ds_read_b128 v[88:91], v151 offset:36864
	s_waitcnt lgkmcnt(9)
	v_mfma_f32_16x16x32_bf16 v[28:31], v[68:71], v[108:111], v[28:31]
	ds_read_b128 v[92:95], v151 offset:38912
	s_waitcnt lgkmcnt(9)
	v_mfma_f32_16x16x32_bf16 v[32:35], v[72:75], v[96:99], v[32:35]
	s_waitcnt lgkmcnt(9)
	v_mfma_f32_16x16x32_bf16 v[36:39], v[72:75], v[100:103], v[36:39]
	s_waitcnt lgkmcnt(9)
	v_mfma_f32_16x16x32_bf16 v[40:43], v[72:75], v[104:107], v[40:43]
	s_waitcnt lgkmcnt(9)
	v_mfma_f32_16x16x32_bf16 v[44:47], v[72:75], v[108:111], v[44:47]
	s_waitcnt vmcnt(0) lgkmcnt(0)
	s_barrier
	s_add_u32 m0, s38, 32768
	s_nop 0
	global_load_lds_dwordx4 v164, s[98:99]
	s_waitcnt lgkmcnt(8)
	v_mfma_f32_16x16x32_bf16 v[48:51], v[76:79], v[96:99], v[48:51]
	s_add_u32 m0, s38, 36864
	s_nop 0
	global_load_lds_dwordx4 v165, s[98:99]
	s_waitcnt lgkmcnt(8)
	v_mfma_f32_16x16x32_bf16 v[52:55], v[76:79], v[100:103], v[52:55]
	s_add_u32 m0, s38, 40960
	s_nop 0
	global_load_lds_dwordx4 v166, s[98:99]
	s_waitcnt lgkmcnt(8)
	v_mfma_f32_16x16x32_bf16 v[56:59], v[76:79], v[104:107], v[56:59]
	s_add_u32 m0, s38, 45056
	s_nop 0
	global_load_lds_dwordx4 v167, s[98:99]
	s_add_u32 s98, s98, 128
	s_addc_u32 s99, s99, 0
	s_waitcnt lgkmcnt(8)
	v_mfma_f32_16x16x32_bf16 v[60:63], v[76:79], v[108:111], v[60:63]
	s_add_u32 m0, s38, 49152
	s_nop 0
	global_load_lds_dwordx4 v164, s[100:101]
	s_waitcnt lgkmcnt(6)
	v_mfma_f32_16x16x32_bf16 v[0:3], v[80:83], v[112:115], v[0:3]
	ds_read_b128 v[64:67], v150 offset:0
	s_add_u32 m0, s38, 53248
	s_nop 0
	global_load_lds_dwordx4 v165, s[100:101]
	s_waitcnt lgkmcnt(6)
	v_mfma_f32_16x16x32_bf16 v[4:7], v[80:83], v[116:119], v[4:7]
	ds_read_b128 v[96:99], v162 offset:16384
	s_add_u32 m0, s38, 57344
	s_nop 0
	global_load_lds_dwordx4 v166, s[100:101]
	s_waitcnt lgkmcnt(6)
	v_mfma_f32_16x16x32_bf16 v[8:11], v[80:83], v[120:123], v[8:11]
	ds_read_b128 v[100:103], v162 offset:18432
	s_add_u32 m0, s38, 61440
	s_nop 0
	global_load_lds_dwordx4 v167, s[100:101]
	s_add_u32 s100, s100, 128
	s_addc_u32 s101, s101, 0
	s_waitcnt lgkmcnt(6)
	v_mfma_f32_16x16x32_bf16 v[12:15], v[80:83], v[124:127], v[12:15]
	ds_read_b128 v[104:107], v162 offset:20480
	s_waitcnt lgkmcnt(6)
	v_mfma_f32_16x16x32_bf16 v[16:19], v[84:87], v[112:115], v[16:19]
	ds_read_b128 v[108:111], v162 offset:22528
	s_waitcnt lgkmcnt(7)
	v_mfma_f32_16x16x32_bf16 v[20:23], v[84:87], v[116:119], v[20:23]
	ds_read_b128 v[68:71], v150 offset:2048
	s_waitcnt lgkmcnt(8)
	v_mfma_f32_16x16x32_bf16 v[24:27], v[84:87], v[120:123], v[24:27]
	ds_read_b128 v[72:75], v150 offset:4096
	s_waitcnt lgkmcnt(9)
	v_mfma_f32_16x16x32_bf16 v[28:31], v[84:87], v[124:127], v[28:31]
	ds_read_b128 v[76:79], v150 offset:6144
	s_waitcnt lgkmcnt(9)
	v_mfma_f32_16x16x32_bf16 v[32:35], v[88:91], v[112:115], v[32:35]
	s_waitcnt lgkmcnt(9)
	v_mfma_f32_16x16x32_bf16 v[36:39], v[88:91], v[116:119], v[36:39]
	s_waitcnt lgkmcnt(9)
	v_mfma_f32_16x16x32_bf16 v[40:43], v[88:91], v[120:123], v[40:43]
	s_waitcnt lgkmcnt(9)
	v_mfma_f32_16x16x32_bf16 v[44:47], v[88:91], v[124:127], v[44:47]
	s_waitcnt lgkmcnt(8)
	v_mfma_f32_16x16x32_bf16 v[48:51], v[92:95], v[112:115], v[48:51]
	s_waitcnt lgkmcnt(8)
	v_mfma_f32_16x16x32_bf16 v[52:55], v[92:95], v[116:119], v[52:55]
	s_waitcnt lgkmcnt(8)
	v_mfma_f32_16x16x32_bf16 v[56:59], v[92:95], v[120:123], v[56:59]
	s_waitcnt lgkmcnt(8)
	v_mfma_f32_16x16x32_bf16 v[60:63], v[92:95], v[124:127], v[60:63]
	s_waitcnt lgkmcnt(6)
	v_mfma_f32_16x16x32_bf16 v[0:3], v[64:67], v[96:99], v[0:3]
	ds_read_b128 v[80:83], v151 offset:0
	s_waitcnt lgkmcnt(6)
	v_mfma_f32_16x16x32_bf16 v[4:7], v[64:67], v[100:103], v[4:7]
	ds_read_b128 v[112:115], v163 offset:16384
	s_waitcnt lgkmcnt(6)
	v_mfma_f32_16x16x32_bf16 v[8:11], v[64:67], v[104:107], v[8:11]
	ds_read_b128 v[116:119], v163 offset:18432
	s_waitcnt lgkmcnt(6)
	v_mfma_f32_16x16x32_bf16 v[12:15], v[64:67], v[108:111], v[12:15]
	ds_read_b128 v[120:123], v163 offset:20480
	s_waitcnt lgkmcnt(6)
	v_mfma_f32_16x16x32_bf16 v[16:19], v[68:71], v[96:99], v[16:19]
	ds_read_b128 v[124:127], v163 offset:22528
	s_waitcnt lgkmcnt(7)
	v_mfma_f32_16x16x32_bf16 v[20:23], v[68:71], v[100:103], v[20:23]
	ds_read_b128 v[84:87], v151 offset:2048
	s_waitcnt lgkmcnt(8)
	v_mfma_f32_16x16x32_bf16 v[24:27], v[68:71], v[104:107], v[24:27]
	ds_read_b128 v[88:91], v151 offset:4096
	s_waitcnt lgkmcnt(9)
	v_mfma_f32_16x16x32_bf16 v[28:31], v[68:71], v[108:111], v[28:31]
	ds_read_b128 v[92:95], v151 offset:6144
	s_waitcnt lgkmcnt(9)
	v_mfma_f32_16x16x32_bf16 v[32:35], v[72:75], v[96:99], v[32:35]
	s_waitcnt lgkmcnt(9)
	v_mfma_f32_16x16x32_bf16 v[36:39], v[72:75], v[100:103], v[36:39]
	s_waitcnt lgkmcnt(9)
	v_mfma_f32_16x16x32_bf16 v[40:43], v[72:75], v[104:107], v[40:43]
	s_waitcnt lgkmcnt(9)
	v_mfma_f32_16x16x32_bf16 v[44:47], v[72:75], v[108:111], v[44:47]
	s_waitcnt vmcnt(0) lgkmcnt(0)
	s_barrier
	s_add_u32 m0, s38, 0
	s_nop 0
	global_load_lds_dwordx4 v164, s[98:99]
	s_waitcnt lgkmcnt(8)
	v_mfma_f32_16x16x32_bf16 v[48:51], v[76:79], v[96:99], v[48:51]
	s_add_u32 m0, s38, 4096
	s_nop 0
	global_load_lds_dwordx4 v165, s[98:99]
	s_waitcnt lgkmcnt(8)
	v_mfma_f32_16x16x32_bf16 v[52:55], v[76:79], v[100:103], v[52:55]
	s_add_u32 m0, s38, 8192
	s_nop 0
	global_load_lds_dwordx4 v166, s[98:99]
	s_waitcnt lgkmcnt(8)
	v_mfma_f32_16x16x32_bf16 v[56:59], v[76:79], v[104:107], v[56:59]
	s_add_u32 m0, s38, 12288
	s_nop 0
	global_load_lds_dwordx4 v167, s[98:99]
	s_add_u32 s98, s98, 128
	s_addc_u32 s99, s99, 0
	s_waitcnt lgkmcnt(8)
	v_mfma_f32_16x16x32_bf16 v[60:63], v[76:79], v[108:111], v[60:63]
	s_add_u32 m0, s38, 16384
	s_nop 0
	global_load_lds_dwordx4 v164, s[100:101]
	s_waitcnt lgkmcnt(6)
	v_mfma_f32_16x16x32_bf16 v[0:3], v[80:83], v[112:115], v[0:3]
	ds_read_b128 v[64:67], v150 offset:32768
	s_add_u32 m0, s38, 20480
	s_nop 0
	global_load_lds_dwordx4 v165, s[100:101]
	s_waitcnt lgkmcnt(6)
	v_mfma_f32_16x16x32_bf16 v[4:7], v[80:83], v[116:119], v[4:7]
	ds_read_b128 v[96:99], v162 offset:49152
	s_add_u32 m0, s38, 24576
	s_nop 0
	global_load_lds_dwordx4 v166, s[100:101]
	s_waitcnt lgkmcnt(6)
	v_mfma_f32_16x16x32_bf16 v[8:11], v[80:83], v[120:123], v[8:11]
	ds_read_b128 v[100:103], v162 offset:51200
	s_add_u32 m0, s38, 28672
	s_nop 0
	global_load_lds_dwordx4 v167, s[100:101]
	s_add_u32 s100, s100, 128
	s_addc_u32 s101, s101, 0
	s_waitcnt lgkmcnt(6)
	v_mfma_f32_16x16x32_bf16 v[12:15], v[80:83], v[124:127], v[12:15]
	ds_read_b128 v[104:107], v162 offset:53248
	s_waitcnt lgkmcnt(6)
	v_mfma_f32_16x16x32_bf16 v[16:19], v[84:87], v[112:115], v[16:19]
	ds_read_b128 v[108:111], v162 offset:55296
	s_waitcnt lgkmcnt(7)
	v_mfma_f32_16x16x32_bf16 v[20:23], v[84:87], v[116:119], v[20:23]
	ds_read_b128 v[68:71], v150 offset:34816
	s_waitcnt lgkmcnt(8)
	v_mfma_f32_16x16x32_bf16 v[24:27], v[84:87], v[120:123], v[24:27]
	ds_read_b128 v[72:75], v150 offset:36864
	s_waitcnt lgkmcnt(9)
	v_mfma_f32_16x16x32_bf16 v[28:31], v[84:87], v[124:127], v[28:31]
	ds_read_b128 v[76:79], v150 offset:38912
	s_waitcnt lgkmcnt(9)
	v_mfma_f32_16x16x32_bf16 v[32:35], v[88:91], v[112:115], v[32:35]
	s_waitcnt lgkmcnt(9)
	v_mfma_f32_16x16x32_bf16 v[36:39], v[88:91], v[116:119], v[36:39]
	s_waitcnt lgkmcnt(9)
	v_mfma_f32_16x16x32_bf16 v[40:43], v[88:91], v[120:123], v[40:43]
	s_waitcnt lgkmcnt(9)
	v_mfma_f32_16x16x32_bf16 v[44:47], v[88:91], v[124:127], v[44:47]
	s_waitcnt lgkmcnt(8)
	v_mfma_f32_16x16x32_bf16 v[48:51], v[92:95], v[112:115], v[48:51]
	s_waitcnt lgkmcnt(8)
	v_mfma_f32_16x16x32_bf16 v[52:55], v[92:95], v[116:119], v[52:55]
	s_waitcnt lgkmcnt(8)
	v_mfma_f32_16x16x32_bf16 v[56:59], v[92:95], v[120:123], v[56:59]
	s_waitcnt lgkmcnt(8)
	v_mfma_f32_16x16x32_bf16 v[60:63], v[92:95], v[124:127], v[60:63]
	s_waitcnt lgkmcnt(6)
	v_mfma_f32_16x16x32_bf16 v[0:3], v[64:67], v[96:99], v[0:3]
	ds_read_b128 v[80:83], v151 offset:32768
	s_waitcnt lgkmcnt(6)
	v_mfma_f32_16x16x32_bf16 v[4:7], v[64:67], v[100:103], v[4:7]
	ds_read_b128 v[112:115], v163 offset:49152
	s_waitcnt lgkmcnt(6)
	v_mfma_f32_16x16x32_bf16 v[8:11], v[64:67], v[104:107], v[8:11]
	ds_read_b128 v[116:119], v163 offset:51200
	s_waitcnt lgkmcnt(6)
	v_mfma_f32_16x16x32_bf16 v[12:15], v[64:67], v[108:111], v[12:15]
	ds_read_b128 v[120:123], v163 offset:53248
	s_waitcnt lgkmcnt(6)
	v_mfma_f32_16x16x32_bf16 v[16:19], v[68:71], v[96:99], v[16:19]
	ds_read_b128 v[124:127], v163 offset:55296
	s_waitcnt lgkmcnt(7)
	v_mfma_f32_16x16x32_bf16 v[20:23], v[68:71], v[100:103], v[20:23]
	ds_read_b128 v[84:87], v151 offset:34816
	s_waitcnt lgkmcnt(8)
	v_mfma_f32_16x16x32_bf16 v[24:27], v[68:71], v[104:107], v[24:27]
	ds_read_b128 v[88:91], v151 offset:36864
	s_waitcnt lgkmcnt(9)
	v_mfma_f32_16x16x32_bf16 v[28:31], v[68:71], v[108:111], v[28:31]
	ds_read_b128 v[92:95], v151 offset:38912
	s_waitcnt lgkmcnt(9)
	v_mfma_f32_16x16x32_bf16 v[32:35], v[72:75], v[96:99], v[32:35]
	s_waitcnt lgkmcnt(9)
	v_mfma_f32_16x16x32_bf16 v[36:39], v[72:75], v[100:103], v[36:39]
	s_waitcnt lgkmcnt(9)
	v_mfma_f32_16x16x32_bf16 v[40:43], v[72:75], v[104:107], v[40:43]
	s_waitcnt lgkmcnt(9)
	v_mfma_f32_16x16x32_bf16 v[44:47], v[72:75], v[108:111], v[44:47]
	s_waitcnt vmcnt(0) lgkmcnt(0)
	s_barrier
	s_add_u32 m0, s38, 32768
	s_nop 0
	global_load_lds_dwordx4 v164, s[98:99]
	s_waitcnt lgkmcnt(8)
	v_mfma_f32_16x16x32_bf16 v[48:51], v[76:79], v[96:99], v[48:51]
	s_add_u32 m0, s38, 36864
	s_nop 0
	global_load_lds_dwordx4 v165, s[98:99]
	s_waitcnt lgkmcnt(8)
	v_mfma_f32_16x16x32_bf16 v[52:55], v[76:79], v[100:103], v[52:55]
	s_add_u32 m0, s38, 40960
	s_nop 0
	global_load_lds_dwordx4 v166, s[98:99]
	s_waitcnt lgkmcnt(8)
	v_mfma_f32_16x16x32_bf16 v[56:59], v[76:79], v[104:107], v[56:59]
	s_add_u32 m0, s38, 45056
	s_nop 0
	global_load_lds_dwordx4 v167, s[98:99]
	s_add_u32 s98, s98, 128
	s_addc_u32 s99, s99, 0
	s_waitcnt lgkmcnt(8)
	v_mfma_f32_16x16x32_bf16 v[60:63], v[76:79], v[108:111], v[60:63]
	s_add_u32 m0, s38, 49152
	s_nop 0
	global_load_lds_dwordx4 v164, s[100:101]
	s_waitcnt lgkmcnt(6)
	v_mfma_f32_16x16x32_bf16 v[0:3], v[80:83], v[112:115], v[0:3]
	ds_read_b128 v[64:67], v150 offset:0
	s_add_u32 m0, s38, 53248
	s_nop 0
	global_load_lds_dwordx4 v165, s[100:101]
	s_waitcnt lgkmcnt(6)
	v_mfma_f32_16x16x32_bf16 v[4:7], v[80:83], v[116:119], v[4:7]
	ds_read_b128 v[96:99], v162 offset:16384
	s_add_u32 m0, s38, 57344
	s_nop 0
	global_load_lds_dwordx4 v166, s[100:101]
	s_waitcnt lgkmcnt(6)
	v_mfma_f32_16x16x32_bf16 v[8:11], v[80:83], v[120:123], v[8:11]
	ds_read_b128 v[100:103], v162 offset:18432
	s_add_u32 m0, s38, 61440
	s_nop 0
	global_load_lds_dwordx4 v167, s[100:101]
	s_add_u32 s100, s100, 128
	s_addc_u32 s101, s101, 0
	s_waitcnt lgkmcnt(6)
	v_mfma_f32_16x16x32_bf16 v[12:15], v[80:83], v[124:127], v[12:15]
	ds_read_b128 v[104:107], v162 offset:20480
	s_waitcnt lgkmcnt(6)
	v_mfma_f32_16x16x32_bf16 v[16:19], v[84:87], v[112:115], v[16:19]
	ds_read_b128 v[108:111], v162 offset:22528
	s_waitcnt lgkmcnt(7)
	v_mfma_f32_16x16x32_bf16 v[20:23], v[84:87], v[116:119], v[20:23]
	ds_read_b128 v[68:71], v150 offset:2048
	s_waitcnt lgkmcnt(8)
	v_mfma_f32_16x16x32_bf16 v[24:27], v[84:87], v[120:123], v[24:27]
	ds_read_b128 v[72:75], v150 offset:4096
	s_waitcnt lgkmcnt(9)
	v_mfma_f32_16x16x32_bf16 v[28:31], v[84:87], v[124:127], v[28:31]
	ds_read_b128 v[76:79], v150 offset:6144
	s_waitcnt lgkmcnt(9)
	v_mfma_f32_16x16x32_bf16 v[32:35], v[88:91], v[112:115], v[32:35]
	s_waitcnt lgkmcnt(9)
	v_mfma_f32_16x16x32_bf16 v[36:39], v[88:91], v[116:119], v[36:39]
	s_waitcnt lgkmcnt(9)
	v_mfma_f32_16x16x32_bf16 v[40:43], v[88:91], v[120:123], v[40:43]
	s_waitcnt lgkmcnt(9)
	v_mfma_f32_16x16x32_bf16 v[44:47], v[88:91], v[124:127], v[44:47]
	s_waitcnt lgkmcnt(8)
	v_mfma_f32_16x16x32_bf16 v[48:51], v[92:95], v[112:115], v[48:51]
	s_waitcnt lgkmcnt(8)
	v_mfma_f32_16x16x32_bf16 v[52:55], v[92:95], v[116:119], v[52:55]
	s_waitcnt lgkmcnt(8)
	v_mfma_f32_16x16x32_bf16 v[56:59], v[92:95], v[120:123], v[56:59]
	s_waitcnt lgkmcnt(8)
	v_mfma_f32_16x16x32_bf16 v[60:63], v[92:95], v[124:127], v[60:63]
	s_waitcnt lgkmcnt(6)
	v_mfma_f32_16x16x32_bf16 v[0:3], v[64:67], v[96:99], v[0:3]
	ds_read_b128 v[80:83], v151 offset:0
	s_waitcnt lgkmcnt(6)
	v_mfma_f32_16x16x32_bf16 v[4:7], v[64:67], v[100:103], v[4:7]
	ds_read_b128 v[112:115], v163 offset:16384
	s_waitcnt lgkmcnt(6)
	v_mfma_f32_16x16x32_bf16 v[8:11], v[64:67], v[104:107], v[8:11]
	ds_read_b128 v[116:119], v163 offset:18432
	s_waitcnt lgkmcnt(6)
	v_mfma_f32_16x16x32_bf16 v[12:15], v[64:67], v[108:111], v[12:15]
	ds_read_b128 v[120:123], v163 offset:20480
	s_waitcnt lgkmcnt(6)
	v_mfma_f32_16x16x32_bf16 v[16:19], v[68:71], v[96:99], v[16:19]
	ds_read_b128 v[124:127], v163 offset:22528
	s_waitcnt lgkmcnt(7)
	v_mfma_f32_16x16x32_bf16 v[20:23], v[68:71], v[100:103], v[20:23]
	ds_read_b128 v[84:87], v151 offset:2048
	s_waitcnt lgkmcnt(8)
	v_mfma_f32_16x16x32_bf16 v[24:27], v[68:71], v[104:107], v[24:27]
	ds_read_b128 v[88:91], v151 offset:4096
	s_waitcnt lgkmcnt(9)
	v_mfma_f32_16x16x32_bf16 v[28:31], v[68:71], v[108:111], v[28:31]
	ds_read_b128 v[92:95], v151 offset:6144
	s_waitcnt lgkmcnt(9)
	v_mfma_f32_16x16x32_bf16 v[32:35], v[72:75], v[96:99], v[32:35]
	s_waitcnt lgkmcnt(9)
	v_mfma_f32_16x16x32_bf16 v[36:39], v[72:75], v[100:103], v[36:39]
	s_waitcnt lgkmcnt(9)
	v_mfma_f32_16x16x32_bf16 v[40:43], v[72:75], v[104:107], v[40:43]
	s_waitcnt lgkmcnt(9)
	v_mfma_f32_16x16x32_bf16 v[44:47], v[72:75], v[108:111], v[44:47]
	s_waitcnt vmcnt(0) lgkmcnt(0)
	s_barrier
	s_add_u32 m0, s38, 0
	s_nop 0
	global_load_lds_dwordx4 v164, s[98:99]
	s_waitcnt lgkmcnt(8)
	v_mfma_f32_16x16x32_bf16 v[48:51], v[76:79], v[96:99], v[48:51]
	s_add_u32 m0, s38, 4096
	s_nop 0
	global_load_lds_dwordx4 v165, s[98:99]
	s_waitcnt lgkmcnt(8)
	v_mfma_f32_16x16x32_bf16 v[52:55], v[76:79], v[100:103], v[52:55]
	s_add_u32 m0, s38, 8192
	s_nop 0
	global_load_lds_dwordx4 v166, s[98:99]
	s_waitcnt lgkmcnt(8)
	v_mfma_f32_16x16x32_bf16 v[56:59], v[76:79], v[104:107], v[56:59]
	s_add_u32 m0, s38, 12288
	s_nop 0
	global_load_lds_dwordx4 v167, s[98:99]
	s_add_u32 s98, s98, 128
	s_addc_u32 s99, s99, 0
	s_waitcnt lgkmcnt(8)
	v_mfma_f32_16x16x32_bf16 v[60:63], v[76:79], v[108:111], v[60:63]
	s_add_u32 m0, s38, 16384
	s_nop 0
	global_load_lds_dwordx4 v164, s[100:101]
	s_waitcnt lgkmcnt(6)
	v_mfma_f32_16x16x32_bf16 v[0:3], v[80:83], v[112:115], v[0:3]
	ds_read_b128 v[64:67], v150 offset:32768
	s_add_u32 m0, s38, 20480
	s_nop 0
	global_load_lds_dwordx4 v165, s[100:101]
	s_waitcnt lgkmcnt(6)
	v_mfma_f32_16x16x32_bf16 v[4:7], v[80:83], v[116:119], v[4:7]
	ds_read_b128 v[96:99], v162 offset:49152
	s_add_u32 m0, s38, 24576
	s_nop 0
	global_load_lds_dwordx4 v166, s[100:101]
	s_waitcnt lgkmcnt(6)
	v_mfma_f32_16x16x32_bf16 v[8:11], v[80:83], v[120:123], v[8:11]
	ds_read_b128 v[100:103], v162 offset:51200
	s_add_u32 m0, s38, 28672
	s_nop 0
	global_load_lds_dwordx4 v167, s[100:101]
	s_add_u32 s100, s100, 128
	s_addc_u32 s101, s101, 0
	s_waitcnt lgkmcnt(6)
	v_mfma_f32_16x16x32_bf16 v[12:15], v[80:83], v[124:127], v[12:15]
	ds_read_b128 v[104:107], v162 offset:53248
	s_waitcnt lgkmcnt(6)
	v_mfma_f32_16x16x32_bf16 v[16:19], v[84:87], v[112:115], v[16:19]
	ds_read_b128 v[108:111], v162 offset:55296
	s_waitcnt lgkmcnt(7)
	v_mfma_f32_16x16x32_bf16 v[20:23], v[84:87], v[116:119], v[20:23]
	ds_read_b128 v[68:71], v150 offset:34816
	s_waitcnt lgkmcnt(8)
	v_mfma_f32_16x16x32_bf16 v[24:27], v[84:87], v[120:123], v[24:27]
	ds_read_b128 v[72:75], v150 offset:36864
	s_waitcnt lgkmcnt(9)
	v_mfma_f32_16x16x32_bf16 v[28:31], v[84:87], v[124:127], v[28:31]
	ds_read_b128 v[76:79], v150 offset:38912
	s_waitcnt lgkmcnt(9)
	v_mfma_f32_16x16x32_bf16 v[32:35], v[88:91], v[112:115], v[32:35]
	s_waitcnt lgkmcnt(9)
	v_mfma_f32_16x16x32_bf16 v[36:39], v[88:91], v[116:119], v[36:39]
	s_waitcnt lgkmcnt(9)
	v_mfma_f32_16x16x32_bf16 v[40:43], v[88:91], v[120:123], v[40:43]
	s_waitcnt lgkmcnt(9)
	v_mfma_f32_16x16x32_bf16 v[44:47], v[88:91], v[124:127], v[44:47]
	s_waitcnt lgkmcnt(8)
	v_mfma_f32_16x16x32_bf16 v[48:51], v[92:95], v[112:115], v[48:51]
	s_waitcnt lgkmcnt(8)
	v_mfma_f32_16x16x32_bf16 v[52:55], v[92:95], v[116:119], v[52:55]
	s_waitcnt lgkmcnt(8)
	v_mfma_f32_16x16x32_bf16 v[56:59], v[92:95], v[120:123], v[56:59]
	s_waitcnt lgkmcnt(8)
	v_mfma_f32_16x16x32_bf16 v[60:63], v[92:95], v[124:127], v[60:63]
	s_waitcnt lgkmcnt(6)
	v_mfma_f32_16x16x32_bf16 v[0:3], v[64:67], v[96:99], v[0:3]
	ds_read_b128 v[80:83], v151 offset:32768
	s_waitcnt lgkmcnt(6)
	v_mfma_f32_16x16x32_bf16 v[4:7], v[64:67], v[100:103], v[4:7]
	ds_read_b128 v[112:115], v163 offset:49152
	s_waitcnt lgkmcnt(6)
	v_mfma_f32_16x16x32_bf16 v[8:11], v[64:67], v[104:107], v[8:11]
	ds_read_b128 v[116:119], v163 offset:51200
	s_waitcnt lgkmcnt(6)
	v_mfma_f32_16x16x32_bf16 v[12:15], v[64:67], v[108:111], v[12:15]
	ds_read_b128 v[120:123], v163 offset:53248
	s_waitcnt lgkmcnt(6)
	v_mfma_f32_16x16x32_bf16 v[16:19], v[68:71], v[96:99], v[16:19]
	ds_read_b128 v[124:127], v163 offset:55296
	s_waitcnt lgkmcnt(7)
	v_mfma_f32_16x16x32_bf16 v[20:23], v[68:71], v[100:103], v[20:23]
	ds_read_b128 v[84:87], v151 offset:34816
	s_waitcnt lgkmcnt(8)
	v_mfma_f32_16x16x32_bf16 v[24:27], v[68:71], v[104:107], v[24:27]
	ds_read_b128 v[88:91], v151 offset:36864
	s_waitcnt lgkmcnt(9)
	v_mfma_f32_16x16x32_bf16 v[28:31], v[68:71], v[108:111], v[28:31]
	ds_read_b128 v[92:95], v151 offset:38912
	s_waitcnt lgkmcnt(9)
	v_mfma_f32_16x16x32_bf16 v[32:35], v[72:75], v[96:99], v[32:35]
	s_waitcnt lgkmcnt(9)
	v_mfma_f32_16x16x32_bf16 v[36:39], v[72:75], v[100:103], v[36:39]
	s_waitcnt lgkmcnt(9)
	v_mfma_f32_16x16x32_bf16 v[40:43], v[72:75], v[104:107], v[40:43]
	s_waitcnt lgkmcnt(9)
	v_mfma_f32_16x16x32_bf16 v[44:47], v[72:75], v[108:111], v[44:47]
	s_waitcnt vmcnt(0) lgkmcnt(0)
	s_barrier
	s_add_u32 m0, s38, 32768
	s_nop 0
	global_load_lds_dwordx4 v164, s[98:99]
	s_waitcnt lgkmcnt(8)
	v_mfma_f32_16x16x32_bf16 v[48:51], v[76:79], v[96:99], v[48:51]
	s_add_u32 m0, s38, 36864
	s_nop 0
	global_load_lds_dwordx4 v165, s[98:99]
	s_waitcnt lgkmcnt(8)
	v_mfma_f32_16x16x32_bf16 v[52:55], v[76:79], v[100:103], v[52:55]
	s_add_u32 m0, s38, 40960
	s_nop 0
	global_load_lds_dwordx4 v166, s[98:99]
	s_waitcnt lgkmcnt(8)
	v_mfma_f32_16x16x32_bf16 v[56:59], v[76:79], v[104:107], v[56:59]
	s_add_u32 m0, s38, 45056
	s_nop 0
	global_load_lds_dwordx4 v167, s[98:99]
	s_add_u32 s98, s98, 128
	s_addc_u32 s99, s99, 0
	s_waitcnt lgkmcnt(8)
	v_mfma_f32_16x16x32_bf16 v[60:63], v[76:79], v[108:111], v[60:63]
	s_add_u32 m0, s38, 49152
	s_nop 0
	global_load_lds_dwordx4 v164, s[100:101]
	s_waitcnt lgkmcnt(6)
	v_mfma_f32_16x16x32_bf16 v[0:3], v[80:83], v[112:115], v[0:3]
	ds_read_b128 v[64:67], v150 offset:0
	s_add_u32 m0, s38, 53248
	s_nop 0
	global_load_lds_dwordx4 v165, s[100:101]
	s_waitcnt lgkmcnt(6)
	v_mfma_f32_16x16x32_bf16 v[4:7], v[80:83], v[116:119], v[4:7]
	ds_read_b128 v[96:99], v162 offset:16384
	s_add_u32 m0, s38, 57344
	s_nop 0
	global_load_lds_dwordx4 v166, s[100:101]
	s_waitcnt lgkmcnt(6)
	v_mfma_f32_16x16x32_bf16 v[8:11], v[80:83], v[120:123], v[8:11]
	ds_read_b128 v[100:103], v162 offset:18432
	s_add_u32 m0, s38, 61440
	s_nop 0
	global_load_lds_dwordx4 v167, s[100:101]
	s_add_u32 s100, s100, 128
	s_addc_u32 s101, s101, 0
	s_waitcnt lgkmcnt(6)
	v_mfma_f32_16x16x32_bf16 v[12:15], v[80:83], v[124:127], v[12:15]
	ds_read_b128 v[104:107], v162 offset:20480
	s_waitcnt lgkmcnt(6)
	v_mfma_f32_16x16x32_bf16 v[16:19], v[84:87], v[112:115], v[16:19]
	ds_read_b128 v[108:111], v162 offset:22528
	s_waitcnt lgkmcnt(7)
	v_mfma_f32_16x16x32_bf16 v[20:23], v[84:87], v[116:119], v[20:23]
	ds_read_b128 v[68:71], v150 offset:2048
	s_waitcnt lgkmcnt(8)
	v_mfma_f32_16x16x32_bf16 v[24:27], v[84:87], v[120:123], v[24:27]
	ds_read_b128 v[72:75], v150 offset:4096
	s_waitcnt lgkmcnt(9)
	v_mfma_f32_16x16x32_bf16 v[28:31], v[84:87], v[124:127], v[28:31]
	ds_read_b128 v[76:79], v150 offset:6144
	s_waitcnt lgkmcnt(9)
	v_mfma_f32_16x16x32_bf16 v[32:35], v[88:91], v[112:115], v[32:35]
	s_waitcnt lgkmcnt(9)
	v_mfma_f32_16x16x32_bf16 v[36:39], v[88:91], v[116:119], v[36:39]
	s_waitcnt lgkmcnt(9)
	v_mfma_f32_16x16x32_bf16 v[40:43], v[88:91], v[120:123], v[40:43]
	s_waitcnt lgkmcnt(9)
	v_mfma_f32_16x16x32_bf16 v[44:47], v[88:91], v[124:127], v[44:47]
	s_waitcnt lgkmcnt(8)
	v_mfma_f32_16x16x32_bf16 v[48:51], v[92:95], v[112:115], v[48:51]
	s_waitcnt lgkmcnt(8)
	v_mfma_f32_16x16x32_bf16 v[52:55], v[92:95], v[116:119], v[52:55]
	s_waitcnt lgkmcnt(8)
	v_mfma_f32_16x16x32_bf16 v[56:59], v[92:95], v[120:123], v[56:59]
	s_waitcnt lgkmcnt(8)
	v_mfma_f32_16x16x32_bf16 v[60:63], v[92:95], v[124:127], v[60:63]
	s_waitcnt lgkmcnt(6)
	v_mfma_f32_16x16x32_bf16 v[0:3], v[64:67], v[96:99], v[0:3]
	ds_read_b128 v[80:83], v151 offset:0
	s_waitcnt lgkmcnt(6)
	v_mfma_f32_16x16x32_bf16 v[4:7], v[64:67], v[100:103], v[4:7]
	ds_read_b128 v[112:115], v163 offset:16384
	s_waitcnt lgkmcnt(6)
	v_mfma_f32_16x16x32_bf16 v[8:11], v[64:67], v[104:107], v[8:11]
	ds_read_b128 v[116:119], v163 offset:18432
	s_waitcnt lgkmcnt(6)
	v_mfma_f32_16x16x32_bf16 v[12:15], v[64:67], v[108:111], v[12:15]
	ds_read_b128 v[120:123], v163 offset:20480
	s_waitcnt lgkmcnt(6)
	v_mfma_f32_16x16x32_bf16 v[16:19], v[68:71], v[96:99], v[16:19]
	ds_read_b128 v[124:127], v163 offset:22528
	s_waitcnt lgkmcnt(7)
	v_mfma_f32_16x16x32_bf16 v[20:23], v[68:71], v[100:103], v[20:23]
	ds_read_b128 v[84:87], v151 offset:2048
	s_waitcnt lgkmcnt(8)
	v_mfma_f32_16x16x32_bf16 v[24:27], v[68:71], v[104:107], v[24:27]
	ds_read_b128 v[88:91], v151 offset:4096
	s_waitcnt lgkmcnt(9)
	v_mfma_f32_16x16x32_bf16 v[28:31], v[68:71], v[108:111], v[28:31]
	ds_read_b128 v[92:95], v151 offset:6144
	s_waitcnt lgkmcnt(9)
	v_mfma_f32_16x16x32_bf16 v[32:35], v[72:75], v[96:99], v[32:35]
	s_waitcnt lgkmcnt(9)
	v_mfma_f32_16x16x32_bf16 v[36:39], v[72:75], v[100:103], v[36:39]
	s_waitcnt lgkmcnt(9)
	v_mfma_f32_16x16x32_bf16 v[40:43], v[72:75], v[104:107], v[40:43]
	s_waitcnt lgkmcnt(9)
	v_mfma_f32_16x16x32_bf16 v[44:47], v[72:75], v[108:111], v[44:47]
	s_waitcnt vmcnt(0) lgkmcnt(0)
	s_barrier
	s_add_u32 m0, s38, 0
	s_nop 0
	global_load_lds_dwordx4 v164, s[98:99]
	s_waitcnt lgkmcnt(8)
	v_mfma_f32_16x16x32_bf16 v[48:51], v[76:79], v[96:99], v[48:51]
	s_add_u32 m0, s38, 4096
	s_nop 0
	global_load_lds_dwordx4 v165, s[98:99]
	s_waitcnt lgkmcnt(8)
	v_mfma_f32_16x16x32_bf16 v[52:55], v[76:79], v[100:103], v[52:55]
	s_add_u32 m0, s38, 8192
	s_nop 0
	global_load_lds_dwordx4 v166, s[98:99]
	s_waitcnt lgkmcnt(8)
	v_mfma_f32_16x16x32_bf16 v[56:59], v[76:79], v[104:107], v[56:59]
	s_add_u32 m0, s38, 12288
	s_nop 0
	global_load_lds_dwordx4 v167, s[98:99]
	s_add_u32 s98, s98, 128
	s_addc_u32 s99, s99, 0
	s_waitcnt lgkmcnt(8)
	v_mfma_f32_16x16x32_bf16 v[60:63], v[76:79], v[108:111], v[60:63]
	s_add_u32 m0, s38, 16384
	s_nop 0
	global_load_lds_dwordx4 v164, s[100:101]
	s_waitcnt lgkmcnt(6)
	v_mfma_f32_16x16x32_bf16 v[0:3], v[80:83], v[112:115], v[0:3]
	ds_read_b128 v[64:67], v150 offset:32768
	s_add_u32 m0, s38, 20480
	s_nop 0
	global_load_lds_dwordx4 v165, s[100:101]
	s_waitcnt lgkmcnt(6)
	v_mfma_f32_16x16x32_bf16 v[4:7], v[80:83], v[116:119], v[4:7]
	ds_read_b128 v[96:99], v162 offset:49152
	s_add_u32 m0, s38, 24576
	s_nop 0
	global_load_lds_dwordx4 v166, s[100:101]
	s_waitcnt lgkmcnt(6)
	v_mfma_f32_16x16x32_bf16 v[8:11], v[80:83], v[120:123], v[8:11]
	ds_read_b128 v[100:103], v162 offset:51200
	s_add_u32 m0, s38, 28672
	s_nop 0
	global_load_lds_dwordx4 v167, s[100:101]
	s_add_u32 s100, s100, 128
	s_addc_u32 s101, s101, 0
	s_waitcnt lgkmcnt(6)
	v_mfma_f32_16x16x32_bf16 v[12:15], v[80:83], v[124:127], v[12:15]
	ds_read_b128 v[104:107], v162 offset:53248
	s_waitcnt lgkmcnt(6)
	v_mfma_f32_16x16x32_bf16 v[16:19], v[84:87], v[112:115], v[16:19]
	ds_read_b128 v[108:111], v162 offset:55296
	s_waitcnt lgkmcnt(7)
	v_mfma_f32_16x16x32_bf16 v[20:23], v[84:87], v[116:119], v[20:23]
	ds_read_b128 v[68:71], v150 offset:34816
	s_waitcnt lgkmcnt(8)
	v_mfma_f32_16x16x32_bf16 v[24:27], v[84:87], v[120:123], v[24:27]
	ds_read_b128 v[72:75], v150 offset:36864
	s_waitcnt lgkmcnt(9)
	v_mfma_f32_16x16x32_bf16 v[28:31], v[84:87], v[124:127], v[28:31]
	ds_read_b128 v[76:79], v150 offset:38912
	s_waitcnt lgkmcnt(9)
	v_mfma_f32_16x16x32_bf16 v[32:35], v[88:91], v[112:115], v[32:35]
	s_waitcnt lgkmcnt(9)
	v_mfma_f32_16x16x32_bf16 v[36:39], v[88:91], v[116:119], v[36:39]
	s_waitcnt lgkmcnt(9)
	v_mfma_f32_16x16x32_bf16 v[40:43], v[88:91], v[120:123], v[40:43]
	s_waitcnt lgkmcnt(9)
	v_mfma_f32_16x16x32_bf16 v[44:47], v[88:91], v[124:127], v[44:47]
	s_waitcnt lgkmcnt(8)
	v_mfma_f32_16x16x32_bf16 v[48:51], v[92:95], v[112:115], v[48:51]
	s_waitcnt lgkmcnt(8)
	v_mfma_f32_16x16x32_bf16 v[52:55], v[92:95], v[116:119], v[52:55]
	s_waitcnt lgkmcnt(8)
	v_mfma_f32_16x16x32_bf16 v[56:59], v[92:95], v[120:123], v[56:59]
	s_waitcnt lgkmcnt(8)
	v_mfma_f32_16x16x32_bf16 v[60:63], v[92:95], v[124:127], v[60:63]
	s_waitcnt lgkmcnt(6)
	v_mfma_f32_16x16x32_bf16 v[0:3], v[64:67], v[96:99], v[0:3]
	ds_read_b128 v[80:83], v151 offset:32768
	s_waitcnt lgkmcnt(6)
	v_mfma_f32_16x16x32_bf16 v[4:7], v[64:67], v[100:103], v[4:7]
	ds_read_b128 v[112:115], v163 offset:49152
	s_waitcnt lgkmcnt(6)
	v_mfma_f32_16x16x32_bf16 v[8:11], v[64:67], v[104:107], v[8:11]
	ds_read_b128 v[116:119], v163 offset:51200
	s_waitcnt lgkmcnt(6)
	v_mfma_f32_16x16x32_bf16 v[12:15], v[64:67], v[108:111], v[12:15]
	ds_read_b128 v[120:123], v163 offset:53248
	s_waitcnt lgkmcnt(6)
	v_mfma_f32_16x16x32_bf16 v[16:19], v[68:71], v[96:99], v[16:19]
	ds_read_b128 v[124:127], v163 offset:55296
	s_waitcnt lgkmcnt(7)
	v_mfma_f32_16x16x32_bf16 v[20:23], v[68:71], v[100:103], v[20:23]
	ds_read_b128 v[84:87], v151 offset:34816
	s_waitcnt lgkmcnt(8)
	v_mfma_f32_16x16x32_bf16 v[24:27], v[68:71], v[104:107], v[24:27]
	ds_read_b128 v[88:91], v151 offset:36864
	s_waitcnt lgkmcnt(9)
	v_mfma_f32_16x16x32_bf16 v[28:31], v[68:71], v[108:111], v[28:31]
	ds_read_b128 v[92:95], v151 offset:38912
	s_waitcnt lgkmcnt(9)
	v_mfma_f32_16x16x32_bf16 v[32:35], v[72:75], v[96:99], v[32:35]
	s_waitcnt lgkmcnt(9)
	v_mfma_f32_16x16x32_bf16 v[36:39], v[72:75], v[100:103], v[36:39]
	s_waitcnt lgkmcnt(9)
	v_mfma_f32_16x16x32_bf16 v[40:43], v[72:75], v[104:107], v[40:43]
	s_waitcnt lgkmcnt(9)
	v_mfma_f32_16x16x32_bf16 v[44:47], v[72:75], v[108:111], v[44:47]
	s_waitcnt vmcnt(0) lgkmcnt(0)
	s_barrier
	s_add_u32 m0, s38, 32768
	s_nop 0
	global_load_lds_dwordx4 v164, s[98:99]
	s_waitcnt lgkmcnt(8)
	v_mfma_f32_16x16x32_bf16 v[48:51], v[76:79], v[96:99], v[48:51]
	s_add_u32 m0, s38, 36864
	s_nop 0
	global_load_lds_dwordx4 v165, s[98:99]
	s_waitcnt lgkmcnt(8)
	v_mfma_f32_16x16x32_bf16 v[52:55], v[76:79], v[100:103], v[52:55]
	s_add_u32 m0, s38, 40960
	s_nop 0
	global_load_lds_dwordx4 v166, s[98:99]
	s_waitcnt lgkmcnt(8)
	v_mfma_f32_16x16x32_bf16 v[56:59], v[76:79], v[104:107], v[56:59]
	s_add_u32 m0, s38, 45056
	s_nop 0
	global_load_lds_dwordx4 v167, s[98:99]
	s_add_u32 s98, s98, 128
	s_addc_u32 s99, s99, 0
	s_waitcnt lgkmcnt(8)
	v_mfma_f32_16x16x32_bf16 v[60:63], v[76:79], v[108:111], v[60:63]
	s_add_u32 m0, s38, 49152
	s_nop 0
	global_load_lds_dwordx4 v164, s[100:101]
	s_waitcnt lgkmcnt(6)
	v_mfma_f32_16x16x32_bf16 v[0:3], v[80:83], v[112:115], v[0:3]
	ds_read_b128 v[64:67], v150 offset:0
	s_add_u32 m0, s38, 53248
	s_nop 0
	global_load_lds_dwordx4 v165, s[100:101]
	s_waitcnt lgkmcnt(6)
	v_mfma_f32_16x16x32_bf16 v[4:7], v[80:83], v[116:119], v[4:7]
	ds_read_b128 v[96:99], v162 offset:16384
	s_add_u32 m0, s38, 57344
	s_nop 0
	global_load_lds_dwordx4 v166, s[100:101]
	s_waitcnt lgkmcnt(6)
	v_mfma_f32_16x16x32_bf16 v[8:11], v[80:83], v[120:123], v[8:11]
	ds_read_b128 v[100:103], v162 offset:18432
	s_add_u32 m0, s38, 61440
	s_nop 0
	global_load_lds_dwordx4 v167, s[100:101]
	s_add_u32 s100, s100, 128
	s_addc_u32 s101, s101, 0
	s_waitcnt lgkmcnt(6)
	v_mfma_f32_16x16x32_bf16 v[12:15], v[80:83], v[124:127], v[12:15]
	ds_read_b128 v[104:107], v162 offset:20480
	s_waitcnt lgkmcnt(6)
	v_mfma_f32_16x16x32_bf16 v[16:19], v[84:87], v[112:115], v[16:19]
	ds_read_b128 v[108:111], v162 offset:22528
	s_waitcnt lgkmcnt(7)
	v_mfma_f32_16x16x32_bf16 v[20:23], v[84:87], v[116:119], v[20:23]
	ds_read_b128 v[68:71], v150 offset:2048
	s_waitcnt lgkmcnt(8)
	v_mfma_f32_16x16x32_bf16 v[24:27], v[84:87], v[120:123], v[24:27]
	ds_read_b128 v[72:75], v150 offset:4096
	s_waitcnt lgkmcnt(9)
	v_mfma_f32_16x16x32_bf16 v[28:31], v[84:87], v[124:127], v[28:31]
	ds_read_b128 v[76:79], v150 offset:6144
	s_waitcnt lgkmcnt(9)
	v_mfma_f32_16x16x32_bf16 v[32:35], v[88:91], v[112:115], v[32:35]
	s_waitcnt lgkmcnt(9)
	v_mfma_f32_16x16x32_bf16 v[36:39], v[88:91], v[116:119], v[36:39]
	s_waitcnt lgkmcnt(9)
	v_mfma_f32_16x16x32_bf16 v[40:43], v[88:91], v[120:123], v[40:43]
	s_waitcnt lgkmcnt(9)
	v_mfma_f32_16x16x32_bf16 v[44:47], v[88:91], v[124:127], v[44:47]
	s_waitcnt lgkmcnt(8)
	v_mfma_f32_16x16x32_bf16 v[48:51], v[92:95], v[112:115], v[48:51]
	s_waitcnt lgkmcnt(8)
	v_mfma_f32_16x16x32_bf16 v[52:55], v[92:95], v[116:119], v[52:55]
	s_waitcnt lgkmcnt(8)
	v_mfma_f32_16x16x32_bf16 v[56:59], v[92:95], v[120:123], v[56:59]
	s_waitcnt lgkmcnt(8)
	v_mfma_f32_16x16x32_bf16 v[60:63], v[92:95], v[124:127], v[60:63]
	s_waitcnt lgkmcnt(6)
	v_mfma_f32_16x16x32_bf16 v[0:3], v[64:67], v[96:99], v[0:3]
	ds_read_b128 v[80:83], v151 offset:0
	s_waitcnt lgkmcnt(6)
	v_mfma_f32_16x16x32_bf16 v[4:7], v[64:67], v[100:103], v[4:7]
	ds_read_b128 v[112:115], v163 offset:16384
	s_waitcnt lgkmcnt(6)
	v_mfma_f32_16x16x32_bf16 v[8:11], v[64:67], v[104:107], v[8:11]
	ds_read_b128 v[116:119], v163 offset:18432
	s_waitcnt lgkmcnt(6)
	v_mfma_f32_16x16x32_bf16 v[12:15], v[64:67], v[108:111], v[12:15]
	ds_read_b128 v[120:123], v163 offset:20480
	s_waitcnt lgkmcnt(6)
	v_mfma_f32_16x16x32_bf16 v[16:19], v[68:71], v[96:99], v[16:19]
	ds_read_b128 v[124:127], v163 offset:22528
	s_waitcnt lgkmcnt(7)
	v_mfma_f32_16x16x32_bf16 v[20:23], v[68:71], v[100:103], v[20:23]
	ds_read_b128 v[84:87], v151 offset:2048
	s_waitcnt lgkmcnt(8)
	v_mfma_f32_16x16x32_bf16 v[24:27], v[68:71], v[104:107], v[24:27]
	ds_read_b128 v[88:91], v151 offset:4096
	s_waitcnt lgkmcnt(9)
	v_mfma_f32_16x16x32_bf16 v[28:31], v[68:71], v[108:111], v[28:31]
	ds_read_b128 v[92:95], v151 offset:6144
	s_waitcnt lgkmcnt(9)
	v_mfma_f32_16x16x32_bf16 v[32:35], v[72:75], v[96:99], v[32:35]
	s_waitcnt lgkmcnt(9)
	v_mfma_f32_16x16x32_bf16 v[36:39], v[72:75], v[100:103], v[36:39]
	s_waitcnt lgkmcnt(9)
	v_mfma_f32_16x16x32_bf16 v[40:43], v[72:75], v[104:107], v[40:43]
	s_waitcnt lgkmcnt(9)
	v_mfma_f32_16x16x32_bf16 v[44:47], v[72:75], v[108:111], v[44:47]
	s_waitcnt vmcnt(0) lgkmcnt(0)
	s_barrier
	s_add_u32 m0, s38, 0
	s_nop 0
	global_load_lds_dwordx4 v164, s[98:99]
	s_waitcnt lgkmcnt(8)
	v_mfma_f32_16x16x32_bf16 v[48:51], v[76:79], v[96:99], v[48:51]
	s_add_u32 m0, s38, 4096
	s_nop 0
	global_load_lds_dwordx4 v165, s[98:99]
	s_waitcnt lgkmcnt(8)
	v_mfma_f32_16x16x32_bf16 v[52:55], v[76:79], v[100:103], v[52:55]
	s_add_u32 m0, s38, 8192
	s_nop 0
	global_load_lds_dwordx4 v166, s[98:99]
	s_waitcnt lgkmcnt(8)
	v_mfma_f32_16x16x32_bf16 v[56:59], v[76:79], v[104:107], v[56:59]
	s_add_u32 m0, s38, 12288
	s_nop 0
	global_load_lds_dwordx4 v167, s[98:99]
	s_add_u32 s98, s98, 128
	s_addc_u32 s99, s99, 0
	s_waitcnt lgkmcnt(8)
	v_mfma_f32_16x16x32_bf16 v[60:63], v[76:79], v[108:111], v[60:63]
	s_add_u32 m0, s38, 16384
	s_nop 0
	global_load_lds_dwordx4 v164, s[100:101]
	s_waitcnt lgkmcnt(6)
	v_mfma_f32_16x16x32_bf16 v[0:3], v[80:83], v[112:115], v[0:3]
	ds_read_b128 v[64:67], v150 offset:32768
	s_add_u32 m0, s38, 20480
	s_nop 0
	global_load_lds_dwordx4 v165, s[100:101]
	s_waitcnt lgkmcnt(6)
	v_mfma_f32_16x16x32_bf16 v[4:7], v[80:83], v[116:119], v[4:7]
	ds_read_b128 v[96:99], v162 offset:49152
	s_add_u32 m0, s38, 24576
	s_nop 0
	global_load_lds_dwordx4 v166, s[100:101]
	s_waitcnt lgkmcnt(6)
	v_mfma_f32_16x16x32_bf16 v[8:11], v[80:83], v[120:123], v[8:11]
	ds_read_b128 v[100:103], v162 offset:51200
	s_add_u32 m0, s38, 28672
	s_nop 0
	global_load_lds_dwordx4 v167, s[100:101]
	s_add_u32 s100, s100, 128
	s_addc_u32 s101, s101, 0
	s_waitcnt lgkmcnt(6)
	v_mfma_f32_16x16x32_bf16 v[12:15], v[80:83], v[124:127], v[12:15]
	ds_read_b128 v[104:107], v162 offset:53248
	s_waitcnt lgkmcnt(6)
	v_mfma_f32_16x16x32_bf16 v[16:19], v[84:87], v[112:115], v[16:19]
	ds_read_b128 v[108:111], v162 offset:55296
	s_waitcnt lgkmcnt(7)
	v_mfma_f32_16x16x32_bf16 v[20:23], v[84:87], v[116:119], v[20:23]
	ds_read_b128 v[68:71], v150 offset:34816
	s_waitcnt lgkmcnt(8)
	v_mfma_f32_16x16x32_bf16 v[24:27], v[84:87], v[120:123], v[24:27]
	ds_read_b128 v[72:75], v150 offset:36864
	s_waitcnt lgkmcnt(9)
	v_mfma_f32_16x16x32_bf16 v[28:31], v[84:87], v[124:127], v[28:31]
	ds_read_b128 v[76:79], v150 offset:38912
	s_waitcnt lgkmcnt(9)
	v_mfma_f32_16x16x32_bf16 v[32:35], v[88:91], v[112:115], v[32:35]
	s_waitcnt lgkmcnt(9)
	v_mfma_f32_16x16x32_bf16 v[36:39], v[88:91], v[116:119], v[36:39]
	s_waitcnt lgkmcnt(9)
	v_mfma_f32_16x16x32_bf16 v[40:43], v[88:91], v[120:123], v[40:43]
	s_waitcnt lgkmcnt(9)
	v_mfma_f32_16x16x32_bf16 v[44:47], v[88:91], v[124:127], v[44:47]
	s_waitcnt lgkmcnt(8)
	v_mfma_f32_16x16x32_bf16 v[48:51], v[92:95], v[112:115], v[48:51]
	s_waitcnt lgkmcnt(8)
	v_mfma_f32_16x16x32_bf16 v[52:55], v[92:95], v[116:119], v[52:55]
	s_waitcnt lgkmcnt(8)
	v_mfma_f32_16x16x32_bf16 v[56:59], v[92:95], v[120:123], v[56:59]
	s_waitcnt lgkmcnt(8)
	v_mfma_f32_16x16x32_bf16 v[60:63], v[92:95], v[124:127], v[60:63]
	s_waitcnt lgkmcnt(6)
	v_mfma_f32_16x16x32_bf16 v[0:3], v[64:67], v[96:99], v[0:3]
	ds_read_b128 v[80:83], v151 offset:32768
	s_waitcnt lgkmcnt(6)
	v_mfma_f32_16x16x32_bf16 v[4:7], v[64:67], v[100:103], v[4:7]
	ds_read_b128 v[112:115], v163 offset:49152
	s_waitcnt lgkmcnt(6)
	v_mfma_f32_16x16x32_bf16 v[8:11], v[64:67], v[104:107], v[8:11]
	ds_read_b128 v[116:119], v163 offset:51200
	s_waitcnt lgkmcnt(6)
	v_mfma_f32_16x16x32_bf16 v[12:15], v[64:67], v[108:111], v[12:15]
	ds_read_b128 v[120:123], v163 offset:53248
	s_waitcnt lgkmcnt(6)
	v_mfma_f32_16x16x32_bf16 v[16:19], v[68:71], v[96:99], v[16:19]
	ds_read_b128 v[124:127], v163 offset:55296
	s_waitcnt lgkmcnt(7)
	v_mfma_f32_16x16x32_bf16 v[20:23], v[68:71], v[100:103], v[20:23]
	ds_read_b128 v[84:87], v151 offset:34816
	s_waitcnt lgkmcnt(8)
	v_mfma_f32_16x16x32_bf16 v[24:27], v[68:71], v[104:107], v[24:27]
	ds_read_b128 v[88:91], v151 offset:36864
	s_waitcnt lgkmcnt(9)
	v_mfma_f32_16x16x32_bf16 v[28:31], v[68:71], v[108:111], v[28:31]
	ds_read_b128 v[92:95], v151 offset:38912
	s_waitcnt lgkmcnt(9)
	v_mfma_f32_16x16x32_bf16 v[32:35], v[72:75], v[96:99], v[32:35]
	s_waitcnt lgkmcnt(9)
	v_mfma_f32_16x16x32_bf16 v[36:39], v[72:75], v[100:103], v[36:39]
	s_waitcnt lgkmcnt(9)
	v_mfma_f32_16x16x32_bf16 v[40:43], v[72:75], v[104:107], v[40:43]
	s_waitcnt lgkmcnt(9)
	v_mfma_f32_16x16x32_bf16 v[44:47], v[72:75], v[108:111], v[44:47]
	s_waitcnt vmcnt(0) lgkmcnt(0)
	s_barrier
	s_add_u32 m0, s38, 32768
	s_nop 0
	global_load_lds_dwordx4 v164, s[98:99]
	s_waitcnt lgkmcnt(8)
	v_mfma_f32_16x16x32_bf16 v[48:51], v[76:79], v[96:99], v[48:51]
	s_add_u32 m0, s38, 36864
	s_nop 0
	global_load_lds_dwordx4 v165, s[98:99]
	s_waitcnt lgkmcnt(8)
	v_mfma_f32_16x16x32_bf16 v[52:55], v[76:79], v[100:103], v[52:55]
	s_add_u32 m0, s38, 40960
	s_nop 0
	global_load_lds_dwordx4 v166, s[98:99]
	s_waitcnt lgkmcnt(8)
	v_mfma_f32_16x16x32_bf16 v[56:59], v[76:79], v[104:107], v[56:59]
	s_add_u32 m0, s38, 45056
	s_nop 0
	global_load_lds_dwordx4 v167, s[98:99]
	s_add_u32 s98, s98, 128
	s_addc_u32 s99, s99, 0
	s_waitcnt lgkmcnt(8)
	v_mfma_f32_16x16x32_bf16 v[60:63], v[76:79], v[108:111], v[60:63]
	s_add_u32 m0, s38, 49152
	s_nop 0
	global_load_lds_dwordx4 v164, s[100:101]
	s_waitcnt lgkmcnt(6)
	v_mfma_f32_16x16x32_bf16 v[0:3], v[80:83], v[112:115], v[0:3]
	ds_read_b128 v[64:67], v150 offset:0
	s_add_u32 m0, s38, 53248
	s_nop 0
	global_load_lds_dwordx4 v165, s[100:101]
	s_waitcnt lgkmcnt(6)
	v_mfma_f32_16x16x32_bf16 v[4:7], v[80:83], v[116:119], v[4:7]
	ds_read_b128 v[96:99], v162 offset:16384
	s_add_u32 m0, s38, 57344
	s_nop 0
	global_load_lds_dwordx4 v166, s[100:101]
	s_waitcnt lgkmcnt(6)
	v_mfma_f32_16x16x32_bf16 v[8:11], v[80:83], v[120:123], v[8:11]
	ds_read_b128 v[100:103], v162 offset:18432
	s_add_u32 m0, s38, 61440
	s_nop 0
	global_load_lds_dwordx4 v167, s[100:101]
	s_add_u32 s100, s100, 128
	s_addc_u32 s101, s101, 0
	s_waitcnt lgkmcnt(6)
	v_mfma_f32_16x16x32_bf16 v[12:15], v[80:83], v[124:127], v[12:15]
	ds_read_b128 v[104:107], v162 offset:20480
	s_waitcnt lgkmcnt(6)
	v_mfma_f32_16x16x32_bf16 v[16:19], v[84:87], v[112:115], v[16:19]
	ds_read_b128 v[108:111], v162 offset:22528
	s_waitcnt lgkmcnt(7)
	v_mfma_f32_16x16x32_bf16 v[20:23], v[84:87], v[116:119], v[20:23]
	ds_read_b128 v[68:71], v150 offset:2048
	s_waitcnt lgkmcnt(8)
	v_mfma_f32_16x16x32_bf16 v[24:27], v[84:87], v[120:123], v[24:27]
	ds_read_b128 v[72:75], v150 offset:4096
	s_waitcnt lgkmcnt(9)
	v_mfma_f32_16x16x32_bf16 v[28:31], v[84:87], v[124:127], v[28:31]
	ds_read_b128 v[76:79], v150 offset:6144
	s_waitcnt lgkmcnt(9)
	v_mfma_f32_16x16x32_bf16 v[32:35], v[88:91], v[112:115], v[32:35]
	s_waitcnt lgkmcnt(9)
	v_mfma_f32_16x16x32_bf16 v[36:39], v[88:91], v[116:119], v[36:39]
	s_waitcnt lgkmcnt(9)
	v_mfma_f32_16x16x32_bf16 v[40:43], v[88:91], v[120:123], v[40:43]
	s_waitcnt lgkmcnt(9)
	v_mfma_f32_16x16x32_bf16 v[44:47], v[88:91], v[124:127], v[44:47]
	s_waitcnt lgkmcnt(8)
	v_mfma_f32_16x16x32_bf16 v[48:51], v[92:95], v[112:115], v[48:51]
	s_waitcnt lgkmcnt(8)
	v_mfma_f32_16x16x32_bf16 v[52:55], v[92:95], v[116:119], v[52:55]
	s_waitcnt lgkmcnt(8)
	v_mfma_f32_16x16x32_bf16 v[56:59], v[92:95], v[120:123], v[56:59]
	s_waitcnt lgkmcnt(8)
	v_mfma_f32_16x16x32_bf16 v[60:63], v[92:95], v[124:127], v[60:63]
	s_waitcnt lgkmcnt(6)
	v_mfma_f32_16x16x32_bf16 v[0:3], v[64:67], v[96:99], v[0:3]
	ds_read_b128 v[80:83], v151 offset:0
	s_waitcnt lgkmcnt(6)
	v_mfma_f32_16x16x32_bf16 v[4:7], v[64:67], v[100:103], v[4:7]
	ds_read_b128 v[112:115], v163 offset:16384
	s_waitcnt lgkmcnt(6)
	v_mfma_f32_16x16x32_bf16 v[8:11], v[64:67], v[104:107], v[8:11]
	ds_read_b128 v[116:119], v163 offset:18432
	s_waitcnt lgkmcnt(6)
	v_mfma_f32_16x16x32_bf16 v[12:15], v[64:67], v[108:111], v[12:15]
	ds_read_b128 v[120:123], v163 offset:20480
	s_waitcnt lgkmcnt(6)
	v_mfma_f32_16x16x32_bf16 v[16:19], v[68:71], v[96:99], v[16:19]
	ds_read_b128 v[124:127], v163 offset:22528
	s_waitcnt lgkmcnt(7)
	v_mfma_f32_16x16x32_bf16 v[20:23], v[68:71], v[100:103], v[20:23]
	ds_read_b128 v[84:87], v151 offset:2048
	s_waitcnt lgkmcnt(8)
	v_mfma_f32_16x16x32_bf16 v[24:27], v[68:71], v[104:107], v[24:27]
	ds_read_b128 v[88:91], v151 offset:4096
	s_waitcnt lgkmcnt(9)
	v_mfma_f32_16x16x32_bf16 v[28:31], v[68:71], v[108:111], v[28:31]
	ds_read_b128 v[92:95], v151 offset:6144
	s_waitcnt lgkmcnt(9)
	v_mfma_f32_16x16x32_bf16 v[32:35], v[72:75], v[96:99], v[32:35]
	s_waitcnt lgkmcnt(9)
	v_mfma_f32_16x16x32_bf16 v[36:39], v[72:75], v[100:103], v[36:39]
	s_waitcnt lgkmcnt(9)
	v_mfma_f32_16x16x32_bf16 v[40:43], v[72:75], v[104:107], v[40:43]
	s_waitcnt lgkmcnt(9)
	v_mfma_f32_16x16x32_bf16 v[44:47], v[72:75], v[108:111], v[44:47]
	s_waitcnt vmcnt(0) lgkmcnt(0)
	s_barrier
	s_add_u32 m0, s38, 0
	s_nop 0
	global_load_lds_dwordx4 v164, s[98:99]
	s_waitcnt lgkmcnt(8)
	v_mfma_f32_16x16x32_bf16 v[48:51], v[76:79], v[96:99], v[48:51]
	s_add_u32 m0, s38, 4096
	s_nop 0
	global_load_lds_dwordx4 v165, s[98:99]
	s_waitcnt lgkmcnt(8)
	v_mfma_f32_16x16x32_bf16 v[52:55], v[76:79], v[100:103], v[52:55]
	s_add_u32 m0, s38, 8192
	s_nop 0
	global_load_lds_dwordx4 v166, s[98:99]
	s_waitcnt lgkmcnt(8)
	v_mfma_f32_16x16x32_bf16 v[56:59], v[76:79], v[104:107], v[56:59]
	s_add_u32 m0, s38, 12288
	s_nop 0
	global_load_lds_dwordx4 v167, s[98:99]
	s_add_u32 s98, s98, 128
	s_addc_u32 s99, s99, 0
	s_waitcnt lgkmcnt(8)
	v_mfma_f32_16x16x32_bf16 v[60:63], v[76:79], v[108:111], v[60:63]
	s_add_u32 m0, s38, 16384
	s_nop 0
	global_load_lds_dwordx4 v164, s[100:101]
	s_waitcnt lgkmcnt(6)
	v_mfma_f32_16x16x32_bf16 v[0:3], v[80:83], v[112:115], v[0:3]
	ds_read_b128 v[64:67], v150 offset:32768
	s_add_u32 m0, s38, 20480
	s_nop 0
	global_load_lds_dwordx4 v165, s[100:101]
	s_waitcnt lgkmcnt(6)
	v_mfma_f32_16x16x32_bf16 v[4:7], v[80:83], v[116:119], v[4:7]
	ds_read_b128 v[96:99], v162 offset:49152
	s_add_u32 m0, s38, 24576
	s_nop 0
	global_load_lds_dwordx4 v166, s[100:101]
	s_waitcnt lgkmcnt(6)
	v_mfma_f32_16x16x32_bf16 v[8:11], v[80:83], v[120:123], v[8:11]
	ds_read_b128 v[100:103], v162 offset:51200
	s_add_u32 m0, s38, 28672
	s_nop 0
	global_load_lds_dwordx4 v167, s[100:101]
	s_add_u32 s100, s100, 128
	s_addc_u32 s101, s101, 0
	s_waitcnt lgkmcnt(6)
	v_mfma_f32_16x16x32_bf16 v[12:15], v[80:83], v[124:127], v[12:15]
	ds_read_b128 v[104:107], v162 offset:53248
	s_waitcnt lgkmcnt(6)
	v_mfma_f32_16x16x32_bf16 v[16:19], v[84:87], v[112:115], v[16:19]
	ds_read_b128 v[108:111], v162 offset:55296
	s_waitcnt lgkmcnt(7)
	v_mfma_f32_16x16x32_bf16 v[20:23], v[84:87], v[116:119], v[20:23]
	ds_read_b128 v[68:71], v150 offset:34816
	s_waitcnt lgkmcnt(8)
	v_mfma_f32_16x16x32_bf16 v[24:27], v[84:87], v[120:123], v[24:27]
	ds_read_b128 v[72:75], v150 offset:36864
	s_waitcnt lgkmcnt(9)
	v_mfma_f32_16x16x32_bf16 v[28:31], v[84:87], v[124:127], v[28:31]
	ds_read_b128 v[76:79], v150 offset:38912
	s_waitcnt lgkmcnt(9)
	v_mfma_f32_16x16x32_bf16 v[32:35], v[88:91], v[112:115], v[32:35]
	s_waitcnt lgkmcnt(9)
	v_mfma_f32_16x16x32_bf16 v[36:39], v[88:91], v[116:119], v[36:39]
	s_waitcnt lgkmcnt(9)
	v_mfma_f32_16x16x32_bf16 v[40:43], v[88:91], v[120:123], v[40:43]
	s_waitcnt lgkmcnt(9)
	v_mfma_f32_16x16x32_bf16 v[44:47], v[88:91], v[124:127], v[44:47]
	s_waitcnt lgkmcnt(8)
	v_mfma_f32_16x16x32_bf16 v[48:51], v[92:95], v[112:115], v[48:51]
	s_waitcnt lgkmcnt(8)
	v_mfma_f32_16x16x32_bf16 v[52:55], v[92:95], v[116:119], v[52:55]
	s_waitcnt lgkmcnt(8)
	v_mfma_f32_16x16x32_bf16 v[56:59], v[92:95], v[120:123], v[56:59]
	s_waitcnt lgkmcnt(8)
	v_mfma_f32_16x16x32_bf16 v[60:63], v[92:95], v[124:127], v[60:63]
	s_waitcnt lgkmcnt(6)
	v_mfma_f32_16x16x32_bf16 v[0:3], v[64:67], v[96:99], v[0:3]
	ds_read_b128 v[80:83], v151 offset:32768
	s_waitcnt lgkmcnt(6)
	v_mfma_f32_16x16x32_bf16 v[4:7], v[64:67], v[100:103], v[4:7]
	ds_read_b128 v[112:115], v163 offset:49152
	s_waitcnt lgkmcnt(6)
	v_mfma_f32_16x16x32_bf16 v[8:11], v[64:67], v[104:107], v[8:11]
	ds_read_b128 v[116:119], v163 offset:51200
	s_waitcnt lgkmcnt(6)
	v_mfma_f32_16x16x32_bf16 v[12:15], v[64:67], v[108:111], v[12:15]
	ds_read_b128 v[120:123], v163 offset:53248
	s_waitcnt lgkmcnt(6)
	v_mfma_f32_16x16x32_bf16 v[16:19], v[68:71], v[96:99], v[16:19]
	ds_read_b128 v[124:127], v163 offset:55296
	s_waitcnt lgkmcnt(7)
	v_mfma_f32_16x16x32_bf16 v[20:23], v[68:71], v[100:103], v[20:23]
	ds_read_b128 v[84:87], v151 offset:34816
	s_waitcnt lgkmcnt(8)
	v_mfma_f32_16x16x32_bf16 v[24:27], v[68:71], v[104:107], v[24:27]
	ds_read_b128 v[88:91], v151 offset:36864
	s_waitcnt lgkmcnt(9)
	v_mfma_f32_16x16x32_bf16 v[28:31], v[68:71], v[108:111], v[28:31]
	ds_read_b128 v[92:95], v151 offset:38912
	s_waitcnt lgkmcnt(9)
	v_mfma_f32_16x16x32_bf16 v[32:35], v[72:75], v[96:99], v[32:35]
	s_waitcnt lgkmcnt(9)
	v_mfma_f32_16x16x32_bf16 v[36:39], v[72:75], v[100:103], v[36:39]
	s_waitcnt lgkmcnt(9)
	v_mfma_f32_16x16x32_bf16 v[40:43], v[72:75], v[104:107], v[40:43]
	s_waitcnt lgkmcnt(9)
	v_mfma_f32_16x16x32_bf16 v[44:47], v[72:75], v[108:111], v[44:47]
	s_waitcnt vmcnt(0) lgkmcnt(0)
	s_barrier
	s_add_u32 m0, s38, 32768
	s_nop 0
	global_load_lds_dwordx4 v164, s[98:99]
	s_waitcnt lgkmcnt(8)
	v_mfma_f32_16x16x32_bf16 v[48:51], v[76:79], v[96:99], v[48:51]
	s_add_u32 m0, s38, 36864
	s_nop 0
	global_load_lds_dwordx4 v165, s[98:99]
	s_waitcnt lgkmcnt(8)
	v_mfma_f32_16x16x32_bf16 v[52:55], v[76:79], v[100:103], v[52:55]
	s_add_u32 m0, s38, 40960
	s_nop 0
	global_load_lds_dwordx4 v166, s[98:99]
	s_waitcnt lgkmcnt(8)
	v_mfma_f32_16x16x32_bf16 v[56:59], v[76:79], v[104:107], v[56:59]
	s_add_u32 m0, s38, 45056
	s_nop 0
	global_load_lds_dwordx4 v167, s[98:99]
	s_add_u32 s98, s98, 128
	s_addc_u32 s99, s99, 0
	s_waitcnt lgkmcnt(8)
	v_mfma_f32_16x16x32_bf16 v[60:63], v[76:79], v[108:111], v[60:63]
	s_add_u32 m0, s38, 49152
	s_nop 0
	global_load_lds_dwordx4 v164, s[100:101]
	s_waitcnt lgkmcnt(6)
	v_mfma_f32_16x16x32_bf16 v[0:3], v[80:83], v[112:115], v[0:3]
	ds_read_b128 v[64:67], v150 offset:0
	s_add_u32 m0, s38, 53248
	s_nop 0
	global_load_lds_dwordx4 v165, s[100:101]
	s_waitcnt lgkmcnt(6)
	v_mfma_f32_16x16x32_bf16 v[4:7], v[80:83], v[116:119], v[4:7]
	ds_read_b128 v[96:99], v162 offset:16384
	s_add_u32 m0, s38, 57344
	s_nop 0
	global_load_lds_dwordx4 v166, s[100:101]
	s_waitcnt lgkmcnt(6)
	v_mfma_f32_16x16x32_bf16 v[8:11], v[80:83], v[120:123], v[8:11]
	ds_read_b128 v[100:103], v162 offset:18432
	s_add_u32 m0, s38, 61440
	s_nop 0
	global_load_lds_dwordx4 v167, s[100:101]
	s_add_u32 s100, s100, 128
	s_addc_u32 s101, s101, 0
	s_waitcnt lgkmcnt(6)
	v_mfma_f32_16x16x32_bf16 v[12:15], v[80:83], v[124:127], v[12:15]
	ds_read_b128 v[104:107], v162 offset:20480
	s_waitcnt lgkmcnt(6)
	v_mfma_f32_16x16x32_bf16 v[16:19], v[84:87], v[112:115], v[16:19]
	ds_read_b128 v[108:111], v162 offset:22528
	s_waitcnt lgkmcnt(7)
	v_mfma_f32_16x16x32_bf16 v[20:23], v[84:87], v[116:119], v[20:23]
	ds_read_b128 v[68:71], v150 offset:2048
	s_waitcnt lgkmcnt(8)
	v_mfma_f32_16x16x32_bf16 v[24:27], v[84:87], v[120:123], v[24:27]
	ds_read_b128 v[72:75], v150 offset:4096
	s_waitcnt lgkmcnt(9)
	v_mfma_f32_16x16x32_bf16 v[28:31], v[84:87], v[124:127], v[28:31]
	ds_read_b128 v[76:79], v150 offset:6144
	s_waitcnt lgkmcnt(9)
	v_mfma_f32_16x16x32_bf16 v[32:35], v[88:91], v[112:115], v[32:35]
	s_waitcnt lgkmcnt(9)
	v_mfma_f32_16x16x32_bf16 v[36:39], v[88:91], v[116:119], v[36:39]
	s_waitcnt lgkmcnt(9)
	v_mfma_f32_16x16x32_bf16 v[40:43], v[88:91], v[120:123], v[40:43]
	s_waitcnt lgkmcnt(9)
	v_mfma_f32_16x16x32_bf16 v[44:47], v[88:91], v[124:127], v[44:47]
	s_waitcnt lgkmcnt(8)
	v_mfma_f32_16x16x32_bf16 v[48:51], v[92:95], v[112:115], v[48:51]
	s_waitcnt lgkmcnt(8)
	v_mfma_f32_16x16x32_bf16 v[52:55], v[92:95], v[116:119], v[52:55]
	s_waitcnt lgkmcnt(8)
	v_mfma_f32_16x16x32_bf16 v[56:59], v[92:95], v[120:123], v[56:59]
	s_waitcnt lgkmcnt(8)
	v_mfma_f32_16x16x32_bf16 v[60:63], v[92:95], v[124:127], v[60:63]
	s_waitcnt lgkmcnt(6)
	v_mfma_f32_16x16x32_bf16 v[0:3], v[64:67], v[96:99], v[0:3]
	ds_read_b128 v[80:83], v151 offset:0
	s_waitcnt lgkmcnt(6)
	v_mfma_f32_16x16x32_bf16 v[4:7], v[64:67], v[100:103], v[4:7]
	ds_read_b128 v[112:115], v163 offset:16384
	s_waitcnt lgkmcnt(6)
	v_mfma_f32_16x16x32_bf16 v[8:11], v[64:67], v[104:107], v[8:11]
	ds_read_b128 v[116:119], v163 offset:18432
	s_waitcnt lgkmcnt(6)
	v_mfma_f32_16x16x32_bf16 v[12:15], v[64:67], v[108:111], v[12:15]
	ds_read_b128 v[120:123], v163 offset:20480
	s_waitcnt lgkmcnt(6)
	v_mfma_f32_16x16x32_bf16 v[16:19], v[68:71], v[96:99], v[16:19]
	ds_read_b128 v[124:127], v163 offset:22528
	s_waitcnt lgkmcnt(7)
	v_mfma_f32_16x16x32_bf16 v[20:23], v[68:71], v[100:103], v[20:23]
	ds_read_b128 v[84:87], v151 offset:2048
	s_waitcnt lgkmcnt(8)
	v_mfma_f32_16x16x32_bf16 v[24:27], v[68:71], v[104:107], v[24:27]
	ds_read_b128 v[88:91], v151 offset:4096
	s_waitcnt lgkmcnt(9)
	v_mfma_f32_16x16x32_bf16 v[28:31], v[68:71], v[108:111], v[28:31]
	ds_read_b128 v[92:95], v151 offset:6144
	s_waitcnt lgkmcnt(9)
	v_mfma_f32_16x16x32_bf16 v[32:35], v[72:75], v[96:99], v[32:35]
	s_waitcnt lgkmcnt(9)
	v_mfma_f32_16x16x32_bf16 v[36:39], v[72:75], v[100:103], v[36:39]
	s_waitcnt lgkmcnt(9)
	v_mfma_f32_16x16x32_bf16 v[40:43], v[72:75], v[104:107], v[40:43]
	s_waitcnt lgkmcnt(9)
	v_mfma_f32_16x16x32_bf16 v[44:47], v[72:75], v[108:111], v[44:47]
	s_waitcnt vmcnt(0) lgkmcnt(0)
	s_barrier
	s_add_u32 m0, s38, 0
	s_nop 0
	global_load_lds_dwordx4 v164, s[98:99]
	s_waitcnt lgkmcnt(8)
	v_mfma_f32_16x16x32_bf16 v[48:51], v[76:79], v[96:99], v[48:51]
	s_add_u32 m0, s38, 4096
	s_nop 0
	global_load_lds_dwordx4 v165, s[98:99]
	s_waitcnt lgkmcnt(8)
	v_mfma_f32_16x16x32_bf16 v[52:55], v[76:79], v[100:103], v[52:55]
	s_add_u32 m0, s38, 8192
	s_nop 0
	global_load_lds_dwordx4 v166, s[98:99]
	s_waitcnt lgkmcnt(8)
	v_mfma_f32_16x16x32_bf16 v[56:59], v[76:79], v[104:107], v[56:59]
	s_add_u32 m0, s38, 12288
	s_nop 0
	global_load_lds_dwordx4 v167, s[98:99]
	s_add_u32 s98, s98, 128
	s_addc_u32 s99, s99, 0
	s_waitcnt lgkmcnt(8)
	v_mfma_f32_16x16x32_bf16 v[60:63], v[76:79], v[108:111], v[60:63]
	s_add_u32 m0, s38, 16384
	s_nop 0
	global_load_lds_dwordx4 v164, s[100:101]
	s_waitcnt lgkmcnt(6)
	v_mfma_f32_16x16x32_bf16 v[0:3], v[80:83], v[112:115], v[0:3]
	ds_read_b128 v[64:67], v150 offset:32768
	s_add_u32 m0, s38, 20480
	s_nop 0
	global_load_lds_dwordx4 v165, s[100:101]
	s_waitcnt lgkmcnt(6)
	v_mfma_f32_16x16x32_bf16 v[4:7], v[80:83], v[116:119], v[4:7]
	ds_read_b128 v[96:99], v162 offset:49152
	s_add_u32 m0, s38, 24576
	s_nop 0
	global_load_lds_dwordx4 v166, s[100:101]
	s_waitcnt lgkmcnt(6)
	v_mfma_f32_16x16x32_bf16 v[8:11], v[80:83], v[120:123], v[8:11]
	ds_read_b128 v[100:103], v162 offset:51200
	s_add_u32 m0, s38, 28672
	s_nop 0
	global_load_lds_dwordx4 v167, s[100:101]
	s_add_u32 s100, s100, 128
	s_addc_u32 s101, s101, 0
	s_waitcnt lgkmcnt(6)
	v_mfma_f32_16x16x32_bf16 v[12:15], v[80:83], v[124:127], v[12:15]
	ds_read_b128 v[104:107], v162 offset:53248
	s_waitcnt lgkmcnt(6)
	v_mfma_f32_16x16x32_bf16 v[16:19], v[84:87], v[112:115], v[16:19]
	ds_read_b128 v[108:111], v162 offset:55296
	s_waitcnt lgkmcnt(7)
	v_mfma_f32_16x16x32_bf16 v[20:23], v[84:87], v[116:119], v[20:23]
	ds_read_b128 v[68:71], v150 offset:34816
	s_waitcnt lgkmcnt(8)
	v_mfma_f32_16x16x32_bf16 v[24:27], v[84:87], v[120:123], v[24:27]
	ds_read_b128 v[72:75], v150 offset:36864
	s_waitcnt lgkmcnt(9)
	v_mfma_f32_16x16x32_bf16 v[28:31], v[84:87], v[124:127], v[28:31]
	ds_read_b128 v[76:79], v150 offset:38912
	s_waitcnt lgkmcnt(9)
	v_mfma_f32_16x16x32_bf16 v[32:35], v[88:91], v[112:115], v[32:35]
	s_waitcnt lgkmcnt(9)
	v_mfma_f32_16x16x32_bf16 v[36:39], v[88:91], v[116:119], v[36:39]
	s_waitcnt lgkmcnt(9)
	v_mfma_f32_16x16x32_bf16 v[40:43], v[88:91], v[120:123], v[40:43]
	s_waitcnt lgkmcnt(9)
	v_mfma_f32_16x16x32_bf16 v[44:47], v[88:91], v[124:127], v[44:47]
	s_waitcnt lgkmcnt(8)
	v_mfma_f32_16x16x32_bf16 v[48:51], v[92:95], v[112:115], v[48:51]
	s_waitcnt lgkmcnt(8)
	v_mfma_f32_16x16x32_bf16 v[52:55], v[92:95], v[116:119], v[52:55]
	s_waitcnt lgkmcnt(8)
	v_mfma_f32_16x16x32_bf16 v[56:59], v[92:95], v[120:123], v[56:59]
	s_waitcnt lgkmcnt(8)
	v_mfma_f32_16x16x32_bf16 v[60:63], v[92:95], v[124:127], v[60:63]
	s_waitcnt lgkmcnt(6)
	v_mfma_f32_16x16x32_bf16 v[0:3], v[64:67], v[96:99], v[0:3]
	ds_read_b128 v[80:83], v151 offset:32768
	s_waitcnt lgkmcnt(6)
	v_mfma_f32_16x16x32_bf16 v[4:7], v[64:67], v[100:103], v[4:7]
	ds_read_b128 v[112:115], v163 offset:49152
	s_waitcnt lgkmcnt(6)
	v_mfma_f32_16x16x32_bf16 v[8:11], v[64:67], v[104:107], v[8:11]
	ds_read_b128 v[116:119], v163 offset:51200
	s_waitcnt lgkmcnt(6)
	v_mfma_f32_16x16x32_bf16 v[12:15], v[64:67], v[108:111], v[12:15]
	ds_read_b128 v[120:123], v163 offset:53248
	s_waitcnt lgkmcnt(6)
	v_mfma_f32_16x16x32_bf16 v[16:19], v[68:71], v[96:99], v[16:19]
	ds_read_b128 v[124:127], v163 offset:55296
	s_waitcnt lgkmcnt(7)
	v_mfma_f32_16x16x32_bf16 v[20:23], v[68:71], v[100:103], v[20:23]
	ds_read_b128 v[84:87], v151 offset:34816
	s_waitcnt lgkmcnt(8)
	v_mfma_f32_16x16x32_bf16 v[24:27], v[68:71], v[104:107], v[24:27]
	ds_read_b128 v[88:91], v151 offset:36864
	s_waitcnt lgkmcnt(9)
	v_mfma_f32_16x16x32_bf16 v[28:31], v[68:71], v[108:111], v[28:31]
	ds_read_b128 v[92:95], v151 offset:38912
	s_waitcnt lgkmcnt(9)
	v_mfma_f32_16x16x32_bf16 v[32:35], v[72:75], v[96:99], v[32:35]
	s_waitcnt lgkmcnt(9)
	v_mfma_f32_16x16x32_bf16 v[36:39], v[72:75], v[100:103], v[36:39]
	s_waitcnt lgkmcnt(9)
	v_mfma_f32_16x16x32_bf16 v[40:43], v[72:75], v[104:107], v[40:43]
	s_waitcnt lgkmcnt(9)
	v_mfma_f32_16x16x32_bf16 v[44:47], v[72:75], v[108:111], v[44:47]
	s_waitcnt vmcnt(0) lgkmcnt(0)
	s_barrier
	s_add_u32 m0, s38, 32768
	s_nop 0
	global_load_lds_dwordx4 v164, s[98:99]
	s_waitcnt lgkmcnt(8)
	v_mfma_f32_16x16x32_bf16 v[48:51], v[76:79], v[96:99], v[48:51]
	s_add_u32 m0, s38, 36864
	s_nop 0
	global_load_lds_dwordx4 v165, s[98:99]
	s_waitcnt lgkmcnt(8)
	v_mfma_f32_16x16x32_bf16 v[52:55], v[76:79], v[100:103], v[52:55]
	s_add_u32 m0, s38, 40960
	s_nop 0
	global_load_lds_dwordx4 v166, s[98:99]
	s_waitcnt lgkmcnt(8)
	v_mfma_f32_16x16x32_bf16 v[56:59], v[76:79], v[104:107], v[56:59]
	s_add_u32 m0, s38, 45056
	s_nop 0
	global_load_lds_dwordx4 v167, s[98:99]
	s_add_u32 s98, s98, 128
	s_addc_u32 s99, s99, 0
	s_waitcnt lgkmcnt(8)
	v_mfma_f32_16x16x32_bf16 v[60:63], v[76:79], v[108:111], v[60:63]
	s_add_u32 m0, s38, 49152
	s_nop 0
	global_load_lds_dwordx4 v164, s[100:101]
	s_waitcnt lgkmcnt(6)
	v_mfma_f32_16x16x32_bf16 v[0:3], v[80:83], v[112:115], v[0:3]
	ds_read_b128 v[64:67], v150 offset:0
	s_add_u32 m0, s38, 53248
	s_nop 0
	global_load_lds_dwordx4 v165, s[100:101]
	s_waitcnt lgkmcnt(6)
	v_mfma_f32_16x16x32_bf16 v[4:7], v[80:83], v[116:119], v[4:7]
	ds_read_b128 v[96:99], v162 offset:16384
	s_add_u32 m0, s38, 57344
	s_nop 0
	global_load_lds_dwordx4 v166, s[100:101]
	s_waitcnt lgkmcnt(6)
	v_mfma_f32_16x16x32_bf16 v[8:11], v[80:83], v[120:123], v[8:11]
	ds_read_b128 v[100:103], v162 offset:18432
	s_add_u32 m0, s38, 61440
	s_nop 0
	global_load_lds_dwordx4 v167, s[100:101]
	s_add_u32 s100, s100, 128
	s_addc_u32 s101, s101, 0
	s_waitcnt lgkmcnt(6)
	v_mfma_f32_16x16x32_bf16 v[12:15], v[80:83], v[124:127], v[12:15]
	ds_read_b128 v[104:107], v162 offset:20480
	s_waitcnt lgkmcnt(6)
	v_mfma_f32_16x16x32_bf16 v[16:19], v[84:87], v[112:115], v[16:19]
	ds_read_b128 v[108:111], v162 offset:22528
	s_waitcnt lgkmcnt(7)
	v_mfma_f32_16x16x32_bf16 v[20:23], v[84:87], v[116:119], v[20:23]
	ds_read_b128 v[68:71], v150 offset:2048
	s_waitcnt lgkmcnt(8)
	v_mfma_f32_16x16x32_bf16 v[24:27], v[84:87], v[120:123], v[24:27]
	ds_read_b128 v[72:75], v150 offset:4096
	s_waitcnt lgkmcnt(9)
	v_mfma_f32_16x16x32_bf16 v[28:31], v[84:87], v[124:127], v[28:31]
	ds_read_b128 v[76:79], v150 offset:6144
	s_waitcnt lgkmcnt(9)
	v_mfma_f32_16x16x32_bf16 v[32:35], v[88:91], v[112:115], v[32:35]
	s_waitcnt lgkmcnt(9)
	v_mfma_f32_16x16x32_bf16 v[36:39], v[88:91], v[116:119], v[36:39]
	s_waitcnt lgkmcnt(9)
	v_mfma_f32_16x16x32_bf16 v[40:43], v[88:91], v[120:123], v[40:43]
	s_waitcnt lgkmcnt(9)
	v_mfma_f32_16x16x32_bf16 v[44:47], v[88:91], v[124:127], v[44:47]
	s_waitcnt lgkmcnt(8)
	v_mfma_f32_16x16x32_bf16 v[48:51], v[92:95], v[112:115], v[48:51]
	s_waitcnt lgkmcnt(8)
	v_mfma_f32_16x16x32_bf16 v[52:55], v[92:95], v[116:119], v[52:55]
	s_waitcnt lgkmcnt(8)
	v_mfma_f32_16x16x32_bf16 v[56:59], v[92:95], v[120:123], v[56:59]
	s_waitcnt lgkmcnt(8)
	v_mfma_f32_16x16x32_bf16 v[60:63], v[92:95], v[124:127], v[60:63]
	s_waitcnt lgkmcnt(6)
	v_mfma_f32_16x16x32_bf16 v[0:3], v[64:67], v[96:99], v[0:3]
	ds_read_b128 v[80:83], v151 offset:0
	s_waitcnt lgkmcnt(6)
	v_mfma_f32_16x16x32_bf16 v[4:7], v[64:67], v[100:103], v[4:7]
	ds_read_b128 v[112:115], v163 offset:16384
	s_waitcnt lgkmcnt(6)
	v_mfma_f32_16x16x32_bf16 v[8:11], v[64:67], v[104:107], v[8:11]
	ds_read_b128 v[116:119], v163 offset:18432
	s_waitcnt lgkmcnt(6)
	v_mfma_f32_16x16x32_bf16 v[12:15], v[64:67], v[108:111], v[12:15]
	ds_read_b128 v[120:123], v163 offset:20480
	s_waitcnt lgkmcnt(6)
	v_mfma_f32_16x16x32_bf16 v[16:19], v[68:71], v[96:99], v[16:19]
	ds_read_b128 v[124:127], v163 offset:22528
	s_waitcnt lgkmcnt(7)
	v_mfma_f32_16x16x32_bf16 v[20:23], v[68:71], v[100:103], v[20:23]
	ds_read_b128 v[84:87], v151 offset:2048
	s_waitcnt lgkmcnt(8)
	v_mfma_f32_16x16x32_bf16 v[24:27], v[68:71], v[104:107], v[24:27]
	ds_read_b128 v[88:91], v151 offset:4096
	s_waitcnt lgkmcnt(9)
	v_mfma_f32_16x16x32_bf16 v[28:31], v[68:71], v[108:111], v[28:31]
	ds_read_b128 v[92:95], v151 offset:6144
	s_waitcnt lgkmcnt(9)
	v_mfma_f32_16x16x32_bf16 v[32:35], v[72:75], v[96:99], v[32:35]
	s_waitcnt lgkmcnt(9)
	v_mfma_f32_16x16x32_bf16 v[36:39], v[72:75], v[100:103], v[36:39]
	s_waitcnt lgkmcnt(9)
	v_mfma_f32_16x16x32_bf16 v[40:43], v[72:75], v[104:107], v[40:43]
	s_waitcnt lgkmcnt(9)
	v_mfma_f32_16x16x32_bf16 v[44:47], v[72:75], v[108:111], v[44:47]
	s_waitcnt vmcnt(0) lgkmcnt(0)
	s_barrier
	s_add_u32 m0, s38, 0
	s_nop 0
	global_load_lds_dwordx4 v164, s[98:99]
	s_waitcnt lgkmcnt(8)
	v_mfma_f32_16x16x32_bf16 v[48:51], v[76:79], v[96:99], v[48:51]
	s_add_u32 m0, s38, 4096
	s_nop 0
	global_load_lds_dwordx4 v165, s[98:99]
	s_waitcnt lgkmcnt(8)
	v_mfma_f32_16x16x32_bf16 v[52:55], v[76:79], v[100:103], v[52:55]
	s_add_u32 m0, s38, 8192
	s_nop 0
	global_load_lds_dwordx4 v166, s[98:99]
	s_waitcnt lgkmcnt(8)
	v_mfma_f32_16x16x32_bf16 v[56:59], v[76:79], v[104:107], v[56:59]
	s_add_u32 m0, s38, 12288
	s_nop 0
	global_load_lds_dwordx4 v167, s[98:99]
	s_add_u32 s98, s98, 128
	s_addc_u32 s99, s99, 0
	s_waitcnt lgkmcnt(8)
	v_mfma_f32_16x16x32_bf16 v[60:63], v[76:79], v[108:111], v[60:63]
	s_add_u32 m0, s38, 16384
	s_nop 0
	global_load_lds_dwordx4 v164, s[100:101]
	s_waitcnt lgkmcnt(6)
	v_mfma_f32_16x16x32_bf16 v[0:3], v[80:83], v[112:115], v[0:3]
	ds_read_b128 v[64:67], v150 offset:32768
	s_add_u32 m0, s38, 20480
	s_nop 0
	global_load_lds_dwordx4 v165, s[100:101]
	s_waitcnt lgkmcnt(6)
	v_mfma_f32_16x16x32_bf16 v[4:7], v[80:83], v[116:119], v[4:7]
	ds_read_b128 v[96:99], v162 offset:49152
	s_add_u32 m0, s38, 24576
	s_nop 0
	global_load_lds_dwordx4 v166, s[100:101]
	s_waitcnt lgkmcnt(6)
	v_mfma_f32_16x16x32_bf16 v[8:11], v[80:83], v[120:123], v[8:11]
	ds_read_b128 v[100:103], v162 offset:51200
	s_add_u32 m0, s38, 28672
	s_nop 0
	global_load_lds_dwordx4 v167, s[100:101]
	s_add_u32 s100, s100, 128
	s_addc_u32 s101, s101, 0
	s_waitcnt lgkmcnt(6)
	v_mfma_f32_16x16x32_bf16 v[12:15], v[80:83], v[124:127], v[12:15]
	ds_read_b128 v[104:107], v162 offset:53248
	s_waitcnt lgkmcnt(6)
	v_mfma_f32_16x16x32_bf16 v[16:19], v[84:87], v[112:115], v[16:19]
	ds_read_b128 v[108:111], v162 offset:55296
	s_waitcnt lgkmcnt(7)
	v_mfma_f32_16x16x32_bf16 v[20:23], v[84:87], v[116:119], v[20:23]
	ds_read_b128 v[68:71], v150 offset:34816
	s_waitcnt lgkmcnt(8)
	v_mfma_f32_16x16x32_bf16 v[24:27], v[84:87], v[120:123], v[24:27]
	ds_read_b128 v[72:75], v150 offset:36864
	s_waitcnt lgkmcnt(9)
	v_mfma_f32_16x16x32_bf16 v[28:31], v[84:87], v[124:127], v[28:31]
	ds_read_b128 v[76:79], v150 offset:38912
	s_waitcnt lgkmcnt(9)
	v_mfma_f32_16x16x32_bf16 v[32:35], v[88:91], v[112:115], v[32:35]
	s_waitcnt lgkmcnt(9)
	v_mfma_f32_16x16x32_bf16 v[36:39], v[88:91], v[116:119], v[36:39]
	s_waitcnt lgkmcnt(9)
	v_mfma_f32_16x16x32_bf16 v[40:43], v[88:91], v[120:123], v[40:43]
	s_waitcnt lgkmcnt(9)
	v_mfma_f32_16x16x32_bf16 v[44:47], v[88:91], v[124:127], v[44:47]
	s_waitcnt lgkmcnt(8)
	v_mfma_f32_16x16x32_bf16 v[48:51], v[92:95], v[112:115], v[48:51]
	s_waitcnt lgkmcnt(8)
	v_mfma_f32_16x16x32_bf16 v[52:55], v[92:95], v[116:119], v[52:55]
	s_waitcnt lgkmcnt(8)
	v_mfma_f32_16x16x32_bf16 v[56:59], v[92:95], v[120:123], v[56:59]
	s_waitcnt lgkmcnt(8)
	v_mfma_f32_16x16x32_bf16 v[60:63], v[92:95], v[124:127], v[60:63]
	s_waitcnt lgkmcnt(6)
	v_mfma_f32_16x16x32_bf16 v[0:3], v[64:67], v[96:99], v[0:3]
	ds_read_b128 v[80:83], v151 offset:32768
	s_waitcnt lgkmcnt(6)
	v_mfma_f32_16x16x32_bf16 v[4:7], v[64:67], v[100:103], v[4:7]
	ds_read_b128 v[112:115], v163 offset:49152
	s_waitcnt lgkmcnt(6)
	v_mfma_f32_16x16x32_bf16 v[8:11], v[64:67], v[104:107], v[8:11]
	ds_read_b128 v[116:119], v163 offset:51200
	s_waitcnt lgkmcnt(6)
	v_mfma_f32_16x16x32_bf16 v[12:15], v[64:67], v[108:111], v[12:15]
	ds_read_b128 v[120:123], v163 offset:53248
	s_waitcnt lgkmcnt(6)
	v_mfma_f32_16x16x32_bf16 v[16:19], v[68:71], v[96:99], v[16:19]
	ds_read_b128 v[124:127], v163 offset:55296
	s_waitcnt lgkmcnt(7)
	v_mfma_f32_16x16x32_bf16 v[20:23], v[68:71], v[100:103], v[20:23]
	ds_read_b128 v[84:87], v151 offset:34816
	s_waitcnt lgkmcnt(8)
	v_mfma_f32_16x16x32_bf16 v[24:27], v[68:71], v[104:107], v[24:27]
	ds_read_b128 v[88:91], v151 offset:36864
	s_waitcnt lgkmcnt(9)
	v_mfma_f32_16x16x32_bf16 v[28:31], v[68:71], v[108:111], v[28:31]
	ds_read_b128 v[92:95], v151 offset:38912
	s_waitcnt lgkmcnt(9)
	v_mfma_f32_16x16x32_bf16 v[32:35], v[72:75], v[96:99], v[32:35]
	s_waitcnt lgkmcnt(9)
	v_mfma_f32_16x16x32_bf16 v[36:39], v[72:75], v[100:103], v[36:39]
	s_waitcnt lgkmcnt(9)
	v_mfma_f32_16x16x32_bf16 v[40:43], v[72:75], v[104:107], v[40:43]
	s_waitcnt lgkmcnt(9)
	v_mfma_f32_16x16x32_bf16 v[44:47], v[72:75], v[108:111], v[44:47]
	s_waitcnt vmcnt(0) lgkmcnt(0)
	s_barrier
	s_add_u32 m0, s38, 32768
	s_nop 0
	global_load_lds_dwordx4 v164, s[98:99]
	s_waitcnt lgkmcnt(8)
	v_mfma_f32_16x16x32_bf16 v[48:51], v[76:79], v[96:99], v[48:51]
	s_add_u32 m0, s38, 36864
	s_nop 0
	global_load_lds_dwordx4 v165, s[98:99]
	s_waitcnt lgkmcnt(8)
	v_mfma_f32_16x16x32_bf16 v[52:55], v[76:79], v[100:103], v[52:55]
	s_add_u32 m0, s38, 40960
	s_nop 0
	global_load_lds_dwordx4 v166, s[98:99]
	s_waitcnt lgkmcnt(8)
	v_mfma_f32_16x16x32_bf16 v[56:59], v[76:79], v[104:107], v[56:59]
	s_add_u32 m0, s38, 45056
	s_nop 0
	global_load_lds_dwordx4 v167, s[98:99]
	s_add_u32 s98, s98, 128
	s_addc_u32 s99, s99, 0
	s_waitcnt lgkmcnt(8)
	v_mfma_f32_16x16x32_bf16 v[60:63], v[76:79], v[108:111], v[60:63]
	s_add_u32 m0, s38, 49152
	s_nop 0
	global_load_lds_dwordx4 v164, s[100:101]
	s_waitcnt lgkmcnt(6)
	v_mfma_f32_16x16x32_bf16 v[0:3], v[80:83], v[112:115], v[0:3]
	ds_read_b128 v[64:67], v150 offset:0
	s_add_u32 m0, s38, 53248
	s_nop 0
	global_load_lds_dwordx4 v165, s[100:101]
	s_waitcnt lgkmcnt(6)
	v_mfma_f32_16x16x32_bf16 v[4:7], v[80:83], v[116:119], v[4:7]
	ds_read_b128 v[96:99], v162 offset:16384
	s_add_u32 m0, s38, 57344
	s_nop 0
	global_load_lds_dwordx4 v166, s[100:101]
	s_waitcnt lgkmcnt(6)
	v_mfma_f32_16x16x32_bf16 v[8:11], v[80:83], v[120:123], v[8:11]
	ds_read_b128 v[100:103], v162 offset:18432
	s_add_u32 m0, s38, 61440
	s_nop 0
	global_load_lds_dwordx4 v167, s[100:101]
	s_add_u32 s100, s100, 128
	s_addc_u32 s101, s101, 0
	s_waitcnt lgkmcnt(6)
	v_mfma_f32_16x16x32_bf16 v[12:15], v[80:83], v[124:127], v[12:15]
	ds_read_b128 v[104:107], v162 offset:20480
	s_waitcnt lgkmcnt(6)
	v_mfma_f32_16x16x32_bf16 v[16:19], v[84:87], v[112:115], v[16:19]
	ds_read_b128 v[108:111], v162 offset:22528
	s_waitcnt lgkmcnt(7)
	v_mfma_f32_16x16x32_bf16 v[20:23], v[84:87], v[116:119], v[20:23]
	ds_read_b128 v[68:71], v150 offset:2048
	s_waitcnt lgkmcnt(8)
	v_mfma_f32_16x16x32_bf16 v[24:27], v[84:87], v[120:123], v[24:27]
	ds_read_b128 v[72:75], v150 offset:4096
	s_waitcnt lgkmcnt(9)
	v_mfma_f32_16x16x32_bf16 v[28:31], v[84:87], v[124:127], v[28:31]
	ds_read_b128 v[76:79], v150 offset:6144
	s_waitcnt lgkmcnt(9)
	v_mfma_f32_16x16x32_bf16 v[32:35], v[88:91], v[112:115], v[32:35]
	s_waitcnt lgkmcnt(9)
	v_mfma_f32_16x16x32_bf16 v[36:39], v[88:91], v[116:119], v[36:39]
	s_waitcnt lgkmcnt(9)
	v_mfma_f32_16x16x32_bf16 v[40:43], v[88:91], v[120:123], v[40:43]
	s_waitcnt lgkmcnt(9)
	v_mfma_f32_16x16x32_bf16 v[44:47], v[88:91], v[124:127], v[44:47]
	s_waitcnt lgkmcnt(8)
	v_mfma_f32_16x16x32_bf16 v[48:51], v[92:95], v[112:115], v[48:51]
	s_waitcnt lgkmcnt(8)
	v_mfma_f32_16x16x32_bf16 v[52:55], v[92:95], v[116:119], v[52:55]
	s_waitcnt lgkmcnt(8)
	v_mfma_f32_16x16x32_bf16 v[56:59], v[92:95], v[120:123], v[56:59]
	s_waitcnt lgkmcnt(8)
	v_mfma_f32_16x16x32_bf16 v[60:63], v[92:95], v[124:127], v[60:63]
	s_waitcnt lgkmcnt(6)
	v_mfma_f32_16x16x32_bf16 v[0:3], v[64:67], v[96:99], v[0:3]
	ds_read_b128 v[80:83], v151 offset:0
	s_waitcnt lgkmcnt(6)
	v_mfma_f32_16x16x32_bf16 v[4:7], v[64:67], v[100:103], v[4:7]
	ds_read_b128 v[112:115], v163 offset:16384
	s_waitcnt lgkmcnt(6)
	v_mfma_f32_16x16x32_bf16 v[8:11], v[64:67], v[104:107], v[8:11]
	ds_read_b128 v[116:119], v163 offset:18432
	s_waitcnt lgkmcnt(6)
	v_mfma_f32_16x16x32_bf16 v[12:15], v[64:67], v[108:111], v[12:15]
	ds_read_b128 v[120:123], v163 offset:20480
	s_waitcnt lgkmcnt(6)
	v_mfma_f32_16x16x32_bf16 v[16:19], v[68:71], v[96:99], v[16:19]
	ds_read_b128 v[124:127], v163 offset:22528
	s_waitcnt lgkmcnt(7)
	v_mfma_f32_16x16x32_bf16 v[20:23], v[68:71], v[100:103], v[20:23]
	ds_read_b128 v[84:87], v151 offset:2048
	s_waitcnt lgkmcnt(8)
	v_mfma_f32_16x16x32_bf16 v[24:27], v[68:71], v[104:107], v[24:27]
	ds_read_b128 v[88:91], v151 offset:4096
	s_waitcnt lgkmcnt(9)
	v_mfma_f32_16x16x32_bf16 v[28:31], v[68:71], v[108:111], v[28:31]
	ds_read_b128 v[92:95], v151 offset:6144
	s_waitcnt lgkmcnt(9)
	v_mfma_f32_16x16x32_bf16 v[32:35], v[72:75], v[96:99], v[32:35]
	s_waitcnt lgkmcnt(9)
	v_mfma_f32_16x16x32_bf16 v[36:39], v[72:75], v[100:103], v[36:39]
	s_waitcnt lgkmcnt(9)
	v_mfma_f32_16x16x32_bf16 v[40:43], v[72:75], v[104:107], v[40:43]
	s_waitcnt lgkmcnt(9)
	v_mfma_f32_16x16x32_bf16 v[44:47], v[72:75], v[108:111], v[44:47]
	s_waitcnt vmcnt(0) lgkmcnt(0)
	s_barrier
	s_add_u32 m0, s38, 0
	s_nop 0
	global_load_lds_dwordx4 v164, s[98:99]
	s_waitcnt lgkmcnt(8)
	v_mfma_f32_16x16x32_bf16 v[48:51], v[76:79], v[96:99], v[48:51]
	s_add_u32 m0, s38, 4096
	s_nop 0
	global_load_lds_dwordx4 v165, s[98:99]
	s_waitcnt lgkmcnt(8)
	v_mfma_f32_16x16x32_bf16 v[52:55], v[76:79], v[100:103], v[52:55]
	s_add_u32 m0, s38, 8192
	s_nop 0
	global_load_lds_dwordx4 v166, s[98:99]
	s_waitcnt lgkmcnt(8)
	v_mfma_f32_16x16x32_bf16 v[56:59], v[76:79], v[104:107], v[56:59]
	s_add_u32 m0, s38, 12288
	s_nop 0
	global_load_lds_dwordx4 v167, s[98:99]
	s_add_u32 s98, s98, 128
	s_addc_u32 s99, s99, 0
	s_waitcnt lgkmcnt(8)
	v_mfma_f32_16x16x32_bf16 v[60:63], v[76:79], v[108:111], v[60:63]
	s_add_u32 m0, s38, 16384
	s_nop 0
	global_load_lds_dwordx4 v164, s[100:101]
	s_waitcnt lgkmcnt(6)
	v_mfma_f32_16x16x32_bf16 v[0:3], v[80:83], v[112:115], v[0:3]
	ds_read_b128 v[64:67], v150 offset:32768
	s_add_u32 m0, s38, 20480
	s_nop 0
	global_load_lds_dwordx4 v165, s[100:101]
	s_waitcnt lgkmcnt(6)
	v_mfma_f32_16x16x32_bf16 v[4:7], v[80:83], v[116:119], v[4:7]
	ds_read_b128 v[96:99], v162 offset:49152
	s_add_u32 m0, s38, 24576
	s_nop 0
	global_load_lds_dwordx4 v166, s[100:101]
	s_waitcnt lgkmcnt(6)
	v_mfma_f32_16x16x32_bf16 v[8:11], v[80:83], v[120:123], v[8:11]
	ds_read_b128 v[100:103], v162 offset:51200
	s_add_u32 m0, s38, 28672
	s_nop 0
	global_load_lds_dwordx4 v167, s[100:101]
	s_add_u32 s100, s100, 128
	s_addc_u32 s101, s101, 0
	s_waitcnt lgkmcnt(6)
	v_mfma_f32_16x16x32_bf16 v[12:15], v[80:83], v[124:127], v[12:15]
	ds_read_b128 v[104:107], v162 offset:53248
	s_waitcnt lgkmcnt(6)
	v_mfma_f32_16x16x32_bf16 v[16:19], v[84:87], v[112:115], v[16:19]
	ds_read_b128 v[108:111], v162 offset:55296
	s_waitcnt lgkmcnt(7)
	v_mfma_f32_16x16x32_bf16 v[20:23], v[84:87], v[116:119], v[20:23]
	ds_read_b128 v[68:71], v150 offset:34816
	s_waitcnt lgkmcnt(8)
	v_mfma_f32_16x16x32_bf16 v[24:27], v[84:87], v[120:123], v[24:27]
	ds_read_b128 v[72:75], v150 offset:36864
	s_waitcnt lgkmcnt(9)
	v_mfma_f32_16x16x32_bf16 v[28:31], v[84:87], v[124:127], v[28:31]
	ds_read_b128 v[76:79], v150 offset:38912
	s_waitcnt lgkmcnt(9)
	v_mfma_f32_16x16x32_bf16 v[32:35], v[88:91], v[112:115], v[32:35]
	s_waitcnt lgkmcnt(9)
	v_mfma_f32_16x16x32_bf16 v[36:39], v[88:91], v[116:119], v[36:39]
	s_waitcnt lgkmcnt(9)
	v_mfma_f32_16x16x32_bf16 v[40:43], v[88:91], v[120:123], v[40:43]
	s_waitcnt lgkmcnt(9)
	v_mfma_f32_16x16x32_bf16 v[44:47], v[88:91], v[124:127], v[44:47]
	s_waitcnt lgkmcnt(8)
	v_mfma_f32_16x16x32_bf16 v[48:51], v[92:95], v[112:115], v[48:51]
	s_waitcnt lgkmcnt(8)
	v_mfma_f32_16x16x32_bf16 v[52:55], v[92:95], v[116:119], v[52:55]
	s_waitcnt lgkmcnt(8)
	v_mfma_f32_16x16x32_bf16 v[56:59], v[92:95], v[120:123], v[56:59]
	s_waitcnt lgkmcnt(8)
	v_mfma_f32_16x16x32_bf16 v[60:63], v[92:95], v[124:127], v[60:63]
	s_waitcnt lgkmcnt(6)
	v_mfma_f32_16x16x32_bf16 v[0:3], v[64:67], v[96:99], v[0:3]
	ds_read_b128 v[80:83], v151 offset:32768
	s_waitcnt lgkmcnt(6)
	v_mfma_f32_16x16x32_bf16 v[4:7], v[64:67], v[100:103], v[4:7]
	ds_read_b128 v[112:115], v163 offset:49152
	s_waitcnt lgkmcnt(6)
	v_mfma_f32_16x16x32_bf16 v[8:11], v[64:67], v[104:107], v[8:11]
	ds_read_b128 v[116:119], v163 offset:51200
	s_waitcnt lgkmcnt(6)
	v_mfma_f32_16x16x32_bf16 v[12:15], v[64:67], v[108:111], v[12:15]
	ds_read_b128 v[120:123], v163 offset:53248
	s_waitcnt lgkmcnt(6)
	v_mfma_f32_16x16x32_bf16 v[16:19], v[68:71], v[96:99], v[16:19]
	ds_read_b128 v[124:127], v163 offset:55296
	s_waitcnt lgkmcnt(7)
	v_mfma_f32_16x16x32_bf16 v[20:23], v[68:71], v[100:103], v[20:23]
	ds_read_b128 v[84:87], v151 offset:34816
	s_waitcnt lgkmcnt(8)
	v_mfma_f32_16x16x32_bf16 v[24:27], v[68:71], v[104:107], v[24:27]
	ds_read_b128 v[88:91], v151 offset:36864
	s_waitcnt lgkmcnt(9)
	v_mfma_f32_16x16x32_bf16 v[28:31], v[68:71], v[108:111], v[28:31]
	ds_read_b128 v[92:95], v151 offset:38912
	s_waitcnt lgkmcnt(9)
	v_mfma_f32_16x16x32_bf16 v[32:35], v[72:75], v[96:99], v[32:35]
	s_waitcnt lgkmcnt(9)
	v_mfma_f32_16x16x32_bf16 v[36:39], v[72:75], v[100:103], v[36:39]
	s_waitcnt lgkmcnt(9)
	v_mfma_f32_16x16x32_bf16 v[40:43], v[72:75], v[104:107], v[40:43]
	s_waitcnt lgkmcnt(9)
	v_mfma_f32_16x16x32_bf16 v[44:47], v[72:75], v[108:111], v[44:47]
	s_waitcnt vmcnt(0) lgkmcnt(0)
	s_barrier
	s_add_u32 m0, s38, 32768
	s_nop 0
	global_load_lds_dwordx4 v164, s[98:99]
	s_waitcnt lgkmcnt(8)
	v_mfma_f32_16x16x32_bf16 v[48:51], v[76:79], v[96:99], v[48:51]
	s_add_u32 m0, s38, 36864
	s_nop 0
	global_load_lds_dwordx4 v165, s[98:99]
	s_waitcnt lgkmcnt(8)
	v_mfma_f32_16x16x32_bf16 v[52:55], v[76:79], v[100:103], v[52:55]
	s_add_u32 m0, s38, 40960
	s_nop 0
	global_load_lds_dwordx4 v166, s[98:99]
	s_waitcnt lgkmcnt(8)
	v_mfma_f32_16x16x32_bf16 v[56:59], v[76:79], v[104:107], v[56:59]
	s_add_u32 m0, s38, 45056
	s_nop 0
	global_load_lds_dwordx4 v167, s[98:99]
	s_add_u32 s98, s98, 128
	s_addc_u32 s99, s99, 0
	s_waitcnt lgkmcnt(8)
	v_mfma_f32_16x16x32_bf16 v[60:63], v[76:79], v[108:111], v[60:63]
	s_add_u32 m0, s38, 49152
	s_nop 0
	global_load_lds_dwordx4 v164, s[100:101]
	s_waitcnt lgkmcnt(6)
	v_mfma_f32_16x16x32_bf16 v[0:3], v[80:83], v[112:115], v[0:3]
	ds_read_b128 v[64:67], v150 offset:0
	s_add_u32 m0, s38, 53248
	s_nop 0
	global_load_lds_dwordx4 v165, s[100:101]
	s_waitcnt lgkmcnt(6)
	v_mfma_f32_16x16x32_bf16 v[4:7], v[80:83], v[116:119], v[4:7]
	ds_read_b128 v[96:99], v162 offset:16384
	s_add_u32 m0, s38, 57344
	s_nop 0
	global_load_lds_dwordx4 v166, s[100:101]
	s_waitcnt lgkmcnt(6)
	v_mfma_f32_16x16x32_bf16 v[8:11], v[80:83], v[120:123], v[8:11]
	ds_read_b128 v[100:103], v162 offset:18432
	s_add_u32 m0, s38, 61440
	s_nop 0
	global_load_lds_dwordx4 v167, s[100:101]
	s_add_u32 s100, s100, 128
	s_addc_u32 s101, s101, 0
	s_waitcnt lgkmcnt(6)
	v_mfma_f32_16x16x32_bf16 v[12:15], v[80:83], v[124:127], v[12:15]
	ds_read_b128 v[104:107], v162 offset:20480
	s_waitcnt lgkmcnt(6)
	v_mfma_f32_16x16x32_bf16 v[16:19], v[84:87], v[112:115], v[16:19]
	ds_read_b128 v[108:111], v162 offset:22528
	s_waitcnt lgkmcnt(7)
	v_mfma_f32_16x16x32_bf16 v[20:23], v[84:87], v[116:119], v[20:23]
	ds_read_b128 v[68:71], v150 offset:2048
	s_waitcnt lgkmcnt(8)
	v_mfma_f32_16x16x32_bf16 v[24:27], v[84:87], v[120:123], v[24:27]
	ds_read_b128 v[72:75], v150 offset:4096
	s_waitcnt lgkmcnt(9)
	v_mfma_f32_16x16x32_bf16 v[28:31], v[84:87], v[124:127], v[28:31]
	ds_read_b128 v[76:79], v150 offset:6144
	s_waitcnt lgkmcnt(9)
	v_mfma_f32_16x16x32_bf16 v[32:35], v[88:91], v[112:115], v[32:35]
	s_waitcnt lgkmcnt(9)
	v_mfma_f32_16x16x32_bf16 v[36:39], v[88:91], v[116:119], v[36:39]
	s_waitcnt lgkmcnt(9)
	v_mfma_f32_16x16x32_bf16 v[40:43], v[88:91], v[120:123], v[40:43]
	s_waitcnt lgkmcnt(9)
	v_mfma_f32_16x16x32_bf16 v[44:47], v[88:91], v[124:127], v[44:47]
	s_waitcnt lgkmcnt(8)
	v_mfma_f32_16x16x32_bf16 v[48:51], v[92:95], v[112:115], v[48:51]
	s_waitcnt lgkmcnt(8)
	v_mfma_f32_16x16x32_bf16 v[52:55], v[92:95], v[116:119], v[52:55]
	s_waitcnt lgkmcnt(8)
	v_mfma_f32_16x16x32_bf16 v[56:59], v[92:95], v[120:123], v[56:59]
	s_waitcnt lgkmcnt(8)
	v_mfma_f32_16x16x32_bf16 v[60:63], v[92:95], v[124:127], v[60:63]
	s_waitcnt lgkmcnt(6)
	v_mfma_f32_16x16x32_bf16 v[0:3], v[64:67], v[96:99], v[0:3]
	ds_read_b128 v[80:83], v151 offset:0
	s_waitcnt lgkmcnt(6)
	v_mfma_f32_16x16x32_bf16 v[4:7], v[64:67], v[100:103], v[4:7]
	ds_read_b128 v[112:115], v163 offset:16384
	s_waitcnt lgkmcnt(6)
	v_mfma_f32_16x16x32_bf16 v[8:11], v[64:67], v[104:107], v[8:11]
	ds_read_b128 v[116:119], v163 offset:18432
	s_waitcnt lgkmcnt(6)
	v_mfma_f32_16x16x32_bf16 v[12:15], v[64:67], v[108:111], v[12:15]
	ds_read_b128 v[120:123], v163 offset:20480
	s_waitcnt lgkmcnt(6)
	v_mfma_f32_16x16x32_bf16 v[16:19], v[68:71], v[96:99], v[16:19]
	ds_read_b128 v[124:127], v163 offset:22528
	s_waitcnt lgkmcnt(7)
	v_mfma_f32_16x16x32_bf16 v[20:23], v[68:71], v[100:103], v[20:23]
	ds_read_b128 v[84:87], v151 offset:2048
	s_waitcnt lgkmcnt(8)
	v_mfma_f32_16x16x32_bf16 v[24:27], v[68:71], v[104:107], v[24:27]
	ds_read_b128 v[88:91], v151 offset:4096
	s_waitcnt lgkmcnt(9)
	v_mfma_f32_16x16x32_bf16 v[28:31], v[68:71], v[108:111], v[28:31]
	ds_read_b128 v[92:95], v151 offset:6144
	s_waitcnt lgkmcnt(9)
	v_mfma_f32_16x16x32_bf16 v[32:35], v[72:75], v[96:99], v[32:35]
	s_waitcnt lgkmcnt(9)
	v_mfma_f32_16x16x32_bf16 v[36:39], v[72:75], v[100:103], v[36:39]
	s_waitcnt lgkmcnt(9)
	v_mfma_f32_16x16x32_bf16 v[40:43], v[72:75], v[104:107], v[40:43]
	s_waitcnt lgkmcnt(9)
	v_mfma_f32_16x16x32_bf16 v[44:47], v[72:75], v[108:111], v[44:47]
	s_waitcnt vmcnt(0) lgkmcnt(0)
	s_barrier
	s_add_u32 m0, s38, 0
	s_nop 0
	global_load_lds_dwordx4 v164, s[98:99]
	s_waitcnt lgkmcnt(8)
	v_mfma_f32_16x16x32_bf16 v[48:51], v[76:79], v[96:99], v[48:51]
	s_add_u32 m0, s38, 4096
	s_nop 0
	global_load_lds_dwordx4 v165, s[98:99]
	s_waitcnt lgkmcnt(8)
	v_mfma_f32_16x16x32_bf16 v[52:55], v[76:79], v[100:103], v[52:55]
	s_add_u32 m0, s38, 8192
	s_nop 0
	global_load_lds_dwordx4 v166, s[98:99]
	s_waitcnt lgkmcnt(8)
	v_mfma_f32_16x16x32_bf16 v[56:59], v[76:79], v[104:107], v[56:59]
	s_add_u32 m0, s38, 12288
	s_nop 0
	global_load_lds_dwordx4 v167, s[98:99]
	s_add_u32 s98, s98, 128
	s_addc_u32 s99, s99, 0
	s_waitcnt lgkmcnt(8)
	v_mfma_f32_16x16x32_bf16 v[60:63], v[76:79], v[108:111], v[60:63]
	s_add_u32 m0, s38, 16384
	s_nop 0
	global_load_lds_dwordx4 v164, s[100:101]
	s_waitcnt lgkmcnt(6)
	v_mfma_f32_16x16x32_bf16 v[0:3], v[80:83], v[112:115], v[0:3]
	ds_read_b128 v[64:67], v150 offset:32768
	s_add_u32 m0, s38, 20480
	s_nop 0
	global_load_lds_dwordx4 v165, s[100:101]
	s_waitcnt lgkmcnt(6)
	v_mfma_f32_16x16x32_bf16 v[4:7], v[80:83], v[116:119], v[4:7]
	ds_read_b128 v[96:99], v162 offset:49152
	s_add_u32 m0, s38, 24576
	s_nop 0
	global_load_lds_dwordx4 v166, s[100:101]
	s_waitcnt lgkmcnt(6)
	v_mfma_f32_16x16x32_bf16 v[8:11], v[80:83], v[120:123], v[8:11]
	ds_read_b128 v[100:103], v162 offset:51200
	s_add_u32 m0, s38, 28672
	s_nop 0
	global_load_lds_dwordx4 v167, s[100:101]
	s_add_u32 s100, s100, 128
	s_addc_u32 s101, s101, 0
	s_waitcnt lgkmcnt(6)
	v_mfma_f32_16x16x32_bf16 v[12:15], v[80:83], v[124:127], v[12:15]
	ds_read_b128 v[104:107], v162 offset:53248
	s_waitcnt lgkmcnt(6)
	v_mfma_f32_16x16x32_bf16 v[16:19], v[84:87], v[112:115], v[16:19]
	ds_read_b128 v[108:111], v162 offset:55296
	s_waitcnt lgkmcnt(7)
	v_mfma_f32_16x16x32_bf16 v[20:23], v[84:87], v[116:119], v[20:23]
	ds_read_b128 v[68:71], v150 offset:34816
	s_waitcnt lgkmcnt(8)
	v_mfma_f32_16x16x32_bf16 v[24:27], v[84:87], v[120:123], v[24:27]
	ds_read_b128 v[72:75], v150 offset:36864
	s_waitcnt lgkmcnt(9)
	v_mfma_f32_16x16x32_bf16 v[28:31], v[84:87], v[124:127], v[28:31]
	ds_read_b128 v[76:79], v150 offset:38912
	s_waitcnt lgkmcnt(9)
	v_mfma_f32_16x16x32_bf16 v[32:35], v[88:91], v[112:115], v[32:35]
	s_waitcnt lgkmcnt(9)
	v_mfma_f32_16x16x32_bf16 v[36:39], v[88:91], v[116:119], v[36:39]
	s_waitcnt lgkmcnt(9)
	v_mfma_f32_16x16x32_bf16 v[40:43], v[88:91], v[120:123], v[40:43]
	s_waitcnt lgkmcnt(9)
	v_mfma_f32_16x16x32_bf16 v[44:47], v[88:91], v[124:127], v[44:47]
	s_waitcnt lgkmcnt(8)
	v_mfma_f32_16x16x32_bf16 v[48:51], v[92:95], v[112:115], v[48:51]
	s_waitcnt lgkmcnt(8)
	v_mfma_f32_16x16x32_bf16 v[52:55], v[92:95], v[116:119], v[52:55]
	s_waitcnt lgkmcnt(8)
	v_mfma_f32_16x16x32_bf16 v[56:59], v[92:95], v[120:123], v[56:59]
	s_waitcnt lgkmcnt(8)
	v_mfma_f32_16x16x32_bf16 v[60:63], v[92:95], v[124:127], v[60:63]
	s_waitcnt lgkmcnt(6)
	v_mfma_f32_16x16x32_bf16 v[0:3], v[64:67], v[96:99], v[0:3]
	ds_read_b128 v[80:83], v151 offset:32768
	s_waitcnt lgkmcnt(6)
	v_mfma_f32_16x16x32_bf16 v[4:7], v[64:67], v[100:103], v[4:7]
	ds_read_b128 v[112:115], v163 offset:49152
	s_waitcnt lgkmcnt(6)
	v_mfma_f32_16x16x32_bf16 v[8:11], v[64:67], v[104:107], v[8:11]
	ds_read_b128 v[116:119], v163 offset:51200
	s_waitcnt lgkmcnt(6)
	v_mfma_f32_16x16x32_bf16 v[12:15], v[64:67], v[108:111], v[12:15]
	ds_read_b128 v[120:123], v163 offset:53248
	s_waitcnt lgkmcnt(6)
	v_mfma_f32_16x16x32_bf16 v[16:19], v[68:71], v[96:99], v[16:19]
	ds_read_b128 v[124:127], v163 offset:55296
	s_waitcnt lgkmcnt(7)
	v_mfma_f32_16x16x32_bf16 v[20:23], v[68:71], v[100:103], v[20:23]
	ds_read_b128 v[84:87], v151 offset:34816
	s_waitcnt lgkmcnt(8)
	v_mfma_f32_16x16x32_bf16 v[24:27], v[68:71], v[104:107], v[24:27]
	ds_read_b128 v[88:91], v151 offset:36864
	s_waitcnt lgkmcnt(9)
	v_mfma_f32_16x16x32_bf16 v[28:31], v[68:71], v[108:111], v[28:31]
	ds_read_b128 v[92:95], v151 offset:38912
	s_waitcnt lgkmcnt(9)
	v_mfma_f32_16x16x32_bf16 v[32:35], v[72:75], v[96:99], v[32:35]
	s_waitcnt lgkmcnt(9)
	v_mfma_f32_16x16x32_bf16 v[36:39], v[72:75], v[100:103], v[36:39]
	s_waitcnt lgkmcnt(9)
	v_mfma_f32_16x16x32_bf16 v[40:43], v[72:75], v[104:107], v[40:43]
	s_waitcnt lgkmcnt(9)
	v_mfma_f32_16x16x32_bf16 v[44:47], v[72:75], v[108:111], v[44:47]
	s_waitcnt vmcnt(0) lgkmcnt(0)
	s_barrier
	s_add_u32 m0, s38, 32768
	s_nop 0
	global_load_lds_dwordx4 v164, s[98:99]
	s_waitcnt lgkmcnt(8)
	v_mfma_f32_16x16x32_bf16 v[48:51], v[76:79], v[96:99], v[48:51]
	s_add_u32 m0, s38, 36864
	s_nop 0
	global_load_lds_dwordx4 v165, s[98:99]
	s_waitcnt lgkmcnt(8)
	v_mfma_f32_16x16x32_bf16 v[52:55], v[76:79], v[100:103], v[52:55]
	s_add_u32 m0, s38, 40960
	s_nop 0
	global_load_lds_dwordx4 v166, s[98:99]
	s_waitcnt lgkmcnt(8)
	v_mfma_f32_16x16x32_bf16 v[56:59], v[76:79], v[104:107], v[56:59]
	s_add_u32 m0, s38, 45056
	s_nop 0
	global_load_lds_dwordx4 v167, s[98:99]
	s_add_u32 s98, s98, 128
	s_addc_u32 s99, s99, 0
	s_waitcnt lgkmcnt(8)
	v_mfma_f32_16x16x32_bf16 v[60:63], v[76:79], v[108:111], v[60:63]
	s_add_u32 m0, s38, 49152
	s_nop 0
	global_load_lds_dwordx4 v164, s[100:101]
	s_waitcnt lgkmcnt(6)
	v_mfma_f32_16x16x32_bf16 v[0:3], v[80:83], v[112:115], v[0:3]
	ds_read_b128 v[64:67], v150 offset:0
	s_add_u32 m0, s38, 53248
	s_nop 0
	global_load_lds_dwordx4 v165, s[100:101]
	s_waitcnt lgkmcnt(6)
	v_mfma_f32_16x16x32_bf16 v[4:7], v[80:83], v[116:119], v[4:7]
	ds_read_b128 v[96:99], v162 offset:16384
	s_add_u32 m0, s38, 57344
	s_nop 0
	global_load_lds_dwordx4 v166, s[100:101]
	s_waitcnt lgkmcnt(6)
	v_mfma_f32_16x16x32_bf16 v[8:11], v[80:83], v[120:123], v[8:11]
	ds_read_b128 v[100:103], v162 offset:18432
	s_add_u32 m0, s38, 61440
	s_nop 0
	global_load_lds_dwordx4 v167, s[100:101]
	s_add_u32 s100, s100, 128
	s_addc_u32 s101, s101, 0
	s_waitcnt lgkmcnt(6)
	v_mfma_f32_16x16x32_bf16 v[12:15], v[80:83], v[124:127], v[12:15]
	ds_read_b128 v[104:107], v162 offset:20480
	s_waitcnt lgkmcnt(6)
	v_mfma_f32_16x16x32_bf16 v[16:19], v[84:87], v[112:115], v[16:19]
	ds_read_b128 v[108:111], v162 offset:22528
	s_waitcnt lgkmcnt(7)
	v_mfma_f32_16x16x32_bf16 v[20:23], v[84:87], v[116:119], v[20:23]
	ds_read_b128 v[68:71], v150 offset:2048
	s_waitcnt lgkmcnt(8)
	v_mfma_f32_16x16x32_bf16 v[24:27], v[84:87], v[120:123], v[24:27]
	ds_read_b128 v[72:75], v150 offset:4096
	s_waitcnt lgkmcnt(9)
	v_mfma_f32_16x16x32_bf16 v[28:31], v[84:87], v[124:127], v[28:31]
	ds_read_b128 v[76:79], v150 offset:6144
	s_waitcnt lgkmcnt(9)
	v_mfma_f32_16x16x32_bf16 v[32:35], v[88:91], v[112:115], v[32:35]
	s_waitcnt lgkmcnt(9)
	v_mfma_f32_16x16x32_bf16 v[36:39], v[88:91], v[116:119], v[36:39]
	s_waitcnt lgkmcnt(9)
	v_mfma_f32_16x16x32_bf16 v[40:43], v[88:91], v[120:123], v[40:43]
	s_waitcnt lgkmcnt(9)
	v_mfma_f32_16x16x32_bf16 v[44:47], v[88:91], v[124:127], v[44:47]
	s_waitcnt lgkmcnt(8)
	v_mfma_f32_16x16x32_bf16 v[48:51], v[92:95], v[112:115], v[48:51]
	s_waitcnt lgkmcnt(8)
	v_mfma_f32_16x16x32_bf16 v[52:55], v[92:95], v[116:119], v[52:55]
	s_waitcnt lgkmcnt(8)
	v_mfma_f32_16x16x32_bf16 v[56:59], v[92:95], v[120:123], v[56:59]
	s_waitcnt lgkmcnt(8)
	v_mfma_f32_16x16x32_bf16 v[60:63], v[92:95], v[124:127], v[60:63]
	s_waitcnt lgkmcnt(6)
	v_mfma_f32_16x16x32_bf16 v[0:3], v[64:67], v[96:99], v[0:3]
	ds_read_b128 v[80:83], v151 offset:0
	s_waitcnt lgkmcnt(6)
	v_mfma_f32_16x16x32_bf16 v[4:7], v[64:67], v[100:103], v[4:7]
	ds_read_b128 v[112:115], v163 offset:16384
	s_waitcnt lgkmcnt(6)
	v_mfma_f32_16x16x32_bf16 v[8:11], v[64:67], v[104:107], v[8:11]
	ds_read_b128 v[116:119], v163 offset:18432
	s_waitcnt lgkmcnt(6)
	v_mfma_f32_16x16x32_bf16 v[12:15], v[64:67], v[108:111], v[12:15]
	ds_read_b128 v[120:123], v163 offset:20480
	s_waitcnt lgkmcnt(6)
	v_mfma_f32_16x16x32_bf16 v[16:19], v[68:71], v[96:99], v[16:19]
	ds_read_b128 v[124:127], v163 offset:22528
	s_waitcnt lgkmcnt(7)
	v_mfma_f32_16x16x32_bf16 v[20:23], v[68:71], v[100:103], v[20:23]
	ds_read_b128 v[84:87], v151 offset:2048
	s_waitcnt lgkmcnt(8)
	v_mfma_f32_16x16x32_bf16 v[24:27], v[68:71], v[104:107], v[24:27]
	ds_read_b128 v[88:91], v151 offset:4096
	s_waitcnt lgkmcnt(9)
	v_mfma_f32_16x16x32_bf16 v[28:31], v[68:71], v[108:111], v[28:31]
	ds_read_b128 v[92:95], v151 offset:6144
	s_waitcnt lgkmcnt(9)
	v_mfma_f32_16x16x32_bf16 v[32:35], v[72:75], v[96:99], v[32:35]
	s_waitcnt lgkmcnt(9)
	v_mfma_f32_16x16x32_bf16 v[36:39], v[72:75], v[100:103], v[36:39]
	s_waitcnt lgkmcnt(9)
	v_mfma_f32_16x16x32_bf16 v[40:43], v[72:75], v[104:107], v[40:43]
	s_waitcnt lgkmcnt(9)
	v_mfma_f32_16x16x32_bf16 v[44:47], v[72:75], v[108:111], v[44:47]
	s_waitcnt vmcnt(0) lgkmcnt(0)
	s_barrier
	s_add_u32 m0, s38, 0
	s_nop 0
	global_load_lds_dwordx4 v164, s[98:99]
	s_add_u32 m0, s38, 4096
	s_nop 0
	global_load_lds_dwordx4 v165, s[98:99]
	s_waitcnt lgkmcnt(8)
	v_mfma_f32_16x16x32_bf16 v[48:51], v[76:79], v[96:99], v[48:51]
	s_add_u32 m0, s38, 8192
	s_nop 0
	global_load_lds_dwordx4 v166, s[98:99]
	s_add_u32 m0, s38, 12288
	s_nop 0
	global_load_lds_dwordx4 v167, s[98:99]
	s_add_u32 s98, s98, 128
	s_addc_u32 s99, s99, 0
	s_waitcnt lgkmcnt(8)
	v_mfma_f32_16x16x32_bf16 v[52:55], v[76:79], v[100:103], v[52:55]
	s_add_u32 m0, s38, 16384
	s_nop 0
	global_load_lds_dwordx4 v164, s[100:101]
	s_add_u32 m0, s38, 20480
	s_nop 0
	global_load_lds_dwordx4 v165, s[100:101]
	s_waitcnt lgkmcnt(8)
	v_mfma_f32_16x16x32_bf16 v[56:59], v[76:79], v[104:107], v[56:59]
	s_add_u32 m0, s38, 24576
	s_nop 0
	global_load_lds_dwordx4 v166, s[100:101]
	s_add_u32 m0, s38, 28672
	s_nop 0
	global_load_lds_dwordx4 v167, s[100:101]
	s_add_u32 s100, s100, 128
	s_addc_u32 s101, s101, 0
	s_waitcnt lgkmcnt(8)
	v_mfma_f32_16x16x32_bf16 v[60:63], v[76:79], v[108:111], v[60:63]
	global_load_dwordx4 v[172:175], v168, s[14:15] nt
	s_waitcnt lgkmcnt(6)
	v_mfma_f32_16x16x32_bf16 v[0:3], v[80:83], v[112:115], v[0:3]
	ds_read_b128 v[64:67], v150 offset:32768
	global_load_dwordx4 v[176:179], v168, s[14:15] offset:16 nt
	s_add_u32 s14, s14, 0x8000
	s_addc_u32 s15, s15, 0
	s_waitcnt lgkmcnt(6)
	v_mfma_f32_16x16x32_bf16 v[4:7], v[80:83], v[116:119], v[4:7]
	ds_read_b128 v[96:99], v162 offset:49152
	global_load_dwordx4 v[180:183], v168, s[14:15] nt
	s_waitcnt lgkmcnt(6)
	v_mfma_f32_16x16x32_bf16 v[8:11], v[80:83], v[120:123], v[8:11]
	ds_read_b128 v[100:103], v162 offset:51200
	global_load_dwordx4 v[184:187], v168, s[14:15] offset:16 nt
	s_add_u32 s14, s14, 0x8000
	s_addc_u32 s15, s15, 0
	s_waitcnt lgkmcnt(6)
	v_mfma_f32_16x16x32_bf16 v[12:15], v[80:83], v[124:127], v[12:15]
	ds_read_b128 v[104:107], v162 offset:53248
	global_load_dwordx4 v[188:191], v168, s[14:15] nt
	s_waitcnt lgkmcnt(6)
	v_mfma_f32_16x16x32_bf16 v[16:19], v[84:87], v[112:115], v[16:19]
	ds_read_b128 v[108:111], v162 offset:55296
	global_load_dwordx4 v[192:195], v168, s[14:15] offset:16 nt
	s_add_u32 s14, s14, 0x8000
	s_addc_u32 s15, s15, 0
	s_waitcnt lgkmcnt(7)
	v_mfma_f32_16x16x32_bf16 v[20:23], v[84:87], v[116:119], v[20:23]
	ds_read_b128 v[68:71], v150 offset:34816
	global_load_dwordx4 v[196:199], v168, s[14:15] nt
	s_waitcnt lgkmcnt(8)
	v_mfma_f32_16x16x32_bf16 v[24:27], v[84:87], v[120:123], v[24:27]
	ds_read_b128 v[72:75], v150 offset:36864
	global_load_dwordx4 v[200:203], v168, s[14:15] offset:16 nt
	s_add_u32 s14, s14, 0x8000
	s_addc_u32 s15, s15, 0
	s_waitcnt lgkmcnt(9)
	v_mfma_f32_16x16x32_bf16 v[28:31], v[84:87], v[124:127], v[28:31]
	ds_read_b128 v[76:79], v150 offset:38912
	s_waitcnt lgkmcnt(9)
	v_mfma_f32_16x16x32_bf16 v[32:35], v[88:91], v[112:115], v[32:35]
	s_waitcnt lgkmcnt(9)
	v_mfma_f32_16x16x32_bf16 v[36:39], v[88:91], v[116:119], v[36:39]
	s_waitcnt lgkmcnt(9)
	v_mfma_f32_16x16x32_bf16 v[40:43], v[88:91], v[120:123], v[40:43]
	s_waitcnt lgkmcnt(9)
	v_mfma_f32_16x16x32_bf16 v[44:47], v[88:91], v[124:127], v[44:47]
	s_waitcnt lgkmcnt(8)
	v_mfma_f32_16x16x32_bf16 v[48:51], v[92:95], v[112:115], v[48:51]
	s_waitcnt lgkmcnt(8)
	v_mfma_f32_16x16x32_bf16 v[52:55], v[92:95], v[116:119], v[52:55]
	s_waitcnt lgkmcnt(8)
	v_mfma_f32_16x16x32_bf16 v[56:59], v[92:95], v[120:123], v[56:59]
	s_waitcnt lgkmcnt(8)
	v_mfma_f32_16x16x32_bf16 v[60:63], v[92:95], v[124:127], v[60:63]
	s_waitcnt lgkmcnt(6)
	v_mfma_f32_16x16x32_bf16 v[0:3], v[64:67], v[96:99], v[0:3]
	ds_read_b128 v[80:83], v151 offset:32768
	s_waitcnt lgkmcnt(6)
	v_mfma_f32_16x16x32_bf16 v[4:7], v[64:67], v[100:103], v[4:7]
	ds_read_b128 v[112:115], v163 offset:49152
	s_waitcnt lgkmcnt(6)
	v_mfma_f32_16x16x32_bf16 v[8:11], v[64:67], v[104:107], v[8:11]
	ds_read_b128 v[116:119], v163 offset:51200
	s_waitcnt lgkmcnt(6)
	v_mfma_f32_16x16x32_bf16 v[12:15], v[64:67], v[108:111], v[12:15]
	ds_read_b128 v[120:123], v163 offset:53248
	s_waitcnt lgkmcnt(6)
	v_mfma_f32_16x16x32_bf16 v[16:19], v[68:71], v[96:99], v[16:19]
	ds_read_b128 v[124:127], v163 offset:55296
	s_waitcnt lgkmcnt(7)
	v_mfma_f32_16x16x32_bf16 v[20:23], v[68:71], v[100:103], v[20:23]
	ds_read_b128 v[84:87], v151 offset:34816
	s_waitcnt lgkmcnt(8)
	v_mfma_f32_16x16x32_bf16 v[24:27], v[68:71], v[104:107], v[24:27]
	ds_read_b128 v[88:91], v151 offset:36864
	s_waitcnt lgkmcnt(9)
	v_mfma_f32_16x16x32_bf16 v[28:31], v[68:71], v[108:111], v[28:31]
	ds_read_b128 v[92:95], v151 offset:38912
	s_waitcnt lgkmcnt(9)
	v_mfma_f32_16x16x32_bf16 v[32:35], v[72:75], v[96:99], v[32:35]
	s_waitcnt lgkmcnt(9)
	v_mfma_f32_16x16x32_bf16 v[36:39], v[72:75], v[100:103], v[36:39]
	s_waitcnt lgkmcnt(9)
	v_mfma_f32_16x16x32_bf16 v[40:43], v[72:75], v[104:107], v[40:43]
	s_waitcnt lgkmcnt(9)
	v_mfma_f32_16x16x32_bf16 v[44:47], v[72:75], v[108:111], v[44:47]
	s_waitcnt vmcnt(8) lgkmcnt(0)
	s_barrier
	s_add_u32 m0, s38, 32768
	s_nop 0
	global_load_lds_dwordx4 v164, s[98:99]
	s_waitcnt lgkmcnt(8)
	v_mfma_f32_16x16x32_bf16 v[48:51], v[76:79], v[96:99], v[48:51]
	s_add_u32 m0, s38, 36864
	s_nop 0
	global_load_lds_dwordx4 v165, s[98:99]
	s_waitcnt lgkmcnt(8)
	v_mfma_f32_16x16x32_bf16 v[52:55], v[76:79], v[100:103], v[52:55]
	s_add_u32 m0, s38, 40960
	s_nop 0
	global_load_lds_dwordx4 v166, s[98:99]
	s_waitcnt lgkmcnt(8)
	v_mfma_f32_16x16x32_bf16 v[56:59], v[76:79], v[104:107], v[56:59]
	s_add_u32 m0, s38, 45056
	s_nop 0
	global_load_lds_dwordx4 v167, s[98:99]
	s_add_u32 s98, s98, 128
	s_addc_u32 s99, s99, 0
	s_waitcnt lgkmcnt(8)
	v_mfma_f32_16x16x32_bf16 v[60:63], v[76:79], v[108:111], v[60:63]
	s_add_u32 m0, s38, 49152
	s_nop 0
	global_load_lds_dwordx4 v164, s[100:101]
	s_waitcnt lgkmcnt(6)
	v_mfma_f32_16x16x32_bf16 v[0:3], v[80:83], v[112:115], v[0:3]
	ds_read_b128 v[64:67], v150 offset:0
	s_add_u32 m0, s38, 53248
	s_nop 0
	global_load_lds_dwordx4 v165, s[100:101]
	s_waitcnt lgkmcnt(6)
	v_mfma_f32_16x16x32_bf16 v[4:7], v[80:83], v[116:119], v[4:7]
	ds_read_b128 v[96:99], v162 offset:16384
	s_add_u32 m0, s38, 57344
	s_nop 0
	global_load_lds_dwordx4 v166, s[100:101]
	s_waitcnt lgkmcnt(6)
	v_mfma_f32_16x16x32_bf16 v[8:11], v[80:83], v[120:123], v[8:11]
	ds_read_b128 v[100:103], v162 offset:18432
	s_add_u32 m0, s38, 61440
	s_nop 0
	global_load_lds_dwordx4 v167, s[100:101]
	s_add_u32 s100, s100, 128
	s_addc_u32 s101, s101, 0
	s_waitcnt lgkmcnt(6)
	v_mfma_f32_16x16x32_bf16 v[12:15], v[80:83], v[124:127], v[12:15]
	ds_read_b128 v[104:107], v162 offset:20480
	s_waitcnt lgkmcnt(6)
	v_mfma_f32_16x16x32_bf16 v[16:19], v[84:87], v[112:115], v[16:19]
	ds_read_b128 v[108:111], v162 offset:22528
	s_waitcnt lgkmcnt(7)
	v_mfma_f32_16x16x32_bf16 v[20:23], v[84:87], v[116:119], v[20:23]
	ds_read_b128 v[68:71], v150 offset:2048
	s_waitcnt lgkmcnt(8)
	v_mfma_f32_16x16x32_bf16 v[24:27], v[84:87], v[120:123], v[24:27]
	ds_read_b128 v[72:75], v150 offset:4096
	s_waitcnt lgkmcnt(9)
	v_mfma_f32_16x16x32_bf16 v[28:31], v[84:87], v[124:127], v[28:31]
	ds_read_b128 v[76:79], v150 offset:6144
	s_waitcnt lgkmcnt(9)
	v_mfma_f32_16x16x32_bf16 v[32:35], v[88:91], v[112:115], v[32:35]
	s_waitcnt lgkmcnt(9)
	v_mfma_f32_16x16x32_bf16 v[36:39], v[88:91], v[116:119], v[36:39]
	s_waitcnt lgkmcnt(9)
	v_mfma_f32_16x16x32_bf16 v[40:43], v[88:91], v[120:123], v[40:43]
	s_waitcnt lgkmcnt(9)
	v_mfma_f32_16x16x32_bf16 v[44:47], v[88:91], v[124:127], v[44:47]
	s_waitcnt lgkmcnt(8)
	v_mfma_f32_16x16x32_bf16 v[48:51], v[92:95], v[112:115], v[48:51]
	s_waitcnt lgkmcnt(8)
	v_mfma_f32_16x16x32_bf16 v[52:55], v[92:95], v[116:119], v[52:55]
	s_waitcnt lgkmcnt(8)
	v_mfma_f32_16x16x32_bf16 v[56:59], v[92:95], v[120:123], v[56:59]
	s_waitcnt lgkmcnt(8)
	v_mfma_f32_16x16x32_bf16 v[60:63], v[92:95], v[124:127], v[60:63]
	s_waitcnt lgkmcnt(6)
	v_mfma_f32_16x16x32_bf16 v[0:3], v[64:67], v[96:99], v[0:3]
	ds_read_b128 v[80:83], v151 offset:0
	s_waitcnt lgkmcnt(6)
	v_mfma_f32_16x16x32_bf16 v[4:7], v[64:67], v[100:103], v[4:7]
	ds_read_b128 v[112:115], v163 offset:16384
	s_waitcnt lgkmcnt(6)
	v_mfma_f32_16x16x32_bf16 v[8:11], v[64:67], v[104:107], v[8:11]
	ds_read_b128 v[116:119], v163 offset:18432
	s_waitcnt lgkmcnt(6)
	v_mfma_f32_16x16x32_bf16 v[12:15], v[64:67], v[108:111], v[12:15]
	ds_read_b128 v[120:123], v163 offset:20480
	s_waitcnt lgkmcnt(6)
	v_mfma_f32_16x16x32_bf16 v[16:19], v[68:71], v[96:99], v[16:19]
	ds_read_b128 v[124:127], v163 offset:22528
	s_waitcnt lgkmcnt(7)
	v_mfma_f32_16x16x32_bf16 v[20:23], v[68:71], v[100:103], v[20:23]
	ds_read_b128 v[84:87], v151 offset:2048
	s_waitcnt lgkmcnt(8)
	v_mfma_f32_16x16x32_bf16 v[24:27], v[68:71], v[104:107], v[24:27]
	ds_read_b128 v[88:91], v151 offset:4096
	s_waitcnt lgkmcnt(9)
	v_mfma_f32_16x16x32_bf16 v[28:31], v[68:71], v[108:111], v[28:31]
	ds_read_b128 v[92:95], v151 offset:6144
	s_waitcnt lgkmcnt(9)
	v_mfma_f32_16x16x32_bf16 v[32:35], v[72:75], v[96:99], v[32:35]
	s_waitcnt lgkmcnt(9)
	v_mfma_f32_16x16x32_bf16 v[36:39], v[72:75], v[100:103], v[36:39]
	s_waitcnt lgkmcnt(9)
	v_mfma_f32_16x16x32_bf16 v[40:43], v[72:75], v[104:107], v[40:43]
	s_waitcnt lgkmcnt(9)
	v_mfma_f32_16x16x32_bf16 v[44:47], v[72:75], v[108:111], v[44:47]
	s_waitcnt vmcnt(0) lgkmcnt(0)
	s_barrier
	s_add_u32 m0, s38, 0
	s_nop 0
	global_load_lds_dwordx4 v164, s[98:99]
	s_waitcnt lgkmcnt(8)
	v_mfma_f32_16x16x32_bf16 v[48:51], v[76:79], v[96:99], v[48:51]
	s_add_u32 m0, s38, 4096
	s_nop 0
	global_load_lds_dwordx4 v165, s[98:99]
	s_waitcnt lgkmcnt(8)
	v_mfma_f32_16x16x32_bf16 v[52:55], v[76:79], v[100:103], v[52:55]
	s_add_u32 m0, s38, 8192
	s_nop 0
	global_load_lds_dwordx4 v166, s[98:99]
	s_waitcnt lgkmcnt(8)
	v_mfma_f32_16x16x32_bf16 v[56:59], v[76:79], v[104:107], v[56:59]
	s_add_u32 m0, s38, 12288
	s_nop 0
	global_load_lds_dwordx4 v167, s[98:99]
	s_add_u32 s98, s98, 128
	s_addc_u32 s99, s99, 0
	s_waitcnt lgkmcnt(8)
	v_mfma_f32_16x16x32_bf16 v[60:63], v[76:79], v[108:111], v[60:63]
	s_add_u32 m0, s38, 16384
	s_nop 0
	global_load_lds_dwordx4 v164, s[100:101]
	s_waitcnt lgkmcnt(6)
	v_mfma_f32_16x16x32_bf16 v[0:3], v[80:83], v[112:115], v[0:3]
	ds_read_b128 v[64:67], v150 offset:32768
	s_add_u32 m0, s38, 20480
	s_nop 0
	global_load_lds_dwordx4 v165, s[100:101]
	s_waitcnt lgkmcnt(6)
	v_mfma_f32_16x16x32_bf16 v[4:7], v[80:83], v[116:119], v[4:7]
	ds_read_b128 v[96:99], v162 offset:49152
	s_add_u32 m0, s38, 24576
	s_nop 0
	global_load_lds_dwordx4 v166, s[100:101]
	s_waitcnt lgkmcnt(6)
	v_mfma_f32_16x16x32_bf16 v[8:11], v[80:83], v[120:123], v[8:11]
	ds_read_b128 v[100:103], v162 offset:51200
	s_add_u32 m0, s38, 28672
	s_nop 0
	global_load_lds_dwordx4 v167, s[100:101]
	s_add_u32 s100, s100, 128
	s_addc_u32 s101, s101, 0
	s_waitcnt lgkmcnt(6)
	v_mfma_f32_16x16x32_bf16 v[12:15], v[80:83], v[124:127], v[12:15]
	ds_read_b128 v[104:107], v162 offset:53248
	s_waitcnt lgkmcnt(6)
	v_mfma_f32_16x16x32_bf16 v[16:19], v[84:87], v[112:115], v[16:19]
	ds_read_b128 v[108:111], v162 offset:55296
	s_waitcnt lgkmcnt(7)
	v_mfma_f32_16x16x32_bf16 v[20:23], v[84:87], v[116:119], v[20:23]
	ds_read_b128 v[68:71], v150 offset:34816
	s_waitcnt lgkmcnt(8)
	v_mfma_f32_16x16x32_bf16 v[24:27], v[84:87], v[120:123], v[24:27]
	ds_read_b128 v[72:75], v150 offset:36864
	s_waitcnt lgkmcnt(9)
	v_mfma_f32_16x16x32_bf16 v[28:31], v[84:87], v[124:127], v[28:31]
	ds_read_b128 v[76:79], v150 offset:38912
	s_waitcnt lgkmcnt(9)
	v_mfma_f32_16x16x32_bf16 v[32:35], v[88:91], v[112:115], v[32:35]
	s_waitcnt lgkmcnt(9)
	v_mfma_f32_16x16x32_bf16 v[36:39], v[88:91], v[116:119], v[36:39]
	s_waitcnt lgkmcnt(9)
	v_mfma_f32_16x16x32_bf16 v[40:43], v[88:91], v[120:123], v[40:43]
	s_waitcnt lgkmcnt(9)
	v_mfma_f32_16x16x32_bf16 v[44:47], v[88:91], v[124:127], v[44:47]
	s_waitcnt lgkmcnt(8)
	v_mfma_f32_16x16x32_bf16 v[48:51], v[92:95], v[112:115], v[48:51]
	s_waitcnt lgkmcnt(8)
	v_mfma_f32_16x16x32_bf16 v[52:55], v[92:95], v[116:119], v[52:55]
	s_waitcnt lgkmcnt(8)
	v_mfma_f32_16x16x32_bf16 v[56:59], v[92:95], v[120:123], v[56:59]
	s_waitcnt lgkmcnt(8)
	v_mfma_f32_16x16x32_bf16 v[60:63], v[92:95], v[124:127], v[60:63]
	s_waitcnt lgkmcnt(6)
	v_mfma_f32_16x16x32_bf16 v[0:3], v[64:67], v[96:99], v[0:3]
	ds_read_b128 v[80:83], v151 offset:32768
	s_waitcnt lgkmcnt(6)
	v_mfma_f32_16x16x32_bf16 v[4:7], v[64:67], v[100:103], v[4:7]
	ds_read_b128 v[112:115], v163 offset:49152
	s_waitcnt lgkmcnt(6)
	v_mfma_f32_16x16x32_bf16 v[8:11], v[64:67], v[104:107], v[8:11]
	ds_read_b128 v[116:119], v163 offset:51200
	s_waitcnt lgkmcnt(6)
	v_mfma_f32_16x16x32_bf16 v[12:15], v[64:67], v[108:111], v[12:15]
	ds_read_b128 v[120:123], v163 offset:53248
	s_waitcnt lgkmcnt(6)
	v_mfma_f32_16x16x32_bf16 v[16:19], v[68:71], v[96:99], v[16:19]
	ds_read_b128 v[124:127], v163 offset:55296
	s_waitcnt lgkmcnt(7)
	v_mfma_f32_16x16x32_bf16 v[20:23], v[68:71], v[100:103], v[20:23]
	ds_read_b128 v[84:87], v151 offset:34816
	s_waitcnt lgkmcnt(8)
	v_mfma_f32_16x16x32_bf16 v[24:27], v[68:71], v[104:107], v[24:27]
	ds_read_b128 v[88:91], v151 offset:36864
	s_waitcnt lgkmcnt(9)
	v_mfma_f32_16x16x32_bf16 v[28:31], v[68:71], v[108:111], v[28:31]
	ds_read_b128 v[92:95], v151 offset:38912
	s_waitcnt lgkmcnt(9)
	v_mfma_f32_16x16x32_bf16 v[32:35], v[72:75], v[96:99], v[32:35]
	s_waitcnt lgkmcnt(9)
	v_mfma_f32_16x16x32_bf16 v[36:39], v[72:75], v[100:103], v[36:39]
	s_waitcnt lgkmcnt(9)
	v_mfma_f32_16x16x32_bf16 v[40:43], v[72:75], v[104:107], v[40:43]
	s_waitcnt lgkmcnt(9)
	v_mfma_f32_16x16x32_bf16 v[44:47], v[72:75], v[108:111], v[44:47]
	s_waitcnt vmcnt(0) lgkmcnt(0)
	s_barrier
	s_add_u32 m0, s38, 32768
	s_nop 0
	global_load_lds_dwordx4 v164, s[98:99]
	s_waitcnt lgkmcnt(8)
	v_mfma_f32_16x16x32_bf16 v[48:51], v[76:79], v[96:99], v[48:51]
	s_add_u32 m0, s38, 36864
	s_nop 0
	global_load_lds_dwordx4 v165, s[98:99]
	s_waitcnt lgkmcnt(8)
	v_mfma_f32_16x16x32_bf16 v[52:55], v[76:79], v[100:103], v[52:55]
	s_add_u32 m0, s38, 40960
	s_nop 0
	global_load_lds_dwordx4 v166, s[98:99]
	s_waitcnt lgkmcnt(8)
	v_mfma_f32_16x16x32_bf16 v[56:59], v[76:79], v[104:107], v[56:59]
	s_add_u32 m0, s38, 45056
	s_nop 0
	global_load_lds_dwordx4 v167, s[98:99]
	s_add_u32 s98, s98, 128
	s_addc_u32 s99, s99, 0
	s_waitcnt lgkmcnt(8)
	v_mfma_f32_16x16x32_bf16 v[60:63], v[76:79], v[108:111], v[60:63]
	s_add_u32 m0, s38, 49152
	s_nop 0
	global_load_lds_dwordx4 v164, s[100:101]
	s_waitcnt lgkmcnt(6)
	v_mfma_f32_16x16x32_bf16 v[0:3], v[80:83], v[112:115], v[0:3]
	ds_read_b128 v[64:67], v150 offset:0
	s_add_u32 m0, s38, 53248
	s_nop 0
	global_load_lds_dwordx4 v165, s[100:101]
	s_waitcnt lgkmcnt(6)
	v_mfma_f32_16x16x32_bf16 v[4:7], v[80:83], v[116:119], v[4:7]
	ds_read_b128 v[96:99], v162 offset:16384
	s_add_u32 m0, s38, 57344
	s_nop 0
	global_load_lds_dwordx4 v166, s[100:101]
	s_waitcnt lgkmcnt(6)
	v_mfma_f32_16x16x32_bf16 v[8:11], v[80:83], v[120:123], v[8:11]
	ds_read_b128 v[100:103], v162 offset:18432
	s_add_u32 m0, s38, 61440
	s_nop 0
	global_load_lds_dwordx4 v167, s[100:101]
	s_add_u32 s100, s100, 128
	s_addc_u32 s101, s101, 0
	s_waitcnt lgkmcnt(6)
	v_mfma_f32_16x16x32_bf16 v[12:15], v[80:83], v[124:127], v[12:15]
	ds_read_b128 v[104:107], v162 offset:20480
	s_waitcnt lgkmcnt(6)
	v_mfma_f32_16x16x32_bf16 v[16:19], v[84:87], v[112:115], v[16:19]
	ds_read_b128 v[108:111], v162 offset:22528
	s_waitcnt lgkmcnt(7)
	v_mfma_f32_16x16x32_bf16 v[20:23], v[84:87], v[116:119], v[20:23]
	ds_read_b128 v[68:71], v150 offset:2048
	s_waitcnt lgkmcnt(8)
	v_mfma_f32_16x16x32_bf16 v[24:27], v[84:87], v[120:123], v[24:27]
	ds_read_b128 v[72:75], v150 offset:4096
	s_waitcnt lgkmcnt(9)
	v_mfma_f32_16x16x32_bf16 v[28:31], v[84:87], v[124:127], v[28:31]
	ds_read_b128 v[76:79], v150 offset:6144
	s_waitcnt lgkmcnt(9)
	v_mfma_f32_16x16x32_bf16 v[32:35], v[88:91], v[112:115], v[32:35]
	s_waitcnt lgkmcnt(9)
	v_mfma_f32_16x16x32_bf16 v[36:39], v[88:91], v[116:119], v[36:39]
	s_waitcnt lgkmcnt(9)
	v_mfma_f32_16x16x32_bf16 v[40:43], v[88:91], v[120:123], v[40:43]
	s_waitcnt lgkmcnt(9)
	v_mfma_f32_16x16x32_bf16 v[44:47], v[88:91], v[124:127], v[44:47]
	s_waitcnt lgkmcnt(8)
	v_mfma_f32_16x16x32_bf16 v[48:51], v[92:95], v[112:115], v[48:51]
	s_waitcnt lgkmcnt(8)
	v_mfma_f32_16x16x32_bf16 v[52:55], v[92:95], v[116:119], v[52:55]
	s_waitcnt lgkmcnt(8)
	v_mfma_f32_16x16x32_bf16 v[56:59], v[92:95], v[120:123], v[56:59]
	s_waitcnt lgkmcnt(8)
	v_mfma_f32_16x16x32_bf16 v[60:63], v[92:95], v[124:127], v[60:63]
	s_waitcnt lgkmcnt(6)
	v_mfma_f32_16x16x32_bf16 v[0:3], v[64:67], v[96:99], v[0:3]
	ds_read_b128 v[80:83], v151 offset:0
	s_waitcnt lgkmcnt(6)
	v_mfma_f32_16x16x32_bf16 v[4:7], v[64:67], v[100:103], v[4:7]
	ds_read_b128 v[112:115], v163 offset:16384
	s_waitcnt lgkmcnt(6)
	v_mfma_f32_16x16x32_bf16 v[8:11], v[64:67], v[104:107], v[8:11]
	ds_read_b128 v[116:119], v163 offset:18432
	s_waitcnt lgkmcnt(6)
	v_mfma_f32_16x16x32_bf16 v[12:15], v[64:67], v[108:111], v[12:15]
	ds_read_b128 v[120:123], v163 offset:20480
	s_waitcnt lgkmcnt(6)
	v_mfma_f32_16x16x32_bf16 v[16:19], v[68:71], v[96:99], v[16:19]
	ds_read_b128 v[124:127], v163 offset:22528
	s_waitcnt lgkmcnt(7)
	v_mfma_f32_16x16x32_bf16 v[20:23], v[68:71], v[100:103], v[20:23]
	ds_read_b128 v[84:87], v151 offset:2048
	s_waitcnt lgkmcnt(8)
	v_mfma_f32_16x16x32_bf16 v[24:27], v[68:71], v[104:107], v[24:27]
	ds_read_b128 v[88:91], v151 offset:4096
	s_waitcnt lgkmcnt(9)
	v_mfma_f32_16x16x32_bf16 v[28:31], v[68:71], v[108:111], v[28:31]
	ds_read_b128 v[92:95], v151 offset:6144
	s_waitcnt lgkmcnt(9)
	v_mfma_f32_16x16x32_bf16 v[32:35], v[72:75], v[96:99], v[32:35]
	s_waitcnt lgkmcnt(9)
	v_mfma_f32_16x16x32_bf16 v[36:39], v[72:75], v[100:103], v[36:39]
	s_waitcnt lgkmcnt(9)
	v_mfma_f32_16x16x32_bf16 v[40:43], v[72:75], v[104:107], v[40:43]
	s_waitcnt lgkmcnt(9)
	v_mfma_f32_16x16x32_bf16 v[44:47], v[72:75], v[108:111], v[44:47]
	s_waitcnt vmcnt(0) lgkmcnt(0)
	s_barrier
	s_add_u32 m0, s38, 0
	s_nop 0
	global_load_lds_dwordx4 v164, s[98:99]
	s_waitcnt lgkmcnt(8)
	v_mfma_f32_16x16x32_bf16 v[48:51], v[76:79], v[96:99], v[48:51]
	s_add_u32 m0, s38, 4096
	s_nop 0
	global_load_lds_dwordx4 v165, s[98:99]
	s_waitcnt lgkmcnt(8)
	v_mfma_f32_16x16x32_bf16 v[52:55], v[76:79], v[100:103], v[52:55]
	s_add_u32 m0, s38, 8192
	s_nop 0
	global_load_lds_dwordx4 v166, s[98:99]
	s_waitcnt lgkmcnt(8)
	v_mfma_f32_16x16x32_bf16 v[56:59], v[76:79], v[104:107], v[56:59]
	s_add_u32 m0, s38, 12288
	s_nop 0
	global_load_lds_dwordx4 v167, s[98:99]
	s_add_u32 s98, s98, 128
	s_addc_u32 s99, s99, 0
	s_waitcnt lgkmcnt(8)
	v_mfma_f32_16x16x32_bf16 v[60:63], v[76:79], v[108:111], v[60:63]
	s_add_u32 m0, s38, 16384
	s_nop 0
	global_load_lds_dwordx4 v164, s[100:101]
	s_waitcnt lgkmcnt(6)
	v_mfma_f32_16x16x32_bf16 v[0:3], v[80:83], v[112:115], v[0:3]
	ds_read_b128 v[64:67], v150 offset:32768
	s_add_u32 m0, s38, 20480
	s_nop 0
	global_load_lds_dwordx4 v165, s[100:101]
	s_waitcnt lgkmcnt(6)
	v_mfma_f32_16x16x32_bf16 v[4:7], v[80:83], v[116:119], v[4:7]
	ds_read_b128 v[96:99], v162 offset:49152
	s_add_u32 m0, s38, 24576
	s_nop 0
	global_load_lds_dwordx4 v166, s[100:101]
	s_waitcnt lgkmcnt(6)
	v_mfma_f32_16x16x32_bf16 v[8:11], v[80:83], v[120:123], v[8:11]
	ds_read_b128 v[100:103], v162 offset:51200
	s_add_u32 m0, s38, 28672
	s_nop 0
	global_load_lds_dwordx4 v167, s[100:101]
	s_add_u32 s100, s100, 128
	s_addc_u32 s101, s101, 0
	s_waitcnt lgkmcnt(6)
	v_mfma_f32_16x16x32_bf16 v[12:15], v[80:83], v[124:127], v[12:15]
	ds_read_b128 v[104:107], v162 offset:53248
	s_waitcnt lgkmcnt(6)
	v_mfma_f32_16x16x32_bf16 v[16:19], v[84:87], v[112:115], v[16:19]
	ds_read_b128 v[108:111], v162 offset:55296
	s_waitcnt lgkmcnt(7)
	v_mfma_f32_16x16x32_bf16 v[20:23], v[84:87], v[116:119], v[20:23]
	ds_read_b128 v[68:71], v150 offset:34816
	s_waitcnt lgkmcnt(8)
	v_mfma_f32_16x16x32_bf16 v[24:27], v[84:87], v[120:123], v[24:27]
	ds_read_b128 v[72:75], v150 offset:36864
	s_waitcnt lgkmcnt(9)
	v_mfma_f32_16x16x32_bf16 v[28:31], v[84:87], v[124:127], v[28:31]
	ds_read_b128 v[76:79], v150 offset:38912
	s_waitcnt lgkmcnt(9)
	v_mfma_f32_16x16x32_bf16 v[32:35], v[88:91], v[112:115], v[32:35]
	s_waitcnt lgkmcnt(9)
	v_mfma_f32_16x16x32_bf16 v[36:39], v[88:91], v[116:119], v[36:39]
	s_waitcnt lgkmcnt(9)
	v_mfma_f32_16x16x32_bf16 v[40:43], v[88:91], v[120:123], v[40:43]
	s_waitcnt lgkmcnt(9)
	v_mfma_f32_16x16x32_bf16 v[44:47], v[88:91], v[124:127], v[44:47]
	s_waitcnt lgkmcnt(8)
	v_mfma_f32_16x16x32_bf16 v[48:51], v[92:95], v[112:115], v[48:51]
	s_waitcnt lgkmcnt(8)
	v_mfma_f32_16x16x32_bf16 v[52:55], v[92:95], v[116:119], v[52:55]
	s_waitcnt lgkmcnt(8)
	v_mfma_f32_16x16x32_bf16 v[56:59], v[92:95], v[120:123], v[56:59]
	s_waitcnt lgkmcnt(8)
	v_mfma_f32_16x16x32_bf16 v[60:63], v[92:95], v[124:127], v[60:63]
	s_waitcnt lgkmcnt(6)
	v_mfma_f32_16x16x32_bf16 v[0:3], v[64:67], v[96:99], v[0:3]
	ds_read_b128 v[80:83], v151 offset:32768
	s_waitcnt lgkmcnt(6)
	v_mfma_f32_16x16x32_bf16 v[4:7], v[64:67], v[100:103], v[4:7]
	ds_read_b128 v[112:115], v163 offset:49152
	s_waitcnt lgkmcnt(6)
	v_mfma_f32_16x16x32_bf16 v[8:11], v[64:67], v[104:107], v[8:11]
	ds_read_b128 v[116:119], v163 offset:51200
	s_waitcnt lgkmcnt(6)
	v_mfma_f32_16x16x32_bf16 v[12:15], v[64:67], v[108:111], v[12:15]
	ds_read_b128 v[120:123], v163 offset:53248
	s_waitcnt lgkmcnt(6)
	v_mfma_f32_16x16x32_bf16 v[16:19], v[68:71], v[96:99], v[16:19]
	ds_read_b128 v[124:127], v163 offset:55296
	s_waitcnt lgkmcnt(7)
	v_mfma_f32_16x16x32_bf16 v[20:23], v[68:71], v[100:103], v[20:23]
	ds_read_b128 v[84:87], v151 offset:34816
	s_waitcnt lgkmcnt(8)
	v_mfma_f32_16x16x32_bf16 v[24:27], v[68:71], v[104:107], v[24:27]
	ds_read_b128 v[88:91], v151 offset:36864
	s_waitcnt lgkmcnt(9)
	v_mfma_f32_16x16x32_bf16 v[28:31], v[68:71], v[108:111], v[28:31]
	ds_read_b128 v[92:95], v151 offset:38912
	s_waitcnt lgkmcnt(9)
	v_mfma_f32_16x16x32_bf16 v[32:35], v[72:75], v[96:99], v[32:35]
	s_waitcnt lgkmcnt(9)
	v_mfma_f32_16x16x32_bf16 v[36:39], v[72:75], v[100:103], v[36:39]
	s_waitcnt lgkmcnt(9)
	v_mfma_f32_16x16x32_bf16 v[40:43], v[72:75], v[104:107], v[40:43]
	s_waitcnt lgkmcnt(9)
	v_mfma_f32_16x16x32_bf16 v[44:47], v[72:75], v[108:111], v[44:47]
	s_waitcnt vmcnt(0) lgkmcnt(0)
	s_barrier
	s_add_u32 m0, s38, 32768
	s_nop 0
	global_load_lds_dwordx4 v164, s[98:99]
	s_waitcnt lgkmcnt(8)
	v_mfma_f32_16x16x32_bf16 v[48:51], v[76:79], v[96:99], v[48:51]
	s_add_u32 m0, s38, 36864
	s_nop 0
	global_load_lds_dwordx4 v165, s[98:99]
	s_waitcnt lgkmcnt(8)
	v_mfma_f32_16x16x32_bf16 v[52:55], v[76:79], v[100:103], v[52:55]
	s_add_u32 m0, s38, 40960
	s_nop 0
	global_load_lds_dwordx4 v166, s[98:99]
	s_waitcnt lgkmcnt(8)
	v_mfma_f32_16x16x32_bf16 v[56:59], v[76:79], v[104:107], v[56:59]
	s_add_u32 m0, s38, 45056
	s_nop 0
	global_load_lds_dwordx4 v167, s[98:99]
	s_add_u32 s98, s98, 128
	s_addc_u32 s99, s99, 0
	s_waitcnt lgkmcnt(8)
	v_mfma_f32_16x16x32_bf16 v[60:63], v[76:79], v[108:111], v[60:63]
	s_add_u32 m0, s38, 49152
	s_nop 0
	global_load_lds_dwordx4 v164, s[100:101]
	s_waitcnt lgkmcnt(6)
	v_mfma_f32_16x16x32_bf16 v[0:3], v[80:83], v[112:115], v[0:3]
	ds_read_b128 v[64:67], v150 offset:0
	s_add_u32 m0, s38, 53248
	s_nop 0
	global_load_lds_dwordx4 v165, s[100:101]
	s_waitcnt lgkmcnt(6)
	v_mfma_f32_16x16x32_bf16 v[4:7], v[80:83], v[116:119], v[4:7]
	ds_read_b128 v[96:99], v162 offset:16384
	s_add_u32 m0, s38, 57344
	s_nop 0
	global_load_lds_dwordx4 v166, s[100:101]
	s_waitcnt lgkmcnt(6)
	v_mfma_f32_16x16x32_bf16 v[8:11], v[80:83], v[120:123], v[8:11]
	ds_read_b128 v[100:103], v162 offset:18432
	s_add_u32 m0, s38, 61440
	s_nop 0
	global_load_lds_dwordx4 v167, s[100:101]
	s_add_u32 s100, s100, 128
	s_addc_u32 s101, s101, 0
	s_waitcnt lgkmcnt(6)
	v_mfma_f32_16x16x32_bf16 v[12:15], v[80:83], v[124:127], v[12:15]
	ds_read_b128 v[104:107], v162 offset:20480
	s_waitcnt lgkmcnt(6)
	v_mfma_f32_16x16x32_bf16 v[16:19], v[84:87], v[112:115], v[16:19]
	ds_read_b128 v[108:111], v162 offset:22528
	s_waitcnt lgkmcnt(7)
	v_mfma_f32_16x16x32_bf16 v[20:23], v[84:87], v[116:119], v[20:23]
	ds_read_b128 v[68:71], v150 offset:2048
	s_waitcnt lgkmcnt(8)
	v_mfma_f32_16x16x32_bf16 v[24:27], v[84:87], v[120:123], v[24:27]
	ds_read_b128 v[72:75], v150 offset:4096
	s_waitcnt lgkmcnt(9)
	v_mfma_f32_16x16x32_bf16 v[28:31], v[84:87], v[124:127], v[28:31]
	ds_read_b128 v[76:79], v150 offset:6144
	s_waitcnt lgkmcnt(9)
	v_mfma_f32_16x16x32_bf16 v[32:35], v[88:91], v[112:115], v[32:35]
	s_waitcnt lgkmcnt(9)
	v_mfma_f32_16x16x32_bf16 v[36:39], v[88:91], v[116:119], v[36:39]
	s_waitcnt lgkmcnt(9)
	v_mfma_f32_16x16x32_bf16 v[40:43], v[88:91], v[120:123], v[40:43]
	s_waitcnt lgkmcnt(9)
	v_mfma_f32_16x16x32_bf16 v[44:47], v[88:91], v[124:127], v[44:47]
	s_waitcnt lgkmcnt(8)
	v_mfma_f32_16x16x32_bf16 v[48:51], v[92:95], v[112:115], v[48:51]
	s_waitcnt lgkmcnt(8)
	v_mfma_f32_16x16x32_bf16 v[52:55], v[92:95], v[116:119], v[52:55]
	s_waitcnt lgkmcnt(8)
	v_mfma_f32_16x16x32_bf16 v[56:59], v[92:95], v[120:123], v[56:59]
	s_waitcnt lgkmcnt(8)
	v_mfma_f32_16x16x32_bf16 v[60:63], v[92:95], v[124:127], v[60:63]
	s_waitcnt lgkmcnt(6)
	v_mfma_f32_16x16x32_bf16 v[0:3], v[64:67], v[96:99], v[0:3]
	ds_read_b128 v[80:83], v151 offset:0
	s_waitcnt lgkmcnt(6)
	v_mfma_f32_16x16x32_bf16 v[4:7], v[64:67], v[100:103], v[4:7]
	ds_read_b128 v[112:115], v163 offset:16384
	s_waitcnt lgkmcnt(6)
	v_mfma_f32_16x16x32_bf16 v[8:11], v[64:67], v[104:107], v[8:11]
	ds_read_b128 v[116:119], v163 offset:18432
	s_waitcnt lgkmcnt(6)
	v_mfma_f32_16x16x32_bf16 v[12:15], v[64:67], v[108:111], v[12:15]
	ds_read_b128 v[120:123], v163 offset:20480
	s_waitcnt lgkmcnt(6)
	v_mfma_f32_16x16x32_bf16 v[16:19], v[68:71], v[96:99], v[16:19]
	ds_read_b128 v[124:127], v163 offset:22528
	s_waitcnt lgkmcnt(7)
	v_mfma_f32_16x16x32_bf16 v[20:23], v[68:71], v[100:103], v[20:23]
	ds_read_b128 v[84:87], v151 offset:2048
	s_waitcnt lgkmcnt(8)
	v_mfma_f32_16x16x32_bf16 v[24:27], v[68:71], v[104:107], v[24:27]
	ds_read_b128 v[88:91], v151 offset:4096
	s_waitcnt lgkmcnt(9)
	v_mfma_f32_16x16x32_bf16 v[28:31], v[68:71], v[108:111], v[28:31]
	ds_read_b128 v[92:95], v151 offset:6144
	s_waitcnt lgkmcnt(9)
	v_mfma_f32_16x16x32_bf16 v[32:35], v[72:75], v[96:99], v[32:35]
	s_waitcnt lgkmcnt(9)
	v_mfma_f32_16x16x32_bf16 v[36:39], v[72:75], v[100:103], v[36:39]
	s_waitcnt lgkmcnt(9)
	v_mfma_f32_16x16x32_bf16 v[40:43], v[72:75], v[104:107], v[40:43]
	s_waitcnt lgkmcnt(9)
	v_mfma_f32_16x16x32_bf16 v[44:47], v[72:75], v[108:111], v[44:47]
	s_waitcnt vmcnt(0) lgkmcnt(0)
	s_barrier
	s_add_u32 m0, s38, 0
	s_nop 0
	global_load_lds_dwordx4 v164, s[98:99]
	s_waitcnt lgkmcnt(8)
	v_mfma_f32_16x16x32_bf16 v[48:51], v[76:79], v[96:99], v[48:51]
	s_add_u32 m0, s38, 4096
	s_nop 0
	global_load_lds_dwordx4 v165, s[98:99]
	s_waitcnt lgkmcnt(8)
	v_mfma_f32_16x16x32_bf16 v[52:55], v[76:79], v[100:103], v[52:55]
	s_add_u32 m0, s38, 8192
	s_nop 0
	global_load_lds_dwordx4 v166, s[98:99]
	s_waitcnt lgkmcnt(8)
	v_mfma_f32_16x16x32_bf16 v[56:59], v[76:79], v[104:107], v[56:59]
	s_add_u32 m0, s38, 12288
	s_nop 0
	global_load_lds_dwordx4 v167, s[98:99]
	s_add_u32 s98, s98, 128
	s_addc_u32 s99, s99, 0
	s_waitcnt lgkmcnt(8)
	v_mfma_f32_16x16x32_bf16 v[60:63], v[76:79], v[108:111], v[60:63]
	s_add_u32 m0, s38, 16384
	s_nop 0
	global_load_lds_dwordx4 v164, s[100:101]
	s_waitcnt lgkmcnt(6)
	v_mfma_f32_16x16x32_bf16 v[0:3], v[80:83], v[112:115], v[0:3]
	ds_read_b128 v[64:67], v150 offset:32768
	s_add_u32 m0, s38, 20480
	s_nop 0
	global_load_lds_dwordx4 v165, s[100:101]
	s_waitcnt lgkmcnt(6)
	v_mfma_f32_16x16x32_bf16 v[4:7], v[80:83], v[116:119], v[4:7]
	ds_read_b128 v[96:99], v162 offset:49152
	s_add_u32 m0, s38, 24576
	s_nop 0
	global_load_lds_dwordx4 v166, s[100:101]
	s_waitcnt lgkmcnt(6)
	v_mfma_f32_16x16x32_bf16 v[8:11], v[80:83], v[120:123], v[8:11]
	ds_read_b128 v[100:103], v162 offset:51200
	s_add_u32 m0, s38, 28672
	s_nop 0
	global_load_lds_dwordx4 v167, s[100:101]
	s_add_u32 s100, s100, 128
	s_addc_u32 s101, s101, 0
	s_waitcnt lgkmcnt(6)
	v_mfma_f32_16x16x32_bf16 v[12:15], v[80:83], v[124:127], v[12:15]
	ds_read_b128 v[104:107], v162 offset:53248
	s_waitcnt lgkmcnt(6)
	v_mfma_f32_16x16x32_bf16 v[16:19], v[84:87], v[112:115], v[16:19]
	ds_read_b128 v[108:111], v162 offset:55296
	s_waitcnt lgkmcnt(7)
	v_mfma_f32_16x16x32_bf16 v[20:23], v[84:87], v[116:119], v[20:23]
	ds_read_b128 v[68:71], v150 offset:34816
	s_waitcnt lgkmcnt(8)
	v_mfma_f32_16x16x32_bf16 v[24:27], v[84:87], v[120:123], v[24:27]
	ds_read_b128 v[72:75], v150 offset:36864
	s_waitcnt lgkmcnt(9)
	v_mfma_f32_16x16x32_bf16 v[28:31], v[84:87], v[124:127], v[28:31]
	ds_read_b128 v[76:79], v150 offset:38912
	s_waitcnt lgkmcnt(9)
	v_mfma_f32_16x16x32_bf16 v[32:35], v[88:91], v[112:115], v[32:35]
	s_waitcnt lgkmcnt(9)
	v_mfma_f32_16x16x32_bf16 v[36:39], v[88:91], v[116:119], v[36:39]
	s_waitcnt lgkmcnt(9)
	v_mfma_f32_16x16x32_bf16 v[40:43], v[88:91], v[120:123], v[40:43]
	s_waitcnt lgkmcnt(9)
	v_mfma_f32_16x16x32_bf16 v[44:47], v[88:91], v[124:127], v[44:47]
	s_waitcnt lgkmcnt(8)
	v_mfma_f32_16x16x32_bf16 v[48:51], v[92:95], v[112:115], v[48:51]
	s_waitcnt lgkmcnt(8)
	v_mfma_f32_16x16x32_bf16 v[52:55], v[92:95], v[116:119], v[52:55]
	s_waitcnt lgkmcnt(8)
	v_mfma_f32_16x16x32_bf16 v[56:59], v[92:95], v[120:123], v[56:59]
	s_waitcnt lgkmcnt(8)
	v_mfma_f32_16x16x32_bf16 v[60:63], v[92:95], v[124:127], v[60:63]
	s_waitcnt lgkmcnt(6)
	v_mfma_f32_16x16x32_bf16 v[0:3], v[64:67], v[96:99], v[0:3]
	ds_read_b128 v[80:83], v151 offset:32768
	s_waitcnt lgkmcnt(6)
	v_mfma_f32_16x16x32_bf16 v[4:7], v[64:67], v[100:103], v[4:7]
	ds_read_b128 v[112:115], v163 offset:49152
	s_waitcnt lgkmcnt(6)
	v_mfma_f32_16x16x32_bf16 v[8:11], v[64:67], v[104:107], v[8:11]
	ds_read_b128 v[116:119], v163 offset:51200
	s_waitcnt lgkmcnt(6)
	v_mfma_f32_16x16x32_bf16 v[12:15], v[64:67], v[108:111], v[12:15]
	ds_read_b128 v[120:123], v163 offset:53248
	s_waitcnt lgkmcnt(6)
	v_mfma_f32_16x16x32_bf16 v[16:19], v[68:71], v[96:99], v[16:19]
	ds_read_b128 v[124:127], v163 offset:55296
	s_waitcnt lgkmcnt(7)
	v_mfma_f32_16x16x32_bf16 v[20:23], v[68:71], v[100:103], v[20:23]
	ds_read_b128 v[84:87], v151 offset:34816
	s_waitcnt lgkmcnt(8)
	v_mfma_f32_16x16x32_bf16 v[24:27], v[68:71], v[104:107], v[24:27]
	ds_read_b128 v[88:91], v151 offset:36864
	s_waitcnt lgkmcnt(9)
	v_mfma_f32_16x16x32_bf16 v[28:31], v[68:71], v[108:111], v[28:31]
	ds_read_b128 v[92:95], v151 offset:38912
	s_waitcnt lgkmcnt(9)
	v_mfma_f32_16x16x32_bf16 v[32:35], v[72:75], v[96:99], v[32:35]
	s_waitcnt lgkmcnt(9)
	v_mfma_f32_16x16x32_bf16 v[36:39], v[72:75], v[100:103], v[36:39]
	s_waitcnt lgkmcnt(9)
	v_mfma_f32_16x16x32_bf16 v[40:43], v[72:75], v[104:107], v[40:43]
	s_waitcnt lgkmcnt(9)
	v_mfma_f32_16x16x32_bf16 v[44:47], v[72:75], v[108:111], v[44:47]
	s_waitcnt vmcnt(0) lgkmcnt(0)
	s_barrier
	s_add_u32 m0, s38, 32768
	s_nop 0
	global_load_lds_dwordx4 v164, s[98:99]
	s_waitcnt lgkmcnt(8)
	v_mfma_f32_16x16x32_bf16 v[48:51], v[76:79], v[96:99], v[48:51]
	s_add_u32 m0, s38, 36864
	s_nop 0
	global_load_lds_dwordx4 v165, s[98:99]
	s_waitcnt lgkmcnt(8)
	v_mfma_f32_16x16x32_bf16 v[52:55], v[76:79], v[100:103], v[52:55]
	s_add_u32 m0, s38, 40960
	s_nop 0
	global_load_lds_dwordx4 v166, s[98:99]
	s_waitcnt lgkmcnt(8)
	v_mfma_f32_16x16x32_bf16 v[56:59], v[76:79], v[104:107], v[56:59]
	s_add_u32 m0, s38, 45056
	s_nop 0
	global_load_lds_dwordx4 v167, s[98:99]
	s_add_u32 s98, s98, 128
	s_addc_u32 s99, s99, 0
	s_waitcnt lgkmcnt(8)
	v_mfma_f32_16x16x32_bf16 v[60:63], v[76:79], v[108:111], v[60:63]
	s_add_u32 m0, s38, 49152
	s_nop 0
	global_load_lds_dwordx4 v164, s[100:101]
	s_waitcnt lgkmcnt(6)
	v_mfma_f32_16x16x32_bf16 v[0:3], v[80:83], v[112:115], v[0:3]
	ds_read_b128 v[64:67], v150 offset:0
	s_add_u32 m0, s38, 53248
	s_nop 0
	global_load_lds_dwordx4 v165, s[100:101]
	s_waitcnt lgkmcnt(6)
	v_mfma_f32_16x16x32_bf16 v[4:7], v[80:83], v[116:119], v[4:7]
	ds_read_b128 v[96:99], v162 offset:16384
	s_add_u32 m0, s38, 57344
	s_nop 0
	global_load_lds_dwordx4 v166, s[100:101]
	s_waitcnt lgkmcnt(6)
	v_mfma_f32_16x16x32_bf16 v[8:11], v[80:83], v[120:123], v[8:11]
	ds_read_b128 v[100:103], v162 offset:18432
	s_add_u32 m0, s38, 61440
	s_nop 0
	global_load_lds_dwordx4 v167, s[100:101]
	s_add_u32 s100, s100, 128
	s_addc_u32 s101, s101, 0
	s_waitcnt lgkmcnt(6)
	v_mfma_f32_16x16x32_bf16 v[12:15], v[80:83], v[124:127], v[12:15]
	ds_read_b128 v[104:107], v162 offset:20480
	s_waitcnt lgkmcnt(6)
	v_mfma_f32_16x16x32_bf16 v[16:19], v[84:87], v[112:115], v[16:19]
	ds_read_b128 v[108:111], v162 offset:22528
	s_waitcnt lgkmcnt(7)
	v_mfma_f32_16x16x32_bf16 v[20:23], v[84:87], v[116:119], v[20:23]
	ds_read_b128 v[68:71], v150 offset:2048
	s_waitcnt lgkmcnt(8)
	v_mfma_f32_16x16x32_bf16 v[24:27], v[84:87], v[120:123], v[24:27]
	ds_read_b128 v[72:75], v150 offset:4096
	s_waitcnt lgkmcnt(9)
	v_mfma_f32_16x16x32_bf16 v[28:31], v[84:87], v[124:127], v[28:31]
	ds_read_b128 v[76:79], v150 offset:6144
	s_waitcnt lgkmcnt(9)
	v_mfma_f32_16x16x32_bf16 v[32:35], v[88:91], v[112:115], v[32:35]
	s_waitcnt lgkmcnt(9)
	v_mfma_f32_16x16x32_bf16 v[36:39], v[88:91], v[116:119], v[36:39]
	s_waitcnt lgkmcnt(9)
	v_mfma_f32_16x16x32_bf16 v[40:43], v[88:91], v[120:123], v[40:43]
	s_waitcnt lgkmcnt(9)
	v_mfma_f32_16x16x32_bf16 v[44:47], v[88:91], v[124:127], v[44:47]
	s_waitcnt lgkmcnt(8)
	v_mfma_f32_16x16x32_bf16 v[48:51], v[92:95], v[112:115], v[48:51]
	s_waitcnt lgkmcnt(8)
	v_mfma_f32_16x16x32_bf16 v[52:55], v[92:95], v[116:119], v[52:55]
	s_waitcnt lgkmcnt(8)
	v_mfma_f32_16x16x32_bf16 v[56:59], v[92:95], v[120:123], v[56:59]
	s_waitcnt lgkmcnt(8)
	v_mfma_f32_16x16x32_bf16 v[60:63], v[92:95], v[124:127], v[60:63]
	s_waitcnt lgkmcnt(6)
	v_mfma_f32_16x16x32_bf16 v[0:3], v[64:67], v[96:99], v[0:3]
	ds_read_b128 v[80:83], v151 offset:0
	s_waitcnt lgkmcnt(6)
	v_mfma_f32_16x16x32_bf16 v[4:7], v[64:67], v[100:103], v[4:7]
	ds_read_b128 v[112:115], v163 offset:16384
	s_waitcnt lgkmcnt(6)
	v_mfma_f32_16x16x32_bf16 v[8:11], v[64:67], v[104:107], v[8:11]
	ds_read_b128 v[116:119], v163 offset:18432
	s_waitcnt lgkmcnt(6)
	v_mfma_f32_16x16x32_bf16 v[12:15], v[64:67], v[108:111], v[12:15]
	ds_read_b128 v[120:123], v163 offset:20480
	s_waitcnt lgkmcnt(6)
	v_mfma_f32_16x16x32_bf16 v[16:19], v[68:71], v[96:99], v[16:19]
	ds_read_b128 v[124:127], v163 offset:22528
	s_waitcnt lgkmcnt(7)
	v_mfma_f32_16x16x32_bf16 v[20:23], v[68:71], v[100:103], v[20:23]
	ds_read_b128 v[84:87], v151 offset:2048
	s_waitcnt lgkmcnt(8)
	v_mfma_f32_16x16x32_bf16 v[24:27], v[68:71], v[104:107], v[24:27]
	ds_read_b128 v[88:91], v151 offset:4096
	s_waitcnt lgkmcnt(9)
	v_mfma_f32_16x16x32_bf16 v[28:31], v[68:71], v[108:111], v[28:31]
	ds_read_b128 v[92:95], v151 offset:6144
	s_waitcnt lgkmcnt(9)
	v_mfma_f32_16x16x32_bf16 v[32:35], v[72:75], v[96:99], v[32:35]
	s_waitcnt lgkmcnt(9)
	v_mfma_f32_16x16x32_bf16 v[36:39], v[72:75], v[100:103], v[36:39]
	s_waitcnt lgkmcnt(9)
	v_mfma_f32_16x16x32_bf16 v[40:43], v[72:75], v[104:107], v[40:43]
	s_waitcnt lgkmcnt(9)
	v_mfma_f32_16x16x32_bf16 v[44:47], v[72:75], v[108:111], v[44:47]
	s_waitcnt vmcnt(0) lgkmcnt(0)
	s_barrier
	s_add_u32 m0, s38, 0
	s_nop 0
	global_load_lds_dwordx4 v164, s[98:99]
	s_waitcnt lgkmcnt(8)
	v_mfma_f32_16x16x32_bf16 v[48:51], v[76:79], v[96:99], v[48:51]
	s_add_u32 m0, s38, 4096
	s_nop 0
	global_load_lds_dwordx4 v165, s[98:99]
	s_waitcnt lgkmcnt(8)
	v_mfma_f32_16x16x32_bf16 v[52:55], v[76:79], v[100:103], v[52:55]
	s_add_u32 m0, s38, 8192
	s_nop 0
	global_load_lds_dwordx4 v166, s[98:99]
	s_waitcnt lgkmcnt(8)
	v_mfma_f32_16x16x32_bf16 v[56:59], v[76:79], v[104:107], v[56:59]
	s_add_u32 m0, s38, 12288
	s_nop 0
	global_load_lds_dwordx4 v167, s[98:99]
	s_add_u32 s98, s98, 128
	s_addc_u32 s99, s99, 0
	s_waitcnt lgkmcnt(8)
	v_mfma_f32_16x16x32_bf16 v[60:63], v[76:79], v[108:111], v[60:63]
	s_add_u32 m0, s38, 16384
	s_nop 0
	global_load_lds_dwordx4 v164, s[100:101]
	s_waitcnt lgkmcnt(6)
	v_mfma_f32_16x16x32_bf16 v[0:3], v[80:83], v[112:115], v[0:3]
	ds_read_b128 v[64:67], v150 offset:32768
	s_add_u32 m0, s38, 20480
	s_nop 0
	global_load_lds_dwordx4 v165, s[100:101]
	s_waitcnt lgkmcnt(6)
	v_mfma_f32_16x16x32_bf16 v[4:7], v[80:83], v[116:119], v[4:7]
	ds_read_b128 v[96:99], v162 offset:49152
	s_add_u32 m0, s38, 24576
	s_nop 0
	global_load_lds_dwordx4 v166, s[100:101]
	s_waitcnt lgkmcnt(6)
	v_mfma_f32_16x16x32_bf16 v[8:11], v[80:83], v[120:123], v[8:11]
	ds_read_b128 v[100:103], v162 offset:51200
	s_add_u32 m0, s38, 28672
	s_nop 0
	global_load_lds_dwordx4 v167, s[100:101]
	s_add_u32 s100, s100, 128
	s_addc_u32 s101, s101, 0
	s_waitcnt lgkmcnt(6)
	v_mfma_f32_16x16x32_bf16 v[12:15], v[80:83], v[124:127], v[12:15]
	ds_read_b128 v[104:107], v162 offset:53248
	s_waitcnt lgkmcnt(6)
	v_mfma_f32_16x16x32_bf16 v[16:19], v[84:87], v[112:115], v[16:19]
	ds_read_b128 v[108:111], v162 offset:55296
	s_waitcnt lgkmcnt(7)
	v_mfma_f32_16x16x32_bf16 v[20:23], v[84:87], v[116:119], v[20:23]
	ds_read_b128 v[68:71], v150 offset:34816
	s_waitcnt lgkmcnt(8)
	v_mfma_f32_16x16x32_bf16 v[24:27], v[84:87], v[120:123], v[24:27]
	ds_read_b128 v[72:75], v150 offset:36864
	s_waitcnt lgkmcnt(9)
	v_mfma_f32_16x16x32_bf16 v[28:31], v[84:87], v[124:127], v[28:31]
	ds_read_b128 v[76:79], v150 offset:38912
	s_waitcnt lgkmcnt(9)
	v_mfma_f32_16x16x32_bf16 v[32:35], v[88:91], v[112:115], v[32:35]
	s_waitcnt lgkmcnt(9)
	v_mfma_f32_16x16x32_bf16 v[36:39], v[88:91], v[116:119], v[36:39]
	s_waitcnt lgkmcnt(9)
	v_mfma_f32_16x16x32_bf16 v[40:43], v[88:91], v[120:123], v[40:43]
	s_waitcnt lgkmcnt(9)
	v_mfma_f32_16x16x32_bf16 v[44:47], v[88:91], v[124:127], v[44:47]
	s_waitcnt lgkmcnt(8)
	v_mfma_f32_16x16x32_bf16 v[48:51], v[92:95], v[112:115], v[48:51]
	s_waitcnt lgkmcnt(8)
	v_mfma_f32_16x16x32_bf16 v[52:55], v[92:95], v[116:119], v[52:55]
	s_waitcnt lgkmcnt(8)
	v_mfma_f32_16x16x32_bf16 v[56:59], v[92:95], v[120:123], v[56:59]
	s_waitcnt lgkmcnt(8)
	v_mfma_f32_16x16x32_bf16 v[60:63], v[92:95], v[124:127], v[60:63]
	s_waitcnt lgkmcnt(6)
	v_mfma_f32_16x16x32_bf16 v[0:3], v[64:67], v[96:99], v[0:3]
	ds_read_b128 v[80:83], v151 offset:32768
	s_waitcnt lgkmcnt(6)
	v_mfma_f32_16x16x32_bf16 v[4:7], v[64:67], v[100:103], v[4:7]
	ds_read_b128 v[112:115], v163 offset:49152
	s_waitcnt lgkmcnt(6)
	v_mfma_f32_16x16x32_bf16 v[8:11], v[64:67], v[104:107], v[8:11]
	ds_read_b128 v[116:119], v163 offset:51200
	s_waitcnt lgkmcnt(6)
	v_mfma_f32_16x16x32_bf16 v[12:15], v[64:67], v[108:111], v[12:15]
	ds_read_b128 v[120:123], v163 offset:53248
	s_waitcnt lgkmcnt(6)
	v_mfma_f32_16x16x32_bf16 v[16:19], v[68:71], v[96:99], v[16:19]
	ds_read_b128 v[124:127], v163 offset:55296
	s_waitcnt lgkmcnt(7)
	v_mfma_f32_16x16x32_bf16 v[20:23], v[68:71], v[100:103], v[20:23]
	ds_read_b128 v[84:87], v151 offset:34816
	s_waitcnt lgkmcnt(8)
	v_mfma_f32_16x16x32_bf16 v[24:27], v[68:71], v[104:107], v[24:27]
	ds_read_b128 v[88:91], v151 offset:36864
	s_waitcnt lgkmcnt(9)
	v_mfma_f32_16x16x32_bf16 v[28:31], v[68:71], v[108:111], v[28:31]
	ds_read_b128 v[92:95], v151 offset:38912
	s_waitcnt lgkmcnt(9)
	v_mfma_f32_16x16x32_bf16 v[32:35], v[72:75], v[96:99], v[32:35]
	s_waitcnt lgkmcnt(9)
	v_mfma_f32_16x16x32_bf16 v[36:39], v[72:75], v[100:103], v[36:39]
	s_waitcnt lgkmcnt(9)
	v_mfma_f32_16x16x32_bf16 v[40:43], v[72:75], v[104:107], v[40:43]
	s_waitcnt lgkmcnt(9)
	v_mfma_f32_16x16x32_bf16 v[44:47], v[72:75], v[108:111], v[44:47]
	s_waitcnt vmcnt(0) lgkmcnt(0)
	s_barrier
	s_add_u32 m0, s38, 32768
	s_nop 0
	global_load_lds_dwordx4 v164, s[98:99]
	s_waitcnt lgkmcnt(8)
	v_mfma_f32_16x16x32_bf16 v[48:51], v[76:79], v[96:99], v[48:51]
	s_add_u32 m0, s38, 36864
	s_nop 0
	global_load_lds_dwordx4 v165, s[98:99]
	s_waitcnt lgkmcnt(8)
	v_mfma_f32_16x16x32_bf16 v[52:55], v[76:79], v[100:103], v[52:55]
	s_add_u32 m0, s38, 40960
	s_nop 0
	global_load_lds_dwordx4 v166, s[98:99]
	s_waitcnt lgkmcnt(8)
	v_mfma_f32_16x16x32_bf16 v[56:59], v[76:79], v[104:107], v[56:59]
	s_add_u32 m0, s38, 45056
	s_nop 0
	global_load_lds_dwordx4 v167, s[98:99]
	s_add_u32 s98, s98, 128
	s_addc_u32 s99, s99, 0
	s_waitcnt lgkmcnt(8)
	v_mfma_f32_16x16x32_bf16 v[60:63], v[76:79], v[108:111], v[60:63]
	s_add_u32 m0, s38, 49152
	s_nop 0
	global_load_lds_dwordx4 v164, s[100:101]
	s_waitcnt lgkmcnt(6)
	v_mfma_f32_16x16x32_bf16 v[0:3], v[80:83], v[112:115], v[0:3]
	ds_read_b128 v[64:67], v150 offset:0
	s_add_u32 m0, s38, 53248
	s_nop 0
	global_load_lds_dwordx4 v165, s[100:101]
	s_waitcnt lgkmcnt(6)
	v_mfma_f32_16x16x32_bf16 v[4:7], v[80:83], v[116:119], v[4:7]
	ds_read_b128 v[96:99], v162 offset:16384
	s_add_u32 m0, s38, 57344
	s_nop 0
	global_load_lds_dwordx4 v166, s[100:101]
	s_waitcnt lgkmcnt(6)
	v_mfma_f32_16x16x32_bf16 v[8:11], v[80:83], v[120:123], v[8:11]
	ds_read_b128 v[100:103], v162 offset:18432
	s_add_u32 m0, s38, 61440
	s_nop 0
	global_load_lds_dwordx4 v167, s[100:101]
	s_add_u32 s100, s100, 128
	s_addc_u32 s101, s101, 0
	s_waitcnt lgkmcnt(6)
	v_mfma_f32_16x16x32_bf16 v[12:15], v[80:83], v[124:127], v[12:15]
	ds_read_b128 v[104:107], v162 offset:20480
	s_waitcnt lgkmcnt(6)
	v_mfma_f32_16x16x32_bf16 v[16:19], v[84:87], v[112:115], v[16:19]
	ds_read_b128 v[108:111], v162 offset:22528
	s_waitcnt lgkmcnt(7)
	v_mfma_f32_16x16x32_bf16 v[20:23], v[84:87], v[116:119], v[20:23]
	ds_read_b128 v[68:71], v150 offset:2048
	s_waitcnt lgkmcnt(8)
	v_mfma_f32_16x16x32_bf16 v[24:27], v[84:87], v[120:123], v[24:27]
	ds_read_b128 v[72:75], v150 offset:4096
	s_waitcnt lgkmcnt(9)
	v_mfma_f32_16x16x32_bf16 v[28:31], v[84:87], v[124:127], v[28:31]
	ds_read_b128 v[76:79], v150 offset:6144
	s_waitcnt lgkmcnt(9)
	v_mfma_f32_16x16x32_bf16 v[32:35], v[88:91], v[112:115], v[32:35]
	s_waitcnt lgkmcnt(9)
	v_mfma_f32_16x16x32_bf16 v[36:39], v[88:91], v[116:119], v[36:39]
	s_waitcnt lgkmcnt(9)
	v_mfma_f32_16x16x32_bf16 v[40:43], v[88:91], v[120:123], v[40:43]
	s_waitcnt lgkmcnt(9)
	v_mfma_f32_16x16x32_bf16 v[44:47], v[88:91], v[124:127], v[44:47]
	s_waitcnt lgkmcnt(8)
	v_mfma_f32_16x16x32_bf16 v[48:51], v[92:95], v[112:115], v[48:51]
	s_waitcnt lgkmcnt(8)
	v_mfma_f32_16x16x32_bf16 v[52:55], v[92:95], v[116:119], v[52:55]
	s_waitcnt lgkmcnt(8)
	v_mfma_f32_16x16x32_bf16 v[56:59], v[92:95], v[120:123], v[56:59]
	s_waitcnt lgkmcnt(8)
	v_mfma_f32_16x16x32_bf16 v[60:63], v[92:95], v[124:127], v[60:63]
	s_waitcnt lgkmcnt(6)
	v_mfma_f32_16x16x32_bf16 v[0:3], v[64:67], v[96:99], v[0:3]
	ds_read_b128 v[80:83], v151 offset:0
	s_waitcnt lgkmcnt(6)
	v_mfma_f32_16x16x32_bf16 v[4:7], v[64:67], v[100:103], v[4:7]
	ds_read_b128 v[112:115], v163 offset:16384
	s_waitcnt lgkmcnt(6)
	v_mfma_f32_16x16x32_bf16 v[8:11], v[64:67], v[104:107], v[8:11]
	ds_read_b128 v[116:119], v163 offset:18432
	s_waitcnt lgkmcnt(6)
	v_mfma_f32_16x16x32_bf16 v[12:15], v[64:67], v[108:111], v[12:15]
	ds_read_b128 v[120:123], v163 offset:20480
	s_waitcnt lgkmcnt(6)
	v_mfma_f32_16x16x32_bf16 v[16:19], v[68:71], v[96:99], v[16:19]
	ds_read_b128 v[124:127], v163 offset:22528
	s_waitcnt lgkmcnt(7)
	v_mfma_f32_16x16x32_bf16 v[20:23], v[68:71], v[100:103], v[20:23]
	ds_read_b128 v[84:87], v151 offset:2048
	s_waitcnt lgkmcnt(8)
	v_mfma_f32_16x16x32_bf16 v[24:27], v[68:71], v[104:107], v[24:27]
	ds_read_b128 v[88:91], v151 offset:4096
	s_waitcnt lgkmcnt(9)
	v_mfma_f32_16x16x32_bf16 v[28:31], v[68:71], v[108:111], v[28:31]
	ds_read_b128 v[92:95], v151 offset:6144
	s_waitcnt lgkmcnt(9)
	v_mfma_f32_16x16x32_bf16 v[32:35], v[72:75], v[96:99], v[32:35]
	s_waitcnt lgkmcnt(9)
	v_mfma_f32_16x16x32_bf16 v[36:39], v[72:75], v[100:103], v[36:39]
	s_waitcnt lgkmcnt(9)
	v_mfma_f32_16x16x32_bf16 v[40:43], v[72:75], v[104:107], v[40:43]
	s_waitcnt lgkmcnt(9)
	v_mfma_f32_16x16x32_bf16 v[44:47], v[72:75], v[108:111], v[44:47]
	s_waitcnt vmcnt(0) lgkmcnt(0)
	s_barrier
	s_waitcnt lgkmcnt(8)
	v_mfma_f32_16x16x32_bf16 v[48:51], v[76:79], v[96:99], v[48:51]
	s_waitcnt lgkmcnt(8)
	v_mfma_f32_16x16x32_bf16 v[52:55], v[76:79], v[100:103], v[52:55]
	s_waitcnt lgkmcnt(8)
	v_mfma_f32_16x16x32_bf16 v[56:59], v[76:79], v[104:107], v[56:59]
	s_waitcnt lgkmcnt(8)
	v_mfma_f32_16x16x32_bf16 v[60:63], v[76:79], v[108:111], v[60:63]
	s_waitcnt lgkmcnt(6)
	v_mfma_f32_16x16x32_bf16 v[0:3], v[80:83], v[112:115], v[0:3]
	ds_read_b128 v[64:67], v150 offset:32768
	s_waitcnt lgkmcnt(6)
	v_mfma_f32_16x16x32_bf16 v[4:7], v[80:83], v[116:119], v[4:7]
	ds_read_b128 v[96:99], v162 offset:49152
	s_waitcnt lgkmcnt(6)
	v_mfma_f32_16x16x32_bf16 v[8:11], v[80:83], v[120:123], v[8:11]
	ds_read_b128 v[100:103], v162 offset:51200
	s_waitcnt lgkmcnt(6)
	v_mfma_f32_16x16x32_bf16 v[12:15], v[80:83], v[124:127], v[12:15]
	ds_read_b128 v[104:107], v162 offset:53248
	s_waitcnt lgkmcnt(6)
	v_mfma_f32_16x16x32_bf16 v[16:19], v[84:87], v[112:115], v[16:19]
	ds_read_b128 v[108:111], v162 offset:55296
	s_waitcnt lgkmcnt(7)
	v_mfma_f32_16x16x32_bf16 v[20:23], v[84:87], v[116:119], v[20:23]
	ds_read_b128 v[68:71], v150 offset:34816
	s_waitcnt lgkmcnt(8)
	v_mfma_f32_16x16x32_bf16 v[24:27], v[84:87], v[120:123], v[24:27]
	ds_read_b128 v[72:75], v150 offset:36864
	s_waitcnt lgkmcnt(9)
	v_mfma_f32_16x16x32_bf16 v[28:31], v[84:87], v[124:127], v[28:31]
	ds_read_b128 v[76:79], v150 offset:38912
	s_waitcnt lgkmcnt(9)
	v_mfma_f32_16x16x32_bf16 v[32:35], v[88:91], v[112:115], v[32:35]
	s_waitcnt lgkmcnt(9)
	v_mfma_f32_16x16x32_bf16 v[36:39], v[88:91], v[116:119], v[36:39]
	s_waitcnt lgkmcnt(9)
	v_mfma_f32_16x16x32_bf16 v[40:43], v[88:91], v[120:123], v[40:43]
	s_waitcnt lgkmcnt(9)
	v_mfma_f32_16x16x32_bf16 v[44:47], v[88:91], v[124:127], v[44:47]
	s_waitcnt lgkmcnt(8)
	v_mfma_f32_16x16x32_bf16 v[48:51], v[92:95], v[112:115], v[48:51]
	s_waitcnt lgkmcnt(8)
	v_mfma_f32_16x16x32_bf16 v[52:55], v[92:95], v[116:119], v[52:55]
	s_waitcnt lgkmcnt(8)
	v_mfma_f32_16x16x32_bf16 v[56:59], v[92:95], v[120:123], v[56:59]
	s_waitcnt lgkmcnt(8)
	v_mfma_f32_16x16x32_bf16 v[60:63], v[92:95], v[124:127], v[60:63]
	s_waitcnt lgkmcnt(6)
	v_mfma_f32_16x16x32_bf16 v[0:3], v[64:67], v[96:99], v[0:3]
	ds_read_b128 v[80:83], v151 offset:32768
	s_waitcnt lgkmcnt(6)
	v_mfma_f32_16x16x32_bf16 v[4:7], v[64:67], v[100:103], v[4:7]
	ds_read_b128 v[112:115], v163 offset:49152
	s_waitcnt lgkmcnt(6)
	v_mfma_f32_16x16x32_bf16 v[8:11], v[64:67], v[104:107], v[8:11]
	ds_read_b128 v[116:119], v163 offset:51200
	s_waitcnt lgkmcnt(6)
	v_mfma_f32_16x16x32_bf16 v[12:15], v[64:67], v[108:111], v[12:15]
	ds_read_b128 v[120:123], v163 offset:53248
	s_waitcnt lgkmcnt(6)
	v_mfma_f32_16x16x32_bf16 v[16:19], v[68:71], v[96:99], v[16:19]
	ds_read_b128 v[124:127], v163 offset:55296
	s_waitcnt lgkmcnt(7)
	v_mfma_f32_16x16x32_bf16 v[20:23], v[68:71], v[100:103], v[20:23]
	ds_read_b128 v[84:87], v151 offset:34816
	s_waitcnt lgkmcnt(8)
	v_mfma_f32_16x16x32_bf16 v[24:27], v[68:71], v[104:107], v[24:27]
	ds_read_b128 v[88:91], v151 offset:36864
	s_waitcnt lgkmcnt(9)
	v_mfma_f32_16x16x32_bf16 v[28:31], v[68:71], v[108:111], v[28:31]
	ds_read_b128 v[92:95], v151 offset:38912
	s_waitcnt lgkmcnt(9)
	v_mfma_f32_16x16x32_bf16 v[32:35], v[72:75], v[96:99], v[32:35]
	s_waitcnt lgkmcnt(9)
	v_mfma_f32_16x16x32_bf16 v[36:39], v[72:75], v[100:103], v[36:39]
	s_waitcnt lgkmcnt(9)
	v_mfma_f32_16x16x32_bf16 v[40:43], v[72:75], v[104:107], v[40:43]
	s_waitcnt lgkmcnt(9)
	v_mfma_f32_16x16x32_bf16 v[44:47], v[72:75], v[108:111], v[44:47]
	s_waitcnt lgkmcnt(8)
	v_mfma_f32_16x16x32_bf16 v[48:51], v[76:79], v[96:99], v[48:51]
	s_waitcnt lgkmcnt(8)
	v_mfma_f32_16x16x32_bf16 v[52:55], v[76:79], v[100:103], v[52:55]
	s_waitcnt lgkmcnt(8)
	v_mfma_f32_16x16x32_bf16 v[56:59], v[76:79], v[104:107], v[56:59]
	s_waitcnt lgkmcnt(8)
	v_mfma_f32_16x16x32_bf16 v[60:63], v[76:79], v[108:111], v[60:63]
	s_waitcnt lgkmcnt(6)
	v_mfma_f32_16x16x32_bf16 v[0:3], v[80:83], v[112:115], v[0:3]
	s_waitcnt lgkmcnt(5)
	v_mfma_f32_16x16x32_bf16 v[4:7], v[80:83], v[116:119], v[4:7]
	s_waitcnt lgkmcnt(4)
	v_mfma_f32_16x16x32_bf16 v[8:11], v[80:83], v[120:123], v[8:11]
	s_waitcnt lgkmcnt(3)
	v_mfma_f32_16x16x32_bf16 v[12:15], v[80:83], v[124:127], v[12:15]
	s_waitcnt lgkmcnt(2)
	v_mfma_f32_16x16x32_bf16 v[16:19], v[84:87], v[112:115], v[16:19]
	s_waitcnt lgkmcnt(2)
	v_mfma_f32_16x16x32_bf16 v[20:23], v[84:87], v[116:119], v[20:23]
	s_waitcnt lgkmcnt(2)
	v_mfma_f32_16x16x32_bf16 v[24:27], v[84:87], v[120:123], v[24:27]
	s_waitcnt lgkmcnt(2)
	v_mfma_f32_16x16x32_bf16 v[28:31], v[84:87], v[124:127], v[28:31]
	s_waitcnt lgkmcnt(1)
	v_mfma_f32_16x16x32_bf16 v[32:35], v[88:91], v[112:115], v[32:35]
	s_waitcnt lgkmcnt(1)
	v_mfma_f32_16x16x32_bf16 v[36:39], v[88:91], v[116:119], v[36:39]
	s_waitcnt lgkmcnt(1)
	v_mfma_f32_16x16x32_bf16 v[40:43], v[88:91], v[120:123], v[40:43]
	s_waitcnt lgkmcnt(1)
	v_mfma_f32_16x16x32_bf16 v[44:47], v[88:91], v[124:127], v[44:47]
	s_waitcnt lgkmcnt(0)
	v_mfma_f32_16x16x32_bf16 v[48:51], v[92:95], v[112:115], v[48:51]
	s_waitcnt lgkmcnt(0)
	v_mfma_f32_16x16x32_bf16 v[52:55], v[92:95], v[116:119], v[52:55]
	s_waitcnt lgkmcnt(0)
	v_mfma_f32_16x16x32_bf16 v[56:59], v[92:95], v[120:123], v[56:59]
	s_waitcnt lgkmcnt(0)
	v_mfma_f32_16x16x32_bf16 v[60:63], v[92:95], v[124:127], v[60:63]
	global_load_dwordx4 v[64:67], v168, s[14:15] nt
	global_load_dwordx4 v[68:71], v168, s[14:15] offset:16 nt
	s_add_u32 s14, s14, 0x8000
	s_addc_u32 s15, s15, 0
	global_load_dwordx4 v[72:75], v168, s[14:15] nt
	global_load_dwordx4 v[76:79], v168, s[14:15] offset:16 nt
	s_add_u32 s14, s14, 0x8000
	s_addc_u32 s15, s15, 0
	global_load_dwordx4 v[80:83], v168, s[14:15] nt
	global_load_dwordx4 v[84:87], v168, s[14:15] offset:16 nt
	s_add_u32 s14, s14, 0x8000
	s_addc_u32 s15, s15, 0
	global_load_dwordx4 v[88:91], v168, s[14:15] nt
	global_load_dwordx4 v[92:95], v168, s[14:15] offset:16 nt
	s_add_u32 s14, s14, 0x8000
	s_addc_u32 s15, s15, 0
	s_nop 7
	s_waitcnt lgkmcnt(0)
	s_barrier
	ds_write_b32 v169, v0 offset:0
	ds_write_b32 v169, v1 offset:256
	ds_write_b32 v169, v2 offset:512
	ds_write_b32 v169, v3 offset:768
	ds_write_b32 v170, v4 offset:0
	ds_write_b32 v170, v5 offset:256
	ds_write_b32 v170, v6 offset:512
	ds_write_b32 v170, v7 offset:768
	ds_write_b32 v171, v8 offset:0
	ds_write_b32 v171, v9 offset:256
	ds_write_b32 v171, v10 offset:512
	ds_write_b32 v171, v11 offset:768
	ds_write_b32 v228, v12 offset:0
	ds_write_b32 v228, v13 offset:256
	ds_write_b32 v228, v14 offset:512
	ds_write_b32 v228, v15 offset:768
	ds_write_b32 v169, v16 offset:4096
	ds_write_b32 v169, v17 offset:4352
	ds_write_b32 v169, v18 offset:4608
	ds_write_b32 v169, v19 offset:4864
	ds_write_b32 v170, v20 offset:4096
	ds_write_b32 v170, v21 offset:4352
	ds_write_b32 v170, v22 offset:4608
	ds_write_b32 v170, v23 offset:4864
	ds_write_b32 v171, v24 offset:4096
	ds_write_b32 v171, v25 offset:4352
	ds_write_b32 v171, v26 offset:4608
	ds_write_b32 v171, v27 offset:4864
	ds_write_b32 v228, v28 offset:4096
	ds_write_b32 v228, v29 offset:4352
	ds_write_b32 v228, v30 offset:4608
	ds_write_b32 v228, v31 offset:4864
	s_waitcnt lgkmcnt(0)
	ds_read_b128 v[0:3], v220
	ds_read_b128 v[4:7], v220 offset:16
	ds_read_b128 v[8:11], v222
	ds_read_b128 v[12:15], v222 offset:16
	ds_read_b128 v[16:19], v224
	ds_read_b128 v[20:23], v224 offset:16
	ds_read_b128 v[24:27], v226
	ds_read_b128 v[28:31], v226 offset:16
	s_waitcnt lgkmcnt(6)
	v_pk_fma_f32 v[0:1], v[142:143], v[0:1], v[172:173]
	v_pk_fma_f32 v[2:3], v[144:145], v[2:3], v[174:175]
	v_pk_fma_f32 v[4:5], v[146:147], v[4:5], v[176:177]
	v_pk_fma_f32 v[6:7], v[160:161], v[6:7], v[178:179]
	global_store_dwordx4 v168, v[0:3], s[18:19]
	global_store_dwordx4 v168, v[4:7], s[18:19] offset:16
	s_add_u32 s18, s18, 0x8000
	s_addc_u32 s19, s19, 0
	s_waitcnt lgkmcnt(4)
	v_pk_fma_f32 v[8:9], v[142:143], v[8:9], v[180:181]
	v_pk_fma_f32 v[10:11], v[144:145], v[10:11], v[182:183]
	v_pk_fma_f32 v[12:13], v[146:147], v[12:13], v[184:185]
	v_pk_fma_f32 v[14:15], v[160:161], v[14:15], v[186:187]
	global_store_dwordx4 v168, v[8:11], s[18:19]
	global_store_dwordx4 v168, v[12:15], s[18:19] offset:16
	s_add_u32 s18, s18, 0x8000
	s_addc_u32 s19, s19, 0
	s_waitcnt lgkmcnt(2)
	v_pk_fma_f32 v[16:17], v[142:143], v[16:17], v[188:189]
	v_pk_fma_f32 v[18:19], v[144:145], v[18:19], v[190:191]
	v_pk_fma_f32 v[20:21], v[146:147], v[20:21], v[192:193]
	v_pk_fma_f32 v[22:23], v[160:161], v[22:23], v[194:195]
	global_store_dwordx4 v168, v[16:19], s[18:19]
	global_store_dwordx4 v168, v[20:23], s[18:19] offset:16
	s_add_u32 s18, s18, 0x8000
	s_addc_u32 s19, s19, 0
	s_waitcnt lgkmcnt(0)
	v_pk_fma_f32 v[24:25], v[142:143], v[24:25], v[196:197]
	v_pk_fma_f32 v[26:27], v[144:145], v[26:27], v[198:199]
	v_pk_fma_f32 v[28:29], v[146:147], v[28:29], v[200:201]
	v_pk_fma_f32 v[30:31], v[160:161], v[30:31], v[202:203]
	global_store_dwordx4 v168, v[24:27], s[18:19]
	global_store_dwordx4 v168, v[28:31], s[18:19] offset:16
	s_add_u32 s18, s18, 0x8000
	s_addc_u32 s19, s19, 0
	ds_write_b32 v169, v32 offset:0
	ds_write_b32 v169, v33 offset:256
	ds_write_b32 v169, v34 offset:512
	ds_write_b32 v169, v35 offset:768
	ds_write_b32 v170, v36 offset:0
	ds_write_b32 v170, v37 offset:256
	ds_write_b32 v170, v38 offset:512
	ds_write_b32 v170, v39 offset:768
	ds_write_b32 v171, v40 offset:0
	ds_write_b32 v171, v41 offset:256
	ds_write_b32 v171, v42 offset:512
	ds_write_b32 v171, v43 offset:768
	ds_write_b32 v228, v44 offset:0
	ds_write_b32 v228, v45 offset:256
	ds_write_b32 v228, v46 offset:512
	ds_write_b32 v228, v47 offset:768
	ds_write_b32 v169, v48 offset:4096
	ds_write_b32 v169, v49 offset:4352
	ds_write_b32 v169, v50 offset:4608
	ds_write_b32 v169, v51 offset:4864
	ds_write_b32 v170, v52 offset:4096
	ds_write_b32 v170, v53 offset:4352
	ds_write_b32 v170, v54 offset:4608
	ds_write_b32 v170, v55 offset:4864
	ds_write_b32 v171, v56 offset:4096
	ds_write_b32 v171, v57 offset:4352
	ds_write_b32 v171, v58 offset:4608
	ds_write_b32 v171, v59 offset:4864
	ds_write_b32 v228, v60 offset:4096
	ds_write_b32 v228, v61 offset:4352
	ds_write_b32 v228, v62 offset:4608
	ds_write_b32 v228, v63 offset:4864
	s_waitcnt lgkmcnt(0)
	ds_read_b128 v[32:35], v220
	ds_read_b128 v[36:39], v220 offset:16
	ds_read_b128 v[40:43], v222
	ds_read_b128 v[44:47], v222 offset:16
	ds_read_b128 v[48:51], v224
	ds_read_b128 v[52:55], v224 offset:16
	ds_read_b128 v[56:59], v226
	ds_read_b128 v[60:63], v226 offset:16
	s_waitcnt vmcnt(14) lgkmcnt(6)
	v_pk_fma_f32 v[32:33], v[142:143], v[32:33], v[64:65]
	v_pk_fma_f32 v[34:35], v[144:145], v[34:35], v[66:67]
	v_pk_fma_f32 v[36:37], v[146:147], v[36:37], v[68:69]
	v_pk_fma_f32 v[38:39], v[160:161], v[38:39], v[70:71]
	global_store_dwordx4 v168, v[32:35], s[18:19]
	global_store_dwordx4 v168, v[36:39], s[18:19] offset:16
	s_add_u32 s18, s18, 0x8000
	s_addc_u32 s19, s19, 0
	s_waitcnt vmcnt(14) lgkmcnt(4)
	v_pk_fma_f32 v[40:41], v[142:143], v[40:41], v[72:73]
	v_pk_fma_f32 v[42:43], v[144:145], v[42:43], v[74:75]
	v_pk_fma_f32 v[44:45], v[146:147], v[44:45], v[76:77]
	v_pk_fma_f32 v[46:47], v[160:161], v[46:47], v[78:79]
	global_store_dwordx4 v168, v[40:43], s[18:19]
	global_store_dwordx4 v168, v[44:47], s[18:19] offset:16
	s_add_u32 s18, s18, 0x8000
	s_addc_u32 s19, s19, 0
	s_waitcnt vmcnt(14) lgkmcnt(2)
	v_pk_fma_f32 v[48:49], v[142:143], v[48:49], v[80:81]
	v_pk_fma_f32 v[50:51], v[144:145], v[50:51], v[82:83]
	v_pk_fma_f32 v[52:53], v[146:147], v[52:53], v[84:85]
	v_pk_fma_f32 v[54:55], v[160:161], v[54:55], v[86:87]
	global_store_dwordx4 v168, v[48:51], s[18:19]
	global_store_dwordx4 v168, v[52:55], s[18:19] offset:16
	s_add_u32 s18, s18, 0x8000
	s_addc_u32 s19, s19, 0
	s_waitcnt vmcnt(14) lgkmcnt(0)
	v_pk_fma_f32 v[56:57], v[142:143], v[56:57], v[88:89]
	v_pk_fma_f32 v[58:59], v[144:145], v[58:59], v[90:91]
	v_pk_fma_f32 v[60:61], v[146:147], v[60:61], v[92:93]
	v_pk_fma_f32 v[62:63], v[160:161], v[62:63], v[94:95]
	global_store_dwordx4 v168, v[56:59], s[18:19]
	global_store_dwordx4 v168, v[60:63], s[18:19] offset:16
	s_add_u32 s18, s18, 0x8000
	s_addc_u32 s19, s19, 0
	s_add_i32 s52, s52, s3
	s_cmpk_lt_i32 s52, 0x400
	s_cbranch_scc1 .Lmy_op0_tile

.LBB0_684:
	s_or_b64 exec, exec, s[0:1]
	s_and_b64 vcc, exec, s[54:55]
	s_waitcnt lgkmcnt(0)
	s_barrier
	s_cbranch_vccnz .LBB0_689
	v_lshrrev_b32_e32 v141, 4, v129
	v_and_b32_e32 v0, 15, v141
	v_bfe_u32 v1, v141, 4, 2
	v_bfe_u32 v2, v141, 1, 3
	v_xor_b32_e32 v2, v1, v2
	v_lshlrev_b32_e32 v2, 4, v2
	v_lshl_or_b32 v3, v0, 7, v2
	v_bfe_u32 v4, v141, 7, 1
	v_bfe_u32 v5, v141, 6, 1
	v_lshl_add_u32 v150, v4, 13, v3
	v_xor_b32_e32 v151, 64, v150
	v_lshl_add_u32 v162, v5, 13, v3
	v_xor_b32_e32 v163, 64, v162
	v_bfe_u32 v6, v141, 4, 3
	v_and_b32_e32 v7, 7, v141
	v_xor_b32_e32 v6, v6, v7
	v_lshlrev_b32_e32 v6, 4, v6
	v_lshrrev_b32_e32 v8, 3, v141
	v_lshl_or_b32 v164, v8, 12, v6
	v_add_u32_e32 v165, 131072, v164
	v_add_u32_e32 v166, 262144, v164
	v_add_u32_e32 v167, 393216, v164
	v_bfe_u32 v9, v141, 3, 3
	v_lshlrev_b32_e32 v10, 8, v5
	v_lshl_add_u32 v148, v7, 5, v10
	v_lshl_add_u32 v10, v4, 6, v9
	v_lshl_add_u32 v168, v10, 12, v148
	v_lshrrev_b32_e32 v10, 6, v141
	v_lshlrev_b32_e32 v10, 13, v10
	v_lshl_add_u32 v11, v1, 10, v10
	v_add_u32_e32 v12, 0, v1
	v_and_b32_e32 v12, 3, v12
	v_lshl_add_u32 v12, v12, 4, v0
	v_lshl_add_u32 v169, v12, 2, v11
	v_add_u32_e32 v12, 1, v1
	v_and_b32_e32 v12, 3, v12
	v_lshl_add_u32 v12, v12, 4, v0
	v_lshl_add_u32 v170, v12, 2, v11
	v_add_u32_e32 v12, 2, v1
	v_and_b32_e32 v12, 3, v12
	v_lshl_add_u32 v12, v12, 4, v0
	v_lshl_add_u32 v171, v12, 2, v11
	v_add_u32_e32 v12, 3, v1
	v_and_b32_e32 v12, 3, v12
	v_lshl_add_u32 v12, v12, 4, v0
	v_lshl_add_u32 v228, v12, 2, v11
	v_lshl_add_u32 v11, v9, 8, v10
	v_lshrrev_b32_e32 v13, 2, v9
	v_lshlrev_b32_e32 v14, 3, v7
	v_add_u32_e32 v12, 0, v13
	v_and_b32_e32 v12, 3, v12
	v_lshl_add_u32 v12, v12, 4, v14
	v_and_b32_e32 v12, 63, v12
	v_lshl_add_u32 v220, v12, 2, v11
	v_add_u32_e32 v12, 2, v13
	v_and_b32_e32 v12, 3, v12
	v_lshl_add_u32 v12, v12, 4, v14
	v_and_b32_e32 v12, 63, v12
	v_lshl_add_u32 v222, v12, 2, v11
	v_add_u32_e32 v222, 2048, v222
	v_add_u32_e32 v12, 4, v13
	v_and_b32_e32 v12, 3, v12
	v_lshl_add_u32 v12, v12, 4, v14
	v_and_b32_e32 v12, 63, v12
	v_lshl_add_u32 v224, v12, 2, v11
	v_add_u32_e32 v224, 4096, v224
	v_add_u32_e32 v12, 6, v13
	v_and_b32_e32 v12, 3, v12
	v_lshl_add_u32 v12, v12, 4, v14
	v_and_b32_e32 v12, 63, v12
	v_lshl_add_u32 v226, v12, 2, v11
	v_add_u32_e32 v226, 6144, v226
	v_readfirstlane_b32 s38, v129
	s_mov_b32 s52, s2
.Lmy_op1_tile:
	s_and_b32 s10, s52, 7
	s_lshr_b32 s11, s52, 9
	s_lshl_b32 s11, s11, 3
	s_add_i32 s10, s10, s11
	s_bfe_u32 s11, s52, 0x30003
	s_lshl_b32 s12, s10, 3
	s_or_b32 s12, s12, s11
	s_bfe_u32 s13, s52, 0x30006
	s_lshl_b32 s10, s12, 19
	s_add_u32 s98, s50, s10
	s_addc_u32 s99, s51, 0
	s_add_u32 s98, s98, 0x5a00000
	s_addc_u32 s99, s99, 0
	s_lshl_b32 s11, s13, 19
	s_add_u32 s100, s50, s11
	s_addc_u32 s101, s51, 0
	s_add_u32 s100, s100, 0xc00000
	s_addc_u32 s101, s101, 0
	s_lshr_b32 s11, s12, 5
	s_mul_i32 s11, s11, 0x3000
	s_lshl_b32 s20, s13, 9
	s_add_i32 s11, s11, s20
	s_add_i32 s11, s11, 0x1122000
	s_add_u32 s4, s50, s11
	s_addc_u32 s5, s51, 0
	s_add_i32 s10, s10, s20
	s_add_u32 s6, s48, s10
	s_addc_u32 s7, s49, 0
	s_add_u32 s8, s48, s10
	s_addc_u32 s9, s49, 0
	s_mov_b32 s14, s6
	s_mov_b32 s15, s7
	s_mov_b32 s18, s8
	s_mov_b32 s19, s9
	global_load_dwordx4 v[172:175], v148, s[4:5]
	global_load_dwordx4 v[176:179], v148, s[4:5] offset:16
	s_add_u32 s4, s4, 0xc000
	s_addc_u32 s5, s5, 0
	global_load_dwordx4 v[180:183], v148, s[4:5]
	global_load_dwordx4 v[184:187], v148, s[4:5] offset:16
	s_add_u32 s4, s4, 0xc000
	s_addc_u32 s5, s5, 0
	global_load_dwordx4 v[188:191], v148, s[4:5]
	global_load_dwordx4 v[192:195], v148, s[4:5] offset:16
	s_add_u32 s4, s4, 0xc000
	s_addc_u32 s5, s5, 0
	global_load_dwordx4 v[196:199], v148, s[4:5]
	global_load_dwordx4 v[200:203], v148, s[4:5] offset:16
	s_add_u32 s4, s4, 0xc000
	s_addc_u32 s5, s5, 0
	global_load_dwordx4 v[204:207], v148, s[4:5]
	global_load_dwordx4 v[208:211], v148, s[4:5] offset:16
	s_add_u32 s4, s4, 0xc000
	s_addc_u32 s5, s5, 0
	global_load_dwordx4 v[212:215], v148, s[4:5]
	global_load_dwordx4 v[216:219], v148, s[4:5] offset:16
	s_add_u32 s4, s4, 0xc000
	s_addc_u32 s5, s5, 0
	global_load_dwordx4 v[230:233], v148, s[4:5]
	global_load_dwordx4 v[234:237], v148, s[4:5] offset:16
	s_add_u32 s4, s4, 0xc000
	s_addc_u32 s5, s5, 0
	global_load_dwordx4 v[238:241], v148, s[4:5]
	global_load_dwordx4 v[242:245], v148, s[4:5] offset:16
	s_barrier
	s_add_u32 m0, s38, 0
	v_mov_b32_e32 v0, 0
	v_mov_b32_e32 v1, 0
	global_load_lds_dwordx4 v164, s[98:99]
	s_add_u32 m0, s38, 4096
	v_mov_b32_e32 v2, 0
	v_mov_b32_e32 v3, 0
	global_load_lds_dwordx4 v165, s[98:99]
	s_add_u32 m0, s38, 8192
	v_mov_b32_e32 v4, 0
	v_mov_b32_e32 v5, 0
	global_load_lds_dwordx4 v166, s[98:99]
	s_add_u32 m0, s38, 12288
	v_mov_b32_e32 v6, 0
	v_mov_b32_e32 v7, 0
	global_load_lds_dwordx4 v167, s[98:99]
	s_add_u32 s98, s98, 128
	s_addc_u32 s99, s99, 0
	s_add_u32 m0, s38, 16384
	v_mov_b32_e32 v8, 0
	v_mov_b32_e32 v9, 0
	global_load_lds_dwordx4 v164, s[100:101]
	s_add_u32 m0, s38, 20480
	v_mov_b32_e32 v10, 0
	v_mov_b32_e32 v11, 0
	global_load_lds_dwordx4 v165, s[100:101]
	s_add_u32 m0, s38, 24576
	v_mov_b32_e32 v12, 0
	v_mov_b32_e32 v13, 0
	global_load_lds_dwordx4 v166, s[100:101]
	s_add_u32 m0, s38, 28672
	v_mov_b32_e32 v14, 0
	v_mov_b32_e32 v15, 0
	global_load_lds_dwordx4 v167, s[100:101]
	s_add_u32 s100, s100, 128
	s_addc_u32 s101, s101, 0
	s_add_u32 m0, s38, 32768
	v_mov_b32_e32 v16, 0
	v_mov_b32_e32 v17, 0
	global_load_lds_dwordx4 v164, s[98:99]
	s_add_u32 m0, s38, 36864
	v_mov_b32_e32 v18, 0
	v_mov_b32_e32 v19, 0
	global_load_lds_dwordx4 v165, s[98:99]
	s_add_u32 m0, s38, 40960
	v_mov_b32_e32 v20, 0
	v_mov_b32_e32 v21, 0
	global_load_lds_dwordx4 v166, s[98:99]
	s_add_u32 m0, s38, 45056
	v_mov_b32_e32 v22, 0
	v_mov_b32_e32 v23, 0
	global_load_lds_dwordx4 v167, s[98:99]
	s_add_u32 s98, s98, 128
	s_addc_u32 s99, s99, 0
	s_add_u32 m0, s38, 49152
	v_mov_b32_e32 v24, 0
	v_mov_b32_e32 v25, 0
	global_load_lds_dwordx4 v164, s[100:101]
	s_add_u32 m0, s38, 53248
	v_mov_b32_e32 v26, 0
	v_mov_b32_e32 v27, 0
	global_load_lds_dwordx4 v165, s[100:101]
	s_add_u32 m0, s38, 57344
	v_mov_b32_e32 v28, 0
	v_mov_b32_e32 v29, 0
	global_load_lds_dwordx4 v166, s[100:101]
	s_add_u32 m0, s38, 61440
	v_mov_b32_e32 v30, 0
	v_mov_b32_e32 v31, 0
	global_load_lds_dwordx4 v167, s[100:101]
	s_add_u32 s100, s100, 128
	s_addc_u32 s101, s101, 0
	v_mov_b32_e32 v32, 0
	v_mov_b32_e32 v33, 0
	v_mov_b32_e32 v34, 0
	v_mov_b32_e32 v35, 0
	v_mov_b32_e32 v36, 0
	v_mov_b32_e32 v37, 0
	v_mov_b32_e32 v38, 0
	v_mov_b32_e32 v39, 0
	v_mov_b32_e32 v40, 0
	v_mov_b32_e32 v41, 0
	v_mov_b32_e32 v42, 0
	v_mov_b32_e32 v43, 0
	v_mov_b32_e32 v44, 0
	v_mov_b32_e32 v45, 0
	v_mov_b32_e32 v46, 0
	v_mov_b32_e32 v47, 0
	v_mov_b32_e32 v48, 0
	v_mov_b32_e32 v49, 0
	v_mov_b32_e32 v50, 0
	v_mov_b32_e32 v51, 0
	v_mov_b32_e32 v52, 0
	v_mov_b32_e32 v53, 0
	v_mov_b32_e32 v54, 0
	v_mov_b32_e32 v55, 0
	v_mov_b32_e32 v56, 0
	v_mov_b32_e32 v57, 0
	v_mov_b32_e32 v58, 0
	v_mov_b32_e32 v59, 0
	v_mov_b32_e32 v60, 0
	v_mov_b32_e32 v61, 0
	v_mov_b32_e32 v62, 0
	v_mov_b32_e32 v63, 0
	s_waitcnt vmcnt(8)
	s_barrier
	ds_read_b128 v[64:67], v150 offset:0
	ds_read_b128 v[96:99], v162 offset:16384
	ds_read_b128 v[100:103], v162 offset:18432
	ds_read_b128 v[104:107], v162 offset:20480
	ds_read_b128 v[108:111], v162 offset:22528
	ds_read_b128 v[68:71], v150 offset:2048
	ds_read_b128 v[72:75], v150 offset:4096
	ds_read_b128 v[76:79], v150 offset:6144
	v_add_f32_e32 v142, 0, v172
	v_add_f32_e32 v143, 0, v173
	v_add_f32_e32 v144, 0, v174
	v_add_f32_e32 v145, 0, v175
	s_waitcnt lgkmcnt(6)
	v_mfma_f32_16x16x32_bf16 v[0:3], v[64:67], v[96:99], v[0:3]
	ds_read_b128 v[80:83], v151 offset:0
	v_add_f32_e32 v146, 0, v176
	v_add_f32_e32 v147, 0, v177
	v_add_f32_e32 v160, 0, v178
	v_add_f32_e32 v161, 0, v179
	s_waitcnt lgkmcnt(6)
	v_mfma_f32_16x16x32_bf16 v[4:7], v[64:67], v[100:103], v[4:7]
	ds_read_b128 v[112:115], v163 offset:16384
	v_add_f32_e32 v142, v142, v180
	v_add_f32_e32 v143, v143, v181
	v_add_f32_e32 v144, v144, v182
	v_add_f32_e32 v145, v145, v183
	s_waitcnt lgkmcnt(6)
	v_mfma_f32_16x16x32_bf16 v[8:11], v[64:67], v[104:107], v[8:11]
	ds_read_b128 v[116:119], v163 offset:18432
	v_add_f32_e32 v146, v146, v184
	v_add_f32_e32 v147, v147, v185
	v_add_f32_e32 v160, v160, v186
	v_add_f32_e32 v161, v161, v187
	s_waitcnt lgkmcnt(6)
	v_mfma_f32_16x16x32_bf16 v[12:15], v[64:67], v[108:111], v[12:15]
	ds_read_b128 v[120:123], v163 offset:20480
	v_add_f32_e32 v142, v142, v188
	v_add_f32_e32 v143, v143, v189
	v_add_f32_e32 v144, v144, v190
	v_add_f32_e32 v145, v145, v191
	s_waitcnt lgkmcnt(6)
	v_mfma_f32_16x16x32_bf16 v[16:19], v[68:71], v[96:99], v[16:19]
	ds_read_b128 v[124:127], v163 offset:22528
	v_add_f32_e32 v146, v146, v192
	v_add_f32_e32 v147, v147, v193
	v_add_f32_e32 v160, v160, v194
	v_add_f32_e32 v161, v161, v195
	s_waitcnt lgkmcnt(7)
	v_mfma_f32_16x16x32_bf16 v[20:23], v[68:71], v[100:103], v[20:23]
	ds_read_b128 v[84:87], v151 offset:2048
	v_add_f32_e32 v142, v142, v196
	v_add_f32_e32 v143, v143, v197
	v_add_f32_e32 v144, v144, v198
	v_add_f32_e32 v145, v145, v199
	s_waitcnt lgkmcnt(8)
	v_mfma_f32_16x16x32_bf16 v[24:27], v[68:71], v[104:107], v[24:27]
	ds_read_b128 v[88:91], v151 offset:4096
	v_add_f32_e32 v146, v146, v200
	v_add_f32_e32 v147, v147, v201
	v_add_f32_e32 v160, v160, v202
	v_add_f32_e32 v161, v161, v203
	s_waitcnt lgkmcnt(9)
	v_mfma_f32_16x16x32_bf16 v[28:31], v[68:71], v[108:111], v[28:31]
	ds_read_b128 v[92:95], v151 offset:6144
	v_add_f32_e32 v142, v142, v204
	v_add_f32_e32 v143, v143, v205
	v_add_f32_e32 v144, v144, v206
	v_add_f32_e32 v145, v145, v207
	s_waitcnt lgkmcnt(9)
	v_mfma_f32_16x16x32_bf16 v[32:35], v[72:75], v[96:99], v[32:35]
	v_add_f32_e32 v146, v146, v208
	v_add_f32_e32 v147, v147, v209
	v_add_f32_e32 v160, v160, v210
	v_add_f32_e32 v161, v161, v211
	s_waitcnt lgkmcnt(9)
	v_mfma_f32_16x16x32_bf16 v[36:39], v[72:75], v[100:103], v[36:39]
	v_add_f32_e32 v142, v142, v212
	v_add_f32_e32 v143, v143, v213
	v_add_f32_e32 v144, v144, v214
	v_add_f32_e32 v145, v145, v215
	s_waitcnt lgkmcnt(9)
	v_mfma_f32_16x16x32_bf16 v[40:43], v[72:75], v[104:107], v[40:43]
	v_add_f32_e32 v146, v146, v216
	v_add_f32_e32 v147, v147, v217
	v_add_f32_e32 v160, v160, v218
	v_add_f32_e32 v161, v161, v219
	s_waitcnt lgkmcnt(9)
	v_mfma_f32_16x16x32_bf16 v[44:47], v[72:75], v[108:111], v[44:47]
	s_waitcnt vmcnt(0) lgkmcnt(0)
	s_barrier
	s_add_u32 m0, s38, 0
	s_nop 0
	global_load_lds_dwordx4 v164, s[98:99]
	v_add_f32_e32 v142, v142, v230
	v_add_f32_e32 v143, v143, v231
	v_add_f32_e32 v144, v144, v232
	v_add_f32_e32 v145, v145, v233
	s_waitcnt lgkmcnt(8)
	v_mfma_f32_16x16x32_bf16 v[48:51], v[76:79], v[96:99], v[48:51]
	s_add_u32 m0, s38, 4096
	s_nop 0
	global_load_lds_dwordx4 v165, s[98:99]
	v_add_f32_e32 v146, v146, v234
	v_add_f32_e32 v147, v147, v235
	v_add_f32_e32 v160, v160, v236
	v_add_f32_e32 v161, v161, v237
	s_waitcnt lgkmcnt(8)
	v_mfma_f32_16x16x32_bf16 v[52:55], v[76:79], v[100:103], v[52:55]
	s_add_u32 m0, s38, 8192
	s_nop 0
	global_load_lds_dwordx4 v166, s[98:99]
	v_add_f32_e32 v142, v142, v238
	v_add_f32_e32 v143, v143, v239
	v_add_f32_e32 v144, v144, v240
	v_add_f32_e32 v145, v145, v241
	s_waitcnt lgkmcnt(8)
	v_mfma_f32_16x16x32_bf16 v[56:59], v[76:79], v[104:107], v[56:59]
	s_add_u32 m0, s38, 12288
	s_nop 0
	global_load_lds_dwordx4 v167, s[98:99]
	s_add_u32 s98, s98, 128
	s_addc_u32 s99, s99, 0
	v_add_f32_e32 v146, v146, v242
	v_add_f32_e32 v147, v147, v243
	v_add_f32_e32 v160, v160, v244
	v_add_f32_e32 v161, v161, v245
	s_waitcnt lgkmcnt(8)
	v_mfma_f32_16x16x32_bf16 v[60:63], v[76:79], v[108:111], v[60:63]
	s_add_u32 m0, s38, 16384
	s_nop 0
	global_load_lds_dwordx4 v164, s[100:101]
	s_waitcnt lgkmcnt(6)
	v_mfma_f32_16x16x32_bf16 v[0:3], v[80:83], v[112:115], v[0:3]
	ds_read_b128 v[64:67], v150 offset:32768
	s_add_u32 m0, s38, 20480
	s_nop 0
	global_load_lds_dwordx4 v165, s[100:101]
	s_waitcnt lgkmcnt(6)
	v_mfma_f32_16x16x32_bf16 v[4:7], v[80:83], v[116:119], v[4:7]
	ds_read_b128 v[96:99], v162 offset:49152
	s_add_u32 m0, s38, 24576
	s_nop 0
	global_load_lds_dwordx4 v166, s[100:101]
	s_waitcnt lgkmcnt(6)
	v_mfma_f32_16x16x32_bf16 v[8:11], v[80:83], v[120:123], v[8:11]
	ds_read_b128 v[100:103], v162 offset:51200
	s_add_u32 m0, s38, 28672
	s_nop 0
	global_load_lds_dwordx4 v167, s[100:101]
	s_add_u32 s100, s100, 128
	s_addc_u32 s101, s101, 0
	s_waitcnt lgkmcnt(6)
	v_mfma_f32_16x16x32_bf16 v[12:15], v[80:83], v[124:127], v[12:15]
	ds_read_b128 v[104:107], v162 offset:53248
	s_waitcnt lgkmcnt(6)
	v_mfma_f32_16x16x32_bf16 v[16:19], v[84:87], v[112:115], v[16:19]
	ds_read_b128 v[108:111], v162 offset:55296
	s_waitcnt lgkmcnt(7)
	v_mfma_f32_16x16x32_bf16 v[20:23], v[84:87], v[116:119], v[20:23]
	ds_read_b128 v[68:71], v150 offset:34816
	s_waitcnt lgkmcnt(8)
	v_mfma_f32_16x16x32_bf16 v[24:27], v[84:87], v[120:123], v[24:27]
	ds_read_b128 v[72:75], v150 offset:36864
	s_waitcnt lgkmcnt(9)
	v_mfma_f32_16x16x32_bf16 v[28:31], v[84:87], v[124:127], v[28:31]
	ds_read_b128 v[76:79], v150 offset:38912
	s_waitcnt lgkmcnt(9)
	v_mfma_f32_16x16x32_bf16 v[32:35], v[88:91], v[112:115], v[32:35]
	s_waitcnt lgkmcnt(9)
	v_mfma_f32_16x16x32_bf16 v[36:39], v[88:91], v[116:119], v[36:39]
	s_waitcnt lgkmcnt(9)
	v_mfma_f32_16x16x32_bf16 v[40:43], v[88:91], v[120:123], v[40:43]
	s_waitcnt lgkmcnt(9)
	v_mfma_f32_16x16x32_bf16 v[44:47], v[88:91], v[124:127], v[44:47]
	s_waitcnt lgkmcnt(8)
	v_mfma_f32_16x16x32_bf16 v[48:51], v[92:95], v[112:115], v[48:51]
	s_waitcnt lgkmcnt(8)
	v_mfma_f32_16x16x32_bf16 v[52:55], v[92:95], v[116:119], v[52:55]
	s_waitcnt lgkmcnt(8)
	v_mfma_f32_16x16x32_bf16 v[56:59], v[92:95], v[120:123], v[56:59]
	s_waitcnt lgkmcnt(8)
	v_mfma_f32_16x16x32_bf16 v[60:63], v[92:95], v[124:127], v[60:63]
	s_waitcnt lgkmcnt(6)
	v_mfma_f32_16x16x32_bf16 v[0:3], v[64:67], v[96:99], v[0:3]
	ds_read_b128 v[80:83], v151 offset:32768
	s_waitcnt lgkmcnt(6)
	v_mfma_f32_16x16x32_bf16 v[4:7], v[64:67], v[100:103], v[4:7]
	ds_read_b128 v[112:115], v163 offset:49152
	s_waitcnt lgkmcnt(6)
	v_mfma_f32_16x16x32_bf16 v[8:11], v[64:67], v[104:107], v[8:11]
	ds_read_b128 v[116:119], v163 offset:51200
	s_waitcnt lgkmcnt(6)
	v_mfma_f32_16x16x32_bf16 v[12:15], v[64:67], v[108:111], v[12:15]
	ds_read_b128 v[120:123], v163 offset:53248
	s_waitcnt lgkmcnt(6)
	v_mfma_f32_16x16x32_bf16 v[16:19], v[68:71], v[96:99], v[16:19]
	ds_read_b128 v[124:127], v163 offset:55296
	s_waitcnt lgkmcnt(7)
	v_mfma_f32_16x16x32_bf16 v[20:23], v[68:71], v[100:103], v[20:23]
	ds_read_b128 v[84:87], v151 offset:34816
	s_waitcnt lgkmcnt(8)
	v_mfma_f32_16x16x32_bf16 v[24:27], v[68:71], v[104:107], v[24:27]
	ds_read_b128 v[88:91], v151 offset:36864
	s_waitcnt lgkmcnt(9)
	v_mfma_f32_16x16x32_bf16 v[28:31], v[68:71], v[108:111], v[28:31]
	ds_read_b128 v[92:95], v151 offset:38912
	s_waitcnt lgkmcnt(9)
	v_mfma_f32_16x16x32_bf16 v[32:35], v[72:75], v[96:99], v[32:35]
	s_waitcnt lgkmcnt(9)
	v_mfma_f32_16x16x32_bf16 v[36:39], v[72:75], v[100:103], v[36:39]
	s_waitcnt lgkmcnt(9)
	v_mfma_f32_16x16x32_bf16 v[40:43], v[72:75], v[104:107], v[40:43]
	s_waitcnt lgkmcnt(9)
	v_mfma_f32_16x16x32_bf16 v[44:47], v[72:75], v[108:111], v[44:47]
	s_waitcnt vmcnt(0) lgkmcnt(0)
	s_barrier
	s_add_u32 m0, s38, 32768
	s_nop 0
	global_load_lds_dwordx4 v164, s[98:99]
	s_waitcnt lgkmcnt(8)
	v_mfma_f32_16x16x32_bf16 v[48:51], v[76:79], v[96:99], v[48:51]
	s_add_u32 m0, s38, 36864
	s_nop 0
	global_load_lds_dwordx4 v165, s[98:99]
	s_waitcnt lgkmcnt(8)
	v_mfma_f32_16x16x32_bf16 v[52:55], v[76:79], v[100:103], v[52:55]
	s_add_u32 m0, s38, 40960
	s_nop 0
	global_load_lds_dwordx4 v166, s[98:99]
	s_waitcnt lgkmcnt(8)
	v_mfma_f32_16x16x32_bf16 v[56:59], v[76:79], v[104:107], v[56:59]
	s_add_u32 m0, s38, 45056
	s_nop 0
	global_load_lds_dwordx4 v167, s[98:99]
	s_add_u32 s98, s98, 128
	s_addc_u32 s99, s99, 0
	s_waitcnt lgkmcnt(8)
	v_mfma_f32_16x16x32_bf16 v[60:63], v[76:79], v[108:111], v[60:63]
	s_add_u32 m0, s38, 49152
	s_nop 0
	global_load_lds_dwordx4 v164, s[100:101]
	s_waitcnt lgkmcnt(6)
	v_mfma_f32_16x16x32_bf16 v[0:3], v[80:83], v[112:115], v[0:3]
	ds_read_b128 v[64:67], v150 offset:0
	s_add_u32 m0, s38, 53248
	s_nop 0
	global_load_lds_dwordx4 v165, s[100:101]
	s_waitcnt lgkmcnt(6)
	v_mfma_f32_16x16x32_bf16 v[4:7], v[80:83], v[116:119], v[4:7]
	ds_read_b128 v[96:99], v162 offset:16384
	s_add_u32 m0, s38, 57344
	s_nop 0
	global_load_lds_dwordx4 v166, s[100:101]
	s_waitcnt lgkmcnt(6)
	v_mfma_f32_16x16x32_bf16 v[8:11], v[80:83], v[120:123], v[8:11]
	ds_read_b128 v[100:103], v162 offset:18432
	s_add_u32 m0, s38, 61440
	s_nop 0
	global_load_lds_dwordx4 v167, s[100:101]
	s_add_u32 s100, s100, 128
	s_addc_u32 s101, s101, 0
	s_waitcnt lgkmcnt(6)
	v_mfma_f32_16x16x32_bf16 v[12:15], v[80:83], v[124:127], v[12:15]
	ds_read_b128 v[104:107], v162 offset:20480
	s_waitcnt lgkmcnt(6)
	v_mfma_f32_16x16x32_bf16 v[16:19], v[84:87], v[112:115], v[16:19]
	ds_read_b128 v[108:111], v162 offset:22528
	s_waitcnt lgkmcnt(7)
	v_mfma_f32_16x16x32_bf16 v[20:23], v[84:87], v[116:119], v[20:23]
	ds_read_b128 v[68:71], v150 offset:2048
	s_waitcnt lgkmcnt(8)
	v_mfma_f32_16x16x32_bf16 v[24:27], v[84:87], v[120:123], v[24:27]
	ds_read_b128 v[72:75], v150 offset:4096
	s_waitcnt lgkmcnt(9)
	v_mfma_f32_16x16x32_bf16 v[28:31], v[84:87], v[124:127], v[28:31]
	ds_read_b128 v[76:79], v150 offset:6144
	s_waitcnt lgkmcnt(9)
	v_mfma_f32_16x16x32_bf16 v[32:35], v[88:91], v[112:115], v[32:35]
	s_waitcnt lgkmcnt(9)
	v_mfma_f32_16x16x32_bf16 v[36:39], v[88:91], v[116:119], v[36:39]
	s_waitcnt lgkmcnt(9)
	v_mfma_f32_16x16x32_bf16 v[40:43], v[88:91], v[120:123], v[40:43]
	s_waitcnt lgkmcnt(9)
	v_mfma_f32_16x16x32_bf16 v[44:47], v[88:91], v[124:127], v[44:47]
	s_waitcnt lgkmcnt(8)
	v_mfma_f32_16x16x32_bf16 v[48:51], v[92:95], v[112:115], v[48:51]
	s_waitcnt lgkmcnt(8)
	v_mfma_f32_16x16x32_bf16 v[52:55], v[92:95], v[116:119], v[52:55]
	s_waitcnt lgkmcnt(8)
	v_mfma_f32_16x16x32_bf16 v[56:59], v[92:95], v[120:123], v[56:59]
	s_waitcnt lgkmcnt(8)
	v_mfma_f32_16x16x32_bf16 v[60:63], v[92:95], v[124:127], v[60:63]
	s_waitcnt lgkmcnt(6)
	v_mfma_f32_16x16x32_bf16 v[0:3], v[64:67], v[96:99], v[0:3]
	ds_read_b128 v[80:83], v151 offset:0
	s_waitcnt lgkmcnt(6)
	v_mfma_f32_16x16x32_bf16 v[4:7], v[64:67], v[100:103], v[4:7]
	ds_read_b128 v[112:115], v163 offset:16384
	s_waitcnt lgkmcnt(6)
	v_mfma_f32_16x16x32_bf16 v[8:11], v[64:67], v[104:107], v[8:11]
	ds_read_b128 v[116:119], v163 offset:18432
	s_waitcnt lgkmcnt(6)
	v_mfma_f32_16x16x32_bf16 v[12:15], v[64:67], v[108:111], v[12:15]
	ds_read_b128 v[120:123], v163 offset:20480
	s_waitcnt lgkmcnt(6)
	v_mfma_f32_16x16x32_bf16 v[16:19], v[68:71], v[96:99], v[16:19]
	ds_read_b128 v[124:127], v163 offset:22528
	s_waitcnt lgkmcnt(7)
	v_mfma_f32_16x16x32_bf16 v[20:23], v[68:71], v[100:103], v[20:23]
	ds_read_b128 v[84:87], v151 offset:2048
	s_waitcnt lgkmcnt(8)
	v_mfma_f32_16x16x32_bf16 v[24:27], v[68:71], v[104:107], v[24:27]
	ds_read_b128 v[88:91], v151 offset:4096
	s_waitcnt lgkmcnt(9)
	v_mfma_f32_16x16x32_bf16 v[28:31], v[68:71], v[108:111], v[28:31]
	ds_read_b128 v[92:95], v151 offset:6144
	s_waitcnt lgkmcnt(9)
	v_mfma_f32_16x16x32_bf16 v[32:35], v[72:75], v[96:99], v[32:35]
	s_waitcnt lgkmcnt(9)
	v_mfma_f32_16x16x32_bf16 v[36:39], v[72:75], v[100:103], v[36:39]
	s_waitcnt lgkmcnt(9)
	v_mfma_f32_16x16x32_bf16 v[40:43], v[72:75], v[104:107], v[40:43]
	s_waitcnt lgkmcnt(9)
	v_mfma_f32_16x16x32_bf16 v[44:47], v[72:75], v[108:111], v[44:47]
	s_waitcnt vmcnt(0) lgkmcnt(0)
	s_barrier
	s_add_u32 m0, s38, 0
	s_nop 0
	global_load_lds_dwordx4 v164, s[98:99]
	s_waitcnt lgkmcnt(8)
	v_mfma_f32_16x16x32_bf16 v[48:51], v[76:79], v[96:99], v[48:51]
	s_add_u32 m0, s38, 4096
	s_nop 0
	global_load_lds_dwordx4 v165, s[98:99]
	s_waitcnt lgkmcnt(8)
	v_mfma_f32_16x16x32_bf16 v[52:55], v[76:79], v[100:103], v[52:55]
	s_add_u32 m0, s38, 8192
	s_nop 0
	global_load_lds_dwordx4 v166, s[98:99]
	s_waitcnt lgkmcnt(8)
	v_mfma_f32_16x16x32_bf16 v[56:59], v[76:79], v[104:107], v[56:59]
	s_add_u32 m0, s38, 12288
	s_nop 0
	global_load_lds_dwordx4 v167, s[98:99]
	s_add_u32 s98, s98, 128
	s_addc_u32 s99, s99, 0
	s_waitcnt lgkmcnt(8)
	v_mfma_f32_16x16x32_bf16 v[60:63], v[76:79], v[108:111], v[60:63]
	s_add_u32 m0, s38, 16384
	s_nop 0
	global_load_lds_dwordx4 v164, s[100:101]
	s_waitcnt lgkmcnt(6)
	v_mfma_f32_16x16x32_bf16 v[0:3], v[80:83], v[112:115], v[0:3]
	ds_read_b128 v[64:67], v150 offset:32768
	s_add_u32 m0, s38, 20480
	s_nop 0
	global_load_lds_dwordx4 v165, s[100:101]
	s_waitcnt lgkmcnt(6)
	v_mfma_f32_16x16x32_bf16 v[4:7], v[80:83], v[116:119], v[4:7]
	ds_read_b128 v[96:99], v162 offset:49152
	s_add_u32 m0, s38, 24576
	s_nop 0
	global_load_lds_dwordx4 v166, s[100:101]
	s_waitcnt lgkmcnt(6)
	v_mfma_f32_16x16x32_bf16 v[8:11], v[80:83], v[120:123], v[8:11]
	ds_read_b128 v[100:103], v162 offset:51200
	s_add_u32 m0, s38, 28672
	s_nop 0
	global_load_lds_dwordx4 v167, s[100:101]
	s_add_u32 s100, s100, 128
	s_addc_u32 s101, s101, 0
	s_waitcnt lgkmcnt(6)
	v_mfma_f32_16x16x32_bf16 v[12:15], v[80:83], v[124:127], v[12:15]
	ds_read_b128 v[104:107], v162 offset:53248
	s_waitcnt lgkmcnt(6)
	v_mfma_f32_16x16x32_bf16 v[16:19], v[84:87], v[112:115], v[16:19]
	ds_read_b128 v[108:111], v162 offset:55296
	s_waitcnt lgkmcnt(7)
	v_mfma_f32_16x16x32_bf16 v[20:23], v[84:87], v[116:119], v[20:23]
	ds_read_b128 v[68:71], v150 offset:34816
	s_waitcnt lgkmcnt(8)
	v_mfma_f32_16x16x32_bf16 v[24:27], v[84:87], v[120:123], v[24:27]
	ds_read_b128 v[72:75], v150 offset:36864
	s_waitcnt lgkmcnt(9)
	v_mfma_f32_16x16x32_bf16 v[28:31], v[84:87], v[124:127], v[28:31]
	ds_read_b128 v[76:79], v150 offset:38912
	s_waitcnt lgkmcnt(9)
	v_mfma_f32_16x16x32_bf16 v[32:35], v[88:91], v[112:115], v[32:35]
	s_waitcnt lgkmcnt(9)
	v_mfma_f32_16x16x32_bf16 v[36:39], v[88:91], v[116:119], v[36:39]
	s_waitcnt lgkmcnt(9)
	v_mfma_f32_16x16x32_bf16 v[40:43], v[88:91], v[120:123], v[40:43]
	s_waitcnt lgkmcnt(9)
	v_mfma_f32_16x16x32_bf16 v[44:47], v[88:91], v[124:127], v[44:47]
	s_waitcnt lgkmcnt(8)
	v_mfma_f32_16x16x32_bf16 v[48:51], v[92:95], v[112:115], v[48:51]
	s_waitcnt lgkmcnt(8)
	v_mfma_f32_16x16x32_bf16 v[52:55], v[92:95], v[116:119], v[52:55]
	s_waitcnt lgkmcnt(8)
	v_mfma_f32_16x16x32_bf16 v[56:59], v[92:95], v[120:123], v[56:59]
	s_waitcnt lgkmcnt(8)
	v_mfma_f32_16x16x32_bf16 v[60:63], v[92:95], v[124:127], v[60:63]
	s_waitcnt lgkmcnt(6)
	v_mfma_f32_16x16x32_bf16 v[0:3], v[64:67], v[96:99], v[0:3]
	ds_read_b128 v[80:83], v151 offset:32768
	s_waitcnt lgkmcnt(6)
	v_mfma_f32_16x16x32_bf16 v[4:7], v[64:67], v[100:103], v[4:7]
	ds_read_b128 v[112:115], v163 offset:49152
	s_waitcnt lgkmcnt(6)
	v_mfma_f32_16x16x32_bf16 v[8:11], v[64:67], v[104:107], v[8:11]
	ds_read_b128 v[116:119], v163 offset:51200
	s_waitcnt lgkmcnt(6)
	v_mfma_f32_16x16x32_bf16 v[12:15], v[64:67], v[108:111], v[12:15]
	ds_read_b128 v[120:123], v163 offset:53248
	s_waitcnt lgkmcnt(6)
	v_mfma_f32_16x16x32_bf16 v[16:19], v[68:71], v[96:99], v[16:19]
	ds_read_b128 v[124:127], v163 offset:55296
	s_waitcnt lgkmcnt(7)
	v_mfma_f32_16x16x32_bf16 v[20:23], v[68:71], v[100:103], v[20:23]
	ds_read_b128 v[84:87], v151 offset:34816
	s_waitcnt lgkmcnt(8)
	v_mfma_f32_16x16x32_bf16 v[24:27], v[68:71], v[104:107], v[24:27]
	ds_read_b128 v[88:91], v151 offset:36864
	s_waitcnt lgkmcnt(9)
	v_mfma_f32_16x16x32_bf16 v[28:31], v[68:71], v[108:111], v[28:31]
	ds_read_b128 v[92:95], v151 offset:38912
	s_waitcnt lgkmcnt(9)
	v_mfma_f32_16x16x32_bf16 v[32:35], v[72:75], v[96:99], v[32:35]
	s_waitcnt lgkmcnt(9)
	v_mfma_f32_16x16x32_bf16 v[36:39], v[72:75], v[100:103], v[36:39]
	s_waitcnt lgkmcnt(9)
	v_mfma_f32_16x16x32_bf16 v[40:43], v[72:75], v[104:107], v[40:43]
	s_waitcnt lgkmcnt(9)
	v_mfma_f32_16x16x32_bf16 v[44:47], v[72:75], v[108:111], v[44:47]
	s_waitcnt vmcnt(0) lgkmcnt(0)
	s_barrier
	s_add_u32 m0, s38, 32768
	s_nop 0
	global_load_lds_dwordx4 v164, s[98:99]
	s_waitcnt lgkmcnt(8)
	v_mfma_f32_16x16x32_bf16 v[48:51], v[76:79], v[96:99], v[48:51]
	s_add_u32 m0, s38, 36864
	s_nop 0
	global_load_lds_dwordx4 v165, s[98:99]
	s_waitcnt lgkmcnt(8)
	v_mfma_f32_16x16x32_bf16 v[52:55], v[76:79], v[100:103], v[52:55]
	s_add_u32 m0, s38, 40960
	s_nop 0
	global_load_lds_dwordx4 v166, s[98:99]
	s_waitcnt lgkmcnt(8)
	v_mfma_f32_16x16x32_bf16 v[56:59], v[76:79], v[104:107], v[56:59]
	s_add_u32 m0, s38, 45056
	s_nop 0
	global_load_lds_dwordx4 v167, s[98:99]
	s_add_u32 s98, s98, 128
	s_addc_u32 s99, s99, 0
	s_waitcnt lgkmcnt(8)
	v_mfma_f32_16x16x32_bf16 v[60:63], v[76:79], v[108:111], v[60:63]
	s_add_u32 m0, s38, 49152
	s_nop 0
	global_load_lds_dwordx4 v164, s[100:101]
	s_waitcnt lgkmcnt(6)
	v_mfma_f32_16x16x32_bf16 v[0:3], v[80:83], v[112:115], v[0:3]
	ds_read_b128 v[64:67], v150 offset:0
	s_add_u32 m0, s38, 53248
	s_nop 0
	global_load_lds_dwordx4 v165, s[100:101]
	s_waitcnt lgkmcnt(6)
	v_mfma_f32_16x16x32_bf16 v[4:7], v[80:83], v[116:119], v[4:7]
	ds_read_b128 v[96:99], v162 offset:16384
	s_add_u32 m0, s38, 57344
	s_nop 0
	global_load_lds_dwordx4 v166, s[100:101]
	s_waitcnt lgkmcnt(6)
	v_mfma_f32_16x16x32_bf16 v[8:11], v[80:83], v[120:123], v[8:11]
	ds_read_b128 v[100:103], v162 offset:18432
	s_add_u32 m0, s38, 61440
	s_nop 0
	global_load_lds_dwordx4 v167, s[100:101]
	s_add_u32 s100, s100, 128
	s_addc_u32 s101, s101, 0
	s_waitcnt lgkmcnt(6)
	v_mfma_f32_16x16x32_bf16 v[12:15], v[80:83], v[124:127], v[12:15]
	ds_read_b128 v[104:107], v162 offset:20480
	s_waitcnt lgkmcnt(6)
	v_mfma_f32_16x16x32_bf16 v[16:19], v[84:87], v[112:115], v[16:19]
	ds_read_b128 v[108:111], v162 offset:22528
	s_waitcnt lgkmcnt(7)
	v_mfma_f32_16x16x32_bf16 v[20:23], v[84:87], v[116:119], v[20:23]
	ds_read_b128 v[68:71], v150 offset:2048
	s_waitcnt lgkmcnt(8)
	v_mfma_f32_16x16x32_bf16 v[24:27], v[84:87], v[120:123], v[24:27]
	ds_read_b128 v[72:75], v150 offset:4096
	s_waitcnt lgkmcnt(9)
	v_mfma_f32_16x16x32_bf16 v[28:31], v[84:87], v[124:127], v[28:31]
	ds_read_b128 v[76:79], v150 offset:6144
	s_waitcnt lgkmcnt(9)
	v_mfma_f32_16x16x32_bf16 v[32:35], v[88:91], v[112:115], v[32:35]
	s_waitcnt lgkmcnt(9)
	v_mfma_f32_16x16x32_bf16 v[36:39], v[88:91], v[116:119], v[36:39]
	s_waitcnt lgkmcnt(9)
	v_mfma_f32_16x16x32_bf16 v[40:43], v[88:91], v[120:123], v[40:43]
	s_waitcnt lgkmcnt(9)
	v_mfma_f32_16x16x32_bf16 v[44:47], v[88:91], v[124:127], v[44:47]
	s_waitcnt lgkmcnt(8)
	v_mfma_f32_16x16x32_bf16 v[48:51], v[92:95], v[112:115], v[48:51]
	s_waitcnt lgkmcnt(8)
	v_mfma_f32_16x16x32_bf16 v[52:55], v[92:95], v[116:119], v[52:55]
	s_waitcnt lgkmcnt(8)
	v_mfma_f32_16x16x32_bf16 v[56:59], v[92:95], v[120:123], v[56:59]
	s_waitcnt lgkmcnt(8)
	v_mfma_f32_16x16x32_bf16 v[60:63], v[92:95], v[124:127], v[60:63]
	s_waitcnt lgkmcnt(6)
	v_mfma_f32_16x16x32_bf16 v[0:3], v[64:67], v[96:99], v[0:3]
	ds_read_b128 v[80:83], v151 offset:0
	s_waitcnt lgkmcnt(6)
	v_mfma_f32_16x16x32_bf16 v[4:7], v[64:67], v[100:103], v[4:7]
	ds_read_b128 v[112:115], v163 offset:16384
	s_waitcnt lgkmcnt(6)
	v_mfma_f32_16x16x32_bf16 v[8:11], v[64:67], v[104:107], v[8:11]
	ds_read_b128 v[116:119], v163 offset:18432
	s_waitcnt lgkmcnt(6)
	v_mfma_f32_16x16x32_bf16 v[12:15], v[64:67], v[108:111], v[12:15]
	ds_read_b128 v[120:123], v163 offset:20480
	s_waitcnt lgkmcnt(6)
	v_mfma_f32_16x16x32_bf16 v[16:19], v[68:71], v[96:99], v[16:19]
	ds_read_b128 v[124:127], v163 offset:22528
	s_waitcnt lgkmcnt(7)
	v_mfma_f32_16x16x32_bf16 v[20:23], v[68:71], v[100:103], v[20:23]
	ds_read_b128 v[84:87], v151 offset:2048
	s_waitcnt lgkmcnt(8)
	v_mfma_f32_16x16x32_bf16 v[24:27], v[68:71], v[104:107], v[24:27]
	ds_read_b128 v[88:91], v151 offset:4096
	s_waitcnt lgkmcnt(9)
	v_mfma_f32_16x16x32_bf16 v[28:31], v[68:71], v[108:111], v[28:31]
	ds_read_b128 v[92:95], v151 offset:6144
	s_waitcnt lgkmcnt(9)
	v_mfma_f32_16x16x32_bf16 v[32:35], v[72:75], v[96:99], v[32:35]
	s_waitcnt lgkmcnt(9)
	v_mfma_f32_16x16x32_bf16 v[36:39], v[72:75], v[100:103], v[36:39]
	s_waitcnt lgkmcnt(9)
	v_mfma_f32_16x16x32_bf16 v[40:43], v[72:75], v[104:107], v[40:43]
	s_waitcnt lgkmcnt(9)
	v_mfma_f32_16x16x32_bf16 v[44:47], v[72:75], v[108:111], v[44:47]
	s_waitcnt vmcnt(0) lgkmcnt(0)
	s_barrier
	s_add_u32 m0, s38, 0
	s_nop 0
	global_load_lds_dwordx4 v164, s[98:99]
	s_waitcnt lgkmcnt(8)
	v_mfma_f32_16x16x32_bf16 v[48:51], v[76:79], v[96:99], v[48:51]
	s_add_u32 m0, s38, 4096
	s_nop 0
	global_load_lds_dwordx4 v165, s[98:99]
	s_waitcnt lgkmcnt(8)
	v_mfma_f32_16x16x32_bf16 v[52:55], v[76:79], v[100:103], v[52:55]
	s_add_u32 m0, s38, 8192
	s_nop 0
	global_load_lds_dwordx4 v166, s[98:99]
	s_waitcnt lgkmcnt(8)
	v_mfma_f32_16x16x32_bf16 v[56:59], v[76:79], v[104:107], v[56:59]
	s_add_u32 m0, s38, 12288
	s_nop 0
	global_load_lds_dwordx4 v167, s[98:99]
	s_add_u32 s98, s98, 128
	s_addc_u32 s99, s99, 0
	s_waitcnt lgkmcnt(8)
	v_mfma_f32_16x16x32_bf16 v[60:63], v[76:79], v[108:111], v[60:63]
	s_add_u32 m0, s38, 16384
	s_nop 0
	global_load_lds_dwordx4 v164, s[100:101]
	s_waitcnt lgkmcnt(6)
	v_mfma_f32_16x16x32_bf16 v[0:3], v[80:83], v[112:115], v[0:3]
	ds_read_b128 v[64:67], v150 offset:32768
	s_add_u32 m0, s38, 20480
	s_nop 0
	global_load_lds_dwordx4 v165, s[100:101]
	s_waitcnt lgkmcnt(6)
	v_mfma_f32_16x16x32_bf16 v[4:7], v[80:83], v[116:119], v[4:7]
	ds_read_b128 v[96:99], v162 offset:49152
	s_add_u32 m0, s38, 24576
	s_nop 0
	global_load_lds_dwordx4 v166, s[100:101]
	s_waitcnt lgkmcnt(6)
	v_mfma_f32_16x16x32_bf16 v[8:11], v[80:83], v[120:123], v[8:11]
	ds_read_b128 v[100:103], v162 offset:51200
	s_add_u32 m0, s38, 28672
	s_nop 0
	global_load_lds_dwordx4 v167, s[100:101]
	s_add_u32 s100, s100, 128
	s_addc_u32 s101, s101, 0
	s_waitcnt lgkmcnt(6)
	v_mfma_f32_16x16x32_bf16 v[12:15], v[80:83], v[124:127], v[12:15]
	ds_read_b128 v[104:107], v162 offset:53248
	s_waitcnt lgkmcnt(6)
	v_mfma_f32_16x16x32_bf16 v[16:19], v[84:87], v[112:115], v[16:19]
	ds_read_b128 v[108:111], v162 offset:55296
	s_waitcnt lgkmcnt(7)
	v_mfma_f32_16x16x32_bf16 v[20:23], v[84:87], v[116:119], v[20:23]
	ds_read_b128 v[68:71], v150 offset:34816
	s_waitcnt lgkmcnt(8)
	v_mfma_f32_16x16x32_bf16 v[24:27], v[84:87], v[120:123], v[24:27]
	ds_read_b128 v[72:75], v150 offset:36864
	s_waitcnt lgkmcnt(9)
	v_mfma_f32_16x16x32_bf16 v[28:31], v[84:87], v[124:127], v[28:31]
	ds_read_b128 v[76:79], v150 offset:38912
	s_waitcnt lgkmcnt(9)
	v_mfma_f32_16x16x32_bf16 v[32:35], v[88:91], v[112:115], v[32:35]
	s_waitcnt lgkmcnt(9)
	v_mfma_f32_16x16x32_bf16 v[36:39], v[88:91], v[116:119], v[36:39]
	s_waitcnt lgkmcnt(9)
	v_mfma_f32_16x16x32_bf16 v[40:43], v[88:91], v[120:123], v[40:43]
	s_waitcnt lgkmcnt(9)
	v_mfma_f32_16x16x32_bf16 v[44:47], v[88:91], v[124:127], v[44:47]
	s_waitcnt lgkmcnt(8)
	v_mfma_f32_16x16x32_bf16 v[48:51], v[92:95], v[112:115], v[48:51]
	s_waitcnt lgkmcnt(8)
	v_mfma_f32_16x16x32_bf16 v[52:55], v[92:95], v[116:119], v[52:55]
	s_waitcnt lgkmcnt(8)
	v_mfma_f32_16x16x32_bf16 v[56:59], v[92:95], v[120:123], v[56:59]
	s_waitcnt lgkmcnt(8)
	v_mfma_f32_16x16x32_bf16 v[60:63], v[92:95], v[124:127], v[60:63]
	s_waitcnt lgkmcnt(6)
	v_mfma_f32_16x16x32_bf16 v[0:3], v[64:67], v[96:99], v[0:3]
	ds_read_b128 v[80:83], v151 offset:32768
	s_waitcnt lgkmcnt(6)
	v_mfma_f32_16x16x32_bf16 v[4:7], v[64:67], v[100:103], v[4:7]
	ds_read_b128 v[112:115], v163 offset:49152
	s_waitcnt lgkmcnt(6)
	v_mfma_f32_16x16x32_bf16 v[8:11], v[64:67], v[104:107], v[8:11]
	ds_read_b128 v[116:119], v163 offset:51200
	s_waitcnt lgkmcnt(6)
	v_mfma_f32_16x16x32_bf16 v[12:15], v[64:67], v[108:111], v[12:15]
	ds_read_b128 v[120:123], v163 offset:53248
	s_waitcnt lgkmcnt(6)
	v_mfma_f32_16x16x32_bf16 v[16:19], v[68:71], v[96:99], v[16:19]
	ds_read_b128 v[124:127], v163 offset:55296
	s_waitcnt lgkmcnt(7)
	v_mfma_f32_16x16x32_bf16 v[20:23], v[68:71], v[100:103], v[20:23]
	ds_read_b128 v[84:87], v151 offset:34816
	s_waitcnt lgkmcnt(8)
	v_mfma_f32_16x16x32_bf16 v[24:27], v[68:71], v[104:107], v[24:27]
	ds_read_b128 v[88:91], v151 offset:36864
	s_waitcnt lgkmcnt(9)
	v_mfma_f32_16x16x32_bf16 v[28:31], v[68:71], v[108:111], v[28:31]
	ds_read_b128 v[92:95], v151 offset:38912
	s_waitcnt lgkmcnt(9)
	v_mfma_f32_16x16x32_bf16 v[32:35], v[72:75], v[96:99], v[32:35]
	s_waitcnt lgkmcnt(9)
	v_mfma_f32_16x16x32_bf16 v[36:39], v[72:75], v[100:103], v[36:39]
	s_waitcnt lgkmcnt(9)
	v_mfma_f32_16x16x32_bf16 v[40:43], v[72:75], v[104:107], v[40:43]
	s_waitcnt lgkmcnt(9)
	v_mfma_f32_16x16x32_bf16 v[44:47], v[72:75], v[108:111], v[44:47]
	s_waitcnt vmcnt(0) lgkmcnt(0)
	s_barrier
	s_add_u32 m0, s38, 32768
	s_nop 0
	global_load_lds_dwordx4 v164, s[98:99]
	s_waitcnt lgkmcnt(8)
	v_mfma_f32_16x16x32_bf16 v[48:51], v[76:79], v[96:99], v[48:51]
	s_add_u32 m0, s38, 36864
	s_nop 0
	global_load_lds_dwordx4 v165, s[98:99]
	s_waitcnt lgkmcnt(8)
	v_mfma_f32_16x16x32_bf16 v[52:55], v[76:79], v[100:103], v[52:55]
	s_add_u32 m0, s38, 40960
	s_nop 0
	global_load_lds_dwordx4 v166, s[98:99]
	s_waitcnt lgkmcnt(8)
	v_mfma_f32_16x16x32_bf16 v[56:59], v[76:79], v[104:107], v[56:59]
	s_add_u32 m0, s38, 45056
	s_nop 0
	global_load_lds_dwordx4 v167, s[98:99]
	s_add_u32 s98, s98, 128
	s_addc_u32 s99, s99, 0
	s_waitcnt lgkmcnt(8)
	v_mfma_f32_16x16x32_bf16 v[60:63], v[76:79], v[108:111], v[60:63]
	s_add_u32 m0, s38, 49152
	s_nop 0
	global_load_lds_dwordx4 v164, s[100:101]
	s_waitcnt lgkmcnt(6)
	v_mfma_f32_16x16x32_bf16 v[0:3], v[80:83], v[112:115], v[0:3]
	ds_read_b128 v[64:67], v150 offset:0
	s_add_u32 m0, s38, 53248
	s_nop 0
	global_load_lds_dwordx4 v165, s[100:101]
	s_waitcnt lgkmcnt(6)
	v_mfma_f32_16x16x32_bf16 v[4:7], v[80:83], v[116:119], v[4:7]
	ds_read_b128 v[96:99], v162 offset:16384
	s_add_u32 m0, s38, 57344
	s_nop 0
	global_load_lds_dwordx4 v166, s[100:101]
	s_waitcnt lgkmcnt(6)
	v_mfma_f32_16x16x32_bf16 v[8:11], v[80:83], v[120:123], v[8:11]
	ds_read_b128 v[100:103], v162 offset:18432
	s_add_u32 m0, s38, 61440
	s_nop 0
	global_load_lds_dwordx4 v167, s[100:101]
	s_add_u32 s100, s100, 128
	s_addc_u32 s101, s101, 0
	s_waitcnt lgkmcnt(6)
	v_mfma_f32_16x16x32_bf16 v[12:15], v[80:83], v[124:127], v[12:15]
	ds_read_b128 v[104:107], v162 offset:20480
	s_waitcnt lgkmcnt(6)
	v_mfma_f32_16x16x32_bf16 v[16:19], v[84:87], v[112:115], v[16:19]
	ds_read_b128 v[108:111], v162 offset:22528
	s_waitcnt lgkmcnt(7)
	v_mfma_f32_16x16x32_bf16 v[20:23], v[84:87], v[116:119], v[20:23]
	ds_read_b128 v[68:71], v150 offset:2048
	s_waitcnt lgkmcnt(8)
	v_mfma_f32_16x16x32_bf16 v[24:27], v[84:87], v[120:123], v[24:27]
	ds_read_b128 v[72:75], v150 offset:4096
	s_waitcnt lgkmcnt(9)
	v_mfma_f32_16x16x32_bf16 v[28:31], v[84:87], v[124:127], v[28:31]
	ds_read_b128 v[76:79], v150 offset:6144
	s_waitcnt lgkmcnt(9)
	v_mfma_f32_16x16x32_bf16 v[32:35], v[88:91], v[112:115], v[32:35]
	s_waitcnt lgkmcnt(9)
	v_mfma_f32_16x16x32_bf16 v[36:39], v[88:91], v[116:119], v[36:39]
	s_waitcnt lgkmcnt(9)
	v_mfma_f32_16x16x32_bf16 v[40:43], v[88:91], v[120:123], v[40:43]
	s_waitcnt lgkmcnt(9)
	v_mfma_f32_16x16x32_bf16 v[44:47], v[88:91], v[124:127], v[44:47]
	s_waitcnt lgkmcnt(8)
	v_mfma_f32_16x16x32_bf16 v[48:51], v[92:95], v[112:115], v[48:51]
	s_waitcnt lgkmcnt(8)
	v_mfma_f32_16x16x32_bf16 v[52:55], v[92:95], v[116:119], v[52:55]
	s_waitcnt lgkmcnt(8)
	v_mfma_f32_16x16x32_bf16 v[56:59], v[92:95], v[120:123], v[56:59]
	s_waitcnt lgkmcnt(8)
	v_mfma_f32_16x16x32_bf16 v[60:63], v[92:95], v[124:127], v[60:63]
	s_waitcnt lgkmcnt(6)
	v_mfma_f32_16x16x32_bf16 v[0:3], v[64:67], v[96:99], v[0:3]
	ds_read_b128 v[80:83], v151 offset:0
	s_waitcnt lgkmcnt(6)
	v_mfma_f32_16x16x32_bf16 v[4:7], v[64:67], v[100:103], v[4:7]
	ds_read_b128 v[112:115], v163 offset:16384
	s_waitcnt lgkmcnt(6)
	v_mfma_f32_16x16x32_bf16 v[8:11], v[64:67], v[104:107], v[8:11]
	ds_read_b128 v[116:119], v163 offset:18432
	s_waitcnt lgkmcnt(6)
	v_mfma_f32_16x16x32_bf16 v[12:15], v[64:67], v[108:111], v[12:15]
	ds_read_b128 v[120:123], v163 offset:20480
	s_waitcnt lgkmcnt(6)
	v_mfma_f32_16x16x32_bf16 v[16:19], v[68:71], v[96:99], v[16:19]
	ds_read_b128 v[124:127], v163 offset:22528
	s_waitcnt lgkmcnt(7)
	v_mfma_f32_16x16x32_bf16 v[20:23], v[68:71], v[100:103], v[20:23]
	ds_read_b128 v[84:87], v151 offset:2048
	s_waitcnt lgkmcnt(8)
	v_mfma_f32_16x16x32_bf16 v[24:27], v[68:71], v[104:107], v[24:27]
	ds_read_b128 v[88:91], v151 offset:4096
	s_waitcnt lgkmcnt(9)
	v_mfma_f32_16x16x32_bf16 v[28:31], v[68:71], v[108:111], v[28:31]
	ds_read_b128 v[92:95], v151 offset:6144
	s_waitcnt lgkmcnt(9)
	v_mfma_f32_16x16x32_bf16 v[32:35], v[72:75], v[96:99], v[32:35]
	s_waitcnt lgkmcnt(9)
	v_mfma_f32_16x16x32_bf16 v[36:39], v[72:75], v[100:103], v[36:39]
	s_waitcnt lgkmcnt(9)
	v_mfma_f32_16x16x32_bf16 v[40:43], v[72:75], v[104:107], v[40:43]
	s_waitcnt lgkmcnt(9)
	v_mfma_f32_16x16x32_bf16 v[44:47], v[72:75], v[108:111], v[44:47]
	s_waitcnt vmcnt(0) lgkmcnt(0)
	s_barrier
	s_add_u32 m0, s38, 0
	s_nop 0
	global_load_lds_dwordx4 v164, s[98:99]
	s_waitcnt lgkmcnt(8)
	v_mfma_f32_16x16x32_bf16 v[48:51], v[76:79], v[96:99], v[48:51]
	s_add_u32 m0, s38, 4096
	s_nop 0
	global_load_lds_dwordx4 v165, s[98:99]
	s_waitcnt lgkmcnt(8)
	v_mfma_f32_16x16x32_bf16 v[52:55], v[76:79], v[100:103], v[52:55]
	s_add_u32 m0, s38, 8192
	s_nop 0
	global_load_lds_dwordx4 v166, s[98:99]
	s_waitcnt lgkmcnt(8)
	v_mfma_f32_16x16x32_bf16 v[56:59], v[76:79], v[104:107], v[56:59]
	s_add_u32 m0, s38, 12288
	s_nop 0
	global_load_lds_dwordx4 v167, s[98:99]
	s_add_u32 s98, s98, 128
	s_addc_u32 s99, s99, 0
	s_waitcnt lgkmcnt(8)
	v_mfma_f32_16x16x32_bf16 v[60:63], v[76:79], v[108:111], v[60:63]
	s_add_u32 m0, s38, 16384
	s_nop 0
	global_load_lds_dwordx4 v164, s[100:101]
	s_waitcnt lgkmcnt(6)
	v_mfma_f32_16x16x32_bf16 v[0:3], v[80:83], v[112:115], v[0:3]
	ds_read_b128 v[64:67], v150 offset:32768
	s_add_u32 m0, s38, 20480
	s_nop 0
	global_load_lds_dwordx4 v165, s[100:101]
	s_waitcnt lgkmcnt(6)
	v_mfma_f32_16x16x32_bf16 v[4:7], v[80:83], v[116:119], v[4:7]
	ds_read_b128 v[96:99], v162 offset:49152
	s_add_u32 m0, s38, 24576
	s_nop 0
	global_load_lds_dwordx4 v166, s[100:101]
	s_waitcnt lgkmcnt(6)
	v_mfma_f32_16x16x32_bf16 v[8:11], v[80:83], v[120:123], v[8:11]
	ds_read_b128 v[100:103], v162 offset:51200
	s_add_u32 m0, s38, 28672
	s_nop 0
	global_load_lds_dwordx4 v167, s[100:101]
	s_add_u32 s100, s100, 128
	s_addc_u32 s101, s101, 0
	s_waitcnt lgkmcnt(6)
	v_mfma_f32_16x16x32_bf16 v[12:15], v[80:83], v[124:127], v[12:15]
	ds_read_b128 v[104:107], v162 offset:53248
	s_waitcnt lgkmcnt(6)
	v_mfma_f32_16x16x32_bf16 v[16:19], v[84:87], v[112:115], v[16:19]
	ds_read_b128 v[108:111], v162 offset:55296
	s_waitcnt lgkmcnt(7)
	v_mfma_f32_16x16x32_bf16 v[20:23], v[84:87], v[116:119], v[20:23]
	ds_read_b128 v[68:71], v150 offset:34816
	s_waitcnt lgkmcnt(8)
	v_mfma_f32_16x16x32_bf16 v[24:27], v[84:87], v[120:123], v[24:27]
	ds_read_b128 v[72:75], v150 offset:36864
	s_waitcnt lgkmcnt(9)
	v_mfma_f32_16x16x32_bf16 v[28:31], v[84:87], v[124:127], v[28:31]
	ds_read_b128 v[76:79], v150 offset:38912
	s_waitcnt lgkmcnt(9)
	v_mfma_f32_16x16x32_bf16 v[32:35], v[88:91], v[112:115], v[32:35]
	s_waitcnt lgkmcnt(9)
	v_mfma_f32_16x16x32_bf16 v[36:39], v[88:91], v[116:119], v[36:39]
	s_waitcnt lgkmcnt(9)
	v_mfma_f32_16x16x32_bf16 v[40:43], v[88:91], v[120:123], v[40:43]
	s_waitcnt lgkmcnt(9)
	v_mfma_f32_16x16x32_bf16 v[44:47], v[88:91], v[124:127], v[44:47]
	s_waitcnt lgkmcnt(8)
	v_mfma_f32_16x16x32_bf16 v[48:51], v[92:95], v[112:115], v[48:51]
	s_waitcnt lgkmcnt(8)
	v_mfma_f32_16x16x32_bf16 v[52:55], v[92:95], v[116:119], v[52:55]
	s_waitcnt lgkmcnt(8)
	v_mfma_f32_16x16x32_bf16 v[56:59], v[92:95], v[120:123], v[56:59]
	s_waitcnt lgkmcnt(8)
	v_mfma_f32_16x16x32_bf16 v[60:63], v[92:95], v[124:127], v[60:63]
	s_waitcnt lgkmcnt(6)
	v_mfma_f32_16x16x32_bf16 v[0:3], v[64:67], v[96:99], v[0:3]
	ds_read_b128 v[80:83], v151 offset:32768
	s_waitcnt lgkmcnt(6)
	v_mfma_f32_16x16x32_bf16 v[4:7], v[64:67], v[100:103], v[4:7]
	ds_read_b128 v[112:115], v163 offset:49152
	s_waitcnt lgkmcnt(6)
	v_mfma_f32_16x16x32_bf16 v[8:11], v[64:67], v[104:107], v[8:11]
	ds_read_b128 v[116:119], v163 offset:51200
	s_waitcnt lgkmcnt(6)
	v_mfma_f32_16x16x32_bf16 v[12:15], v[64:67], v[108:111], v[12:15]
	ds_read_b128 v[120:123], v163 offset:53248
	s_waitcnt lgkmcnt(6)
	v_mfma_f32_16x16x32_bf16 v[16:19], v[68:71], v[96:99], v[16:19]
	ds_read_b128 v[124:127], v163 offset:55296
	s_waitcnt lgkmcnt(7)
	v_mfma_f32_16x16x32_bf16 v[20:23], v[68:71], v[100:103], v[20:23]
	ds_read_b128 v[84:87], v151 offset:34816
	s_waitcnt lgkmcnt(8)
	v_mfma_f32_16x16x32_bf16 v[24:27], v[68:71], v[104:107], v[24:27]
	ds_read_b128 v[88:91], v151 offset:36864
	s_waitcnt lgkmcnt(9)
	v_mfma_f32_16x16x32_bf16 v[28:31], v[68:71], v[108:111], v[28:31]
	ds_read_b128 v[92:95], v151 offset:38912
	s_waitcnt lgkmcnt(9)
	v_mfma_f32_16x16x32_bf16 v[32:35], v[72:75], v[96:99], v[32:35]
	s_waitcnt lgkmcnt(9)
	v_mfma_f32_16x16x32_bf16 v[36:39], v[72:75], v[100:103], v[36:39]
	s_waitcnt lgkmcnt(9)
	v_mfma_f32_16x16x32_bf16 v[40:43], v[72:75], v[104:107], v[40:43]
	s_waitcnt lgkmcnt(9)
	v_mfma_f32_16x16x32_bf16 v[44:47], v[72:75], v[108:111], v[44:47]
	s_waitcnt vmcnt(0) lgkmcnt(0)
	s_barrier
	s_add_u32 m0, s38, 32768
	s_nop 0
	global_load_lds_dwordx4 v164, s[98:99]
	s_waitcnt lgkmcnt(8)
	v_mfma_f32_16x16x32_bf16 v[48:51], v[76:79], v[96:99], v[48:51]
	s_add_u32 m0, s38, 36864
	s_nop 0
	global_load_lds_dwordx4 v165, s[98:99]
	s_waitcnt lgkmcnt(8)
	v_mfma_f32_16x16x32_bf16 v[52:55], v[76:79], v[100:103], v[52:55]
	s_add_u32 m0, s38, 40960
	s_nop 0
	global_load_lds_dwordx4 v166, s[98:99]
	s_waitcnt lgkmcnt(8)
	v_mfma_f32_16x16x32_bf16 v[56:59], v[76:79], v[104:107], v[56:59]
	s_add_u32 m0, s38, 45056
	s_nop 0
	global_load_lds_dwordx4 v167, s[98:99]
	s_add_u32 s98, s98, 128
	s_addc_u32 s99, s99, 0
	s_waitcnt lgkmcnt(8)
	v_mfma_f32_16x16x32_bf16 v[60:63], v[76:79], v[108:111], v[60:63]
	s_add_u32 m0, s38, 49152
	s_nop 0
	global_load_lds_dwordx4 v164, s[100:101]
	s_waitcnt lgkmcnt(6)
	v_mfma_f32_16x16x32_bf16 v[0:3], v[80:83], v[112:115], v[0:3]
	ds_read_b128 v[64:67], v150 offset:0
	s_add_u32 m0, s38, 53248
	s_nop 0
	global_load_lds_dwordx4 v165, s[100:101]
	s_waitcnt lgkmcnt(6)
	v_mfma_f32_16x16x32_bf16 v[4:7], v[80:83], v[116:119], v[4:7]
	ds_read_b128 v[96:99], v162 offset:16384
	s_add_u32 m0, s38, 57344
	s_nop 0
	global_load_lds_dwordx4 v166, s[100:101]
	s_waitcnt lgkmcnt(6)
	v_mfma_f32_16x16x32_bf16 v[8:11], v[80:83], v[120:123], v[8:11]
	ds_read_b128 v[100:103], v162 offset:18432
	s_add_u32 m0, s38, 61440
	s_nop 0
	global_load_lds_dwordx4 v167, s[100:101]
	s_add_u32 s100, s100, 128
	s_addc_u32 s101, s101, 0
	s_waitcnt lgkmcnt(6)
	v_mfma_f32_16x16x32_bf16 v[12:15], v[80:83], v[124:127], v[12:15]
	ds_read_b128 v[104:107], v162 offset:20480
	s_waitcnt lgkmcnt(6)
	v_mfma_f32_16x16x32_bf16 v[16:19], v[84:87], v[112:115], v[16:19]
	ds_read_b128 v[108:111], v162 offset:22528
	s_waitcnt lgkmcnt(7)
	v_mfma_f32_16x16x32_bf16 v[20:23], v[84:87], v[116:119], v[20:23]
	ds_read_b128 v[68:71], v150 offset:2048
	s_waitcnt lgkmcnt(8)
	v_mfma_f32_16x16x32_bf16 v[24:27], v[84:87], v[120:123], v[24:27]
	ds_read_b128 v[72:75], v150 offset:4096
	s_waitcnt lgkmcnt(9)
	v_mfma_f32_16x16x32_bf16 v[28:31], v[84:87], v[124:127], v[28:31]
	ds_read_b128 v[76:79], v150 offset:6144
	s_waitcnt lgkmcnt(9)
	v_mfma_f32_16x16x32_bf16 v[32:35], v[88:91], v[112:115], v[32:35]
	s_waitcnt lgkmcnt(9)
	v_mfma_f32_16x16x32_bf16 v[36:39], v[88:91], v[116:119], v[36:39]
	s_waitcnt lgkmcnt(9)
	v_mfma_f32_16x16x32_bf16 v[40:43], v[88:91], v[120:123], v[40:43]
	s_waitcnt lgkmcnt(9)
	v_mfma_f32_16x16x32_bf16 v[44:47], v[88:91], v[124:127], v[44:47]
	s_waitcnt lgkmcnt(8)
	v_mfma_f32_16x16x32_bf16 v[48:51], v[92:95], v[112:115], v[48:51]
	s_waitcnt lgkmcnt(8)
	v_mfma_f32_16x16x32_bf16 v[52:55], v[92:95], v[116:119], v[52:55]
	s_waitcnt lgkmcnt(8)
	v_mfma_f32_16x16x32_bf16 v[56:59], v[92:95], v[120:123], v[56:59]
	s_waitcnt lgkmcnt(8)
	v_mfma_f32_16x16x32_bf16 v[60:63], v[92:95], v[124:127], v[60:63]
	s_waitcnt lgkmcnt(6)
	v_mfma_f32_16x16x32_bf16 v[0:3], v[64:67], v[96:99], v[0:3]
	ds_read_b128 v[80:83], v151 offset:0
	s_waitcnt lgkmcnt(6)
	v_mfma_f32_16x16x32_bf16 v[4:7], v[64:67], v[100:103], v[4:7]
	ds_read_b128 v[112:115], v163 offset:16384
	s_waitcnt lgkmcnt(6)
	v_mfma_f32_16x16x32_bf16 v[8:11], v[64:67], v[104:107], v[8:11]
	ds_read_b128 v[116:119], v163 offset:18432
	s_waitcnt lgkmcnt(6)
	v_mfma_f32_16x16x32_bf16 v[12:15], v[64:67], v[108:111], v[12:15]
	ds_read_b128 v[120:123], v163 offset:20480
	s_waitcnt lgkmcnt(6)
	v_mfma_f32_16x16x32_bf16 v[16:19], v[68:71], v[96:99], v[16:19]
	ds_read_b128 v[124:127], v163 offset:22528
	s_waitcnt lgkmcnt(7)
	v_mfma_f32_16x16x32_bf16 v[20:23], v[68:71], v[100:103], v[20:23]
	ds_read_b128 v[84:87], v151 offset:2048
	s_waitcnt lgkmcnt(8)
	v_mfma_f32_16x16x32_bf16 v[24:27], v[68:71], v[104:107], v[24:27]
	ds_read_b128 v[88:91], v151 offset:4096
	s_waitcnt lgkmcnt(9)
	v_mfma_f32_16x16x32_bf16 v[28:31], v[68:71], v[108:111], v[28:31]
	ds_read_b128 v[92:95], v151 offset:6144
	s_waitcnt lgkmcnt(9)
	v_mfma_f32_16x16x32_bf16 v[32:35], v[72:75], v[96:99], v[32:35]
	s_waitcnt lgkmcnt(9)
	v_mfma_f32_16x16x32_bf16 v[36:39], v[72:75], v[100:103], v[36:39]
	s_waitcnt lgkmcnt(9)
	v_mfma_f32_16x16x32_bf16 v[40:43], v[72:75], v[104:107], v[40:43]
	s_waitcnt lgkmcnt(9)
	v_mfma_f32_16x16x32_bf16 v[44:47], v[72:75], v[108:111], v[44:47]
	s_waitcnt vmcnt(0) lgkmcnt(0)
	s_barrier
	s_add_u32 m0, s38, 0
	s_nop 0
	global_load_lds_dwordx4 v164, s[98:99]
	s_waitcnt lgkmcnt(8)
	v_mfma_f32_16x16x32_bf16 v[48:51], v[76:79], v[96:99], v[48:51]
	s_add_u32 m0, s38, 4096
	s_nop 0
	global_load_lds_dwordx4 v165, s[98:99]
	s_waitcnt lgkmcnt(8)
	v_mfma_f32_16x16x32_bf16 v[52:55], v[76:79], v[100:103], v[52:55]
	s_add_u32 m0, s38, 8192
	s_nop 0
	global_load_lds_dwordx4 v166, s[98:99]
	s_waitcnt lgkmcnt(8)
	v_mfma_f32_16x16x32_bf16 v[56:59], v[76:79], v[104:107], v[56:59]
	s_add_u32 m0, s38, 12288
	s_nop 0
	global_load_lds_dwordx4 v167, s[98:99]
	s_add_u32 s98, s98, 128
	s_addc_u32 s99, s99, 0
	s_waitcnt lgkmcnt(8)
	v_mfma_f32_16x16x32_bf16 v[60:63], v[76:79], v[108:111], v[60:63]
	s_add_u32 m0, s38, 16384
	s_nop 0
	global_load_lds_dwordx4 v164, s[100:101]
	s_waitcnt lgkmcnt(6)
	v_mfma_f32_16x16x32_bf16 v[0:3], v[80:83], v[112:115], v[0:3]
	ds_read_b128 v[64:67], v150 offset:32768
	s_add_u32 m0, s38, 20480
	s_nop 0
	global_load_lds_dwordx4 v165, s[100:101]
	s_waitcnt lgkmcnt(6)
	v_mfma_f32_16x16x32_bf16 v[4:7], v[80:83], v[116:119], v[4:7]
	ds_read_b128 v[96:99], v162 offset:49152
	s_add_u32 m0, s38, 24576
	s_nop 0
	global_load_lds_dwordx4 v166, s[100:101]
	s_waitcnt lgkmcnt(6)
	v_mfma_f32_16x16x32_bf16 v[8:11], v[80:83], v[120:123], v[8:11]
	ds_read_b128 v[100:103], v162 offset:51200
	s_add_u32 m0, s38, 28672
	s_nop 0
	global_load_lds_dwordx4 v167, s[100:101]
	s_add_u32 s100, s100, 128
	s_addc_u32 s101, s101, 0
	s_waitcnt lgkmcnt(6)
	v_mfma_f32_16x16x32_bf16 v[12:15], v[80:83], v[124:127], v[12:15]
	ds_read_b128 v[104:107], v162 offset:53248
	s_waitcnt lgkmcnt(6)
	v_mfma_f32_16x16x32_bf16 v[16:19], v[84:87], v[112:115], v[16:19]
	ds_read_b128 v[108:111], v162 offset:55296
	s_waitcnt lgkmcnt(7)
	v_mfma_f32_16x16x32_bf16 v[20:23], v[84:87], v[116:119], v[20:23]
	ds_read_b128 v[68:71], v150 offset:34816
	s_waitcnt lgkmcnt(8)
	v_mfma_f32_16x16x32_bf16 v[24:27], v[84:87], v[120:123], v[24:27]
	ds_read_b128 v[72:75], v150 offset:36864
	s_waitcnt lgkmcnt(9)
	v_mfma_f32_16x16x32_bf16 v[28:31], v[84:87], v[124:127], v[28:31]
	ds_read_b128 v[76:79], v150 offset:38912
	s_waitcnt lgkmcnt(9)
	v_mfma_f32_16x16x32_bf16 v[32:35], v[88:91], v[112:115], v[32:35]
	s_waitcnt lgkmcnt(9)
	v_mfma_f32_16x16x32_bf16 v[36:39], v[88:91], v[116:119], v[36:39]
	s_waitcnt lgkmcnt(9)
	v_mfma_f32_16x16x32_bf16 v[40:43], v[88:91], v[120:123], v[40:43]
	s_waitcnt lgkmcnt(9)
	v_mfma_f32_16x16x32_bf16 v[44:47], v[88:91], v[124:127], v[44:47]
	s_waitcnt lgkmcnt(8)
	v_mfma_f32_16x16x32_bf16 v[48:51], v[92:95], v[112:115], v[48:51]
	s_waitcnt lgkmcnt(8)
	v_mfma_f32_16x16x32_bf16 v[52:55], v[92:95], v[116:119], v[52:55]
	s_waitcnt lgkmcnt(8)
	v_mfma_f32_16x16x32_bf16 v[56:59], v[92:95], v[120:123], v[56:59]
	s_waitcnt lgkmcnt(8)
	v_mfma_f32_16x16x32_bf16 v[60:63], v[92:95], v[124:127], v[60:63]
	s_waitcnt lgkmcnt(6)
	v_mfma_f32_16x16x32_bf16 v[0:3], v[64:67], v[96:99], v[0:3]
	ds_read_b128 v[80:83], v151 offset:32768
	s_waitcnt lgkmcnt(6)
	v_mfma_f32_16x16x32_bf16 v[4:7], v[64:67], v[100:103], v[4:7]
	ds_read_b128 v[112:115], v163 offset:49152
	s_waitcnt lgkmcnt(6)
	v_mfma_f32_16x16x32_bf16 v[8:11], v[64:67], v[104:107], v[8:11]
	ds_read_b128 v[116:119], v163 offset:51200
	s_waitcnt lgkmcnt(6)
	v_mfma_f32_16x16x32_bf16 v[12:15], v[64:67], v[108:111], v[12:15]
	ds_read_b128 v[120:123], v163 offset:53248
	s_waitcnt lgkmcnt(6)
	v_mfma_f32_16x16x32_bf16 v[16:19], v[68:71], v[96:99], v[16:19]
	ds_read_b128 v[124:127], v163 offset:55296
	s_waitcnt lgkmcnt(7)
	v_mfma_f32_16x16x32_bf16 v[20:23], v[68:71], v[100:103], v[20:23]
	ds_read_b128 v[84:87], v151 offset:34816
	s_waitcnt lgkmcnt(8)
	v_mfma_f32_16x16x32_bf16 v[24:27], v[68:71], v[104:107], v[24:27]
	ds_read_b128 v[88:91], v151 offset:36864
	s_waitcnt lgkmcnt(9)
	v_mfma_f32_16x16x32_bf16 v[28:31], v[68:71], v[108:111], v[28:31]
	ds_read_b128 v[92:95], v151 offset:38912
	s_waitcnt lgkmcnt(9)
	v_mfma_f32_16x16x32_bf16 v[32:35], v[72:75], v[96:99], v[32:35]
	s_waitcnt lgkmcnt(9)
	v_mfma_f32_16x16x32_bf16 v[36:39], v[72:75], v[100:103], v[36:39]
	s_waitcnt lgkmcnt(9)
	v_mfma_f32_16x16x32_bf16 v[40:43], v[72:75], v[104:107], v[40:43]
	s_waitcnt lgkmcnt(9)
	v_mfma_f32_16x16x32_bf16 v[44:47], v[72:75], v[108:111], v[44:47]
	s_waitcnt vmcnt(0) lgkmcnt(0)
	s_barrier
	s_add_u32 m0, s38, 32768
	s_nop 0
	global_load_lds_dwordx4 v164, s[98:99]
	s_waitcnt lgkmcnt(8)
	v_mfma_f32_16x16x32_bf16 v[48:51], v[76:79], v[96:99], v[48:51]
	s_add_u32 m0, s38, 36864
	s_nop 0
	global_load_lds_dwordx4 v165, s[98:99]
	s_waitcnt lgkmcnt(8)
	v_mfma_f32_16x16x32_bf16 v[52:55], v[76:79], v[100:103], v[52:55]
	s_add_u32 m0, s38, 40960
	s_nop 0
	global_load_lds_dwordx4 v166, s[98:99]
	s_waitcnt lgkmcnt(8)
	v_mfma_f32_16x16x32_bf16 v[56:59], v[76:79], v[104:107], v[56:59]
	s_add_u32 m0, s38, 45056
	s_nop 0
	global_load_lds_dwordx4 v167, s[98:99]
	s_add_u32 s98, s98, 128
	s_addc_u32 s99, s99, 0
	s_waitcnt lgkmcnt(8)
	v_mfma_f32_16x16x32_bf16 v[60:63], v[76:79], v[108:111], v[60:63]
	s_add_u32 m0, s38, 49152
	s_nop 0
	global_load_lds_dwordx4 v164, s[100:101]
	s_waitcnt lgkmcnt(6)
	v_mfma_f32_16x16x32_bf16 v[0:3], v[80:83], v[112:115], v[0:3]
	ds_read_b128 v[64:67], v150 offset:0
	s_add_u32 m0, s38, 53248
	s_nop 0
	global_load_lds_dwordx4 v165, s[100:101]
	s_waitcnt lgkmcnt(6)
	v_mfma_f32_16x16x32_bf16 v[4:7], v[80:83], v[116:119], v[4:7]
	ds_read_b128 v[96:99], v162 offset:16384
	s_add_u32 m0, s38, 57344
	s_nop 0
	global_load_lds_dwordx4 v166, s[100:101]
	s_waitcnt lgkmcnt(6)
	v_mfma_f32_16x16x32_bf16 v[8:11], v[80:83], v[120:123], v[8:11]
	ds_read_b128 v[100:103], v162 offset:18432
	s_add_u32 m0, s38, 61440
	s_nop 0
	global_load_lds_dwordx4 v167, s[100:101]
	s_add_u32 s100, s100, 128
	s_addc_u32 s101, s101, 0
	s_waitcnt lgkmcnt(6)
	v_mfma_f32_16x16x32_bf16 v[12:15], v[80:83], v[124:127], v[12:15]
	ds_read_b128 v[104:107], v162 offset:20480
	s_waitcnt lgkmcnt(6)
	v_mfma_f32_16x16x32_bf16 v[16:19], v[84:87], v[112:115], v[16:19]
	ds_read_b128 v[108:111], v162 offset:22528
	s_waitcnt lgkmcnt(7)
	v_mfma_f32_16x16x32_bf16 v[20:23], v[84:87], v[116:119], v[20:23]
	ds_read_b128 v[68:71], v150 offset:2048
	s_waitcnt lgkmcnt(8)
	v_mfma_f32_16x16x32_bf16 v[24:27], v[84:87], v[120:123], v[24:27]
	ds_read_b128 v[72:75], v150 offset:4096
	s_waitcnt lgkmcnt(9)
	v_mfma_f32_16x16x32_bf16 v[28:31], v[84:87], v[124:127], v[28:31]
	ds_read_b128 v[76:79], v150 offset:6144
	s_waitcnt lgkmcnt(9)
	v_mfma_f32_16x16x32_bf16 v[32:35], v[88:91], v[112:115], v[32:35]
	s_waitcnt lgkmcnt(9)
	v_mfma_f32_16x16x32_bf16 v[36:39], v[88:91], v[116:119], v[36:39]
	s_waitcnt lgkmcnt(9)
	v_mfma_f32_16x16x32_bf16 v[40:43], v[88:91], v[120:123], v[40:43]
	s_waitcnt lgkmcnt(9)
	v_mfma_f32_16x16x32_bf16 v[44:47], v[88:91], v[124:127], v[44:47]
	s_waitcnt lgkmcnt(8)
	v_mfma_f32_16x16x32_bf16 v[48:51], v[92:95], v[112:115], v[48:51]
	s_waitcnt lgkmcnt(8)
	v_mfma_f32_16x16x32_bf16 v[52:55], v[92:95], v[116:119], v[52:55]
	s_waitcnt lgkmcnt(8)
	v_mfma_f32_16x16x32_bf16 v[56:59], v[92:95], v[120:123], v[56:59]
	s_waitcnt lgkmcnt(8)
	v_mfma_f32_16x16x32_bf16 v[60:63], v[92:95], v[124:127], v[60:63]
	s_waitcnt lgkmcnt(6)
	v_mfma_f32_16x16x32_bf16 v[0:3], v[64:67], v[96:99], v[0:3]
	ds_read_b128 v[80:83], v151 offset:0
	s_waitcnt lgkmcnt(6)
	v_mfma_f32_16x16x32_bf16 v[4:7], v[64:67], v[100:103], v[4:7]
	ds_read_b128 v[112:115], v163 offset:16384
	s_waitcnt lgkmcnt(6)
	v_mfma_f32_16x16x32_bf16 v[8:11], v[64:67], v[104:107], v[8:11]
	ds_read_b128 v[116:119], v163 offset:18432
	s_waitcnt lgkmcnt(6)
	v_mfma_f32_16x16x32_bf16 v[12:15], v[64:67], v[108:111], v[12:15]
	ds_read_b128 v[120:123], v163 offset:20480
	s_waitcnt lgkmcnt(6)
	v_mfma_f32_16x16x32_bf16 v[16:19], v[68:71], v[96:99], v[16:19]
	ds_read_b128 v[124:127], v163 offset:22528
	s_waitcnt lgkmcnt(7)
	v_mfma_f32_16x16x32_bf16 v[20:23], v[68:71], v[100:103], v[20:23]
	ds_read_b128 v[84:87], v151 offset:2048
	s_waitcnt lgkmcnt(8)
	v_mfma_f32_16x16x32_bf16 v[24:27], v[68:71], v[104:107], v[24:27]
	ds_read_b128 v[88:91], v151 offset:4096
	s_waitcnt lgkmcnt(9)
	v_mfma_f32_16x16x32_bf16 v[28:31], v[68:71], v[108:111], v[28:31]
	ds_read_b128 v[92:95], v151 offset:6144
	s_waitcnt lgkmcnt(9)
	v_mfma_f32_16x16x32_bf16 v[32:35], v[72:75], v[96:99], v[32:35]
	s_waitcnt lgkmcnt(9)
	v_mfma_f32_16x16x32_bf16 v[36:39], v[72:75], v[100:103], v[36:39]
	s_waitcnt lgkmcnt(9)
	v_mfma_f32_16x16x32_bf16 v[40:43], v[72:75], v[104:107], v[40:43]
	s_waitcnt lgkmcnt(9)
	v_mfma_f32_16x16x32_bf16 v[44:47], v[72:75], v[108:111], v[44:47]
	s_waitcnt vmcnt(0) lgkmcnt(0)
	s_barrier
	s_add_u32 m0, s38, 0
	s_nop 0
	global_load_lds_dwordx4 v164, s[98:99]
	s_waitcnt lgkmcnt(8)
	v_mfma_f32_16x16x32_bf16 v[48:51], v[76:79], v[96:99], v[48:51]
	s_add_u32 m0, s38, 4096
	s_nop 0
	global_load_lds_dwordx4 v165, s[98:99]
	s_waitcnt lgkmcnt(8)
	v_mfma_f32_16x16x32_bf16 v[52:55], v[76:79], v[100:103], v[52:55]
	s_add_u32 m0, s38, 8192
	s_nop 0
	global_load_lds_dwordx4 v166, s[98:99]
	s_waitcnt lgkmcnt(8)
	v_mfma_f32_16x16x32_bf16 v[56:59], v[76:79], v[104:107], v[56:59]
	s_add_u32 m0, s38, 12288
	s_nop 0
	global_load_lds_dwordx4 v167, s[98:99]
	s_add_u32 s98, s98, 128
	s_addc_u32 s99, s99, 0
	s_waitcnt lgkmcnt(8)
	v_mfma_f32_16x16x32_bf16 v[60:63], v[76:79], v[108:111], v[60:63]
	s_add_u32 m0, s38, 16384
	s_nop 0
	global_load_lds_dwordx4 v164, s[100:101]
	s_waitcnt lgkmcnt(6)
	v_mfma_f32_16x16x32_bf16 v[0:3], v[80:83], v[112:115], v[0:3]
	ds_read_b128 v[64:67], v150 offset:32768
	s_add_u32 m0, s38, 20480
	s_nop 0
	global_load_lds_dwordx4 v165, s[100:101]
	s_waitcnt lgkmcnt(6)
	v_mfma_f32_16x16x32_bf16 v[4:7], v[80:83], v[116:119], v[4:7]
	ds_read_b128 v[96:99], v162 offset:49152
	s_add_u32 m0, s38, 24576
	s_nop 0
	global_load_lds_dwordx4 v166, s[100:101]
	s_waitcnt lgkmcnt(6)
	v_mfma_f32_16x16x32_bf16 v[8:11], v[80:83], v[120:123], v[8:11]
	ds_read_b128 v[100:103], v162 offset:51200
	s_add_u32 m0, s38, 28672
	s_nop 0
	global_load_lds_dwordx4 v167, s[100:101]
	s_add_u32 s100, s100, 128
	s_addc_u32 s101, s101, 0
	s_waitcnt lgkmcnt(6)
	v_mfma_f32_16x16x32_bf16 v[12:15], v[80:83], v[124:127], v[12:15]
	ds_read_b128 v[104:107], v162 offset:53248
	s_waitcnt lgkmcnt(6)
	v_mfma_f32_16x16x32_bf16 v[16:19], v[84:87], v[112:115], v[16:19]
	ds_read_b128 v[108:111], v162 offset:55296
	s_waitcnt lgkmcnt(7)
	v_mfma_f32_16x16x32_bf16 v[20:23], v[84:87], v[116:119], v[20:23]
	ds_read_b128 v[68:71], v150 offset:34816
	s_waitcnt lgkmcnt(8)
	v_mfma_f32_16x16x32_bf16 v[24:27], v[84:87], v[120:123], v[24:27]
	ds_read_b128 v[72:75], v150 offset:36864
	s_waitcnt lgkmcnt(9)
	v_mfma_f32_16x16x32_bf16 v[28:31], v[84:87], v[124:127], v[28:31]
	ds_read_b128 v[76:79], v150 offset:38912
	s_waitcnt lgkmcnt(9)
	v_mfma_f32_16x16x32_bf16 v[32:35], v[88:91], v[112:115], v[32:35]
	s_waitcnt lgkmcnt(9)
	v_mfma_f32_16x16x32_bf16 v[36:39], v[88:91], v[116:119], v[36:39]
	s_waitcnt lgkmcnt(9)
	v_mfma_f32_16x16x32_bf16 v[40:43], v[88:91], v[120:123], v[40:43]
	s_waitcnt lgkmcnt(9)
	v_mfma_f32_16x16x32_bf16 v[44:47], v[88:91], v[124:127], v[44:47]
	s_waitcnt lgkmcnt(8)
	v_mfma_f32_16x16x32_bf16 v[48:51], v[92:95], v[112:115], v[48:51]
	s_waitcnt lgkmcnt(8)
	v_mfma_f32_16x16x32_bf16 v[52:55], v[92:95], v[116:119], v[52:55]
	s_waitcnt lgkmcnt(8)
	v_mfma_f32_16x16x32_bf16 v[56:59], v[92:95], v[120:123], v[56:59]
	s_waitcnt lgkmcnt(8)
	v_mfma_f32_16x16x32_bf16 v[60:63], v[92:95], v[124:127], v[60:63]
	s_waitcnt lgkmcnt(6)
	v_mfma_f32_16x16x32_bf16 v[0:3], v[64:67], v[96:99], v[0:3]
	ds_read_b128 v[80:83], v151 offset:32768
	s_waitcnt lgkmcnt(6)
	v_mfma_f32_16x16x32_bf16 v[4:7], v[64:67], v[100:103], v[4:7]
	ds_read_b128 v[112:115], v163 offset:49152
	s_waitcnt lgkmcnt(6)
	v_mfma_f32_16x16x32_bf16 v[8:11], v[64:67], v[104:107], v[8:11]
	ds_read_b128 v[116:119], v163 offset:51200
	s_waitcnt lgkmcnt(6)
	v_mfma_f32_16x16x32_bf16 v[12:15], v[64:67], v[108:111], v[12:15]
	ds_read_b128 v[120:123], v163 offset:53248
	s_waitcnt lgkmcnt(6)
	v_mfma_f32_16x16x32_bf16 v[16:19], v[68:71], v[96:99], v[16:19]
	ds_read_b128 v[124:127], v163 offset:55296
	s_waitcnt lgkmcnt(7)
	v_mfma_f32_16x16x32_bf16 v[20:23], v[68:71], v[100:103], v[20:23]
	ds_read_b128 v[84:87], v151 offset:34816
	s_waitcnt lgkmcnt(8)
	v_mfma_f32_16x16x32_bf16 v[24:27], v[68:71], v[104:107], v[24:27]
	ds_read_b128 v[88:91], v151 offset:36864
	s_waitcnt lgkmcnt(9)
	v_mfma_f32_16x16x32_bf16 v[28:31], v[68:71], v[108:111], v[28:31]
	ds_read_b128 v[92:95], v151 offset:38912
	s_waitcnt lgkmcnt(9)
	v_mfma_f32_16x16x32_bf16 v[32:35], v[72:75], v[96:99], v[32:35]
	s_waitcnt lgkmcnt(9)
	v_mfma_f32_16x16x32_bf16 v[36:39], v[72:75], v[100:103], v[36:39]
	s_waitcnt lgkmcnt(9)
	v_mfma_f32_16x16x32_bf16 v[40:43], v[72:75], v[104:107], v[40:43]
	s_waitcnt lgkmcnt(9)
	v_mfma_f32_16x16x32_bf16 v[44:47], v[72:75], v[108:111], v[44:47]
	s_waitcnt vmcnt(0) lgkmcnt(0)
	s_barrier
	s_add_u32 m0, s38, 32768
	s_nop 0
	global_load_lds_dwordx4 v164, s[98:99]
	s_waitcnt lgkmcnt(8)
	v_mfma_f32_16x16x32_bf16 v[48:51], v[76:79], v[96:99], v[48:51]
	s_add_u32 m0, s38, 36864
	s_nop 0
	global_load_lds_dwordx4 v165, s[98:99]
	s_waitcnt lgkmcnt(8)
	v_mfma_f32_16x16x32_bf16 v[52:55], v[76:79], v[100:103], v[52:55]
	s_add_u32 m0, s38, 40960
	s_nop 0
	global_load_lds_dwordx4 v166, s[98:99]
	s_waitcnt lgkmcnt(8)
	v_mfma_f32_16x16x32_bf16 v[56:59], v[76:79], v[104:107], v[56:59]
	s_add_u32 m0, s38, 45056
	s_nop 0
	global_load_lds_dwordx4 v167, s[98:99]
	s_add_u32 s98, s98, 128
	s_addc_u32 s99, s99, 0
	s_waitcnt lgkmcnt(8)
	v_mfma_f32_16x16x32_bf16 v[60:63], v[76:79], v[108:111], v[60:63]
	s_add_u32 m0, s38, 49152
	s_nop 0
	global_load_lds_dwordx4 v164, s[100:101]
	s_waitcnt lgkmcnt(6)
	v_mfma_f32_16x16x32_bf16 v[0:3], v[80:83], v[112:115], v[0:3]
	ds_read_b128 v[64:67], v150 offset:0
	s_add_u32 m0, s38, 53248
	s_nop 0
	global_load_lds_dwordx4 v165, s[100:101]
	s_waitcnt lgkmcnt(6)
	v_mfma_f32_16x16x32_bf16 v[4:7], v[80:83], v[116:119], v[4:7]
	ds_read_b128 v[96:99], v162 offset:16384
	s_add_u32 m0, s38, 57344
	s_nop 0
	global_load_lds_dwordx4 v166, s[100:101]
	s_waitcnt lgkmcnt(6)
	v_mfma_f32_16x16x32_bf16 v[8:11], v[80:83], v[120:123], v[8:11]
	ds_read_b128 v[100:103], v162 offset:18432
	s_add_u32 m0, s38, 61440
	s_nop 0
	global_load_lds_dwordx4 v167, s[100:101]
	s_add_u32 s100, s100, 128
	s_addc_u32 s101, s101, 0
	s_waitcnt lgkmcnt(6)
	v_mfma_f32_16x16x32_bf16 v[12:15], v[80:83], v[124:127], v[12:15]
	ds_read_b128 v[104:107], v162 offset:20480
	s_waitcnt lgkmcnt(6)
	v_mfma_f32_16x16x32_bf16 v[16:19], v[84:87], v[112:115], v[16:19]
	ds_read_b128 v[108:111], v162 offset:22528
	s_waitcnt lgkmcnt(7)
	v_mfma_f32_16x16x32_bf16 v[20:23], v[84:87], v[116:119], v[20:23]
	ds_read_b128 v[68:71], v150 offset:2048
	s_waitcnt lgkmcnt(8)
	v_mfma_f32_16x16x32_bf16 v[24:27], v[84:87], v[120:123], v[24:27]
	ds_read_b128 v[72:75], v150 offset:4096
	s_waitcnt lgkmcnt(9)
	v_mfma_f32_16x16x32_bf16 v[28:31], v[84:87], v[124:127], v[28:31]
	ds_read_b128 v[76:79], v150 offset:6144
	s_waitcnt lgkmcnt(9)
	v_mfma_f32_16x16x32_bf16 v[32:35], v[88:91], v[112:115], v[32:35]
	s_waitcnt lgkmcnt(9)
	v_mfma_f32_16x16x32_bf16 v[36:39], v[88:91], v[116:119], v[36:39]
	s_waitcnt lgkmcnt(9)
	v_mfma_f32_16x16x32_bf16 v[40:43], v[88:91], v[120:123], v[40:43]
	s_waitcnt lgkmcnt(9)
	v_mfma_f32_16x16x32_bf16 v[44:47], v[88:91], v[124:127], v[44:47]
	s_waitcnt lgkmcnt(8)
	v_mfma_f32_16x16x32_bf16 v[48:51], v[92:95], v[112:115], v[48:51]
	s_waitcnt lgkmcnt(8)
	v_mfma_f32_16x16x32_bf16 v[52:55], v[92:95], v[116:119], v[52:55]
	s_waitcnt lgkmcnt(8)
	v_mfma_f32_16x16x32_bf16 v[56:59], v[92:95], v[120:123], v[56:59]
	s_waitcnt lgkmcnt(8)
	v_mfma_f32_16x16x32_bf16 v[60:63], v[92:95], v[124:127], v[60:63]
	s_waitcnt lgkmcnt(6)
	v_mfma_f32_16x16x32_bf16 v[0:3], v[64:67], v[96:99], v[0:3]
	ds_read_b128 v[80:83], v151 offset:0
	s_waitcnt lgkmcnt(6)
	v_mfma_f32_16x16x32_bf16 v[4:7], v[64:67], v[100:103], v[4:7]
	ds_read_b128 v[112:115], v163 offset:16384
	s_waitcnt lgkmcnt(6)
	v_mfma_f32_16x16x32_bf16 v[8:11], v[64:67], v[104:107], v[8:11]
	ds_read_b128 v[116:119], v163 offset:18432
	s_waitcnt lgkmcnt(6)
	v_mfma_f32_16x16x32_bf16 v[12:15], v[64:67], v[108:111], v[12:15]
	ds_read_b128 v[120:123], v163 offset:20480
	s_waitcnt lgkmcnt(6)
	v_mfma_f32_16x16x32_bf16 v[16:19], v[68:71], v[96:99], v[16:19]
	ds_read_b128 v[124:127], v163 offset:22528
	s_waitcnt lgkmcnt(7)
	v_mfma_f32_16x16x32_bf16 v[20:23], v[68:71], v[100:103], v[20:23]
	ds_read_b128 v[84:87], v151 offset:2048
	s_waitcnt lgkmcnt(8)
	v_mfma_f32_16x16x32_bf16 v[24:27], v[68:71], v[104:107], v[24:27]
	ds_read_b128 v[88:91], v151 offset:4096
	s_waitcnt lgkmcnt(9)
	v_mfma_f32_16x16x32_bf16 v[28:31], v[68:71], v[108:111], v[28:31]
	ds_read_b128 v[92:95], v151 offset:6144
	s_waitcnt lgkmcnt(9)
	v_mfma_f32_16x16x32_bf16 v[32:35], v[72:75], v[96:99], v[32:35]
	s_waitcnt lgkmcnt(9)
	v_mfma_f32_16x16x32_bf16 v[36:39], v[72:75], v[100:103], v[36:39]
	s_waitcnt lgkmcnt(9)
	v_mfma_f32_16x16x32_bf16 v[40:43], v[72:75], v[104:107], v[40:43]
	s_waitcnt lgkmcnt(9)
	v_mfma_f32_16x16x32_bf16 v[44:47], v[72:75], v[108:111], v[44:47]
	s_waitcnt vmcnt(0) lgkmcnt(0)
	s_barrier
	s_add_u32 m0, s38, 0
	s_nop 0
	global_load_lds_dwordx4 v164, s[98:99]
	s_waitcnt lgkmcnt(8)
	v_mfma_f32_16x16x32_bf16 v[48:51], v[76:79], v[96:99], v[48:51]
	s_add_u32 m0, s38, 4096
	s_nop 0
	global_load_lds_dwordx4 v165, s[98:99]
	s_waitcnt lgkmcnt(8)
	v_mfma_f32_16x16x32_bf16 v[52:55], v[76:79], v[100:103], v[52:55]
	s_add_u32 m0, s38, 8192
	s_nop 0
	global_load_lds_dwordx4 v166, s[98:99]
	s_waitcnt lgkmcnt(8)
	v_mfma_f32_16x16x32_bf16 v[56:59], v[76:79], v[104:107], v[56:59]
	s_add_u32 m0, s38, 12288
	s_nop 0
	global_load_lds_dwordx4 v167, s[98:99]
	s_add_u32 s98, s98, 128
	s_addc_u32 s99, s99, 0
	s_waitcnt lgkmcnt(8)
	v_mfma_f32_16x16x32_bf16 v[60:63], v[76:79], v[108:111], v[60:63]
	s_add_u32 m0, s38, 16384
	s_nop 0
	global_load_lds_dwordx4 v164, s[100:101]
	s_waitcnt lgkmcnt(6)
	v_mfma_f32_16x16x32_bf16 v[0:3], v[80:83], v[112:115], v[0:3]
	ds_read_b128 v[64:67], v150 offset:32768
	s_add_u32 m0, s38, 20480
	s_nop 0
	global_load_lds_dwordx4 v165, s[100:101]
	s_waitcnt lgkmcnt(6)
	v_mfma_f32_16x16x32_bf16 v[4:7], v[80:83], v[116:119], v[4:7]
	ds_read_b128 v[96:99], v162 offset:49152
	s_add_u32 m0, s38, 24576
	s_nop 0
	global_load_lds_dwordx4 v166, s[100:101]
	s_waitcnt lgkmcnt(6)
	v_mfma_f32_16x16x32_bf16 v[8:11], v[80:83], v[120:123], v[8:11]
	ds_read_b128 v[100:103], v162 offset:51200
	s_add_u32 m0, s38, 28672
	s_nop 0
	global_load_lds_dwordx4 v167, s[100:101]
	s_add_u32 s100, s100, 128
	s_addc_u32 s101, s101, 0
	s_waitcnt lgkmcnt(6)
	v_mfma_f32_16x16x32_bf16 v[12:15], v[80:83], v[124:127], v[12:15]
	ds_read_b128 v[104:107], v162 offset:53248
	s_waitcnt lgkmcnt(6)
	v_mfma_f32_16x16x32_bf16 v[16:19], v[84:87], v[112:115], v[16:19]
	ds_read_b128 v[108:111], v162 offset:55296
	s_waitcnt lgkmcnt(7)
	v_mfma_f32_16x16x32_bf16 v[20:23], v[84:87], v[116:119], v[20:23]
	ds_read_b128 v[68:71], v150 offset:34816
	s_waitcnt lgkmcnt(8)
	v_mfma_f32_16x16x32_bf16 v[24:27], v[84:87], v[120:123], v[24:27]
	ds_read_b128 v[72:75], v150 offset:36864
	s_waitcnt lgkmcnt(9)
	v_mfma_f32_16x16x32_bf16 v[28:31], v[84:87], v[124:127], v[28:31]
	ds_read_b128 v[76:79], v150 offset:38912
	s_waitcnt lgkmcnt(9)
	v_mfma_f32_16x16x32_bf16 v[32:35], v[88:91], v[112:115], v[32:35]
	s_waitcnt lgkmcnt(9)
	v_mfma_f32_16x16x32_bf16 v[36:39], v[88:91], v[116:119], v[36:39]
	s_waitcnt lgkmcnt(9)
	v_mfma_f32_16x16x32_bf16 v[40:43], v[88:91], v[120:123], v[40:43]
	s_waitcnt lgkmcnt(9)
	v_mfma_f32_16x16x32_bf16 v[44:47], v[88:91], v[124:127], v[44:47]
	s_waitcnt lgkmcnt(8)
	v_mfma_f32_16x16x32_bf16 v[48:51], v[92:95], v[112:115], v[48:51]
	s_waitcnt lgkmcnt(8)
	v_mfma_f32_16x16x32_bf16 v[52:55], v[92:95], v[116:119], v[52:55]
	s_waitcnt lgkmcnt(8)
	v_mfma_f32_16x16x32_bf16 v[56:59], v[92:95], v[120:123], v[56:59]
	s_waitcnt lgkmcnt(8)
	v_mfma_f32_16x16x32_bf16 v[60:63], v[92:95], v[124:127], v[60:63]
	s_waitcnt lgkmcnt(6)
	v_mfma_f32_16x16x32_bf16 v[0:3], v[64:67], v[96:99], v[0:3]
	ds_read_b128 v[80:83], v151 offset:32768
	s_waitcnt lgkmcnt(6)
	v_mfma_f32_16x16x32_bf16 v[4:7], v[64:67], v[100:103], v[4:7]
	ds_read_b128 v[112:115], v163 offset:49152
	s_waitcnt lgkmcnt(6)
	v_mfma_f32_16x16x32_bf16 v[8:11], v[64:67], v[104:107], v[8:11]
	ds_read_b128 v[116:119], v163 offset:51200
	s_waitcnt lgkmcnt(6)
	v_mfma_f32_16x16x32_bf16 v[12:15], v[64:67], v[108:111], v[12:15]
	ds_read_b128 v[120:123], v163 offset:53248
	s_waitcnt lgkmcnt(6)
	v_mfma_f32_16x16x32_bf16 v[16:19], v[68:71], v[96:99], v[16:19]
	ds_read_b128 v[124:127], v163 offset:55296
	s_waitcnt lgkmcnt(7)
	v_mfma_f32_16x16x32_bf16 v[20:23], v[68:71], v[100:103], v[20:23]
	ds_read_b128 v[84:87], v151 offset:34816
	s_waitcnt lgkmcnt(8)
	v_mfma_f32_16x16x32_bf16 v[24:27], v[68:71], v[104:107], v[24:27]
	ds_read_b128 v[88:91], v151 offset:36864
	s_waitcnt lgkmcnt(9)
	v_mfma_f32_16x16x32_bf16 v[28:31], v[68:71], v[108:111], v[28:31]
	ds_read_b128 v[92:95], v151 offset:38912
	s_waitcnt lgkmcnt(9)
	v_mfma_f32_16x16x32_bf16 v[32:35], v[72:75], v[96:99], v[32:35]
	s_waitcnt lgkmcnt(9)
	v_mfma_f32_16x16x32_bf16 v[36:39], v[72:75], v[100:103], v[36:39]
	s_waitcnt lgkmcnt(9)
	v_mfma_f32_16x16x32_bf16 v[40:43], v[72:75], v[104:107], v[40:43]
	s_waitcnt lgkmcnt(9)
	v_mfma_f32_16x16x32_bf16 v[44:47], v[72:75], v[108:111], v[44:47]
	s_waitcnt vmcnt(0) lgkmcnt(0)
	s_barrier
	s_add_u32 m0, s38, 32768
	s_nop 0
	global_load_lds_dwordx4 v164, s[98:99]
	s_waitcnt lgkmcnt(8)
	v_mfma_f32_16x16x32_bf16 v[48:51], v[76:79], v[96:99], v[48:51]
	s_add_u32 m0, s38, 36864
	s_nop 0
	global_load_lds_dwordx4 v165, s[98:99]
	s_waitcnt lgkmcnt(8)
	v_mfma_f32_16x16x32_bf16 v[52:55], v[76:79], v[100:103], v[52:55]
	s_add_u32 m0, s38, 40960
	s_nop 0
	global_load_lds_dwordx4 v166, s[98:99]
	s_waitcnt lgkmcnt(8)
	v_mfma_f32_16x16x32_bf16 v[56:59], v[76:79], v[104:107], v[56:59]
	s_add_u32 m0, s38, 45056
	s_nop 0
	global_load_lds_dwordx4 v167, s[98:99]
	s_add_u32 s98, s98, 128
	s_addc_u32 s99, s99, 0
	s_waitcnt lgkmcnt(8)
	v_mfma_f32_16x16x32_bf16 v[60:63], v[76:79], v[108:111], v[60:63]
	s_add_u32 m0, s38, 49152
	s_nop 0
	global_load_lds_dwordx4 v164, s[100:101]
	s_waitcnt lgkmcnt(6)
	v_mfma_f32_16x16x32_bf16 v[0:3], v[80:83], v[112:115], v[0:3]
	ds_read_b128 v[64:67], v150 offset:0
	s_add_u32 m0, s38, 53248
	s_nop 0
	global_load_lds_dwordx4 v165, s[100:101]
	s_waitcnt lgkmcnt(6)
	v_mfma_f32_16x16x32_bf16 v[4:7], v[80:83], v[116:119], v[4:7]
	ds_read_b128 v[96:99], v162 offset:16384
	s_add_u32 m0, s38, 57344
	s_nop 0
	global_load_lds_dwordx4 v166, s[100:101]
	s_waitcnt lgkmcnt(6)
	v_mfma_f32_16x16x32_bf16 v[8:11], v[80:83], v[120:123], v[8:11]
	ds_read_b128 v[100:103], v162 offset:18432
	s_add_u32 m0, s38, 61440
	s_nop 0
	global_load_lds_dwordx4 v167, s[100:101]
	s_add_u32 s100, s100, 128
	s_addc_u32 s101, s101, 0
	s_waitcnt lgkmcnt(6)
	v_mfma_f32_16x16x32_bf16 v[12:15], v[80:83], v[124:127], v[12:15]
	ds_read_b128 v[104:107], v162 offset:20480
	s_waitcnt lgkmcnt(6)
	v_mfma_f32_16x16x32_bf16 v[16:19], v[84:87], v[112:115], v[16:19]
	ds_read_b128 v[108:111], v162 offset:22528
	s_waitcnt lgkmcnt(7)
	v_mfma_f32_16x16x32_bf16 v[20:23], v[84:87], v[116:119], v[20:23]
	ds_read_b128 v[68:71], v150 offset:2048
	s_waitcnt lgkmcnt(8)
	v_mfma_f32_16x16x32_bf16 v[24:27], v[84:87], v[120:123], v[24:27]
	ds_read_b128 v[72:75], v150 offset:4096
	s_waitcnt lgkmcnt(9)
	v_mfma_f32_16x16x32_bf16 v[28:31], v[84:87], v[124:127], v[28:31]
	ds_read_b128 v[76:79], v150 offset:6144
	s_waitcnt lgkmcnt(9)
	v_mfma_f32_16x16x32_bf16 v[32:35], v[88:91], v[112:115], v[32:35]
	s_waitcnt lgkmcnt(9)
	v_mfma_f32_16x16x32_bf16 v[36:39], v[88:91], v[116:119], v[36:39]
	s_waitcnt lgkmcnt(9)
	v_mfma_f32_16x16x32_bf16 v[40:43], v[88:91], v[120:123], v[40:43]
	s_waitcnt lgkmcnt(9)
	v_mfma_f32_16x16x32_bf16 v[44:47], v[88:91], v[124:127], v[44:47]
	s_waitcnt lgkmcnt(8)
	v_mfma_f32_16x16x32_bf16 v[48:51], v[92:95], v[112:115], v[48:51]
	s_waitcnt lgkmcnt(8)
	v_mfma_f32_16x16x32_bf16 v[52:55], v[92:95], v[116:119], v[52:55]
	s_waitcnt lgkmcnt(8)
	v_mfma_f32_16x16x32_bf16 v[56:59], v[92:95], v[120:123], v[56:59]
	s_waitcnt lgkmcnt(8)
	v_mfma_f32_16x16x32_bf16 v[60:63], v[92:95], v[124:127], v[60:63]
	s_waitcnt lgkmcnt(6)
	v_mfma_f32_16x16x32_bf16 v[0:3], v[64:67], v[96:99], v[0:3]
	ds_read_b128 v[80:83], v151 offset:0
	s_waitcnt lgkmcnt(6)
	v_mfma_f32_16x16x32_bf16 v[4:7], v[64:67], v[100:103], v[4:7]
	ds_read_b128 v[112:115], v163 offset:16384
	s_waitcnt lgkmcnt(6)
	v_mfma_f32_16x16x32_bf16 v[8:11], v[64:67], v[104:107], v[8:11]
	ds_read_b128 v[116:119], v163 offset:18432
	s_waitcnt lgkmcnt(6)
	v_mfma_f32_16x16x32_bf16 v[12:15], v[64:67], v[108:111], v[12:15]
	ds_read_b128 v[120:123], v163 offset:20480
	s_waitcnt lgkmcnt(6)
	v_mfma_f32_16x16x32_bf16 v[16:19], v[68:71], v[96:99], v[16:19]
	ds_read_b128 v[124:127], v163 offset:22528
	s_waitcnt lgkmcnt(7)
	v_mfma_f32_16x16x32_bf16 v[20:23], v[68:71], v[100:103], v[20:23]
	ds_read_b128 v[84:87], v151 offset:2048
	s_waitcnt lgkmcnt(8)
	v_mfma_f32_16x16x32_bf16 v[24:27], v[68:71], v[104:107], v[24:27]
	ds_read_b128 v[88:91], v151 offset:4096
	s_waitcnt lgkmcnt(9)
	v_mfma_f32_16x16x32_bf16 v[28:31], v[68:71], v[108:111], v[28:31]
	ds_read_b128 v[92:95], v151 offset:6144
	s_waitcnt lgkmcnt(9)
	v_mfma_f32_16x16x32_bf16 v[32:35], v[72:75], v[96:99], v[32:35]
	s_waitcnt lgkmcnt(9)
	v_mfma_f32_16x16x32_bf16 v[36:39], v[72:75], v[100:103], v[36:39]
	s_waitcnt lgkmcnt(9)
	v_mfma_f32_16x16x32_bf16 v[40:43], v[72:75], v[104:107], v[40:43]
	s_waitcnt lgkmcnt(9)
	v_mfma_f32_16x16x32_bf16 v[44:47], v[72:75], v[108:111], v[44:47]
	s_waitcnt vmcnt(0) lgkmcnt(0)
	s_barrier
	s_add_u32 m0, s38, 0
	s_nop 0
	global_load_lds_dwordx4 v164, s[98:99]
	s_waitcnt lgkmcnt(8)
	v_mfma_f32_16x16x32_bf16 v[48:51], v[76:79], v[96:99], v[48:51]
	s_add_u32 m0, s38, 4096
	s_nop 0
	global_load_lds_dwordx4 v165, s[98:99]
	s_waitcnt lgkmcnt(8)
	v_mfma_f32_16x16x32_bf16 v[52:55], v[76:79], v[100:103], v[52:55]
	s_add_u32 m0, s38, 8192
	s_nop 0
	global_load_lds_dwordx4 v166, s[98:99]
	s_waitcnt lgkmcnt(8)
	v_mfma_f32_16x16x32_bf16 v[56:59], v[76:79], v[104:107], v[56:59]
	s_add_u32 m0, s38, 12288
	s_nop 0
	global_load_lds_dwordx4 v167, s[98:99]
	s_add_u32 s98, s98, 128
	s_addc_u32 s99, s99, 0
	s_waitcnt lgkmcnt(8)
	v_mfma_f32_16x16x32_bf16 v[60:63], v[76:79], v[108:111], v[60:63]
	s_add_u32 m0, s38, 16384
	s_nop 0
	global_load_lds_dwordx4 v164, s[100:101]
	s_waitcnt lgkmcnt(6)
	v_mfma_f32_16x16x32_bf16 v[0:3], v[80:83], v[112:115], v[0:3]
	ds_read_b128 v[64:67], v150 offset:32768
	s_add_u32 m0, s38, 20480
	s_nop 0
	global_load_lds_dwordx4 v165, s[100:101]
	s_waitcnt lgkmcnt(6)
	v_mfma_f32_16x16x32_bf16 v[4:7], v[80:83], v[116:119], v[4:7]
	ds_read_b128 v[96:99], v162 offset:49152
	s_add_u32 m0, s38, 24576
	s_nop 0
	global_load_lds_dwordx4 v166, s[100:101]
	s_waitcnt lgkmcnt(6)
	v_mfma_f32_16x16x32_bf16 v[8:11], v[80:83], v[120:123], v[8:11]
	ds_read_b128 v[100:103], v162 offset:51200
	s_add_u32 m0, s38, 28672
	s_nop 0
	global_load_lds_dwordx4 v167, s[100:101]
	s_add_u32 s100, s100, 128
	s_addc_u32 s101, s101, 0
	s_waitcnt lgkmcnt(6)
	v_mfma_f32_16x16x32_bf16 v[12:15], v[80:83], v[124:127], v[12:15]
	ds_read_b128 v[104:107], v162 offset:53248
	s_waitcnt lgkmcnt(6)
	v_mfma_f32_16x16x32_bf16 v[16:19], v[84:87], v[112:115], v[16:19]
	ds_read_b128 v[108:111], v162 offset:55296
	s_waitcnt lgkmcnt(7)
	v_mfma_f32_16x16x32_bf16 v[20:23], v[84:87], v[116:119], v[20:23]
	ds_read_b128 v[68:71], v150 offset:34816
	s_waitcnt lgkmcnt(8)
	v_mfma_f32_16x16x32_bf16 v[24:27], v[84:87], v[120:123], v[24:27]
	ds_read_b128 v[72:75], v150 offset:36864
	s_waitcnt lgkmcnt(9)
	v_mfma_f32_16x16x32_bf16 v[28:31], v[84:87], v[124:127], v[28:31]
	ds_read_b128 v[76:79], v150 offset:38912
	s_waitcnt lgkmcnt(9)
	v_mfma_f32_16x16x32_bf16 v[32:35], v[88:91], v[112:115], v[32:35]
	s_waitcnt lgkmcnt(9)
	v_mfma_f32_16x16x32_bf16 v[36:39], v[88:91], v[116:119], v[36:39]
	s_waitcnt lgkmcnt(9)
	v_mfma_f32_16x16x32_bf16 v[40:43], v[88:91], v[120:123], v[40:43]
	s_waitcnt lgkmcnt(9)
	v_mfma_f32_16x16x32_bf16 v[44:47], v[88:91], v[124:127], v[44:47]
	s_waitcnt lgkmcnt(8)
	v_mfma_f32_16x16x32_bf16 v[48:51], v[92:95], v[112:115], v[48:51]
	s_waitcnt lgkmcnt(8)
	v_mfma_f32_16x16x32_bf16 v[52:55], v[92:95], v[116:119], v[52:55]
	s_waitcnt lgkmcnt(8)
	v_mfma_f32_16x16x32_bf16 v[56:59], v[92:95], v[120:123], v[56:59]
	s_waitcnt lgkmcnt(8)
	v_mfma_f32_16x16x32_bf16 v[60:63], v[92:95], v[124:127], v[60:63]
	s_waitcnt lgkmcnt(6)
	v_mfma_f32_16x16x32_bf16 v[0:3], v[64:67], v[96:99], v[0:3]
	ds_read_b128 v[80:83], v151 offset:32768
	s_waitcnt lgkmcnt(6)
	v_mfma_f32_16x16x32_bf16 v[4:7], v[64:67], v[100:103], v[4:7]
	ds_read_b128 v[112:115], v163 offset:49152
	s_waitcnt lgkmcnt(6)
	v_mfma_f32_16x16x32_bf16 v[8:11], v[64:67], v[104:107], v[8:11]
	ds_read_b128 v[116:119], v163 offset:51200
	s_waitcnt lgkmcnt(6)
	v_mfma_f32_16x16x32_bf16 v[12:15], v[64:67], v[108:111], v[12:15]
	ds_read_b128 v[120:123], v163 offset:53248
	s_waitcnt lgkmcnt(6)
	v_mfma_f32_16x16x32_bf16 v[16:19], v[68:71], v[96:99], v[16:19]
	ds_read_b128 v[124:127], v163 offset:55296
	s_waitcnt lgkmcnt(7)
	v_mfma_f32_16x16x32_bf16 v[20:23], v[68:71], v[100:103], v[20:23]
	ds_read_b128 v[84:87], v151 offset:34816
	s_waitcnt lgkmcnt(8)
	v_mfma_f32_16x16x32_bf16 v[24:27], v[68:71], v[104:107], v[24:27]
	ds_read_b128 v[88:91], v151 offset:36864
	s_waitcnt lgkmcnt(9)
	v_mfma_f32_16x16x32_bf16 v[28:31], v[68:71], v[108:111], v[28:31]
	ds_read_b128 v[92:95], v151 offset:38912
	s_waitcnt lgkmcnt(9)
	v_mfma_f32_16x16x32_bf16 v[32:35], v[72:75], v[96:99], v[32:35]
	s_waitcnt lgkmcnt(9)
	v_mfma_f32_16x16x32_bf16 v[36:39], v[72:75], v[100:103], v[36:39]
	s_waitcnt lgkmcnt(9)
	v_mfma_f32_16x16x32_bf16 v[40:43], v[72:75], v[104:107], v[40:43]
	s_waitcnt lgkmcnt(9)
	v_mfma_f32_16x16x32_bf16 v[44:47], v[72:75], v[108:111], v[44:47]
	s_waitcnt vmcnt(0) lgkmcnt(0)
	s_barrier
	s_add_u32 m0, s38, 32768
	s_nop 0
	global_load_lds_dwordx4 v164, s[98:99]
	s_waitcnt lgkmcnt(8)
	v_mfma_f32_16x16x32_bf16 v[48:51], v[76:79], v[96:99], v[48:51]
	s_add_u32 m0, s38, 36864
	s_nop 0
	global_load_lds_dwordx4 v165, s[98:99]
	s_waitcnt lgkmcnt(8)
	v_mfma_f32_16x16x32_bf16 v[52:55], v[76:79], v[100:103], v[52:55]
	s_add_u32 m0, s38, 40960
	s_nop 0
	global_load_lds_dwordx4 v166, s[98:99]
	s_waitcnt lgkmcnt(8)
	v_mfma_f32_16x16x32_bf16 v[56:59], v[76:79], v[104:107], v[56:59]
	s_add_u32 m0, s38, 45056
	s_nop 0
	global_load_lds_dwordx4 v167, s[98:99]
	s_add_u32 s98, s98, 128
	s_addc_u32 s99, s99, 0
	s_waitcnt lgkmcnt(8)
	v_mfma_f32_16x16x32_bf16 v[60:63], v[76:79], v[108:111], v[60:63]
	s_add_u32 m0, s38, 49152
	s_nop 0
	global_load_lds_dwordx4 v164, s[100:101]
	s_waitcnt lgkmcnt(6)
	v_mfma_f32_16x16x32_bf16 v[0:3], v[80:83], v[112:115], v[0:3]
	ds_read_b128 v[64:67], v150 offset:0
	s_add_u32 m0, s38, 53248
	s_nop 0
	global_load_lds_dwordx4 v165, s[100:101]
	s_waitcnt lgkmcnt(6)
	v_mfma_f32_16x16x32_bf16 v[4:7], v[80:83], v[116:119], v[4:7]
	ds_read_b128 v[96:99], v162 offset:16384
	s_add_u32 m0, s38, 57344
	s_nop 0
	global_load_lds_dwordx4 v166, s[100:101]
	s_waitcnt lgkmcnt(6)
	v_mfma_f32_16x16x32_bf16 v[8:11], v[80:83], v[120:123], v[8:11]
	ds_read_b128 v[100:103], v162 offset:18432
	s_add_u32 m0, s38, 61440
	s_nop 0
	global_load_lds_dwordx4 v167, s[100:101]
	s_add_u32 s100, s100, 128
	s_addc_u32 s101, s101, 0
	s_waitcnt lgkmcnt(6)
	v_mfma_f32_16x16x32_bf16 v[12:15], v[80:83], v[124:127], v[12:15]
	ds_read_b128 v[104:107], v162 offset:20480
	s_waitcnt lgkmcnt(6)
	v_mfma_f32_16x16x32_bf16 v[16:19], v[84:87], v[112:115], v[16:19]
	ds_read_b128 v[108:111], v162 offset:22528
	s_waitcnt lgkmcnt(7)
	v_mfma_f32_16x16x32_bf16 v[20:23], v[84:87], v[116:119], v[20:23]
	ds_read_b128 v[68:71], v150 offset:2048
	s_waitcnt lgkmcnt(8)
	v_mfma_f32_16x16x32_bf16 v[24:27], v[84:87], v[120:123], v[24:27]
	ds_read_b128 v[72:75], v150 offset:4096
	s_waitcnt lgkmcnt(9)
	v_mfma_f32_16x16x32_bf16 v[28:31], v[84:87], v[124:127], v[28:31]
	ds_read_b128 v[76:79], v150 offset:6144
	s_waitcnt lgkmcnt(9)
	v_mfma_f32_16x16x32_bf16 v[32:35], v[88:91], v[112:115], v[32:35]
	s_waitcnt lgkmcnt(9)
	v_mfma_f32_16x16x32_bf16 v[36:39], v[88:91], v[116:119], v[36:39]
	s_waitcnt lgkmcnt(9)
	v_mfma_f32_16x16x32_bf16 v[40:43], v[88:91], v[120:123], v[40:43]
	s_waitcnt lgkmcnt(9)
	v_mfma_f32_16x16x32_bf16 v[44:47], v[88:91], v[124:127], v[44:47]
	s_waitcnt lgkmcnt(8)
	v_mfma_f32_16x16x32_bf16 v[48:51], v[92:95], v[112:115], v[48:51]
	s_waitcnt lgkmcnt(8)
	v_mfma_f32_16x16x32_bf16 v[52:55], v[92:95], v[116:119], v[52:55]
	s_waitcnt lgkmcnt(8)
	v_mfma_f32_16x16x32_bf16 v[56:59], v[92:95], v[120:123], v[56:59]
	s_waitcnt lgkmcnt(8)
	v_mfma_f32_16x16x32_bf16 v[60:63], v[92:95], v[124:127], v[60:63]
	s_waitcnt lgkmcnt(6)
	v_mfma_f32_16x16x32_bf16 v[0:3], v[64:67], v[96:99], v[0:3]
	ds_read_b128 v[80:83], v151 offset:0
	s_waitcnt lgkmcnt(6)
	v_mfma_f32_16x16x32_bf16 v[4:7], v[64:67], v[100:103], v[4:7]
	ds_read_b128 v[112:115], v163 offset:16384
	s_waitcnt lgkmcnt(6)
	v_mfma_f32_16x16x32_bf16 v[8:11], v[64:67], v[104:107], v[8:11]
	ds_read_b128 v[116:119], v163 offset:18432
	s_waitcnt lgkmcnt(6)
	v_mfma_f32_16x16x32_bf16 v[12:15], v[64:67], v[108:111], v[12:15]
	ds_read_b128 v[120:123], v163 offset:20480
	s_waitcnt lgkmcnt(6)
	v_mfma_f32_16x16x32_bf16 v[16:19], v[68:71], v[96:99], v[16:19]
	ds_read_b128 v[124:127], v163 offset:22528
	s_waitcnt lgkmcnt(7)
	v_mfma_f32_16x16x32_bf16 v[20:23], v[68:71], v[100:103], v[20:23]
	ds_read_b128 v[84:87], v151 offset:2048
	s_waitcnt lgkmcnt(8)
	v_mfma_f32_16x16x32_bf16 v[24:27], v[68:71], v[104:107], v[24:27]
	ds_read_b128 v[88:91], v151 offset:4096
	s_waitcnt lgkmcnt(9)
	v_mfma_f32_16x16x32_bf16 v[28:31], v[68:71], v[108:111], v[28:31]
	ds_read_b128 v[92:95], v151 offset:6144
	s_waitcnt lgkmcnt(9)
	v_mfma_f32_16x16x32_bf16 v[32:35], v[72:75], v[96:99], v[32:35]
	s_waitcnt lgkmcnt(9)
	v_mfma_f32_16x16x32_bf16 v[36:39], v[72:75], v[100:103], v[36:39]
	s_waitcnt lgkmcnt(9)
	v_mfma_f32_16x16x32_bf16 v[40:43], v[72:75], v[104:107], v[40:43]
	s_waitcnt lgkmcnt(9)
	v_mfma_f32_16x16x32_bf16 v[44:47], v[72:75], v[108:111], v[44:47]
	s_waitcnt vmcnt(0) lgkmcnt(0)
	s_barrier
	s_add_u32 m0, s38, 0
	s_nop 0
	global_load_lds_dwordx4 v164, s[98:99]
	s_waitcnt lgkmcnt(8)
	v_mfma_f32_16x16x32_bf16 v[48:51], v[76:79], v[96:99], v[48:51]
	s_add_u32 m0, s38, 4096
	s_nop 0
	global_load_lds_dwordx4 v165, s[98:99]
	s_waitcnt lgkmcnt(8)
	v_mfma_f32_16x16x32_bf16 v[52:55], v[76:79], v[100:103], v[52:55]
	s_add_u32 m0, s38, 8192
	s_nop 0
	global_load_lds_dwordx4 v166, s[98:99]
	s_waitcnt lgkmcnt(8)
	v_mfma_f32_16x16x32_bf16 v[56:59], v[76:79], v[104:107], v[56:59]
	s_add_u32 m0, s38, 12288
	s_nop 0
	global_load_lds_dwordx4 v167, s[98:99]
	s_add_u32 s98, s98, 128
	s_addc_u32 s99, s99, 0
	s_waitcnt lgkmcnt(8)
	v_mfma_f32_16x16x32_bf16 v[60:63], v[76:79], v[108:111], v[60:63]
	s_add_u32 m0, s38, 16384
	s_nop 0
	global_load_lds_dwordx4 v164, s[100:101]
	s_waitcnt lgkmcnt(6)
	v_mfma_f32_16x16x32_bf16 v[0:3], v[80:83], v[112:115], v[0:3]
	ds_read_b128 v[64:67], v150 offset:32768
	s_add_u32 m0, s38, 20480
	s_nop 0
	global_load_lds_dwordx4 v165, s[100:101]
	s_waitcnt lgkmcnt(6)
	v_mfma_f32_16x16x32_bf16 v[4:7], v[80:83], v[116:119], v[4:7]
	ds_read_b128 v[96:99], v162 offset:49152
	s_add_u32 m0, s38, 24576
	s_nop 0
	global_load_lds_dwordx4 v166, s[100:101]
	s_waitcnt lgkmcnt(6)
	v_mfma_f32_16x16x32_bf16 v[8:11], v[80:83], v[120:123], v[8:11]
	ds_read_b128 v[100:103], v162 offset:51200
	s_add_u32 m0, s38, 28672
	s_nop 0
	global_load_lds_dwordx4 v167, s[100:101]
	s_add_u32 s100, s100, 128
	s_addc_u32 s101, s101, 0
	s_waitcnt lgkmcnt(6)
	v_mfma_f32_16x16x32_bf16 v[12:15], v[80:83], v[124:127], v[12:15]
	ds_read_b128 v[104:107], v162 offset:53248
	s_waitcnt lgkmcnt(6)
	v_mfma_f32_16x16x32_bf16 v[16:19], v[84:87], v[112:115], v[16:19]
	ds_read_b128 v[108:111], v162 offset:55296
	s_waitcnt lgkmcnt(7)
	v_mfma_f32_16x16x32_bf16 v[20:23], v[84:87], v[116:119], v[20:23]
	ds_read_b128 v[68:71], v150 offset:34816
	s_waitcnt lgkmcnt(8)
	v_mfma_f32_16x16x32_bf16 v[24:27], v[84:87], v[120:123], v[24:27]
	ds_read_b128 v[72:75], v150 offset:36864
	s_waitcnt lgkmcnt(9)
	v_mfma_f32_16x16x32_bf16 v[28:31], v[84:87], v[124:127], v[28:31]
	ds_read_b128 v[76:79], v150 offset:38912
	s_waitcnt lgkmcnt(9)
	v_mfma_f32_16x16x32_bf16 v[32:35], v[88:91], v[112:115], v[32:35]
	s_waitcnt lgkmcnt(9)
	v_mfma_f32_16x16x32_bf16 v[36:39], v[88:91], v[116:119], v[36:39]
	s_waitcnt lgkmcnt(9)
	v_mfma_f32_16x16x32_bf16 v[40:43], v[88:91], v[120:123], v[40:43]
	s_waitcnt lgkmcnt(9)
	v_mfma_f32_16x16x32_bf16 v[44:47], v[88:91], v[124:127], v[44:47]
	s_waitcnt lgkmcnt(8)
	v_mfma_f32_16x16x32_bf16 v[48:51], v[92:95], v[112:115], v[48:51]
	s_waitcnt lgkmcnt(8)
	v_mfma_f32_16x16x32_bf16 v[52:55], v[92:95], v[116:119], v[52:55]
	s_waitcnt lgkmcnt(8)
	v_mfma_f32_16x16x32_bf16 v[56:59], v[92:95], v[120:123], v[56:59]
	s_waitcnt lgkmcnt(8)
	v_mfma_f32_16x16x32_bf16 v[60:63], v[92:95], v[124:127], v[60:63]
	s_waitcnt lgkmcnt(6)
	v_mfma_f32_16x16x32_bf16 v[0:3], v[64:67], v[96:99], v[0:3]
	ds_read_b128 v[80:83], v151 offset:32768
	s_waitcnt lgkmcnt(6)
	v_mfma_f32_16x16x32_bf16 v[4:7], v[64:67], v[100:103], v[4:7]
	ds_read_b128 v[112:115], v163 offset:49152
	s_waitcnt lgkmcnt(6)
	v_mfma_f32_16x16x32_bf16 v[8:11], v[64:67], v[104:107], v[8:11]
	ds_read_b128 v[116:119], v163 offset:51200
	s_waitcnt lgkmcnt(6)
	v_mfma_f32_16x16x32_bf16 v[12:15], v[64:67], v[108:111], v[12:15]
	ds_read_b128 v[120:123], v163 offset:53248
	s_waitcnt lgkmcnt(6)
	v_mfma_f32_16x16x32_bf16 v[16:19], v[68:71], v[96:99], v[16:19]
	ds_read_b128 v[124:127], v163 offset:55296
	s_waitcnt lgkmcnt(7)
	v_mfma_f32_16x16x32_bf16 v[20:23], v[68:71], v[100:103], v[20:23]
	ds_read_b128 v[84:87], v151 offset:34816
	s_waitcnt lgkmcnt(8)
	v_mfma_f32_16x16x32_bf16 v[24:27], v[68:71], v[104:107], v[24:27]
	ds_read_b128 v[88:91], v151 offset:36864
	s_waitcnt lgkmcnt(9)
	v_mfma_f32_16x16x32_bf16 v[28:31], v[68:71], v[108:111], v[28:31]
	ds_read_b128 v[92:95], v151 offset:38912
	s_waitcnt lgkmcnt(9)
	v_mfma_f32_16x16x32_bf16 v[32:35], v[72:75], v[96:99], v[32:35]
	s_waitcnt lgkmcnt(9)
	v_mfma_f32_16x16x32_bf16 v[36:39], v[72:75], v[100:103], v[36:39]
	s_waitcnt lgkmcnt(9)
	v_mfma_f32_16x16x32_bf16 v[40:43], v[72:75], v[104:107], v[40:43]
	s_waitcnt lgkmcnt(9)
	v_mfma_f32_16x16x32_bf16 v[44:47], v[72:75], v[108:111], v[44:47]
	s_waitcnt vmcnt(0) lgkmcnt(0)
	s_barrier
	s_add_u32 m0, s38, 32768
	s_nop 0
	global_load_lds_dwordx4 v164, s[98:99]
	s_waitcnt lgkmcnt(8)
	v_mfma_f32_16x16x32_bf16 v[48:51], v[76:79], v[96:99], v[48:51]
	s_add_u32 m0, s38, 36864
	s_nop 0
	global_load_lds_dwordx4 v165, s[98:99]
	s_waitcnt lgkmcnt(8)
	v_mfma_f32_16x16x32_bf16 v[52:55], v[76:79], v[100:103], v[52:55]
	s_add_u32 m0, s38, 40960
	s_nop 0
	global_load_lds_dwordx4 v166, s[98:99]
	s_waitcnt lgkmcnt(8)
	v_mfma_f32_16x16x32_bf16 v[56:59], v[76:79], v[104:107], v[56:59]
	s_add_u32 m0, s38, 45056
	s_nop 0
	global_load_lds_dwordx4 v167, s[98:99]
	s_add_u32 s98, s98, 128
	s_addc_u32 s99, s99, 0
	s_waitcnt lgkmcnt(8)
	v_mfma_f32_16x16x32_bf16 v[60:63], v[76:79], v[108:111], v[60:63]
	s_add_u32 m0, s38, 49152
	s_nop 0
	global_load_lds_dwordx4 v164, s[100:101]
	s_waitcnt lgkmcnt(6)
	v_mfma_f32_16x16x32_bf16 v[0:3], v[80:83], v[112:115], v[0:3]
	ds_read_b128 v[64:67], v150 offset:0
	s_add_u32 m0, s38, 53248
	s_nop 0
	global_load_lds_dwordx4 v165, s[100:101]
	s_waitcnt lgkmcnt(6)
	v_mfma_f32_16x16x32_bf16 v[4:7], v[80:83], v[116:119], v[4:7]
	ds_read_b128 v[96:99], v162 offset:16384
	s_add_u32 m0, s38, 57344
	s_nop 0
	global_load_lds_dwordx4 v166, s[100:101]
	s_waitcnt lgkmcnt(6)
	v_mfma_f32_16x16x32_bf16 v[8:11], v[80:83], v[120:123], v[8:11]
	ds_read_b128 v[100:103], v162 offset:18432
	s_add_u32 m0, s38, 61440
	s_nop 0
	global_load_lds_dwordx4 v167, s[100:101]
	s_add_u32 s100, s100, 128
	s_addc_u32 s101, s101, 0
	s_waitcnt lgkmcnt(6)
	v_mfma_f32_16x16x32_bf16 v[12:15], v[80:83], v[124:127], v[12:15]
	ds_read_b128 v[104:107], v162 offset:20480
	s_waitcnt lgkmcnt(6)
	v_mfma_f32_16x16x32_bf16 v[16:19], v[84:87], v[112:115], v[16:19]
	ds_read_b128 v[108:111], v162 offset:22528
	s_waitcnt lgkmcnt(7)
	v_mfma_f32_16x16x32_bf16 v[20:23], v[84:87], v[116:119], v[20:23]
	ds_read_b128 v[68:71], v150 offset:2048
	s_waitcnt lgkmcnt(8)
	v_mfma_f32_16x16x32_bf16 v[24:27], v[84:87], v[120:123], v[24:27]
	ds_read_b128 v[72:75], v150 offset:4096
	s_waitcnt lgkmcnt(9)
	v_mfma_f32_16x16x32_bf16 v[28:31], v[84:87], v[124:127], v[28:31]
	ds_read_b128 v[76:79], v150 offset:6144
	s_waitcnt lgkmcnt(9)
	v_mfma_f32_16x16x32_bf16 v[32:35], v[88:91], v[112:115], v[32:35]
	s_waitcnt lgkmcnt(9)
	v_mfma_f32_16x16x32_bf16 v[36:39], v[88:91], v[116:119], v[36:39]
	s_waitcnt lgkmcnt(9)
	v_mfma_f32_16x16x32_bf16 v[40:43], v[88:91], v[120:123], v[40:43]
	s_waitcnt lgkmcnt(9)
	v_mfma_f32_16x16x32_bf16 v[44:47], v[88:91], v[124:127], v[44:47]
	s_waitcnt lgkmcnt(8)
	v_mfma_f32_16x16x32_bf16 v[48:51], v[92:95], v[112:115], v[48:51]
	s_waitcnt lgkmcnt(8)
	v_mfma_f32_16x16x32_bf16 v[52:55], v[92:95], v[116:119], v[52:55]
	s_waitcnt lgkmcnt(8)
	v_mfma_f32_16x16x32_bf16 v[56:59], v[92:95], v[120:123], v[56:59]
	s_waitcnt lgkmcnt(8)
	v_mfma_f32_16x16x32_bf16 v[60:63], v[92:95], v[124:127], v[60:63]
	s_waitcnt lgkmcnt(6)
	v_mfma_f32_16x16x32_bf16 v[0:3], v[64:67], v[96:99], v[0:3]
	ds_read_b128 v[80:83], v151 offset:0
	s_waitcnt lgkmcnt(6)
	v_mfma_f32_16x16x32_bf16 v[4:7], v[64:67], v[100:103], v[4:7]
	ds_read_b128 v[112:115], v163 offset:16384
	s_waitcnt lgkmcnt(6)
	v_mfma_f32_16x16x32_bf16 v[8:11], v[64:67], v[104:107], v[8:11]
	ds_read_b128 v[116:119], v163 offset:18432
	s_waitcnt lgkmcnt(6)
	v_mfma_f32_16x16x32_bf16 v[12:15], v[64:67], v[108:111], v[12:15]
	ds_read_b128 v[120:123], v163 offset:20480
	s_waitcnt lgkmcnt(6)
	v_mfma_f32_16x16x32_bf16 v[16:19], v[68:71], v[96:99], v[16:19]
	ds_read_b128 v[124:127], v163 offset:22528
	s_waitcnt lgkmcnt(7)
	v_mfma_f32_16x16x32_bf16 v[20:23], v[68:71], v[100:103], v[20:23]
	ds_read_b128 v[84:87], v151 offset:2048
	s_waitcnt lgkmcnt(8)
	v_mfma_f32_16x16x32_bf16 v[24:27], v[68:71], v[104:107], v[24:27]
	ds_read_b128 v[88:91], v151 offset:4096
	s_waitcnt lgkmcnt(9)
	v_mfma_f32_16x16x32_bf16 v[28:31], v[68:71], v[108:111], v[28:31]
	ds_read_b128 v[92:95], v151 offset:6144
	s_waitcnt lgkmcnt(9)
	v_mfma_f32_16x16x32_bf16 v[32:35], v[72:75], v[96:99], v[32:35]
	s_waitcnt lgkmcnt(9)
	v_mfma_f32_16x16x32_bf16 v[36:39], v[72:75], v[100:103], v[36:39]
	s_waitcnt lgkmcnt(9)
	v_mfma_f32_16x16x32_bf16 v[40:43], v[72:75], v[104:107], v[40:43]
	s_waitcnt lgkmcnt(9)
	v_mfma_f32_16x16x32_bf16 v[44:47], v[72:75], v[108:111], v[44:47]
	s_waitcnt vmcnt(0) lgkmcnt(0)
	s_barrier
	s_add_u32 m0, s38, 0
	s_nop 0
	global_load_lds_dwordx4 v164, s[98:99]
	s_waitcnt lgkmcnt(8)
	v_mfma_f32_16x16x32_bf16 v[48:51], v[76:79], v[96:99], v[48:51]
	s_add_u32 m0, s38, 4096
	s_nop 0
	global_load_lds_dwordx4 v165, s[98:99]
	s_waitcnt lgkmcnt(8)
	v_mfma_f32_16x16x32_bf16 v[52:55], v[76:79], v[100:103], v[52:55]
	s_add_u32 m0, s38, 8192
	s_nop 0
	global_load_lds_dwordx4 v166, s[98:99]
	s_waitcnt lgkmcnt(8)
	v_mfma_f32_16x16x32_bf16 v[56:59], v[76:79], v[104:107], v[56:59]
	s_add_u32 m0, s38, 12288
	s_nop 0
	global_load_lds_dwordx4 v167, s[98:99]
	s_add_u32 s98, s98, 128
	s_addc_u32 s99, s99, 0
	s_waitcnt lgkmcnt(8)
	v_mfma_f32_16x16x32_bf16 v[60:63], v[76:79], v[108:111], v[60:63]
	s_add_u32 m0, s38, 16384
	s_nop 0
	global_load_lds_dwordx4 v164, s[100:101]
	s_waitcnt lgkmcnt(6)
	v_mfma_f32_16x16x32_bf16 v[0:3], v[80:83], v[112:115], v[0:3]
	ds_read_b128 v[64:67], v150 offset:32768
	s_add_u32 m0, s38, 20480
	s_nop 0
	global_load_lds_dwordx4 v165, s[100:101]
	s_waitcnt lgkmcnt(6)
	v_mfma_f32_16x16x32_bf16 v[4:7], v[80:83], v[116:119], v[4:7]
	ds_read_b128 v[96:99], v162 offset:49152
	s_add_u32 m0, s38, 24576
	s_nop 0
	global_load_lds_dwordx4 v166, s[100:101]
	s_waitcnt lgkmcnt(6)
	v_mfma_f32_16x16x32_bf16 v[8:11], v[80:83], v[120:123], v[8:11]
	ds_read_b128 v[100:103], v162 offset:51200
	s_add_u32 m0, s38, 28672
	s_nop 0
	global_load_lds_dwordx4 v167, s[100:101]
	s_add_u32 s100, s100, 128
	s_addc_u32 s101, s101, 0
	s_waitcnt lgkmcnt(6)
	v_mfma_f32_16x16x32_bf16 v[12:15], v[80:83], v[124:127], v[12:15]
	ds_read_b128 v[104:107], v162 offset:53248
	s_waitcnt lgkmcnt(6)
	v_mfma_f32_16x16x32_bf16 v[16:19], v[84:87], v[112:115], v[16:19]
	ds_read_b128 v[108:111], v162 offset:55296
	s_waitcnt lgkmcnt(7)
	v_mfma_f32_16x16x32_bf16 v[20:23], v[84:87], v[116:119], v[20:23]
	ds_read_b128 v[68:71], v150 offset:34816
	s_waitcnt lgkmcnt(8)
	v_mfma_f32_16x16x32_bf16 v[24:27], v[84:87], v[120:123], v[24:27]
	ds_read_b128 v[72:75], v150 offset:36864
	s_waitcnt lgkmcnt(9)
	v_mfma_f32_16x16x32_bf16 v[28:31], v[84:87], v[124:127], v[28:31]
	ds_read_b128 v[76:79], v150 offset:38912
	s_waitcnt lgkmcnt(9)
	v_mfma_f32_16x16x32_bf16 v[32:35], v[88:91], v[112:115], v[32:35]
	s_waitcnt lgkmcnt(9)
	v_mfma_f32_16x16x32_bf16 v[36:39], v[88:91], v[116:119], v[36:39]
	s_waitcnt lgkmcnt(9)
	v_mfma_f32_16x16x32_bf16 v[40:43], v[88:91], v[120:123], v[40:43]
	s_waitcnt lgkmcnt(9)
	v_mfma_f32_16x16x32_bf16 v[44:47], v[88:91], v[124:127], v[44:47]
	s_waitcnt lgkmcnt(8)
	v_mfma_f32_16x16x32_bf16 v[48:51], v[92:95], v[112:115], v[48:51]
	s_waitcnt lgkmcnt(8)
	v_mfma_f32_16x16x32_bf16 v[52:55], v[92:95], v[116:119], v[52:55]
	s_waitcnt lgkmcnt(8)
	v_mfma_f32_16x16x32_bf16 v[56:59], v[92:95], v[120:123], v[56:59]
	s_waitcnt lgkmcnt(8)
	v_mfma_f32_16x16x32_bf16 v[60:63], v[92:95], v[124:127], v[60:63]
	s_waitcnt lgkmcnt(6)
	v_mfma_f32_16x16x32_bf16 v[0:3], v[64:67], v[96:99], v[0:3]
	ds_read_b128 v[80:83], v151 offset:32768
	s_waitcnt lgkmcnt(6)
	v_mfma_f32_16x16x32_bf16 v[4:7], v[64:67], v[100:103], v[4:7]
	ds_read_b128 v[112:115], v163 offset:49152
	s_waitcnt lgkmcnt(6)
	v_mfma_f32_16x16x32_bf16 v[8:11], v[64:67], v[104:107], v[8:11]
	ds_read_b128 v[116:119], v163 offset:51200
	s_waitcnt lgkmcnt(6)
	v_mfma_f32_16x16x32_bf16 v[12:15], v[64:67], v[108:111], v[12:15]
	ds_read_b128 v[120:123], v163 offset:53248
	s_waitcnt lgkmcnt(6)
	v_mfma_f32_16x16x32_bf16 v[16:19], v[68:71], v[96:99], v[16:19]
	ds_read_b128 v[124:127], v163 offset:55296
	s_waitcnt lgkmcnt(7)
	v_mfma_f32_16x16x32_bf16 v[20:23], v[68:71], v[100:103], v[20:23]
	ds_read_b128 v[84:87], v151 offset:34816
	s_waitcnt lgkmcnt(8)
	v_mfma_f32_16x16x32_bf16 v[24:27], v[68:71], v[104:107], v[24:27]
	ds_read_b128 v[88:91], v151 offset:36864
	s_waitcnt lgkmcnt(9)
	v_mfma_f32_16x16x32_bf16 v[28:31], v[68:71], v[108:111], v[28:31]
	ds_read_b128 v[92:95], v151 offset:38912
	s_waitcnt lgkmcnt(9)
	v_mfma_f32_16x16x32_bf16 v[32:35], v[72:75], v[96:99], v[32:35]
	s_waitcnt lgkmcnt(9)
	v_mfma_f32_16x16x32_bf16 v[36:39], v[72:75], v[100:103], v[36:39]
	s_waitcnt lgkmcnt(9)
	v_mfma_f32_16x16x32_bf16 v[40:43], v[72:75], v[104:107], v[40:43]
	s_waitcnt lgkmcnt(9)
	v_mfma_f32_16x16x32_bf16 v[44:47], v[72:75], v[108:111], v[44:47]
	s_waitcnt vmcnt(0) lgkmcnt(0)
	s_barrier
	s_add_u32 m0, s38, 32768
	s_nop 0
	global_load_lds_dwordx4 v164, s[98:99]
	s_waitcnt lgkmcnt(8)
	v_mfma_f32_16x16x32_bf16 v[48:51], v[76:79], v[96:99], v[48:51]
	s_add_u32 m0, s38, 36864
	s_nop 0
	global_load_lds_dwordx4 v165, s[98:99]
	s_waitcnt lgkmcnt(8)
	v_mfma_f32_16x16x32_bf16 v[52:55], v[76:79], v[100:103], v[52:55]
	s_add_u32 m0, s38, 40960
	s_nop 0
	global_load_lds_dwordx4 v166, s[98:99]
	s_waitcnt lgkmcnt(8)
	v_mfma_f32_16x16x32_bf16 v[56:59], v[76:79], v[104:107], v[56:59]
	s_add_u32 m0, s38, 45056
	s_nop 0
	global_load_lds_dwordx4 v167, s[98:99]
	s_add_u32 s98, s98, 128
	s_addc_u32 s99, s99, 0
	s_waitcnt lgkmcnt(8)
	v_mfma_f32_16x16x32_bf16 v[60:63], v[76:79], v[108:111], v[60:63]
	s_add_u32 m0, s38, 49152
	s_nop 0
	global_load_lds_dwordx4 v164, s[100:101]
	s_waitcnt lgkmcnt(6)
	v_mfma_f32_16x16x32_bf16 v[0:3], v[80:83], v[112:115], v[0:3]
	ds_read_b128 v[64:67], v150 offset:0
	s_add_u32 m0, s38, 53248
	s_nop 0
	global_load_lds_dwordx4 v165, s[100:101]
	s_waitcnt lgkmcnt(6)
	v_mfma_f32_16x16x32_bf16 v[4:7], v[80:83], v[116:119], v[4:7]
	ds_read_b128 v[96:99], v162 offset:16384
	s_add_u32 m0, s38, 57344
	s_nop 0
	global_load_lds_dwordx4 v166, s[100:101]
	s_waitcnt lgkmcnt(6)
	v_mfma_f32_16x16x32_bf16 v[8:11], v[80:83], v[120:123], v[8:11]
	ds_read_b128 v[100:103], v162 offset:18432
	s_add_u32 m0, s38, 61440
	s_nop 0
	global_load_lds_dwordx4 v167, s[100:101]
	s_add_u32 s100, s100, 128
	s_addc_u32 s101, s101, 0
	s_waitcnt lgkmcnt(6)
	v_mfma_f32_16x16x32_bf16 v[12:15], v[80:83], v[124:127], v[12:15]
	ds_read_b128 v[104:107], v162 offset:20480
	s_waitcnt lgkmcnt(6)
	v_mfma_f32_16x16x32_bf16 v[16:19], v[84:87], v[112:115], v[16:19]
	ds_read_b128 v[108:111], v162 offset:22528
	s_waitcnt lgkmcnt(7)
	v_mfma_f32_16x16x32_bf16 v[20:23], v[84:87], v[116:119], v[20:23]
	ds_read_b128 v[68:71], v150 offset:2048
	s_waitcnt lgkmcnt(8)
	v_mfma_f32_16x16x32_bf16 v[24:27], v[84:87], v[120:123], v[24:27]
	ds_read_b128 v[72:75], v150 offset:4096
	s_waitcnt lgkmcnt(9)
	v_mfma_f32_16x16x32_bf16 v[28:31], v[84:87], v[124:127], v[28:31]
	ds_read_b128 v[76:79], v150 offset:6144
	s_waitcnt lgkmcnt(9)
	v_mfma_f32_16x16x32_bf16 v[32:35], v[88:91], v[112:115], v[32:35]
	s_waitcnt lgkmcnt(9)
	v_mfma_f32_16x16x32_bf16 v[36:39], v[88:91], v[116:119], v[36:39]
	s_waitcnt lgkmcnt(9)
	v_mfma_f32_16x16x32_bf16 v[40:43], v[88:91], v[120:123], v[40:43]
	s_waitcnt lgkmcnt(9)
	v_mfma_f32_16x16x32_bf16 v[44:47], v[88:91], v[124:127], v[44:47]
	s_waitcnt lgkmcnt(8)
	v_mfma_f32_16x16x32_bf16 v[48:51], v[92:95], v[112:115], v[48:51]
	s_waitcnt lgkmcnt(8)
	v_mfma_f32_16x16x32_bf16 v[52:55], v[92:95], v[116:119], v[52:55]
	s_waitcnt lgkmcnt(8)
	v_mfma_f32_16x16x32_bf16 v[56:59], v[92:95], v[120:123], v[56:59]
	s_waitcnt lgkmcnt(8)
	v_mfma_f32_16x16x32_bf16 v[60:63], v[92:95], v[124:127], v[60:63]
	s_waitcnt lgkmcnt(6)
	v_mfma_f32_16x16x32_bf16 v[0:3], v[64:67], v[96:99], v[0:3]
	ds_read_b128 v[80:83], v151 offset:0
	s_waitcnt lgkmcnt(6)
	v_mfma_f32_16x16x32_bf16 v[4:7], v[64:67], v[100:103], v[4:7]
	ds_read_b128 v[112:115], v163 offset:16384
	s_waitcnt lgkmcnt(6)
	v_mfma_f32_16x16x32_bf16 v[8:11], v[64:67], v[104:107], v[8:11]
	ds_read_b128 v[116:119], v163 offset:18432
	s_waitcnt lgkmcnt(6)
	v_mfma_f32_16x16x32_bf16 v[12:15], v[64:67], v[108:111], v[12:15]
	ds_read_b128 v[120:123], v163 offset:20480
	s_waitcnt lgkmcnt(6)
	v_mfma_f32_16x16x32_bf16 v[16:19], v[68:71], v[96:99], v[16:19]
	ds_read_b128 v[124:127], v163 offset:22528
	s_waitcnt lgkmcnt(7)
	v_mfma_f32_16x16x32_bf16 v[20:23], v[68:71], v[100:103], v[20:23]
	ds_read_b128 v[84:87], v151 offset:2048
	s_waitcnt lgkmcnt(8)
	v_mfma_f32_16x16x32_bf16 v[24:27], v[68:71], v[104:107], v[24:27]
	ds_read_b128 v[88:91], v151 offset:4096
	s_waitcnt lgkmcnt(9)
	v_mfma_f32_16x16x32_bf16 v[28:31], v[68:71], v[108:111], v[28:31]
	ds_read_b128 v[92:95], v151 offset:6144
	s_waitcnt lgkmcnt(9)
	v_mfma_f32_16x16x32_bf16 v[32:35], v[72:75], v[96:99], v[32:35]
	s_waitcnt lgkmcnt(9)
	v_mfma_f32_16x16x32_bf16 v[36:39], v[72:75], v[100:103], v[36:39]
	s_waitcnt lgkmcnt(9)
	v_mfma_f32_16x16x32_bf16 v[40:43], v[72:75], v[104:107], v[40:43]
	s_waitcnt lgkmcnt(9)
	v_mfma_f32_16x16x32_bf16 v[44:47], v[72:75], v[108:111], v[44:47]
	s_waitcnt vmcnt(0) lgkmcnt(0)
	s_barrier
	s_add_u32 m0, s38, 0
	s_nop 0
	global_load_lds_dwordx4 v164, s[98:99]
	s_add_u32 m0, s38, 4096
	s_nop 0
	global_load_lds_dwordx4 v165, s[98:99]
	s_waitcnt lgkmcnt(8)
	v_mfma_f32_16x16x32_bf16 v[48:51], v[76:79], v[96:99], v[48:51]
	s_add_u32 m0, s38, 8192
	s_nop 0
	global_load_lds_dwordx4 v166, s[98:99]
	s_add_u32 m0, s38, 12288
	s_nop 0
	global_load_lds_dwordx4 v167, s[98:99]
	s_add_u32 s98, s98, 128
	s_addc_u32 s99, s99, 0
	s_waitcnt lgkmcnt(8)
	v_mfma_f32_16x16x32_bf16 v[52:55], v[76:79], v[100:103], v[52:55]
	s_add_u32 m0, s38, 16384
	s_nop 0
	global_load_lds_dwordx4 v164, s[100:101]
	s_add_u32 m0, s38, 20480
	s_nop 0
	global_load_lds_dwordx4 v165, s[100:101]
	s_waitcnt lgkmcnt(8)
	v_mfma_f32_16x16x32_bf16 v[56:59], v[76:79], v[104:107], v[56:59]
	s_add_u32 m0, s38, 24576
	s_nop 0
	global_load_lds_dwordx4 v166, s[100:101]
	s_add_u32 m0, s38, 28672
	s_nop 0
	global_load_lds_dwordx4 v167, s[100:101]
	s_add_u32 s100, s100, 128
	s_addc_u32 s101, s101, 0
	s_waitcnt lgkmcnt(8)
	v_mfma_f32_16x16x32_bf16 v[60:63], v[76:79], v[108:111], v[60:63]
	global_load_dwordx4 v[172:175], v168, s[14:15] nt
	s_waitcnt lgkmcnt(6)
	v_mfma_f32_16x16x32_bf16 v[0:3], v[80:83], v[112:115], v[0:3]
	ds_read_b128 v[64:67], v150 offset:32768
	global_load_dwordx4 v[176:179], v168, s[14:15] offset:16 nt
	s_add_u32 s14, s14, 0x8000
	s_addc_u32 s15, s15, 0
	s_waitcnt lgkmcnt(6)
	v_mfma_f32_16x16x32_bf16 v[4:7], v[80:83], v[116:119], v[4:7]
	ds_read_b128 v[96:99], v162 offset:49152
	global_load_dwordx4 v[180:183], v168, s[14:15] nt
	s_waitcnt lgkmcnt(6)
	v_mfma_f32_16x16x32_bf16 v[8:11], v[80:83], v[120:123], v[8:11]
	ds_read_b128 v[100:103], v162 offset:51200
	global_load_dwordx4 v[184:187], v168, s[14:15] offset:16 nt
	s_add_u32 s14, s14, 0x8000
	s_addc_u32 s15, s15, 0
	s_waitcnt lgkmcnt(6)
	v_mfma_f32_16x16x32_bf16 v[12:15], v[80:83], v[124:127], v[12:15]
	ds_read_b128 v[104:107], v162 offset:53248
	global_load_dwordx4 v[188:191], v168, s[14:15] nt
	s_waitcnt lgkmcnt(6)
	v_mfma_f32_16x16x32_bf16 v[16:19], v[84:87], v[112:115], v[16:19]
	ds_read_b128 v[108:111], v162 offset:55296
	global_load_dwordx4 v[192:195], v168, s[14:15] offset:16 nt
	s_add_u32 s14, s14, 0x8000
	s_addc_u32 s15, s15, 0
	s_waitcnt lgkmcnt(7)
	v_mfma_f32_16x16x32_bf16 v[20:23], v[84:87], v[116:119], v[20:23]
	ds_read_b128 v[68:71], v150 offset:34816
	global_load_dwordx4 v[196:199], v168, s[14:15] nt
	s_waitcnt lgkmcnt(8)
	v_mfma_f32_16x16x32_bf16 v[24:27], v[84:87], v[120:123], v[24:27]
	ds_read_b128 v[72:75], v150 offset:36864
	global_load_dwordx4 v[200:203], v168, s[14:15] offset:16 nt
	s_add_u32 s14, s14, 0x8000
	s_addc_u32 s15, s15, 0
	s_waitcnt lgkmcnt(9)
	v_mfma_f32_16x16x32_bf16 v[28:31], v[84:87], v[124:127], v[28:31]
	ds_read_b128 v[76:79], v150 offset:38912
	s_waitcnt lgkmcnt(9)
	v_mfma_f32_16x16x32_bf16 v[32:35], v[88:91], v[112:115], v[32:35]
	s_waitcnt lgkmcnt(9)
	v_mfma_f32_16x16x32_bf16 v[36:39], v[88:91], v[116:119], v[36:39]
	s_waitcnt lgkmcnt(9)
	v_mfma_f32_16x16x32_bf16 v[40:43], v[88:91], v[120:123], v[40:43]
	s_waitcnt lgkmcnt(9)
	v_mfma_f32_16x16x32_bf16 v[44:47], v[88:91], v[124:127], v[44:47]
	s_waitcnt lgkmcnt(8)
	v_mfma_f32_16x16x32_bf16 v[48:51], v[92:95], v[112:115], v[48:51]
	s_waitcnt lgkmcnt(8)
	v_mfma_f32_16x16x32_bf16 v[52:55], v[92:95], v[116:119], v[52:55]
	s_waitcnt lgkmcnt(8)
	v_mfma_f32_16x16x32_bf16 v[56:59], v[92:95], v[120:123], v[56:59]
	s_waitcnt lgkmcnt(8)
	v_mfma_f32_16x16x32_bf16 v[60:63], v[92:95], v[124:127], v[60:63]
	s_waitcnt lgkmcnt(6)
	v_mfma_f32_16x16x32_bf16 v[0:3], v[64:67], v[96:99], v[0:3]
	ds_read_b128 v[80:83], v151 offset:32768
	s_waitcnt lgkmcnt(6)
	v_mfma_f32_16x16x32_bf16 v[4:7], v[64:67], v[100:103], v[4:7]
	ds_read_b128 v[112:115], v163 offset:49152
	s_waitcnt lgkmcnt(6)
	v_mfma_f32_16x16x32_bf16 v[8:11], v[64:67], v[104:107], v[8:11]
	ds_read_b128 v[116:119], v163 offset:51200
	s_waitcnt lgkmcnt(6)
	v_mfma_f32_16x16x32_bf16 v[12:15], v[64:67], v[108:111], v[12:15]
	ds_read_b128 v[120:123], v163 offset:53248
	s_waitcnt lgkmcnt(6)
	v_mfma_f32_16x16x32_bf16 v[16:19], v[68:71], v[96:99], v[16:19]
	ds_read_b128 v[124:127], v163 offset:55296
	s_waitcnt lgkmcnt(7)
	v_mfma_f32_16x16x32_bf16 v[20:23], v[68:71], v[100:103], v[20:23]
	ds_read_b128 v[84:87], v151 offset:34816
	s_waitcnt lgkmcnt(8)
	v_mfma_f32_16x16x32_bf16 v[24:27], v[68:71], v[104:107], v[24:27]
	ds_read_b128 v[88:91], v151 offset:36864
	s_waitcnt lgkmcnt(9)
	v_mfma_f32_16x16x32_bf16 v[28:31], v[68:71], v[108:111], v[28:31]
	ds_read_b128 v[92:95], v151 offset:38912
	s_waitcnt lgkmcnt(9)
	v_mfma_f32_16x16x32_bf16 v[32:35], v[72:75], v[96:99], v[32:35]
	s_waitcnt lgkmcnt(9)
	v_mfma_f32_16x16x32_bf16 v[36:39], v[72:75], v[100:103], v[36:39]
	s_waitcnt lgkmcnt(9)
	v_mfma_f32_16x16x32_bf16 v[40:43], v[72:75], v[104:107], v[40:43]
	s_waitcnt lgkmcnt(9)
	v_mfma_f32_16x16x32_bf16 v[44:47], v[72:75], v[108:111], v[44:47]
	s_waitcnt vmcnt(8) lgkmcnt(0)
	s_barrier
	s_add_u32 m0, s38, 32768
	s_nop 0
	global_load_lds_dwordx4 v164, s[98:99]
	s_waitcnt lgkmcnt(8)
	v_mfma_f32_16x16x32_bf16 v[48:51], v[76:79], v[96:99], v[48:51]
	s_add_u32 m0, s38, 36864
	s_nop 0
	global_load_lds_dwordx4 v165, s[98:99]
	s_waitcnt lgkmcnt(8)
	v_mfma_f32_16x16x32_bf16 v[52:55], v[76:79], v[100:103], v[52:55]
	s_add_u32 m0, s38, 40960
	s_nop 0
	global_load_lds_dwordx4 v166, s[98:99]
	s_waitcnt lgkmcnt(8)
	v_mfma_f32_16x16x32_bf16 v[56:59], v[76:79], v[104:107], v[56:59]
	s_add_u32 m0, s38, 45056
	s_nop 0
	global_load_lds_dwordx4 v167, s[98:99]
	s_add_u32 s98, s98, 128
	s_addc_u32 s99, s99, 0
	s_waitcnt lgkmcnt(8)
	v_mfma_f32_16x16x32_bf16 v[60:63], v[76:79], v[108:111], v[60:63]
	s_add_u32 m0, s38, 49152
	s_nop 0
	global_load_lds_dwordx4 v164, s[100:101]
	s_waitcnt lgkmcnt(6)
	v_mfma_f32_16x16x32_bf16 v[0:3], v[80:83], v[112:115], v[0:3]
	ds_read_b128 v[64:67], v150 offset:0
	s_add_u32 m0, s38, 53248
	s_nop 0
	global_load_lds_dwordx4 v165, s[100:101]
	s_waitcnt lgkmcnt(6)
	v_mfma_f32_16x16x32_bf16 v[4:7], v[80:83], v[116:119], v[4:7]
	ds_read_b128 v[96:99], v162 offset:16384
	s_add_u32 m0, s38, 57344
	s_nop 0
	global_load_lds_dwordx4 v166, s[100:101]
	s_waitcnt lgkmcnt(6)
	v_mfma_f32_16x16x32_bf16 v[8:11], v[80:83], v[120:123], v[8:11]
	ds_read_b128 v[100:103], v162 offset:18432
	s_add_u32 m0, s38, 61440
	s_nop 0
	global_load_lds_dwordx4 v167, s[100:101]
	s_add_u32 s100, s100, 128
	s_addc_u32 s101, s101, 0
	s_waitcnt lgkmcnt(6)
	v_mfma_f32_16x16x32_bf16 v[12:15], v[80:83], v[124:127], v[12:15]
	ds_read_b128 v[104:107], v162 offset:20480
	s_waitcnt lgkmcnt(6)
	v_mfma_f32_16x16x32_bf16 v[16:19], v[84:87], v[112:115], v[16:19]
	ds_read_b128 v[108:111], v162 offset:22528
	s_waitcnt lgkmcnt(7)
	v_mfma_f32_16x16x32_bf16 v[20:23], v[84:87], v[116:119], v[20:23]
	ds_read_b128 v[68:71], v150 offset:2048
	s_waitcnt lgkmcnt(8)
	v_mfma_f32_16x16x32_bf16 v[24:27], v[84:87], v[120:123], v[24:27]
	ds_read_b128 v[72:75], v150 offset:4096
	s_waitcnt lgkmcnt(9)
	v_mfma_f32_16x16x32_bf16 v[28:31], v[84:87], v[124:127], v[28:31]
	ds_read_b128 v[76:79], v150 offset:6144
	s_waitcnt lgkmcnt(9)
	v_mfma_f32_16x16x32_bf16 v[32:35], v[88:91], v[112:115], v[32:35]
	s_waitcnt lgkmcnt(9)
	v_mfma_f32_16x16x32_bf16 v[36:39], v[88:91], v[116:119], v[36:39]
	s_waitcnt lgkmcnt(9)
	v_mfma_f32_16x16x32_bf16 v[40:43], v[88:91], v[120:123], v[40:43]
	s_waitcnt lgkmcnt(9)
	v_mfma_f32_16x16x32_bf16 v[44:47], v[88:91], v[124:127], v[44:47]
	s_waitcnt lgkmcnt(8)
	v_mfma_f32_16x16x32_bf16 v[48:51], v[92:95], v[112:115], v[48:51]
	s_waitcnt lgkmcnt(8)
	v_mfma_f32_16x16x32_bf16 v[52:55], v[92:95], v[116:119], v[52:55]
	s_waitcnt lgkmcnt(8)
	v_mfma_f32_16x16x32_bf16 v[56:59], v[92:95], v[120:123], v[56:59]
	s_waitcnt lgkmcnt(8)
	v_mfma_f32_16x16x32_bf16 v[60:63], v[92:95], v[124:127], v[60:63]
	s_waitcnt lgkmcnt(6)
	v_mfma_f32_16x16x32_bf16 v[0:3], v[64:67], v[96:99], v[0:3]
	ds_read_b128 v[80:83], v151 offset:0
	s_waitcnt lgkmcnt(6)
	v_mfma_f32_16x16x32_bf16 v[4:7], v[64:67], v[100:103], v[4:7]
	ds_read_b128 v[112:115], v163 offset:16384
	s_waitcnt lgkmcnt(6)
	v_mfma_f32_16x16x32_bf16 v[8:11], v[64:67], v[104:107], v[8:11]
	ds_read_b128 v[116:119], v163 offset:18432
	s_waitcnt lgkmcnt(6)
	v_mfma_f32_16x16x32_bf16 v[12:15], v[64:67], v[108:111], v[12:15]
	ds_read_b128 v[120:123], v163 offset:20480
	s_waitcnt lgkmcnt(6)
	v_mfma_f32_16x16x32_bf16 v[16:19], v[68:71], v[96:99], v[16:19]
	ds_read_b128 v[124:127], v163 offset:22528
	s_waitcnt lgkmcnt(7)
	v_mfma_f32_16x16x32_bf16 v[20:23], v[68:71], v[100:103], v[20:23]
	ds_read_b128 v[84:87], v151 offset:2048
	s_waitcnt lgkmcnt(8)
	v_mfma_f32_16x16x32_bf16 v[24:27], v[68:71], v[104:107], v[24:27]
	ds_read_b128 v[88:91], v151 offset:4096
	s_waitcnt lgkmcnt(9)
	v_mfma_f32_16x16x32_bf16 v[28:31], v[68:71], v[108:111], v[28:31]
	ds_read_b128 v[92:95], v151 offset:6144
	s_waitcnt lgkmcnt(9)
	v_mfma_f32_16x16x32_bf16 v[32:35], v[72:75], v[96:99], v[32:35]
	s_waitcnt lgkmcnt(9)
	v_mfma_f32_16x16x32_bf16 v[36:39], v[72:75], v[100:103], v[36:39]
	s_waitcnt lgkmcnt(9)
	v_mfma_f32_16x16x32_bf16 v[40:43], v[72:75], v[104:107], v[40:43]
	s_waitcnt lgkmcnt(9)
	v_mfma_f32_16x16x32_bf16 v[44:47], v[72:75], v[108:111], v[44:47]
	s_waitcnt vmcnt(0) lgkmcnt(0)
	s_barrier
	s_add_u32 m0, s38, 0
	s_nop 0
	global_load_lds_dwordx4 v164, s[98:99]
	s_waitcnt lgkmcnt(8)
	v_mfma_f32_16x16x32_bf16 v[48:51], v[76:79], v[96:99], v[48:51]
	s_add_u32 m0, s38, 4096
	s_nop 0
	global_load_lds_dwordx4 v165, s[98:99]
	s_waitcnt lgkmcnt(8)
	v_mfma_f32_16x16x32_bf16 v[52:55], v[76:79], v[100:103], v[52:55]
	s_add_u32 m0, s38, 8192
	s_nop 0
	global_load_lds_dwordx4 v166, s[98:99]
	s_waitcnt lgkmcnt(8)
	v_mfma_f32_16x16x32_bf16 v[56:59], v[76:79], v[104:107], v[56:59]
	s_add_u32 m0, s38, 12288
	s_nop 0
	global_load_lds_dwordx4 v167, s[98:99]
	s_add_u32 s98, s98, 128
	s_addc_u32 s99, s99, 0
	s_waitcnt lgkmcnt(8)
	v_mfma_f32_16x16x32_bf16 v[60:63], v[76:79], v[108:111], v[60:63]
	s_add_u32 m0, s38, 16384
	s_nop 0
	global_load_lds_dwordx4 v164, s[100:101]
	s_waitcnt lgkmcnt(6)
	v_mfma_f32_16x16x32_bf16 v[0:3], v[80:83], v[112:115], v[0:3]
	ds_read_b128 v[64:67], v150 offset:32768
	s_add_u32 m0, s38, 20480
	s_nop 0
	global_load_lds_dwordx4 v165, s[100:101]
	s_waitcnt lgkmcnt(6)
	v_mfma_f32_16x16x32_bf16 v[4:7], v[80:83], v[116:119], v[4:7]
	ds_read_b128 v[96:99], v162 offset:49152
	s_add_u32 m0, s38, 24576
	s_nop 0
	global_load_lds_dwordx4 v166, s[100:101]
	s_waitcnt lgkmcnt(6)
	v_mfma_f32_16x16x32_bf16 v[8:11], v[80:83], v[120:123], v[8:11]
	ds_read_b128 v[100:103], v162 offset:51200
	s_add_u32 m0, s38, 28672
	s_nop 0
	global_load_lds_dwordx4 v167, s[100:101]
	s_add_u32 s100, s100, 128
	s_addc_u32 s101, s101, 0
	s_waitcnt lgkmcnt(6)
	v_mfma_f32_16x16x32_bf16 v[12:15], v[80:83], v[124:127], v[12:15]
	ds_read_b128 v[104:107], v162 offset:53248
	s_waitcnt lgkmcnt(6)
	v_mfma_f32_16x16x32_bf16 v[16:19], v[84:87], v[112:115], v[16:19]
	ds_read_b128 v[108:111], v162 offset:55296
	s_waitcnt lgkmcnt(7)
	v_mfma_f32_16x16x32_bf16 v[20:23], v[84:87], v[116:119], v[20:23]
	ds_read_b128 v[68:71], v150 offset:34816
	s_waitcnt lgkmcnt(8)
	v_mfma_f32_16x16x32_bf16 v[24:27], v[84:87], v[120:123], v[24:27]
	ds_read_b128 v[72:75], v150 offset:36864
	s_waitcnt lgkmcnt(9)
	v_mfma_f32_16x16x32_bf16 v[28:31], v[84:87], v[124:127], v[28:31]
	ds_read_b128 v[76:79], v150 offset:38912
	s_waitcnt lgkmcnt(9)
	v_mfma_f32_16x16x32_bf16 v[32:35], v[88:91], v[112:115], v[32:35]
	s_waitcnt lgkmcnt(9)
	v_mfma_f32_16x16x32_bf16 v[36:39], v[88:91], v[116:119], v[36:39]
	s_waitcnt lgkmcnt(9)
	v_mfma_f32_16x16x32_bf16 v[40:43], v[88:91], v[120:123], v[40:43]
	s_waitcnt lgkmcnt(9)
	v_mfma_f32_16x16x32_bf16 v[44:47], v[88:91], v[124:127], v[44:47]
	s_waitcnt lgkmcnt(8)
	v_mfma_f32_16x16x32_bf16 v[48:51], v[92:95], v[112:115], v[48:51]
	s_waitcnt lgkmcnt(8)
	v_mfma_f32_16x16x32_bf16 v[52:55], v[92:95], v[116:119], v[52:55]
	s_waitcnt lgkmcnt(8)
	v_mfma_f32_16x16x32_bf16 v[56:59], v[92:95], v[120:123], v[56:59]
	s_waitcnt lgkmcnt(8)
	v_mfma_f32_16x16x32_bf16 v[60:63], v[92:95], v[124:127], v[60:63]
	s_waitcnt lgkmcnt(6)
	v_mfma_f32_16x16x32_bf16 v[0:3], v[64:67], v[96:99], v[0:3]
	ds_read_b128 v[80:83], v151 offset:32768
	s_waitcnt lgkmcnt(6)
	v_mfma_f32_16x16x32_bf16 v[4:7], v[64:67], v[100:103], v[4:7]
	ds_read_b128 v[112:115], v163 offset:49152
	s_waitcnt lgkmcnt(6)
	v_mfma_f32_16x16x32_bf16 v[8:11], v[64:67], v[104:107], v[8:11]
	ds_read_b128 v[116:119], v163 offset:51200
	s_waitcnt lgkmcnt(6)
	v_mfma_f32_16x16x32_bf16 v[12:15], v[64:67], v[108:111], v[12:15]
	ds_read_b128 v[120:123], v163 offset:53248
	s_waitcnt lgkmcnt(6)
	v_mfma_f32_16x16x32_bf16 v[16:19], v[68:71], v[96:99], v[16:19]
	ds_read_b128 v[124:127], v163 offset:55296
	s_waitcnt lgkmcnt(7)
	v_mfma_f32_16x16x32_bf16 v[20:23], v[68:71], v[100:103], v[20:23]
	ds_read_b128 v[84:87], v151 offset:34816
	s_waitcnt lgkmcnt(8)
	v_mfma_f32_16x16x32_bf16 v[24:27], v[68:71], v[104:107], v[24:27]
	ds_read_b128 v[88:91], v151 offset:36864
	s_waitcnt lgkmcnt(9)
	v_mfma_f32_16x16x32_bf16 v[28:31], v[68:71], v[108:111], v[28:31]
	ds_read_b128 v[92:95], v151 offset:38912
	s_waitcnt lgkmcnt(9)
	v_mfma_f32_16x16x32_bf16 v[32:35], v[72:75], v[96:99], v[32:35]
	s_waitcnt lgkmcnt(9)
	v_mfma_f32_16x16x32_bf16 v[36:39], v[72:75], v[100:103], v[36:39]
	s_waitcnt lgkmcnt(9)
	v_mfma_f32_16x16x32_bf16 v[40:43], v[72:75], v[104:107], v[40:43]
	s_waitcnt lgkmcnt(9)
	v_mfma_f32_16x16x32_bf16 v[44:47], v[72:75], v[108:111], v[44:47]
	s_waitcnt vmcnt(0) lgkmcnt(0)
	s_barrier
	s_add_u32 m0, s38, 32768
	s_nop 0
	global_load_lds_dwordx4 v164, s[98:99]
	s_waitcnt lgkmcnt(8)
	v_mfma_f32_16x16x32_bf16 v[48:51], v[76:79], v[96:99], v[48:51]
	s_add_u32 m0, s38, 36864
	s_nop 0
	global_load_lds_dwordx4 v165, s[98:99]
	s_waitcnt lgkmcnt(8)
	v_mfma_f32_16x16x32_bf16 v[52:55], v[76:79], v[100:103], v[52:55]
	s_add_u32 m0, s38, 40960
	s_nop 0
	global_load_lds_dwordx4 v166, s[98:99]
	s_waitcnt lgkmcnt(8)
	v_mfma_f32_16x16x32_bf16 v[56:59], v[76:79], v[104:107], v[56:59]
	s_add_u32 m0, s38, 45056
	s_nop 0
	global_load_lds_dwordx4 v167, s[98:99]
	s_add_u32 s98, s98, 128
	s_addc_u32 s99, s99, 0
	s_waitcnt lgkmcnt(8)
	v_mfma_f32_16x16x32_bf16 v[60:63], v[76:79], v[108:111], v[60:63]
	s_add_u32 m0, s38, 49152
	s_nop 0
	global_load_lds_dwordx4 v164, s[100:101]
	s_waitcnt lgkmcnt(6)
	v_mfma_f32_16x16x32_bf16 v[0:3], v[80:83], v[112:115], v[0:3]
	ds_read_b128 v[64:67], v150 offset:0
	s_add_u32 m0, s38, 53248
	s_nop 0
	global_load_lds_dwordx4 v165, s[100:101]
	s_waitcnt lgkmcnt(6)
	v_mfma_f32_16x16x32_bf16 v[4:7], v[80:83], v[116:119], v[4:7]
	ds_read_b128 v[96:99], v162 offset:16384
	s_add_u32 m0, s38, 57344
	s_nop 0
	global_load_lds_dwordx4 v166, s[100:101]
	s_waitcnt lgkmcnt(6)
	v_mfma_f32_16x16x32_bf16 v[8:11], v[80:83], v[120:123], v[8:11]
	ds_read_b128 v[100:103], v162 offset:18432
	s_add_u32 m0, s38, 61440
	s_nop 0
	global_load_lds_dwordx4 v167, s[100:101]
	s_add_u32 s100, s100, 128
	s_addc_u32 s101, s101, 0
	s_waitcnt lgkmcnt(6)
	v_mfma_f32_16x16x32_bf16 v[12:15], v[80:83], v[124:127], v[12:15]
	ds_read_b128 v[104:107], v162 offset:20480
	s_waitcnt lgkmcnt(6)
	v_mfma_f32_16x16x32_bf16 v[16:19], v[84:87], v[112:115], v[16:19]
	ds_read_b128 v[108:111], v162 offset:22528
	s_waitcnt lgkmcnt(7)
	v_mfma_f32_16x16x32_bf16 v[20:23], v[84:87], v[116:119], v[20:23]
	ds_read_b128 v[68:71], v150 offset:2048
	s_waitcnt lgkmcnt(8)
	v_mfma_f32_16x16x32_bf16 v[24:27], v[84:87], v[120:123], v[24:27]
	ds_read_b128 v[72:75], v150 offset:4096
	s_waitcnt lgkmcnt(9)
	v_mfma_f32_16x16x32_bf16 v[28:31], v[84:87], v[124:127], v[28:31]
	ds_read_b128 v[76:79], v150 offset:6144
	s_waitcnt lgkmcnt(9)
	v_mfma_f32_16x16x32_bf16 v[32:35], v[88:91], v[112:115], v[32:35]
	s_waitcnt lgkmcnt(9)
	v_mfma_f32_16x16x32_bf16 v[36:39], v[88:91], v[116:119], v[36:39]
	s_waitcnt lgkmcnt(9)
	v_mfma_f32_16x16x32_bf16 v[40:43], v[88:91], v[120:123], v[40:43]
	s_waitcnt lgkmcnt(9)
	v_mfma_f32_16x16x32_bf16 v[44:47], v[88:91], v[124:127], v[44:47]
	s_waitcnt lgkmcnt(8)
	v_mfma_f32_16x16x32_bf16 v[48:51], v[92:95], v[112:115], v[48:51]
	s_waitcnt lgkmcnt(8)
	v_mfma_f32_16x16x32_bf16 v[52:55], v[92:95], v[116:119], v[52:55]
	s_waitcnt lgkmcnt(8)
	v_mfma_f32_16x16x32_bf16 v[56:59], v[92:95], v[120:123], v[56:59]
	s_waitcnt lgkmcnt(8)
	v_mfma_f32_16x16x32_bf16 v[60:63], v[92:95], v[124:127], v[60:63]
	s_waitcnt lgkmcnt(6)
	v_mfma_f32_16x16x32_bf16 v[0:3], v[64:67], v[96:99], v[0:3]
	ds_read_b128 v[80:83], v151 offset:0
	s_waitcnt lgkmcnt(6)
	v_mfma_f32_16x16x32_bf16 v[4:7], v[64:67], v[100:103], v[4:7]
	ds_read_b128 v[112:115], v163 offset:16384
	s_waitcnt lgkmcnt(6)
	v_mfma_f32_16x16x32_bf16 v[8:11], v[64:67], v[104:107], v[8:11]
	ds_read_b128 v[116:119], v163 offset:18432
	s_waitcnt lgkmcnt(6)
	v_mfma_f32_16x16x32_bf16 v[12:15], v[64:67], v[108:111], v[12:15]
	ds_read_b128 v[120:123], v163 offset:20480
	s_waitcnt lgkmcnt(6)
	v_mfma_f32_16x16x32_bf16 v[16:19], v[68:71], v[96:99], v[16:19]
	ds_read_b128 v[124:127], v163 offset:22528
	s_waitcnt lgkmcnt(7)
	v_mfma_f32_16x16x32_bf16 v[20:23], v[68:71], v[100:103], v[20:23]
	ds_read_b128 v[84:87], v151 offset:2048
	s_waitcnt lgkmcnt(8)
	v_mfma_f32_16x16x32_bf16 v[24:27], v[68:71], v[104:107], v[24:27]
	ds_read_b128 v[88:91], v151 offset:4096
	s_waitcnt lgkmcnt(9)
	v_mfma_f32_16x16x32_bf16 v[28:31], v[68:71], v[108:111], v[28:31]
	ds_read_b128 v[92:95], v151 offset:6144
	s_waitcnt lgkmcnt(9)
	v_mfma_f32_16x16x32_bf16 v[32:35], v[72:75], v[96:99], v[32:35]
	s_waitcnt lgkmcnt(9)
	v_mfma_f32_16x16x32_bf16 v[36:39], v[72:75], v[100:103], v[36:39]
	s_waitcnt lgkmcnt(9)
	v_mfma_f32_16x16x32_bf16 v[40:43], v[72:75], v[104:107], v[40:43]
	s_waitcnt lgkmcnt(9)
	v_mfma_f32_16x16x32_bf16 v[44:47], v[72:75], v[108:111], v[44:47]
	s_waitcnt vmcnt(0) lgkmcnt(0)
	s_barrier
	s_add_u32 m0, s38, 0
	s_nop 0
	global_load_lds_dwordx4 v164, s[98:99]
	s_waitcnt lgkmcnt(8)
	v_mfma_f32_16x16x32_bf16 v[48:51], v[76:79], v[96:99], v[48:51]
	s_add_u32 m0, s38, 4096
	s_nop 0
	global_load_lds_dwordx4 v165, s[98:99]
	s_waitcnt lgkmcnt(8)
	v_mfma_f32_16x16x32_bf16 v[52:55], v[76:79], v[100:103], v[52:55]
	s_add_u32 m0, s38, 8192
	s_nop 0
	global_load_lds_dwordx4 v166, s[98:99]
	s_waitcnt lgkmcnt(8)
	v_mfma_f32_16x16x32_bf16 v[56:59], v[76:79], v[104:107], v[56:59]
	s_add_u32 m0, s38, 12288
	s_nop 0
	global_load_lds_dwordx4 v167, s[98:99]
	s_add_u32 s98, s98, 128
	s_addc_u32 s99, s99, 0
	s_waitcnt lgkmcnt(8)
	v_mfma_f32_16x16x32_bf16 v[60:63], v[76:79], v[108:111], v[60:63]
	s_add_u32 m0, s38, 16384
	s_nop 0
	global_load_lds_dwordx4 v164, s[100:101]
	s_waitcnt lgkmcnt(6)
	v_mfma_f32_16x16x32_bf16 v[0:3], v[80:83], v[112:115], v[0:3]
	ds_read_b128 v[64:67], v150 offset:32768
	s_add_u32 m0, s38, 20480
	s_nop 0
	global_load_lds_dwordx4 v165, s[100:101]
	s_waitcnt lgkmcnt(6)
	v_mfma_f32_16x16x32_bf16 v[4:7], v[80:83], v[116:119], v[4:7]
	ds_read_b128 v[96:99], v162 offset:49152
	s_add_u32 m0, s38, 24576
	s_nop 0
	global_load_lds_dwordx4 v166, s[100:101]
	s_waitcnt lgkmcnt(6)
	v_mfma_f32_16x16x32_bf16 v[8:11], v[80:83], v[120:123], v[8:11]
	ds_read_b128 v[100:103], v162 offset:51200
	s_add_u32 m0, s38, 28672
	s_nop 0
	global_load_lds_dwordx4 v167, s[100:101]
	s_add_u32 s100, s100, 128
	s_addc_u32 s101, s101, 0
	s_waitcnt lgkmcnt(6)
	v_mfma_f32_16x16x32_bf16 v[12:15], v[80:83], v[124:127], v[12:15]
	ds_read_b128 v[104:107], v162 offset:53248
	s_waitcnt lgkmcnt(6)
	v_mfma_f32_16x16x32_bf16 v[16:19], v[84:87], v[112:115], v[16:19]
	ds_read_b128 v[108:111], v162 offset:55296
	s_waitcnt lgkmcnt(7)
	v_mfma_f32_16x16x32_bf16 v[20:23], v[84:87], v[116:119], v[20:23]
	ds_read_b128 v[68:71], v150 offset:34816
	s_waitcnt lgkmcnt(8)
	v_mfma_f32_16x16x32_bf16 v[24:27], v[84:87], v[120:123], v[24:27]
	ds_read_b128 v[72:75], v150 offset:36864
	s_waitcnt lgkmcnt(9)
	v_mfma_f32_16x16x32_bf16 v[28:31], v[84:87], v[124:127], v[28:31]
	ds_read_b128 v[76:79], v150 offset:38912
	s_waitcnt lgkmcnt(9)
	v_mfma_f32_16x16x32_bf16 v[32:35], v[88:91], v[112:115], v[32:35]
	s_waitcnt lgkmcnt(9)
	v_mfma_f32_16x16x32_bf16 v[36:39], v[88:91], v[116:119], v[36:39]
	s_waitcnt lgkmcnt(9)
	v_mfma_f32_16x16x32_bf16 v[40:43], v[88:91], v[120:123], v[40:43]
	s_waitcnt lgkmcnt(9)
	v_mfma_f32_16x16x32_bf16 v[44:47], v[88:91], v[124:127], v[44:47]
	s_waitcnt lgkmcnt(8)
	v_mfma_f32_16x16x32_bf16 v[48:51], v[92:95], v[112:115], v[48:51]
	s_waitcnt lgkmcnt(8)
	v_mfma_f32_16x16x32_bf16 v[52:55], v[92:95], v[116:119], v[52:55]
	s_waitcnt lgkmcnt(8)
	v_mfma_f32_16x16x32_bf16 v[56:59], v[92:95], v[120:123], v[56:59]
	s_waitcnt lgkmcnt(8)
	v_mfma_f32_16x16x32_bf16 v[60:63], v[92:95], v[124:127], v[60:63]
	s_waitcnt lgkmcnt(6)
	v_mfma_f32_16x16x32_bf16 v[0:3], v[64:67], v[96:99], v[0:3]
	ds_read_b128 v[80:83], v151 offset:32768
	s_waitcnt lgkmcnt(6)
	v_mfma_f32_16x16x32_bf16 v[4:7], v[64:67], v[100:103], v[4:7]
	ds_read_b128 v[112:115], v163 offset:49152
	s_waitcnt lgkmcnt(6)
	v_mfma_f32_16x16x32_bf16 v[8:11], v[64:67], v[104:107], v[8:11]
	ds_read_b128 v[116:119], v163 offset:51200
	s_waitcnt lgkmcnt(6)
	v_mfma_f32_16x16x32_bf16 v[12:15], v[64:67], v[108:111], v[12:15]
	ds_read_b128 v[120:123], v163 offset:53248
	s_waitcnt lgkmcnt(6)
	v_mfma_f32_16x16x32_bf16 v[16:19], v[68:71], v[96:99], v[16:19]
	ds_read_b128 v[124:127], v163 offset:55296
	s_waitcnt lgkmcnt(7)
	v_mfma_f32_16x16x32_bf16 v[20:23], v[68:71], v[100:103], v[20:23]
	ds_read_b128 v[84:87], v151 offset:34816
	s_waitcnt lgkmcnt(8)
	v_mfma_f32_16x16x32_bf16 v[24:27], v[68:71], v[104:107], v[24:27]
	ds_read_b128 v[88:91], v151 offset:36864
	s_waitcnt lgkmcnt(9)
	v_mfma_f32_16x16x32_bf16 v[28:31], v[68:71], v[108:111], v[28:31]
	ds_read_b128 v[92:95], v151 offset:38912
	s_waitcnt lgkmcnt(9)
	v_mfma_f32_16x16x32_bf16 v[32:35], v[72:75], v[96:99], v[32:35]
	s_waitcnt lgkmcnt(9)
	v_mfma_f32_16x16x32_bf16 v[36:39], v[72:75], v[100:103], v[36:39]
	s_waitcnt lgkmcnt(9)
	v_mfma_f32_16x16x32_bf16 v[40:43], v[72:75], v[104:107], v[40:43]
	s_waitcnt lgkmcnt(9)
	v_mfma_f32_16x16x32_bf16 v[44:47], v[72:75], v[108:111], v[44:47]
	s_waitcnt vmcnt(0) lgkmcnt(0)
	s_barrier
	s_add_u32 m0, s38, 32768
	s_nop 0
	global_load_lds_dwordx4 v164, s[98:99]
	s_waitcnt lgkmcnt(8)
	v_mfma_f32_16x16x32_bf16 v[48:51], v[76:79], v[96:99], v[48:51]
	s_add_u32 m0, s38, 36864
	s_nop 0
	global_load_lds_dwordx4 v165, s[98:99]
	s_waitcnt lgkmcnt(8)
	v_mfma_f32_16x16x32_bf16 v[52:55], v[76:79], v[100:103], v[52:55]
	s_add_u32 m0, s38, 40960
	s_nop 0
	global_load_lds_dwordx4 v166, s[98:99]
	s_waitcnt lgkmcnt(8)
	v_mfma_f32_16x16x32_bf16 v[56:59], v[76:79], v[104:107], v[56:59]
	s_add_u32 m0, s38, 45056
	s_nop 0
	global_load_lds_dwordx4 v167, s[98:99]
	s_add_u32 s98, s98, 128
	s_addc_u32 s99, s99, 0
	s_waitcnt lgkmcnt(8)
	v_mfma_f32_16x16x32_bf16 v[60:63], v[76:79], v[108:111], v[60:63]
	s_add_u32 m0, s38, 49152
	s_nop 0
	global_load_lds_dwordx4 v164, s[100:101]
	s_waitcnt lgkmcnt(6)
	v_mfma_f32_16x16x32_bf16 v[0:3], v[80:83], v[112:115], v[0:3]
	ds_read_b128 v[64:67], v150 offset:0
	s_add_u32 m0, s38, 53248
	s_nop 0
	global_load_lds_dwordx4 v165, s[100:101]
	s_waitcnt lgkmcnt(6)
	v_mfma_f32_16x16x32_bf16 v[4:7], v[80:83], v[116:119], v[4:7]
	ds_read_b128 v[96:99], v162 offset:16384
	s_add_u32 m0, s38, 57344
	s_nop 0
	global_load_lds_dwordx4 v166, s[100:101]
	s_waitcnt lgkmcnt(6)
	v_mfma_f32_16x16x32_bf16 v[8:11], v[80:83], v[120:123], v[8:11]
	ds_read_b128 v[100:103], v162 offset:18432
	s_add_u32 m0, s38, 61440
	s_nop 0
	global_load_lds_dwordx4 v167, s[100:101]
	s_add_u32 s100, s100, 128
	s_addc_u32 s101, s101, 0
	s_waitcnt lgkmcnt(6)
	v_mfma_f32_16x16x32_bf16 v[12:15], v[80:83], v[124:127], v[12:15]
	ds_read_b128 v[104:107], v162 offset:20480
	s_waitcnt lgkmcnt(6)
	v_mfma_f32_16x16x32_bf16 v[16:19], v[84:87], v[112:115], v[16:19]
	ds_read_b128 v[108:111], v162 offset:22528
	s_waitcnt lgkmcnt(7)
	v_mfma_f32_16x16x32_bf16 v[20:23], v[84:87], v[116:119], v[20:23]
	ds_read_b128 v[68:71], v150 offset:2048
	s_waitcnt lgkmcnt(8)
	v_mfma_f32_16x16x32_bf16 v[24:27], v[84:87], v[120:123], v[24:27]
	ds_read_b128 v[72:75], v150 offset:4096
	s_waitcnt lgkmcnt(9)
	v_mfma_f32_16x16x32_bf16 v[28:31], v[84:87], v[124:127], v[28:31]
	ds_read_b128 v[76:79], v150 offset:6144
	s_waitcnt lgkmcnt(9)
	v_mfma_f32_16x16x32_bf16 v[32:35], v[88:91], v[112:115], v[32:35]
	s_waitcnt lgkmcnt(9)
	v_mfma_f32_16x16x32_bf16 v[36:39], v[88:91], v[116:119], v[36:39]
	s_waitcnt lgkmcnt(9)
	v_mfma_f32_16x16x32_bf16 v[40:43], v[88:91], v[120:123], v[40:43]
	s_waitcnt lgkmcnt(9)
	v_mfma_f32_16x16x32_bf16 v[44:47], v[88:91], v[124:127], v[44:47]
	s_waitcnt lgkmcnt(8)
	v_mfma_f32_16x16x32_bf16 v[48:51], v[92:95], v[112:115], v[48:51]
	s_waitcnt lgkmcnt(8)
	v_mfma_f32_16x16x32_bf16 v[52:55], v[92:95], v[116:119], v[52:55]
	s_waitcnt lgkmcnt(8)
	v_mfma_f32_16x16x32_bf16 v[56:59], v[92:95], v[120:123], v[56:59]
	s_waitcnt lgkmcnt(8)
	v_mfma_f32_16x16x32_bf16 v[60:63], v[92:95], v[124:127], v[60:63]
	s_waitcnt lgkmcnt(6)
	v_mfma_f32_16x16x32_bf16 v[0:3], v[64:67], v[96:99], v[0:3]
	ds_read_b128 v[80:83], v151 offset:0
	s_waitcnt lgkmcnt(6)
	v_mfma_f32_16x16x32_bf16 v[4:7], v[64:67], v[100:103], v[4:7]
	ds_read_b128 v[112:115], v163 offset:16384
	s_waitcnt lgkmcnt(6)
	v_mfma_f32_16x16x32_bf16 v[8:11], v[64:67], v[104:107], v[8:11]
	ds_read_b128 v[116:119], v163 offset:18432
	s_waitcnt lgkmcnt(6)
	v_mfma_f32_16x16x32_bf16 v[12:15], v[64:67], v[108:111], v[12:15]
	ds_read_b128 v[120:123], v163 offset:20480
	s_waitcnt lgkmcnt(6)
	v_mfma_f32_16x16x32_bf16 v[16:19], v[68:71], v[96:99], v[16:19]
	ds_read_b128 v[124:127], v163 offset:22528
	s_waitcnt lgkmcnt(7)
	v_mfma_f32_16x16x32_bf16 v[20:23], v[68:71], v[100:103], v[20:23]
	ds_read_b128 v[84:87], v151 offset:2048
	s_waitcnt lgkmcnt(8)
	v_mfma_f32_16x16x32_bf16 v[24:27], v[68:71], v[104:107], v[24:27]
	ds_read_b128 v[88:91], v151 offset:4096
	s_waitcnt lgkmcnt(9)
	v_mfma_f32_16x16x32_bf16 v[28:31], v[68:71], v[108:111], v[28:31]
	ds_read_b128 v[92:95], v151 offset:6144
	s_waitcnt lgkmcnt(9)
	v_mfma_f32_16x16x32_bf16 v[32:35], v[72:75], v[96:99], v[32:35]
	s_waitcnt lgkmcnt(9)
	v_mfma_f32_16x16x32_bf16 v[36:39], v[72:75], v[100:103], v[36:39]
	s_waitcnt lgkmcnt(9)
	v_mfma_f32_16x16x32_bf16 v[40:43], v[72:75], v[104:107], v[40:43]
	s_waitcnt lgkmcnt(9)
	v_mfma_f32_16x16x32_bf16 v[44:47], v[72:75], v[108:111], v[44:47]
	s_waitcnt vmcnt(0) lgkmcnt(0)
	s_barrier
	s_add_u32 m0, s38, 0
	s_nop 0
	global_load_lds_dwordx4 v164, s[98:99]
	s_waitcnt lgkmcnt(8)
	v_mfma_f32_16x16x32_bf16 v[48:51], v[76:79], v[96:99], v[48:51]
	s_add_u32 m0, s38, 4096
	s_nop 0
	global_load_lds_dwordx4 v165, s[98:99]
	s_waitcnt lgkmcnt(8)
	v_mfma_f32_16x16x32_bf16 v[52:55], v[76:79], v[100:103], v[52:55]
	s_add_u32 m0, s38, 8192
	s_nop 0
	global_load_lds_dwordx4 v166, s[98:99]
	s_waitcnt lgkmcnt(8)
	v_mfma_f32_16x16x32_bf16 v[56:59], v[76:79], v[104:107], v[56:59]
	s_add_u32 m0, s38, 12288
	s_nop 0
	global_load_lds_dwordx4 v167, s[98:99]
	s_add_u32 s98, s98, 128
	s_addc_u32 s99, s99, 0
	s_waitcnt lgkmcnt(8)
	v_mfma_f32_16x16x32_bf16 v[60:63], v[76:79], v[108:111], v[60:63]
	s_add_u32 m0, s38, 16384
	s_nop 0
	global_load_lds_dwordx4 v164, s[100:101]
	s_waitcnt lgkmcnt(6)
	v_mfma_f32_16x16x32_bf16 v[0:3], v[80:83], v[112:115], v[0:3]
	ds_read_b128 v[64:67], v150 offset:32768
	s_add_u32 m0, s38, 20480
	s_nop 0
	global_load_lds_dwordx4 v165, s[100:101]
	s_waitcnt lgkmcnt(6)
	v_mfma_f32_16x16x32_bf16 v[4:7], v[80:83], v[116:119], v[4:7]
	ds_read_b128 v[96:99], v162 offset:49152
	s_add_u32 m0, s38, 24576
	s_nop 0
	global_load_lds_dwordx4 v166, s[100:101]
	s_waitcnt lgkmcnt(6)
	v_mfma_f32_16x16x32_bf16 v[8:11], v[80:83], v[120:123], v[8:11]
	ds_read_b128 v[100:103], v162 offset:51200
	s_add_u32 m0, s38, 28672
	s_nop 0
	global_load_lds_dwordx4 v167, s[100:101]
	s_add_u32 s100, s100, 128
	s_addc_u32 s101, s101, 0
	s_waitcnt lgkmcnt(6)
	v_mfma_f32_16x16x32_bf16 v[12:15], v[80:83], v[124:127], v[12:15]
	ds_read_b128 v[104:107], v162 offset:53248
	s_waitcnt lgkmcnt(6)
	v_mfma_f32_16x16x32_bf16 v[16:19], v[84:87], v[112:115], v[16:19]
	ds_read_b128 v[108:111], v162 offset:55296
	s_waitcnt lgkmcnt(7)
	v_mfma_f32_16x16x32_bf16 v[20:23], v[84:87], v[116:119], v[20:23]
	ds_read_b128 v[68:71], v150 offset:34816
	s_waitcnt lgkmcnt(8)
	v_mfma_f32_16x16x32_bf16 v[24:27], v[84:87], v[120:123], v[24:27]
	ds_read_b128 v[72:75], v150 offset:36864
	s_waitcnt lgkmcnt(9)
	v_mfma_f32_16x16x32_bf16 v[28:31], v[84:87], v[124:127], v[28:31]
	ds_read_b128 v[76:79], v150 offset:38912
	s_waitcnt lgkmcnt(9)
	v_mfma_f32_16x16x32_bf16 v[32:35], v[88:91], v[112:115], v[32:35]
	s_waitcnt lgkmcnt(9)
	v_mfma_f32_16x16x32_bf16 v[36:39], v[88:91], v[116:119], v[36:39]
	s_waitcnt lgkmcnt(9)
	v_mfma_f32_16x16x32_bf16 v[40:43], v[88:91], v[120:123], v[40:43]
	s_waitcnt lgkmcnt(9)
	v_mfma_f32_16x16x32_bf16 v[44:47], v[88:91], v[124:127], v[44:47]
	s_waitcnt lgkmcnt(8)
	v_mfma_f32_16x16x32_bf16 v[48:51], v[92:95], v[112:115], v[48:51]
	s_waitcnt lgkmcnt(8)
	v_mfma_f32_16x16x32_bf16 v[52:55], v[92:95], v[116:119], v[52:55]
	s_waitcnt lgkmcnt(8)
	v_mfma_f32_16x16x32_bf16 v[56:59], v[92:95], v[120:123], v[56:59]
	s_waitcnt lgkmcnt(8)
	v_mfma_f32_16x16x32_bf16 v[60:63], v[92:95], v[124:127], v[60:63]
	s_waitcnt lgkmcnt(6)
	v_mfma_f32_16x16x32_bf16 v[0:3], v[64:67], v[96:99], v[0:3]
	ds_read_b128 v[80:83], v151 offset:32768
	s_waitcnt lgkmcnt(6)
	v_mfma_f32_16x16x32_bf16 v[4:7], v[64:67], v[100:103], v[4:7]
	ds_read_b128 v[112:115], v163 offset:49152
	s_waitcnt lgkmcnt(6)
	v_mfma_f32_16x16x32_bf16 v[8:11], v[64:67], v[104:107], v[8:11]
	ds_read_b128 v[116:119], v163 offset:51200
	s_waitcnt lgkmcnt(6)
	v_mfma_f32_16x16x32_bf16 v[12:15], v[64:67], v[108:111], v[12:15]
	ds_read_b128 v[120:123], v163 offset:53248
	s_waitcnt lgkmcnt(6)
	v_mfma_f32_16x16x32_bf16 v[16:19], v[68:71], v[96:99], v[16:19]
	ds_read_b128 v[124:127], v163 offset:55296
	s_waitcnt lgkmcnt(7)
	v_mfma_f32_16x16x32_bf16 v[20:23], v[68:71], v[100:103], v[20:23]
	ds_read_b128 v[84:87], v151 offset:34816
	s_waitcnt lgkmcnt(8)
	v_mfma_f32_16x16x32_bf16 v[24:27], v[68:71], v[104:107], v[24:27]
	ds_read_b128 v[88:91], v151 offset:36864
	s_waitcnt lgkmcnt(9)
	v_mfma_f32_16x16x32_bf16 v[28:31], v[68:71], v[108:111], v[28:31]
	ds_read_b128 v[92:95], v151 offset:38912
	s_waitcnt lgkmcnt(9)
	v_mfma_f32_16x16x32_bf16 v[32:35], v[72:75], v[96:99], v[32:35]
	s_waitcnt lgkmcnt(9)
	v_mfma_f32_16x16x32_bf16 v[36:39], v[72:75], v[100:103], v[36:39]
	s_waitcnt lgkmcnt(9)
	v_mfma_f32_16x16x32_bf16 v[40:43], v[72:75], v[104:107], v[40:43]
	s_waitcnt lgkmcnt(9)
	v_mfma_f32_16x16x32_bf16 v[44:47], v[72:75], v[108:111], v[44:47]
	s_waitcnt vmcnt(0) lgkmcnt(0)
	s_barrier
	s_add_u32 m0, s38, 32768
	s_nop 0
	global_load_lds_dwordx4 v164, s[98:99]
	s_waitcnt lgkmcnt(8)
	v_mfma_f32_16x16x32_bf16 v[48:51], v[76:79], v[96:99], v[48:51]
	s_add_u32 m0, s38, 36864
	s_nop 0
	global_load_lds_dwordx4 v165, s[98:99]
	s_waitcnt lgkmcnt(8)
	v_mfma_f32_16x16x32_bf16 v[52:55], v[76:79], v[100:103], v[52:55]
	s_add_u32 m0, s38, 40960
	s_nop 0
	global_load_lds_dwordx4 v166, s[98:99]
	s_waitcnt lgkmcnt(8)
	v_mfma_f32_16x16x32_bf16 v[56:59], v[76:79], v[104:107], v[56:59]
	s_add_u32 m0, s38, 45056
	s_nop 0
	global_load_lds_dwordx4 v167, s[98:99]
	s_add_u32 s98, s98, 128
	s_addc_u32 s99, s99, 0
	s_waitcnt lgkmcnt(8)
	v_mfma_f32_16x16x32_bf16 v[60:63], v[76:79], v[108:111], v[60:63]
	s_add_u32 m0, s38, 49152
	s_nop 0
	global_load_lds_dwordx4 v164, s[100:101]
	s_waitcnt lgkmcnt(6)
	v_mfma_f32_16x16x32_bf16 v[0:3], v[80:83], v[112:115], v[0:3]
	ds_read_b128 v[64:67], v150 offset:0
	s_add_u32 m0, s38, 53248
	s_nop 0
	global_load_lds_dwordx4 v165, s[100:101]
	s_waitcnt lgkmcnt(6)
	v_mfma_f32_16x16x32_bf16 v[4:7], v[80:83], v[116:119], v[4:7]
	ds_read_b128 v[96:99], v162 offset:16384
	s_add_u32 m0, s38, 57344
	s_nop 0
	global_load_lds_dwordx4 v166, s[100:101]
	s_waitcnt lgkmcnt(6)
	v_mfma_f32_16x16x32_bf16 v[8:11], v[80:83], v[120:123], v[8:11]
	ds_read_b128 v[100:103], v162 offset:18432
	s_add_u32 m0, s38, 61440
	s_nop 0
	global_load_lds_dwordx4 v167, s[100:101]
	s_add_u32 s100, s100, 128
	s_addc_u32 s101, s101, 0
	s_waitcnt lgkmcnt(6)
	v_mfma_f32_16x16x32_bf16 v[12:15], v[80:83], v[124:127], v[12:15]
	ds_read_b128 v[104:107], v162 offset:20480
	s_waitcnt lgkmcnt(6)
	v_mfma_f32_16x16x32_bf16 v[16:19], v[84:87], v[112:115], v[16:19]
	ds_read_b128 v[108:111], v162 offset:22528
	s_waitcnt lgkmcnt(7)
	v_mfma_f32_16x16x32_bf16 v[20:23], v[84:87], v[116:119], v[20:23]
	ds_read_b128 v[68:71], v150 offset:2048
	s_waitcnt lgkmcnt(8)
	v_mfma_f32_16x16x32_bf16 v[24:27], v[84:87], v[120:123], v[24:27]
	ds_read_b128 v[72:75], v150 offset:4096
	s_waitcnt lgkmcnt(9)
	v_mfma_f32_16x16x32_bf16 v[28:31], v[84:87], v[124:127], v[28:31]
	ds_read_b128 v[76:79], v150 offset:6144
	s_waitcnt lgkmcnt(9)
	v_mfma_f32_16x16x32_bf16 v[32:35], v[88:91], v[112:115], v[32:35]
	s_waitcnt lgkmcnt(9)
	v_mfma_f32_16x16x32_bf16 v[36:39], v[88:91], v[116:119], v[36:39]
	s_waitcnt lgkmcnt(9)
	v_mfma_f32_16x16x32_bf16 v[40:43], v[88:91], v[120:123], v[40:43]
	s_waitcnt lgkmcnt(9)
	v_mfma_f32_16x16x32_bf16 v[44:47], v[88:91], v[124:127], v[44:47]
	s_waitcnt lgkmcnt(8)
	v_mfma_f32_16x16x32_bf16 v[48:51], v[92:95], v[112:115], v[48:51]
	s_waitcnt lgkmcnt(8)
	v_mfma_f32_16x16x32_bf16 v[52:55], v[92:95], v[116:119], v[52:55]
	s_waitcnt lgkmcnt(8)
	v_mfma_f32_16x16x32_bf16 v[56:59], v[92:95], v[120:123], v[56:59]
	s_waitcnt lgkmcnt(8)
	v_mfma_f32_16x16x32_bf16 v[60:63], v[92:95], v[124:127], v[60:63]
	s_waitcnt lgkmcnt(6)
	v_mfma_f32_16x16x32_bf16 v[0:3], v[64:67], v[96:99], v[0:3]
	ds_read_b128 v[80:83], v151 offset:0
	s_waitcnt lgkmcnt(6)
	v_mfma_f32_16x16x32_bf16 v[4:7], v[64:67], v[100:103], v[4:7]
	ds_read_b128 v[112:115], v163 offset:16384
	s_waitcnt lgkmcnt(6)
	v_mfma_f32_16x16x32_bf16 v[8:11], v[64:67], v[104:107], v[8:11]
	ds_read_b128 v[116:119], v163 offset:18432
	s_waitcnt lgkmcnt(6)
	v_mfma_f32_16x16x32_bf16 v[12:15], v[64:67], v[108:111], v[12:15]
	ds_read_b128 v[120:123], v163 offset:20480
	s_waitcnt lgkmcnt(6)
	v_mfma_f32_16x16x32_bf16 v[16:19], v[68:71], v[96:99], v[16:19]
	ds_read_b128 v[124:127], v163 offset:22528
	s_waitcnt lgkmcnt(7)
	v_mfma_f32_16x16x32_bf16 v[20:23], v[68:71], v[100:103], v[20:23]
	ds_read_b128 v[84:87], v151 offset:2048
	s_waitcnt lgkmcnt(8)
	v_mfma_f32_16x16x32_bf16 v[24:27], v[68:71], v[104:107], v[24:27]
	ds_read_b128 v[88:91], v151 offset:4096
	s_waitcnt lgkmcnt(9)
	v_mfma_f32_16x16x32_bf16 v[28:31], v[68:71], v[108:111], v[28:31]
	ds_read_b128 v[92:95], v151 offset:6144
	s_waitcnt lgkmcnt(9)
	v_mfma_f32_16x16x32_bf16 v[32:35], v[72:75], v[96:99], v[32:35]
	s_waitcnt lgkmcnt(9)
	v_mfma_f32_16x16x32_bf16 v[36:39], v[72:75], v[100:103], v[36:39]
	s_waitcnt lgkmcnt(9)
	v_mfma_f32_16x16x32_bf16 v[40:43], v[72:75], v[104:107], v[40:43]
	s_waitcnt lgkmcnt(9)
	v_mfma_f32_16x16x32_bf16 v[44:47], v[72:75], v[108:111], v[44:47]
	s_waitcnt vmcnt(0) lgkmcnt(0)
	s_barrier
	s_add_u32 m0, s38, 0
	s_nop 0
	global_load_lds_dwordx4 v164, s[98:99]
	s_waitcnt lgkmcnt(8)
	v_mfma_f32_16x16x32_bf16 v[48:51], v[76:79], v[96:99], v[48:51]
	s_add_u32 m0, s38, 4096
	s_nop 0
	global_load_lds_dwordx4 v165, s[98:99]
	s_waitcnt lgkmcnt(8)
	v_mfma_f32_16x16x32_bf16 v[52:55], v[76:79], v[100:103], v[52:55]
	s_add_u32 m0, s38, 8192
	s_nop 0
	global_load_lds_dwordx4 v166, s[98:99]
	s_waitcnt lgkmcnt(8)
	v_mfma_f32_16x16x32_bf16 v[56:59], v[76:79], v[104:107], v[56:59]
	s_add_u32 m0, s38, 12288
	s_nop 0
	global_load_lds_dwordx4 v167, s[98:99]
	s_add_u32 s98, s98, 128
	s_addc_u32 s99, s99, 0
	s_waitcnt lgkmcnt(8)
	v_mfma_f32_16x16x32_bf16 v[60:63], v[76:79], v[108:111], v[60:63]
	s_add_u32 m0, s38, 16384
	s_nop 0
	global_load_lds_dwordx4 v164, s[100:101]
	s_waitcnt lgkmcnt(6)
	v_mfma_f32_16x16x32_bf16 v[0:3], v[80:83], v[112:115], v[0:3]
	ds_read_b128 v[64:67], v150 offset:32768
	s_add_u32 m0, s38, 20480
	s_nop 0
	global_load_lds_dwordx4 v165, s[100:101]
	s_waitcnt lgkmcnt(6)
	v_mfma_f32_16x16x32_bf16 v[4:7], v[80:83], v[116:119], v[4:7]
	ds_read_b128 v[96:99], v162 offset:49152
	s_add_u32 m0, s38, 24576
	s_nop 0
	global_load_lds_dwordx4 v166, s[100:101]
	s_waitcnt lgkmcnt(6)
	v_mfma_f32_16x16x32_bf16 v[8:11], v[80:83], v[120:123], v[8:11]
	ds_read_b128 v[100:103], v162 offset:51200
	s_add_u32 m0, s38, 28672
	s_nop 0
	global_load_lds_dwordx4 v167, s[100:101]
	s_add_u32 s100, s100, 128
	s_addc_u32 s101, s101, 0
	s_waitcnt lgkmcnt(6)
	v_mfma_f32_16x16x32_bf16 v[12:15], v[80:83], v[124:127], v[12:15]
	ds_read_b128 v[104:107], v162 offset:53248
	s_waitcnt lgkmcnt(6)
	v_mfma_f32_16x16x32_bf16 v[16:19], v[84:87], v[112:115], v[16:19]
	ds_read_b128 v[108:111], v162 offset:55296
	s_waitcnt lgkmcnt(7)
	v_mfma_f32_16x16x32_bf16 v[20:23], v[84:87], v[116:119], v[20:23]
	ds_read_b128 v[68:71], v150 offset:34816
	s_waitcnt lgkmcnt(8)
	v_mfma_f32_16x16x32_bf16 v[24:27], v[84:87], v[120:123], v[24:27]
	ds_read_b128 v[72:75], v150 offset:36864
	s_waitcnt lgkmcnt(9)
	v_mfma_f32_16x16x32_bf16 v[28:31], v[84:87], v[124:127], v[28:31]
	ds_read_b128 v[76:79], v150 offset:38912
	s_waitcnt lgkmcnt(9)
	v_mfma_f32_16x16x32_bf16 v[32:35], v[88:91], v[112:115], v[32:35]
	s_waitcnt lgkmcnt(9)
	v_mfma_f32_16x16x32_bf16 v[36:39], v[88:91], v[116:119], v[36:39]
	s_waitcnt lgkmcnt(9)
	v_mfma_f32_16x16x32_bf16 v[40:43], v[88:91], v[120:123], v[40:43]
	s_waitcnt lgkmcnt(9)
	v_mfma_f32_16x16x32_bf16 v[44:47], v[88:91], v[124:127], v[44:47]
	s_waitcnt lgkmcnt(8)
	v_mfma_f32_16x16x32_bf16 v[48:51], v[92:95], v[112:115], v[48:51]
	s_waitcnt lgkmcnt(8)
	v_mfma_f32_16x16x32_bf16 v[52:55], v[92:95], v[116:119], v[52:55]
	s_waitcnt lgkmcnt(8)
	v_mfma_f32_16x16x32_bf16 v[56:59], v[92:95], v[120:123], v[56:59]
	s_waitcnt lgkmcnt(8)
	v_mfma_f32_16x16x32_bf16 v[60:63], v[92:95], v[124:127], v[60:63]
	s_waitcnt lgkmcnt(6)
	v_mfma_f32_16x16x32_bf16 v[0:3], v[64:67], v[96:99], v[0:3]
	ds_read_b128 v[80:83], v151 offset:32768
	s_waitcnt lgkmcnt(6)
	v_mfma_f32_16x16x32_bf16 v[4:7], v[64:67], v[100:103], v[4:7]
	ds_read_b128 v[112:115], v163 offset:49152
	s_waitcnt lgkmcnt(6)
	v_mfma_f32_16x16x32_bf16 v[8:11], v[64:67], v[104:107], v[8:11]
	ds_read_b128 v[116:119], v163 offset:51200
	s_waitcnt lgkmcnt(6)
	v_mfma_f32_16x16x32_bf16 v[12:15], v[64:67], v[108:111], v[12:15]
	ds_read_b128 v[120:123], v163 offset:53248
	s_waitcnt lgkmcnt(6)
	v_mfma_f32_16x16x32_bf16 v[16:19], v[68:71], v[96:99], v[16:19]
	ds_read_b128 v[124:127], v163 offset:55296
	s_waitcnt lgkmcnt(7)
	v_mfma_f32_16x16x32_bf16 v[20:23], v[68:71], v[100:103], v[20:23]
	ds_read_b128 v[84:87], v151 offset:34816
	s_waitcnt lgkmcnt(8)
	v_mfma_f32_16x16x32_bf16 v[24:27], v[68:71], v[104:107], v[24:27]
	ds_read_b128 v[88:91], v151 offset:36864
	s_waitcnt lgkmcnt(9)
	v_mfma_f32_16x16x32_bf16 v[28:31], v[68:71], v[108:111], v[28:31]
	ds_read_b128 v[92:95], v151 offset:38912
	s_waitcnt lgkmcnt(9)
	v_mfma_f32_16x16x32_bf16 v[32:35], v[72:75], v[96:99], v[32:35]
	s_waitcnt lgkmcnt(9)
	v_mfma_f32_16x16x32_bf16 v[36:39], v[72:75], v[100:103], v[36:39]
	s_waitcnt lgkmcnt(9)
	v_mfma_f32_16x16x32_bf16 v[40:43], v[72:75], v[104:107], v[40:43]
	s_waitcnt lgkmcnt(9)
	v_mfma_f32_16x16x32_bf16 v[44:47], v[72:75], v[108:111], v[44:47]
	s_waitcnt vmcnt(0) lgkmcnt(0)
	s_barrier
	s_add_u32 m0, s38, 32768
	s_nop 0
	global_load_lds_dwordx4 v164, s[98:99]
	s_waitcnt lgkmcnt(8)
	v_mfma_f32_16x16x32_bf16 v[48:51], v[76:79], v[96:99], v[48:51]
	s_add_u32 m0, s38, 36864
	s_nop 0
	global_load_lds_dwordx4 v165, s[98:99]
	s_waitcnt lgkmcnt(8)
	v_mfma_f32_16x16x32_bf16 v[52:55], v[76:79], v[100:103], v[52:55]
	s_add_u32 m0, s38, 40960
	s_nop 0
	global_load_lds_dwordx4 v166, s[98:99]
	s_waitcnt lgkmcnt(8)
	v_mfma_f32_16x16x32_bf16 v[56:59], v[76:79], v[104:107], v[56:59]
	s_add_u32 m0, s38, 45056
	s_nop 0
	global_load_lds_dwordx4 v167, s[98:99]
	s_add_u32 s98, s98, 128
	s_addc_u32 s99, s99, 0
	s_waitcnt lgkmcnt(8)
	v_mfma_f32_16x16x32_bf16 v[60:63], v[76:79], v[108:111], v[60:63]
	s_add_u32 m0, s38, 49152
	s_nop 0
	global_load_lds_dwordx4 v164, s[100:101]
	s_waitcnt lgkmcnt(6)
	v_mfma_f32_16x16x32_bf16 v[0:3], v[80:83], v[112:115], v[0:3]
	ds_read_b128 v[64:67], v150 offset:0
	s_add_u32 m0, s38, 53248
	s_nop 0
	global_load_lds_dwordx4 v165, s[100:101]
	s_waitcnt lgkmcnt(6)
	v_mfma_f32_16x16x32_bf16 v[4:7], v[80:83], v[116:119], v[4:7]
	ds_read_b128 v[96:99], v162 offset:16384
	s_add_u32 m0, s38, 57344
	s_nop 0
	global_load_lds_dwordx4 v166, s[100:101]
	s_waitcnt lgkmcnt(6)
	v_mfma_f32_16x16x32_bf16 v[8:11], v[80:83], v[120:123], v[8:11]
	ds_read_b128 v[100:103], v162 offset:18432
	s_add_u32 m0, s38, 61440
	s_nop 0
	global_load_lds_dwordx4 v167, s[100:101]
	s_add_u32 s100, s100, 128
	s_addc_u32 s101, s101, 0
	s_waitcnt lgkmcnt(6)
	v_mfma_f32_16x16x32_bf16 v[12:15], v[80:83], v[124:127], v[12:15]
	ds_read_b128 v[104:107], v162 offset:20480
	s_waitcnt lgkmcnt(6)
	v_mfma_f32_16x16x32_bf16 v[16:19], v[84:87], v[112:115], v[16:19]
	ds_read_b128 v[108:111], v162 offset:22528
	s_waitcnt lgkmcnt(7)
	v_mfma_f32_16x16x32_bf16 v[20:23], v[84:87], v[116:119], v[20:23]
	ds_read_b128 v[68:71], v150 offset:2048
	s_waitcnt lgkmcnt(8)
	v_mfma_f32_16x16x32_bf16 v[24:27], v[84:87], v[120:123], v[24:27]
	ds_read_b128 v[72:75], v150 offset:4096
	s_waitcnt lgkmcnt(9)
	v_mfma_f32_16x16x32_bf16 v[28:31], v[84:87], v[124:127], v[28:31]
	ds_read_b128 v[76:79], v150 offset:6144
	s_waitcnt lgkmcnt(9)
	v_mfma_f32_16x16x32_bf16 v[32:35], v[88:91], v[112:115], v[32:35]
	s_waitcnt lgkmcnt(9)
	v_mfma_f32_16x16x32_bf16 v[36:39], v[88:91], v[116:119], v[36:39]
	s_waitcnt lgkmcnt(9)
	v_mfma_f32_16x16x32_bf16 v[40:43], v[88:91], v[120:123], v[40:43]
	s_waitcnt lgkmcnt(9)
	v_mfma_f32_16x16x32_bf16 v[44:47], v[88:91], v[124:127], v[44:47]
	s_waitcnt lgkmcnt(8)
	v_mfma_f32_16x16x32_bf16 v[48:51], v[92:95], v[112:115], v[48:51]
	s_waitcnt lgkmcnt(8)
	v_mfma_f32_16x16x32_bf16 v[52:55], v[92:95], v[116:119], v[52:55]
	s_waitcnt lgkmcnt(8)
	v_mfma_f32_16x16x32_bf16 v[56:59], v[92:95], v[120:123], v[56:59]
	s_waitcnt lgkmcnt(8)
	v_mfma_f32_16x16x32_bf16 v[60:63], v[92:95], v[124:127], v[60:63]
	s_waitcnt lgkmcnt(6)
	v_mfma_f32_16x16x32_bf16 v[0:3], v[64:67], v[96:99], v[0:3]
	ds_read_b128 v[80:83], v151 offset:0
	s_waitcnt lgkmcnt(6)
	v_mfma_f32_16x16x32_bf16 v[4:7], v[64:67], v[100:103], v[4:7]
	ds_read_b128 v[112:115], v163 offset:16384
	s_waitcnt lgkmcnt(6)
	v_mfma_f32_16x16x32_bf16 v[8:11], v[64:67], v[104:107], v[8:11]
	ds_read_b128 v[116:119], v163 offset:18432
	s_waitcnt lgkmcnt(6)
	v_mfma_f32_16x16x32_bf16 v[12:15], v[64:67], v[108:111], v[12:15]
	ds_read_b128 v[120:123], v163 offset:20480
	s_waitcnt lgkmcnt(6)
	v_mfma_f32_16x16x32_bf16 v[16:19], v[68:71], v[96:99], v[16:19]
	ds_read_b128 v[124:127], v163 offset:22528
	s_waitcnt lgkmcnt(7)
	v_mfma_f32_16x16x32_bf16 v[20:23], v[68:71], v[100:103], v[20:23]
	ds_read_b128 v[84:87], v151 offset:2048
	s_waitcnt lgkmcnt(8)
	v_mfma_f32_16x16x32_bf16 v[24:27], v[68:71], v[104:107], v[24:27]
	ds_read_b128 v[88:91], v151 offset:4096
	s_waitcnt lgkmcnt(9)
	v_mfma_f32_16x16x32_bf16 v[28:31], v[68:71], v[108:111], v[28:31]
	ds_read_b128 v[92:95], v151 offset:6144
	s_waitcnt lgkmcnt(9)
	v_mfma_f32_16x16x32_bf16 v[32:35], v[72:75], v[96:99], v[32:35]
	s_waitcnt lgkmcnt(9)
	v_mfma_f32_16x16x32_bf16 v[36:39], v[72:75], v[100:103], v[36:39]
	s_waitcnt lgkmcnt(9)
	v_mfma_f32_16x16x32_bf16 v[40:43], v[72:75], v[104:107], v[40:43]
	s_waitcnt lgkmcnt(9)
	v_mfma_f32_16x16x32_bf16 v[44:47], v[72:75], v[108:111], v[44:47]
	s_waitcnt vmcnt(0) lgkmcnt(0)
	s_barrier
	s_waitcnt lgkmcnt(8)
	v_mfma_f32_16x16x32_bf16 v[48:51], v[76:79], v[96:99], v[48:51]
	s_waitcnt lgkmcnt(8)
	v_mfma_f32_16x16x32_bf16 v[52:55], v[76:79], v[100:103], v[52:55]
	s_waitcnt lgkmcnt(8)
	v_mfma_f32_16x16x32_bf16 v[56:59], v[76:79], v[104:107], v[56:59]
	s_waitcnt lgkmcnt(8)
	v_mfma_f32_16x16x32_bf16 v[60:63], v[76:79], v[108:111], v[60:63]
	s_waitcnt lgkmcnt(6)
	v_mfma_f32_16x16x32_bf16 v[0:3], v[80:83], v[112:115], v[0:3]
	ds_read_b128 v[64:67], v150 offset:32768
	s_waitcnt lgkmcnt(6)
	v_mfma_f32_16x16x32_bf16 v[4:7], v[80:83], v[116:119], v[4:7]
	ds_read_b128 v[96:99], v162 offset:49152
	s_waitcnt lgkmcnt(6)
	v_mfma_f32_16x16x32_bf16 v[8:11], v[80:83], v[120:123], v[8:11]
	ds_read_b128 v[100:103], v162 offset:51200
	s_waitcnt lgkmcnt(6)
	v_mfma_f32_16x16x32_bf16 v[12:15], v[80:83], v[124:127], v[12:15]
	ds_read_b128 v[104:107], v162 offset:53248
	s_waitcnt lgkmcnt(6)
	v_mfma_f32_16x16x32_bf16 v[16:19], v[84:87], v[112:115], v[16:19]
	ds_read_b128 v[108:111], v162 offset:55296
	s_waitcnt lgkmcnt(7)
	v_mfma_f32_16x16x32_bf16 v[20:23], v[84:87], v[116:119], v[20:23]
	ds_read_b128 v[68:71], v150 offset:34816
	s_waitcnt lgkmcnt(8)
	v_mfma_f32_16x16x32_bf16 v[24:27], v[84:87], v[120:123], v[24:27]
	ds_read_b128 v[72:75], v150 offset:36864
	s_waitcnt lgkmcnt(9)
	v_mfma_f32_16x16x32_bf16 v[28:31], v[84:87], v[124:127], v[28:31]
	ds_read_b128 v[76:79], v150 offset:38912
	s_waitcnt lgkmcnt(9)
	v_mfma_f32_16x16x32_bf16 v[32:35], v[88:91], v[112:115], v[32:35]
	s_waitcnt lgkmcnt(9)
	v_mfma_f32_16x16x32_bf16 v[36:39], v[88:91], v[116:119], v[36:39]
	s_waitcnt lgkmcnt(9)
	v_mfma_f32_16x16x32_bf16 v[40:43], v[88:91], v[120:123], v[40:43]
	s_waitcnt lgkmcnt(9)
	v_mfma_f32_16x16x32_bf16 v[44:47], v[88:91], v[124:127], v[44:47]
	s_waitcnt lgkmcnt(8)
	v_mfma_f32_16x16x32_bf16 v[48:51], v[92:95], v[112:115], v[48:51]
	s_waitcnt lgkmcnt(8)
	v_mfma_f32_16x16x32_bf16 v[52:55], v[92:95], v[116:119], v[52:55]
	s_waitcnt lgkmcnt(8)
	v_mfma_f32_16x16x32_bf16 v[56:59], v[92:95], v[120:123], v[56:59]
	s_waitcnt lgkmcnt(8)
	v_mfma_f32_16x16x32_bf16 v[60:63], v[92:95], v[124:127], v[60:63]
	s_waitcnt lgkmcnt(6)
	v_mfma_f32_16x16x32_bf16 v[0:3], v[64:67], v[96:99], v[0:3]
	ds_read_b128 v[80:83], v151 offset:32768
	s_waitcnt lgkmcnt(6)
	v_mfma_f32_16x16x32_bf16 v[4:7], v[64:67], v[100:103], v[4:7]
	ds_read_b128 v[112:115], v163 offset:49152
	s_waitcnt lgkmcnt(6)
	v_mfma_f32_16x16x32_bf16 v[8:11], v[64:67], v[104:107], v[8:11]
	ds_read_b128 v[116:119], v163 offset:51200
	s_waitcnt lgkmcnt(6)
	v_mfma_f32_16x16x32_bf16 v[12:15], v[64:67], v[108:111], v[12:15]
	ds_read_b128 v[120:123], v163 offset:53248
	s_waitcnt lgkmcnt(6)
	v_mfma_f32_16x16x32_bf16 v[16:19], v[68:71], v[96:99], v[16:19]
	ds_read_b128 v[124:127], v163 offset:55296
	s_waitcnt lgkmcnt(7)
	v_mfma_f32_16x16x32_bf16 v[20:23], v[68:71], v[100:103], v[20:23]
	ds_read_b128 v[84:87], v151 offset:34816
	s_waitcnt lgkmcnt(8)
	v_mfma_f32_16x16x32_bf16 v[24:27], v[68:71], v[104:107], v[24:27]
	ds_read_b128 v[88:91], v151 offset:36864
	s_waitcnt lgkmcnt(9)
	v_mfma_f32_16x16x32_bf16 v[28:31], v[68:71], v[108:111], v[28:31]
	ds_read_b128 v[92:95], v151 offset:38912
	s_waitcnt lgkmcnt(9)
	v_mfma_f32_16x16x32_bf16 v[32:35], v[72:75], v[96:99], v[32:35]
	s_waitcnt lgkmcnt(9)
	v_mfma_f32_16x16x32_bf16 v[36:39], v[72:75], v[100:103], v[36:39]
	s_waitcnt lgkmcnt(9)
	v_mfma_f32_16x16x32_bf16 v[40:43], v[72:75], v[104:107], v[40:43]
	s_waitcnt lgkmcnt(9)
	v_mfma_f32_16x16x32_bf16 v[44:47], v[72:75], v[108:111], v[44:47]
	s_waitcnt lgkmcnt(8)
	v_mfma_f32_16x16x32_bf16 v[48:51], v[76:79], v[96:99], v[48:51]
	s_waitcnt lgkmcnt(8)
	v_mfma_f32_16x16x32_bf16 v[52:55], v[76:79], v[100:103], v[52:55]
	s_waitcnt lgkmcnt(8)
	v_mfma_f32_16x16x32_bf16 v[56:59], v[76:79], v[104:107], v[56:59]
	s_waitcnt lgkmcnt(8)
	v_mfma_f32_16x16x32_bf16 v[60:63], v[76:79], v[108:111], v[60:63]
	s_waitcnt lgkmcnt(6)
	v_mfma_f32_16x16x32_bf16 v[0:3], v[80:83], v[112:115], v[0:3]
	s_waitcnt lgkmcnt(5)
	v_mfma_f32_16x16x32_bf16 v[4:7], v[80:83], v[116:119], v[4:7]
	s_waitcnt lgkmcnt(4)
	v_mfma_f32_16x16x32_bf16 v[8:11], v[80:83], v[120:123], v[8:11]
	s_waitcnt lgkmcnt(3)
	v_mfma_f32_16x16x32_bf16 v[12:15], v[80:83], v[124:127], v[12:15]
	s_waitcnt lgkmcnt(2)
	v_mfma_f32_16x16x32_bf16 v[16:19], v[84:87], v[112:115], v[16:19]
	s_waitcnt lgkmcnt(2)
	v_mfma_f32_16x16x32_bf16 v[20:23], v[84:87], v[116:119], v[20:23]
	s_waitcnt lgkmcnt(2)
	v_mfma_f32_16x16x32_bf16 v[24:27], v[84:87], v[120:123], v[24:27]
	s_waitcnt lgkmcnt(2)
	v_mfma_f32_16x16x32_bf16 v[28:31], v[84:87], v[124:127], v[28:31]
	s_waitcnt lgkmcnt(1)
	v_mfma_f32_16x16x32_bf16 v[32:35], v[88:91], v[112:115], v[32:35]
	s_waitcnt lgkmcnt(1)
	v_mfma_f32_16x16x32_bf16 v[36:39], v[88:91], v[116:119], v[36:39]
	s_waitcnt lgkmcnt(1)
	v_mfma_f32_16x16x32_bf16 v[40:43], v[88:91], v[120:123], v[40:43]
	s_waitcnt lgkmcnt(1)
	v_mfma_f32_16x16x32_bf16 v[44:47], v[88:91], v[124:127], v[44:47]
	s_waitcnt lgkmcnt(0)
	v_mfma_f32_16x16x32_bf16 v[48:51], v[92:95], v[112:115], v[48:51]
	s_waitcnt lgkmcnt(0)
	v_mfma_f32_16x16x32_bf16 v[52:55], v[92:95], v[116:119], v[52:55]
	s_waitcnt lgkmcnt(0)
	v_mfma_f32_16x16x32_bf16 v[56:59], v[92:95], v[120:123], v[56:59]
	s_waitcnt lgkmcnt(0)
	v_mfma_f32_16x16x32_bf16 v[60:63], v[92:95], v[124:127], v[60:63]
	global_load_dwordx4 v[64:67], v168, s[14:15] nt
	global_load_dwordx4 v[68:71], v168, s[14:15] offset:16 nt
	s_add_u32 s14, s14, 0x8000
	s_addc_u32 s15, s15, 0
	global_load_dwordx4 v[72:75], v168, s[14:15] nt
	global_load_dwordx4 v[76:79], v168, s[14:15] offset:16 nt
	s_add_u32 s14, s14, 0x8000
	s_addc_u32 s15, s15, 0
	global_load_dwordx4 v[80:83], v168, s[14:15] nt
	global_load_dwordx4 v[84:87], v168, s[14:15] offset:16 nt
	s_add_u32 s14, s14, 0x8000
	s_addc_u32 s15, s15, 0
	global_load_dwordx4 v[88:91], v168, s[14:15] nt
	global_load_dwordx4 v[92:95], v168, s[14:15] offset:16 nt
	s_add_u32 s14, s14, 0x8000
	s_addc_u32 s15, s15, 0
	s_nop 7
	s_waitcnt lgkmcnt(0)
	s_barrier
	ds_write_b32 v169, v0 offset:0
	ds_write_b32 v169, v1 offset:256
	ds_write_b32 v169, v2 offset:512
	ds_write_b32 v169, v3 offset:768
	ds_write_b32 v170, v4 offset:0
	ds_write_b32 v170, v5 offset:256
	ds_write_b32 v170, v6 offset:512
	ds_write_b32 v170, v7 offset:768
	ds_write_b32 v171, v8 offset:0
	ds_write_b32 v171, v9 offset:256
	ds_write_b32 v171, v10 offset:512
	ds_write_b32 v171, v11 offset:768
	ds_write_b32 v228, v12 offset:0
	ds_write_b32 v228, v13 offset:256
	ds_write_b32 v228, v14 offset:512
	ds_write_b32 v228, v15 offset:768
	ds_write_b32 v169, v16 offset:4096
	ds_write_b32 v169, v17 offset:4352
	ds_write_b32 v169, v18 offset:4608
	ds_write_b32 v169, v19 offset:4864
	ds_write_b32 v170, v20 offset:4096
	ds_write_b32 v170, v21 offset:4352
	ds_write_b32 v170, v22 offset:4608
	ds_write_b32 v170, v23 offset:4864
	ds_write_b32 v171, v24 offset:4096
	ds_write_b32 v171, v25 offset:4352
	ds_write_b32 v171, v26 offset:4608
	ds_write_b32 v171, v27 offset:4864
	ds_write_b32 v228, v28 offset:4096
	ds_write_b32 v228, v29 offset:4352
	ds_write_b32 v228, v30 offset:4608
	ds_write_b32 v228, v31 offset:4864
	s_waitcnt lgkmcnt(0)
	ds_read_b128 v[0:3], v220
	ds_read_b128 v[4:7], v220 offset:16
	ds_read_b128 v[8:11], v222
	ds_read_b128 v[12:15], v222 offset:16
	ds_read_b128 v[16:19], v224
	ds_read_b128 v[20:23], v224 offset:16
	ds_read_b128 v[24:27], v226
	ds_read_b128 v[28:31], v226 offset:16
	s_waitcnt lgkmcnt(6)
	v_pk_fma_f32 v[0:1], v[142:143], v[0:1], v[172:173]
	v_pk_fma_f32 v[2:3], v[144:145], v[2:3], v[174:175]
	v_pk_fma_f32 v[4:5], v[146:147], v[4:5], v[176:177]
	v_pk_fma_f32 v[6:7], v[160:161], v[6:7], v[178:179]
	global_store_dwordx4 v168, v[0:3], s[18:19]
	global_store_dwordx4 v168, v[4:7], s[18:19] offset:16
	s_add_u32 s18, s18, 0x8000
	s_addc_u32 s19, s19, 0
	s_waitcnt lgkmcnt(4)
	v_pk_fma_f32 v[8:9], v[142:143], v[8:9], v[180:181]
	v_pk_fma_f32 v[10:11], v[144:145], v[10:11], v[182:183]
	v_pk_fma_f32 v[12:13], v[146:147], v[12:13], v[184:185]
	v_pk_fma_f32 v[14:15], v[160:161], v[14:15], v[186:187]
	global_store_dwordx4 v168, v[8:11], s[18:19]
	global_store_dwordx4 v168, v[12:15], s[18:19] offset:16
	s_add_u32 s18, s18, 0x8000
	s_addc_u32 s19, s19, 0
	s_waitcnt lgkmcnt(2)
	v_pk_fma_f32 v[16:17], v[142:143], v[16:17], v[188:189]
	v_pk_fma_f32 v[18:19], v[144:145], v[18:19], v[190:191]
	v_pk_fma_f32 v[20:21], v[146:147], v[20:21], v[192:193]
	v_pk_fma_f32 v[22:23], v[160:161], v[22:23], v[194:195]
	global_store_dwordx4 v168, v[16:19], s[18:19]
	global_store_dwordx4 v168, v[20:23], s[18:19] offset:16
	s_add_u32 s18, s18, 0x8000
	s_addc_u32 s19, s19, 0
	s_waitcnt lgkmcnt(0)
	v_pk_fma_f32 v[24:25], v[142:143], v[24:25], v[196:197]
	v_pk_fma_f32 v[26:27], v[144:145], v[26:27], v[198:199]
	v_pk_fma_f32 v[28:29], v[146:147], v[28:29], v[200:201]
	v_pk_fma_f32 v[30:31], v[160:161], v[30:31], v[202:203]
	global_store_dwordx4 v168, v[24:27], s[18:19]
	global_store_dwordx4 v168, v[28:31], s[18:19] offset:16
	s_add_u32 s18, s18, 0x8000
	s_addc_u32 s19, s19, 0
	ds_write_b32 v169, v32 offset:0
	ds_write_b32 v169, v33 offset:256
	ds_write_b32 v169, v34 offset:512
	ds_write_b32 v169, v35 offset:768
	ds_write_b32 v170, v36 offset:0
	ds_write_b32 v170, v37 offset:256
	ds_write_b32 v170, v38 offset:512
	ds_write_b32 v170, v39 offset:768
	ds_write_b32 v171, v40 offset:0
	ds_write_b32 v171, v41 offset:256
	ds_write_b32 v171, v42 offset:512
	ds_write_b32 v171, v43 offset:768
	ds_write_b32 v228, v44 offset:0
	ds_write_b32 v228, v45 offset:256
	ds_write_b32 v228, v46 offset:512
	ds_write_b32 v228, v47 offset:768
	ds_write_b32 v169, v48 offset:4096
	ds_write_b32 v169, v49 offset:4352
	ds_write_b32 v169, v50 offset:4608
	ds_write_b32 v169, v51 offset:4864
	ds_write_b32 v170, v52 offset:4096
	ds_write_b32 v170, v53 offset:4352
	ds_write_b32 v170, v54 offset:4608
	ds_write_b32 v170, v55 offset:4864
	ds_write_b32 v171, v56 offset:4096
	ds_write_b32 v171, v57 offset:4352
	ds_write_b32 v171, v58 offset:4608
	ds_write_b32 v171, v59 offset:4864
	ds_write_b32 v228, v60 offset:4096
	ds_write_b32 v228, v61 offset:4352
	ds_write_b32 v228, v62 offset:4608
	ds_write_b32 v228, v63 offset:4864
	s_waitcnt lgkmcnt(0)
	ds_read_b128 v[32:35], v220
	ds_read_b128 v[36:39], v220 offset:16
	ds_read_b128 v[40:43], v222
	ds_read_b128 v[44:47], v222 offset:16
	ds_read_b128 v[48:51], v224
	ds_read_b128 v[52:55], v224 offset:16
	ds_read_b128 v[56:59], v226
	ds_read_b128 v[60:63], v226 offset:16
	s_waitcnt vmcnt(14) lgkmcnt(6)
	v_pk_fma_f32 v[32:33], v[142:143], v[32:33], v[64:65]
	v_pk_fma_f32 v[34:35], v[144:145], v[34:35], v[66:67]
	v_pk_fma_f32 v[36:37], v[146:147], v[36:37], v[68:69]
	v_pk_fma_f32 v[38:39], v[160:161], v[38:39], v[70:71]
	global_store_dwordx4 v168, v[32:35], s[18:19]
	global_store_dwordx4 v168, v[36:39], s[18:19] offset:16
	s_add_u32 s18, s18, 0x8000
	s_addc_u32 s19, s19, 0
	s_waitcnt vmcnt(14) lgkmcnt(4)
	v_pk_fma_f32 v[40:41], v[142:143], v[40:41], v[72:73]
	v_pk_fma_f32 v[42:43], v[144:145], v[42:43], v[74:75]
	v_pk_fma_f32 v[44:45], v[146:147], v[44:45], v[76:77]
	v_pk_fma_f32 v[46:47], v[160:161], v[46:47], v[78:79]
	global_store_dwordx4 v168, v[40:43], s[18:19]
	global_store_dwordx4 v168, v[44:47], s[18:19] offset:16
	s_add_u32 s18, s18, 0x8000
	s_addc_u32 s19, s19, 0
	s_waitcnt vmcnt(14) lgkmcnt(2)
	v_pk_fma_f32 v[48:49], v[142:143], v[48:49], v[80:81]
	v_pk_fma_f32 v[50:51], v[144:145], v[50:51], v[82:83]
	v_pk_fma_f32 v[52:53], v[146:147], v[52:53], v[84:85]
	v_pk_fma_f32 v[54:55], v[160:161], v[54:55], v[86:87]
	global_store_dwordx4 v168, v[48:51], s[18:19]
	global_store_dwordx4 v168, v[52:55], s[18:19] offset:16
	s_add_u32 s18, s18, 0x8000
	s_addc_u32 s19, s19, 0
	s_waitcnt vmcnt(14) lgkmcnt(0)
	v_pk_fma_f32 v[56:57], v[142:143], v[56:57], v[88:89]
	v_pk_fma_f32 v[58:59], v[144:145], v[58:59], v[90:91]
	v_pk_fma_f32 v[60:61], v[146:147], v[60:61], v[92:93]
	v_pk_fma_f32 v[62:63], v[160:161], v[62:63], v[94:95]
	global_store_dwordx4 v168, v[56:59], s[18:19]
	global_store_dwordx4 v168, v[60:63], s[18:19] offset:16
	s_add_u32 s18, s18, 0x8000
	s_addc_u32 s19, s19, 0
	s_add_i32 s52, s52, s3
	s_cmpk_lt_i32 s52, 0x400
	s_cbranch_scc1 .Lmy_op1_tile
